# c18 + .p2align 6 in front of every MFMA loop head (64-byte I-cache line alignment of back-edge targets)
# baseline (speedup 1.0000x reference)
; #define PG8_STAGE(bufoff, gbase, voff) do { _Pragma("unroll") for (int _i = 0; _i < 2; ++_i) \
;         __builtin_amdgcn_global_load_lds((const unsigned*)((const char*)(gbase) + (voff)[_i]), (LAS unsigned*)(lds + (bufoff) + ldsw + _i * 8192), 16, 0, 0); } while (0)
; #define PG8_WAIT_V(n) asm volatile("s_waitcnt vmcnt(" #n ")" ::: "memory")
; #define PG8_BAR __builtin_amdgcn_s_barrier()
; #define PG8_TOUCH(p) asm volatile("global_load_dword %0, %1, off" : "+v"(pfd) : "v"(p) : "memory")
;     int tid = threadIdx.x; asm volatile("" : "+v"(tid));
;     const int wid = __builtin_amdgcn_readfirstlane(tid >> 6), lane = tid & 63, wr = wid >> 2, wc = wid & 3, fr = lane & 15, fq = lane >> 4;
;     const int K = g.K, nt = K / BK;
;     unsigned voffA[2], voffB[2];
; #pragma unroll
;     for (int i = 0; i < 2; ++i) { int R, C; stage_rc(tid * 16 + i * 8192, R, C); const int Rb = Epi::PERM ? ((R & ~31) + perm32(R & 31)) : R;
;         voffA[i] = (unsigned)(R * g.lda + C) * 2u; voffB[i] = (unsigned)(Rb * g.ldb + C) * 2u; }
;     const size_t kstep = (size_t)(BK * 2);
;     const size_t hstepA = (size_t)HALF * g.lda * 2, hstepB = (size_t)HALF * g.ldb * 2;
;     const unsigned ldsw = (unsigned)wid * 1024u;
;     const int aoff = lds_byte(wr * 64 + fr, fq * 8), boff = lds_byte(wc * 32 + fr, fq * 8);
;     ...
;     PG8_STAGE(PG8_SB(0, 0), cB, voffB); PG8_STAGE(PG8_SB(0, 1), cB + hstepB, voffB); PG8_STAGE(PG8_SA(0, 0), cA, voffA); PG8_STAGE(PG8_SA(0, 1), cA + hstepA, voffA);
;     if (wr == 1) PG8_BAR;
;     PG8_WAIT_V(2); PG8_BAR;
;     PG8_STAGE(PG8_SB(1, 0), cB + kstep, voffB); PG8_STAGE(PG8_SA(1, 0), cA + kstep, voffA); PG8_STAGE(PG8_SB(1, 1), cB + hstepB + kstep, voffB);
;     PG8_WAIT_V(6); PG8_BAR;
;     if constexpr (PF > 0) { const char* p0 = PG8_PFPTR(cA, cB) + (size_t)(2 + PF) * kstep; PG8_TOUCH(p0); }
;     for (;;) {
.LBB0_243:
	s_lshl_b32 s8, s8, 12
	s_lshl_b32 s4, s9, 13
	s_and_b32 s14, s8, 0x3000
	s_mov_b64 s[8:9], 0x80
	s_add_i32 m0, s29, 0x18000
	v_lshl_add_u64 v[8:9], v[8:9], 0, s[8:9]
	s_waitcnt vmcnt(2)
	s_barrier
	global_load_lds_dwordx4 v[8:9], off
	v_lshl_add_u64 v[6:7], v[6:7], 0, s[8:9]
	s_add_i32 m0, s29, 0x1a000
	s_add_i32 s65, s29, 0x8000
	s_add_i32 s76, s29, 0xa000
	global_load_lds_dwordx4 v[6:7], off
	v_lshl_add_u64 v[2:3], v[2:3], 0, s[8:9]
	s_mov_b32 m0, s65
	s_add_u32 s12, s66, 0x100080
	global_load_lds_dwordx4 v[2:3], off
	v_lshl_add_u64 v[2:3], v[4:5], 0, s[8:9]
	s_mov_b32 m0, s76
	s_addc_u32 s13, s67, 0
	global_load_lds_dwordx4 v[2:3], off
	s_add_i32 m0, s29, 0x1c000
	v_lshl_add_u64 v[2:3], s[12:13], 0, v[134:135]
	global_load_lds_dwordx4 v[2:3], off
	v_lshl_add_u64 v[2:3], s[12:13], 0, v[130:131]
	s_add_i32 m0, s29, 0x1e000
	v_and_b32_e32 v0, 15, v11
	global_load_lds_dwordx4 v[2:3], off
	v_and_b32_e32 v2, 48, v11
	v_lshlrev_b32_e32 v0, 6, v0
	v_lshlrev_b32_e32 v4, 2, v11
	v_or_b32_e32 v3, v0, v2
	v_and_b32_e32 v4, 32, v4
	v_bitop3_b32 v0, v0, v4, v2 bitop3:0x36
	v_bitop3_b32 v2, v3, s4, v4 bitop3:0xde
	v_lshlrev_b32_e32 v3, 16, v15
	v_and_b32_e32 v3, 0xfffe0000, v3
	v_lshl_add_u32 v3, v14, 13, v3
	v_and_b32_e32 v4, 1, v15
	v_lshl_or_b32 v3, v4, 6, v3
	v_lshl_add_u32 v138, v16, 1, v3
	v_lshlrev_b32_e32 v3, 16, v10
	s_cmpk_lt_u32 s1, 0x100
	v_and_b32_e32 v3, 0xfffe0000, v3
	v_or_b32_e32 v0, s14, v0
	s_waitcnt vmcnt(6)
	s_cselect_b64 s[12:13], -1, 0
	v_lshl_add_u32 v3, v12, 13, v3
	v_and_b32_e32 v4, 1, v10
	s_add_i32 s81, 0, 0x10000
	s_add_i32 s83, 0, 0x14000
	s_add_i32 s87, 0, 0x18000
	v_lshl_or_b32 v3, v4, 6, v3
	v_add_u32_e32 v146, s81, v0
	v_add_u32_e32 v147, s83, v0
	s_add_i32 s81, s81, s0
	s_add_i32 s83, s83, s0
	v_add_u32_e32 v149, s87, v0
	s_add_i32 s89, 0, 0x1c000
	s_add_i32 s87, s87, s0
	s_ashr_i32 s77, s3, 31
	v_mov_b32_e32 v139, v135
	v_lshl_add_u32 v140, v13, 1, v3
	v_mov_b32_e32 v141, v135
	v_mov_b64_e32 v[144:145], 0x157f
	v_add_u32_e32 v148, 0, v2
	s_add_i32 s78, s29, 0xc000
	s_add_i32 s79, s29, 0xe000
	s_mov_b64 s[18:19], 0x100
	s_mov_b64 s[30:31], 0x180
	s_movk_i32 s80, 0x5600
	s_add_i32 s82, s81, 0x2000
	s_add_i32 s86, s83, 0x2000
	v_add_u32_e32 v150, s89, v0
	s_add_i32 s88, s87, 0x2000
	s_add_i32 s89, s89, s0
	s_mov_b32 s90, 0
	s_barrier
	s_branch .LBB0_246
	.p2align	6
.LBB0_244:
	s_mov_b64 s[0:1], 0
	.p2align	6

;     __host__ __device__ bool next(int i, Unit& u) const { if (!StaticOrder::next(i >> 1, u)) return false; u.seg = i & 1; return true; }
;     ...
;         const bool has_next = S.next(ui + 1, nxt);
;         const char* nA = has_next ? PG8_APTR(nxt) : cA; const char* nB = has_next ? PG8_BPTR(nxt) : cB;
;         const char* pfc = PG8_PFPTR(cA, cB); const char* pfn = PG8_PFPTR(nA, nB);
;         PG8_KITER(0);
.LBB0_248:
	s_ashr_i32 s47, s46, 31
	ds_read_b128 v[2:5], v146
	ds_read_b128 v[6:9], v146 offset:1024
	ds_read_b128 v[10:13], v146 offset:2048
	ds_read_b128 v[14:17], v146 offset:3072
	ds_read_b128 v[18:21], v147
	ds_read_b128 v[22:25], v147 offset:1024
	ds_read_b128 v[26:29], v147 offset:2048
	ds_read_b128 v[30:33], v147 offset:3072
	s_lshl_b64 s[14:15], s[46:47], 21
	s_add_u32 s60, s36, s14
	s_addc_u32 s61, s37, s15
	s_and_b64 s[14:15], s[0:1], exec
	s_cselect_b32 s47, s61, s71
	s_cselect_b32 s93, s60, s70
	s_and_b32 s4, s91, 0x7fffffff
	s_lshl_b64 s[14:15], s[4:5], 21
	s_add_u32 s62, s96, s14
	s_addc_u32 s63, s97, s15
	s_and_b64 s[14:15], s[0:1], exec
	s_cselect_b32 s4, s63, s67
	s_cselect_b32 s94, s62, s66
	s_add_u32 s14, s70, 0x100080
	s_addc_u32 s15, s71, 0
	s_mov_b32 m0, s78
	v_lshl_add_u64 v[66:67], s[14:15], 0, v[136:137]
	ds_read_b128 v[34:37], v148
	ds_read_b128 v[38:41], v148 offset:1024
	ds_read_b128 v[42:45], v148 offset:2048
	ds_read_b128 v[46:49], v148 offset:3072
	ds_read_b128 v[50:53], v148 offset:4096
	ds_read_b128 v[54:57], v148 offset:5120
	ds_read_b128 v[58:61], v148 offset:6144
	ds_read_b128 v[62:65], v148 offset:7168
	global_load_lds_dwordx4 v[66:67], off
	v_lshl_add_u64 v[66:67], s[14:15], 0, v[132:133]
	s_mov_b32 m0, s79
	s_nop 0
	global_load_lds_dwordx4 v[66:67], off
	s_waitcnt vmcnt(8)
	s_waitcnt lgkmcnt(0)
	s_setprio 1
	s_barrier
	v_mfma_f32_16x16x32_bf16 v[90:93], v[2:5], v[58:61], 0
	v_mfma_f32_16x16x32_bf16 v[66:69], v[2:5], v[34:37], 0
	v_mfma_f32_16x16x32_bf16 v[70:73], v[10:13], v[34:37], 0
	v_mfma_f32_16x16x32_bf16 v[74:77], v[2:5], v[42:45], 0
	v_mfma_f32_16x16x32_bf16 v[78:81], v[10:13], v[42:45], 0
	v_mfma_f32_16x16x32_bf16 v[82:85], v[2:5], v[50:53], 0
	v_mfma_f32_16x16x32_bf16 v[86:89], v[10:13], v[50:53], 0
	v_mfma_f32_16x16x32_bf16 v[94:97], v[6:9], v[62:65], v[90:93]
	v_mfma_f32_16x16x32_bf16 v[90:93], v[10:13], v[58:61], 0
	v_mfma_f32_16x16x32_bf16 v[66:69], v[6:9], v[38:41], v[66:69]
	v_mfma_f32_16x16x32_bf16 v[70:73], v[14:17], v[38:41], v[70:73]
	v_mfma_f32_16x16x32_bf16 v[74:77], v[6:9], v[46:49], v[74:77]
	v_mfma_f32_16x16x32_bf16 v[78:81], v[14:17], v[46:49], v[78:81]
	v_mfma_f32_16x16x32_bf16 v[82:85], v[6:9], v[54:57], v[82:85]
	v_mfma_f32_16x16x32_bf16 v[86:89], v[14:17], v[54:57], v[86:89]
	v_mfma_f32_16x16x32_bf16 v[102:105], v[14:17], v[62:65], v[90:93]
	s_setprio 0
	s_setprio 1
	v_mfma_f32_16x16x32_bf16 v[90:93], v[18:21], v[34:37], 0
	v_mfma_f32_16x16x32_bf16 v[34:37], v[26:29], v[34:37], 0
	v_mfma_f32_16x16x32_bf16 v[110:113], v[22:25], v[38:41], v[90:93]
	v_mfma_f32_16x16x32_bf16 v[34:37], v[30:33], v[38:41], v[34:37]
	v_mfma_f32_16x16x32_bf16 v[38:41], v[18:21], v[42:45], 0
	v_mfma_f32_16x16x32_bf16 v[42:45], v[26:29], v[42:45], 0
	v_mfma_f32_16x16x32_bf16 v[38:41], v[22:25], v[46:49], v[38:41]
	v_mfma_f32_16x16x32_bf16 v[42:45], v[30:33], v[46:49], v[42:45]
	v_mfma_f32_16x16x32_bf16 v[46:49], v[18:21], v[50:53], 0
	v_mfma_f32_16x16x32_bf16 v[50:53], v[26:29], v[50:53], 0
	v_mfma_f32_16x16x32_bf16 v[46:49], v[22:25], v[54:57], v[46:49]
	v_mfma_f32_16x16x32_bf16 v[50:53], v[30:33], v[54:57], v[50:53]
	v_mfma_f32_16x16x32_bf16 v[54:57], v[18:21], v[58:61], 0
	v_mfma_f32_16x16x32_bf16 v[58:61], v[26:29], v[58:61], 0
	v_mfma_f32_16x16x32_bf16 v[54:57], v[22:25], v[62:65], v[54:57]
	v_mfma_f32_16x16x32_bf16 v[62:65], v[30:33], v[62:65], v[58:61]
	s_barrier
	s_setprio 0
	v_lshl_add_u64 v[248:249], s[66:67], 0, v[134:135]
	s_mov_b32 m0, s81
	v_lshl_add_u64 v[152:153], v[248:249], 0, s[18:19]
	v_lshl_add_u64 v[250:251], s[66:67], 0, v[130:131]
	s_add_u32 s14, s66, 0x100100
	ds_read_b128 v[58:61], v148 offset:16384
	ds_read_b128 v[90:93], v148 offset:17408
	ds_read_b128 v[98:101], v148 offset:18432
	ds_read_b128 v[106:109], v148 offset:19456
	ds_read_b128 v[114:117], v148 offset:20480
	ds_read_b128 v[118:121], v148 offset:21504
	ds_read_b128 v[122:125], v148 offset:22528
	ds_read_b128 v[126:129], v148 offset:23552
	global_load_lds_dwordx4 v[152:153], off
	v_lshl_add_u64 v[152:153], v[250:251], 0, s[18:19]
	s_mov_b32 m0, s82
	s_addc_u32 s15, s67, 0
	global_load_lds_dwordx4 v[152:153], off
	v_lshl_add_u64 v[152:153], s[14:15], 0, v[134:135]
	s_mov_b32 m0, s83
	v_lshl_add_u64 v[252:253], s[70:71], 0, v[136:137]
	global_load_lds_dwordx4 v[152:153], off
	v_lshl_add_u64 v[152:153], s[14:15], 0, v[130:131]
	s_mov_b32 m0, s86
	v_lshl_add_u64 v[142:143], s[70:71], 0, v[132:133]
	global_load_lds_dwordx4 v[152:153], off
	v_lshl_add_u64 v[152:153], v[252:253], 0, s[18:19]
	s_mov_b32 m0, s29
	s_nop 0
	global_load_lds_dwordx4 v[152:153], off
	v_lshl_add_u64 v[152:153], v[142:143], 0, s[18:19]
	s_mov_b32 m0, s33
	s_nop 0
	global_load_lds_dwordx4 v[152:153], off
	s_waitcnt vmcnt(8)
	s_waitcnt lgkmcnt(0)
	s_setprio 1
	s_barrier
	v_mfma_f32_16x16x32_bf16 v[152:155], v[2:5], v[58:61], 0
	v_mfma_f32_16x16x32_bf16 v[160:163], v[2:5], v[98:101], 0
	v_mfma_f32_16x16x32_bf16 v[168:171], v[2:5], v[114:117], 0
	v_mfma_f32_16x16x32_bf16 v[2:5], v[2:5], v[122:125], 0
	v_mfma_f32_16x16x32_bf16 v[152:155], v[6:9], v[90:93], v[152:155]
	v_mfma_f32_16x16x32_bf16 v[160:163], v[6:9], v[106:109], v[160:163]
	v_mfma_f32_16x16x32_bf16 v[168:171], v[6:9], v[118:121], v[168:171]
	v_mfma_f32_16x16x32_bf16 v[2:5], v[6:9], v[126:129], v[2:5]
	v_mfma_f32_16x16x32_bf16 v[6:9], v[10:13], v[122:125], 0
	v_mfma_f32_16x16x32_bf16 v[156:159], v[10:13], v[58:61], 0
	v_mfma_f32_16x16x32_bf16 v[164:167], v[10:13], v[98:101], 0
	v_mfma_f32_16x16x32_bf16 v[172:175], v[10:13], v[114:117], 0
	v_mfma_f32_16x16x32_bf16 v[6:9], v[14:17], v[126:129], v[6:9]
	v_mfma_f32_16x16x32_bf16 v[156:159], v[14:17], v[90:93], v[156:159]
	v_mfma_f32_16x16x32_bf16 v[164:167], v[14:17], v[106:109], v[164:167]
	v_mfma_f32_16x16x32_bf16 v[172:175], v[14:17], v[118:121], v[172:175]
	s_setprio 0
	s_setprio 1
	v_mfma_f32_16x16x32_bf16 v[10:13], v[18:21], v[58:61], 0
	v_mfma_f32_16x16x32_bf16 v[14:17], v[22:25], v[90:93], v[10:13]
	v_mfma_f32_16x16x32_bf16 v[10:13], v[26:29], v[58:61], 0
	v_mfma_f32_16x16x32_bf16 v[176:179], v[30:33], v[90:93], v[10:13]
	v_mfma_f32_16x16x32_bf16 v[10:13], v[18:21], v[98:101], 0
	v_mfma_f32_16x16x32_bf16 v[180:183], v[22:25], v[106:109], v[10:13]
	v_mfma_f32_16x16x32_bf16 v[10:13], v[26:29], v[98:101], 0
	v_mfma_f32_16x16x32_bf16 v[184:187], v[30:33], v[106:109], v[10:13]
	v_mfma_f32_16x16x32_bf16 v[10:13], v[18:21], v[114:117], 0
	v_mfma_f32_16x16x32_bf16 v[188:191], v[22:25], v[118:121], v[10:13]
	v_mfma_f32_16x16x32_bf16 v[10:13], v[26:29], v[114:117], 0
	v_mfma_f32_16x16x32_bf16 v[192:195], v[30:33], v[118:121], v[10:13]
	v_mfma_f32_16x16x32_bf16 v[10:13], v[18:21], v[122:125], 0
	v_mfma_f32_16x16x32_bf16 v[196:199], v[22:25], v[126:129], v[10:13]
	v_mfma_f32_16x16x32_bf16 v[10:13], v[26:29], v[122:125], 0
	v_mfma_f32_16x16x32_bf16 v[200:203], v[30:33], v[126:129], v[10:13]
	s_barrier
	s_setprio 0
	s_nop 4
	ds_read_b128 v[10:13], v149
	ds_read_b128 v[22:25], v149 offset:1024
	ds_read_b128 v[30:33], v149 offset:2048
	ds_read_b128 v[204:207], v149 offset:3072
	ds_read_b128 v[208:211], v150
	ds_read_b128 v[212:215], v150 offset:1024
	ds_read_b128 v[216:219], v150 offset:2048
	ds_read_b128 v[220:223], v150 offset:3072
	s_add_u32 s14, s70, 0x100100
	s_addc_u32 s15, s71, 0
	s_mov_b32 m0, s58
	v_lshl_add_u64 v[58:59], s[14:15], 0, v[136:137]
	ds_read_b128 v[18:21], v148 offset:32768
	ds_read_b128 v[26:29], v148 offset:33792
	ds_read_b128 v[224:227], v148 offset:34816
	ds_read_b128 v[228:231], v148 offset:35840
	ds_read_b128 v[232:235], v148 offset:36864
	ds_read_b128 v[236:239], v148 offset:37888
	ds_read_b128 v[240:243], v148 offset:38912
	ds_read_b128 v[244:247], v148 offset:39936
	global_load_lds_dwordx4 v[58:59], off
	v_lshl_add_u64 v[58:59], s[14:15], 0, v[132:133]
	s_mov_b32 m0, s59
	s_nop 0
	global_load_lds_dwordx4 v[58:59], off
	s_waitcnt vmcnt(8)
	s_waitcnt lgkmcnt(0)
	s_setprio 1
	s_barrier
	v_mfma_f32_16x16x32_bf16 v[58:61], v[10:13], v[18:21], v[66:69]
	v_mfma_f32_16x16x32_bf16 v[122:125], v[22:25], v[26:29], v[58:61]
	v_mfma_f32_16x16x32_bf16 v[58:61], v[30:33], v[18:21], v[70:73]
	v_mfma_f32_16x16x32_bf16 v[114:117], v[204:207], v[26:29], v[58:61]
	v_mfma_f32_16x16x32_bf16 v[58:61], v[10:13], v[224:227], v[74:77]
	v_mfma_f32_16x16x32_bf16 v[106:109], v[22:25], v[228:231], v[58:61]
	v_mfma_f32_16x16x32_bf16 v[58:61], v[30:33], v[224:227], v[78:81]
	v_mfma_f32_16x16x32_bf16 v[98:101], v[204:207], v[228:231], v[58:61]
	v_mfma_f32_16x16x32_bf16 v[58:61], v[10:13], v[232:235], v[82:85]
	v_mfma_f32_16x16x32_bf16 v[90:93], v[22:25], v[236:239], v[58:61]
	v_mfma_f32_16x16x32_bf16 v[58:61], v[30:33], v[232:235], v[86:89]
	v_mfma_f32_16x16x32_bf16 v[82:85], v[204:207], v[236:239], v[58:61]
	v_mfma_f32_16x16x32_bf16 v[58:61], v[10:13], v[240:243], v[94:97]
	v_mfma_f32_16x16x32_bf16 v[74:77], v[22:25], v[244:247], v[58:61]
	v_mfma_f32_16x16x32_bf16 v[58:61], v[30:33], v[240:243], v[102:105]
	v_mfma_f32_16x16x32_bf16 v[58:61], v[204:207], v[244:247], v[58:61]
	s_setprio 0
	s_setprio 1
	v_mfma_f32_16x16x32_bf16 v[66:69], v[208:211], v[18:21], v[110:113]
	v_mfma_f32_16x16x32_bf16 v[18:21], v[216:219], v[18:21], v[34:37]
	v_mfma_f32_16x16x32_bf16 v[118:121], v[220:223], v[26:29], v[18:21]
	v_mfma_f32_16x16x32_bf16 v[18:21], v[208:211], v[224:227], v[38:41]
	v_mfma_f32_16x16x32_bf16 v[110:113], v[212:215], v[228:231], v[18:21]
	v_mfma_f32_16x16x32_bf16 v[18:21], v[216:219], v[224:227], v[42:45]
	v_mfma_f32_16x16x32_bf16 v[102:105], v[220:223], v[228:231], v[18:21]
	v_mfma_f32_16x16x32_bf16 v[18:21], v[208:211], v[232:235], v[46:49]
	v_mfma_f32_16x16x32_bf16 v[94:97], v[212:215], v[236:239], v[18:21]
	v_mfma_f32_16x16x32_bf16 v[18:21], v[216:219], v[232:235], v[50:53]
	v_mfma_f32_16x16x32_bf16 v[86:89], v[220:223], v[236:239], v[18:21]
	v_mfma_f32_16x16x32_bf16 v[18:21], v[208:211], v[240:243], v[54:57]
	v_mfma_f32_16x16x32_bf16 v[78:81], v[212:215], v[244:247], v[18:21]
	v_mfma_f32_16x16x32_bf16 v[18:21], v[216:219], v[240:243], v[62:65]
	v_mfma_f32_16x16x32_bf16 v[126:129], v[212:215], v[26:29], v[66:69]
	v_mfma_f32_16x16x32_bf16 v[66:69], v[220:223], v[244:247], v[18:21]
	s_barrier
;     ...
;         for (int t = 2; t < nt; t += 2) PG8_KITER(t);
	s_setprio 0
	s_mov_b32 m0, s87
	s_nop 2
	v_lshl_add_u64 v[18:19], v[248:249], 0, s[30:31]
	s_add_u32 s14, s66, 0x100180
	ds_read_b128 v[38:41], v148 offset:49152
	ds_read_b128 v[46:49], v148 offset:50176
	ds_read_b128 v[224:227], v148 offset:51200
	ds_read_b128 v[228:231], v148 offset:52224
	ds_read_b128 v[232:235], v148 offset:53248
	ds_read_b128 v[236:239], v148 offset:54272
	ds_read_b128 v[240:243], v148 offset:55296
	ds_read_b128 v[244:247], v148 offset:56320
	global_load_lds_dwordx4 v[18:19], off
	v_lshl_add_u64 v[18:19], v[250:251], 0, s[30:31]
	s_mov_b32 m0, s88
	s_addc_u32 s15, s67, 0
	global_load_lds_dwordx4 v[18:19], off
	v_lshl_add_u64 v[18:19], s[14:15], 0, v[134:135]
	s_mov_b32 m0, s89
	s_add_i32 s56, s89, 0x2000
	global_load_lds_dwordx4 v[18:19], off
	v_lshl_add_u64 v[18:19], s[14:15], 0, v[130:131]
	s_mov_b32 m0, s56
	s_nop 0
	global_load_lds_dwordx4 v[18:19], off
	v_lshl_add_u64 v[18:19], v[252:253], 0, s[30:31]
	s_mov_b32 m0, s65
	s_nop 0
	global_load_lds_dwordx4 v[18:19], off
	v_lshl_add_u64 v[18:19], v[142:143], 0, s[30:31]
	s_mov_b32 m0, s76
	s_nop 0
	global_load_lds_dwordx4 v[18:19], off
	s_waitcnt vmcnt(8)
	s_waitcnt lgkmcnt(0)
	s_setprio 1
	s_barrier
	v_mfma_f32_16x16x32_bf16 v[18:21], v[10:13], v[38:41], v[152:155]
	v_mfma_f32_16x16x32_bf16 v[62:65], v[22:25], v[46:49], v[18:21]
	v_mfma_f32_16x16x32_bf16 v[18:21], v[30:33], v[38:41], v[156:159]
	v_mfma_f32_16x16x32_bf16 v[50:53], v[204:207], v[46:49], v[18:21]
	v_mfma_f32_16x16x32_bf16 v[18:21], v[10:13], v[224:227], v[160:163]
	v_mfma_f32_16x16x32_bf16 v[42:45], v[22:25], v[228:231], v[18:21]
	v_mfma_f32_16x16x32_bf16 v[18:21], v[30:33], v[224:227], v[164:167]
	v_mfma_f32_16x16x32_bf16 v[34:37], v[204:207], v[228:231], v[18:21]
	v_mfma_f32_16x16x32_bf16 v[18:21], v[10:13], v[232:235], v[168:171]
	v_mfma_f32_16x16x32_bf16 v[2:5], v[10:13], v[240:243], v[2:5]
	v_mfma_f32_16x16x32_bf16 v[26:29], v[22:25], v[236:239], v[18:21]
	v_mfma_f32_16x16x32_bf16 v[18:21], v[30:33], v[232:235], v[172:175]
	v_mfma_f32_16x16x32_bf16 v[10:13], v[22:25], v[244:247], v[2:5]
	v_mfma_f32_16x16x32_bf16 v[2:5], v[30:33], v[240:243], v[6:9]
	v_mfma_f32_16x16x32_bf16 v[18:21], v[204:207], v[236:239], v[18:21]
	v_mfma_f32_16x16x32_bf16 v[2:5], v[204:207], v[244:247], v[2:5]
	s_setprio 0
	s_setprio 1
	v_mfma_f32_16x16x32_bf16 v[6:9], v[208:211], v[38:41], v[14:17]
	v_mfma_f32_16x16x32_bf16 v[70:73], v[212:215], v[46:49], v[6:9]
	v_mfma_f32_16x16x32_bf16 v[6:9], v[216:219], v[38:41], v[176:179]
	v_mfma_f32_16x16x32_bf16 v[54:57], v[220:223], v[46:49], v[6:9]
	v_mfma_f32_16x16x32_bf16 v[6:9], v[208:211], v[224:227], v[180:183]
	v_mfma_f32_16x16x32_bf16 v[46:49], v[212:215], v[228:231], v[6:9]
	v_mfma_f32_16x16x32_bf16 v[6:9], v[216:219], v[224:227], v[184:187]
	v_mfma_f32_16x16x32_bf16 v[38:41], v[220:223], v[228:231], v[6:9]
	v_mfma_f32_16x16x32_bf16 v[6:9], v[208:211], v[232:235], v[188:191]
	v_mfma_f32_16x16x32_bf16 v[30:33], v[212:215], v[236:239], v[6:9]
	v_mfma_f32_16x16x32_bf16 v[6:9], v[216:219], v[232:235], v[192:195]
	v_mfma_f32_16x16x32_bf16 v[22:25], v[220:223], v[236:239], v[6:9]
	v_mfma_f32_16x16x32_bf16 v[6:9], v[208:211], v[240:243], v[196:199]
	v_mfma_f32_16x16x32_bf16 v[14:17], v[212:215], v[244:247], v[6:9]
	v_mfma_f32_16x16x32_bf16 v[6:9], v[216:219], v[240:243], v[200:203]
	v_mfma_f32_16x16x32_bf16 v[6:9], v[220:223], v[244:247], v[6:9]
	s_barrier
	s_setprio 0
	s_add_u32 s70, s70, 0x100180
	s_addc_u32 s71, s71, 0
	s_add_u32 s57, s66, 0x200
	s_addc_u32 s14, s67, 0
	s_mov_b32 s15, 0
	.p2align	6

; #define PG8_STAGE(bufoff, gbase, voff) do { _Pragma("unroll") for (int _i = 0; _i < 2; ++_i) \
;         __builtin_amdgcn_global_load_lds((const unsigned*)((const char*)(gbase) + (voff)[_i]), (LAS unsigned*)(lds + (bufoff) + ldsw + _i * 8192), 16, 0, 0); } while (0)
; #define PG8_WAIT_V(n) asm volatile("s_waitcnt vmcnt(" #n ")" ::: "memory")
; #define PG8_BAR __builtin_amdgcn_s_barrier()
; #define PG8_TOUCH(p) asm volatile("global_load_dword %0, %1, off" : "+v"(pfd) : "v"(p) : "memory")
;     int tid = threadIdx.x; asm volatile("" : "+v"(tid));
;     const int wid = __builtin_amdgcn_readfirstlane(tid >> 6), lane = tid & 63, wr = wid >> 2, wc = wid & 3, fr = lane & 15, fq = lane >> 4;
;     const int K = g.K, nt = K / BK;
;     unsigned voffA[2], voffB[2];
; #pragma unroll
;     for (int i = 0; i < 2; ++i) { int R, C; stage_rc(tid * 16 + i * 8192, R, C); const int Rb = Epi::PERM ? ((R & ~31) + perm32(R & 31)) : R;
;         voffA[i] = (unsigned)(R * g.lda + C) * 2u; voffB[i] = (unsigned)(Rb * g.ldb + C) * 2u; }
;     const size_t kstep = (size_t)(BK * 2);
;     const size_t hstepA = (size_t)HALF * g.lda * 2, hstepB = (size_t)HALF * g.ldb * 2;
;     const unsigned ldsw = (unsigned)wid * 1024u;
;     const int aoff = lds_byte(wr * 64 + fr, fq * 8), boff = lds_byte(wc * 32 + fr, fq * 8);
;     ...
;     PG8_STAGE(PG8_SB(0, 0), cB, voffB); PG8_STAGE(PG8_SB(0, 1), cB + hstepB, voffB); PG8_STAGE(PG8_SA(0, 0), cA, voffA); PG8_STAGE(PG8_SA(0, 1), cA + hstepA, voffA);
;     if (wr == 1) PG8_BAR;
;     PG8_WAIT_V(2); PG8_BAR;
;     PG8_STAGE(PG8_SB(1, 0), cB + kstep, voffB); PG8_STAGE(PG8_SA(1, 0), cA + kstep, voffA); PG8_STAGE(PG8_SB(1, 1), cB + hstepB + kstep, voffB);
;     PG8_WAIT_V(6); PG8_BAR;
;     if constexpr (PF > 0) { const char* p0 = PG8_PFPTR(cA, cB) + (size_t)(2 + PF) * kstep; PG8_TOUCH(p0); }
;     for (;;) {
.LBB0_317:
	s_mov_b64 s[18:19], 0x80
	s_lshl_b32 s1, s1, 12
	s_add_i32 m0, s11, 0x18000
	v_lshl_add_u64 v[8:9], v[8:9], 0, s[18:19]
	s_lshl_b32 s15, s4, 13
	s_and_b32 s1, s1, 0x3000
	s_waitcnt vmcnt(2)
	s_barrier
	global_load_lds_dwordx4 v[8:9], off
	v_lshl_add_u64 v[6:7], v[6:7], 0, s[18:19]
	s_add_i32 m0, s11, 0x1a000
	s_add_i32 s58, s11, 0x8000
	s_add_i32 s59, s11, 0xa000
	global_load_lds_dwordx4 v[6:7], off
	v_lshl_add_u64 v[2:3], v[2:3], 0, s[18:19]
	s_mov_b32 m0, s58
	s_add_u32 s4, s70, 0x2b0080
	global_load_lds_dwordx4 v[2:3], off
	v_lshl_add_u64 v[2:3], v[4:5], 0, s[18:19]
	s_mov_b32 m0, s59
	s_addc_u32 s5, s71, 0
	global_load_lds_dwordx4 v[2:3], off
	s_add_i32 m0, s11, 0x1c000
	v_lshl_add_u64 v[2:3], s[4:5], 0, v[180:181]
	global_load_lds_dwordx4 v[2:3], off
	v_lshl_add_u64 v[2:3], s[4:5], 0, v[184:185]
	s_add_i32 m0, s11, 0x1e000
	v_and_b32_e32 v0, 15, v10
	global_load_lds_dwordx4 v[2:3], off
	v_lshlrev_b32_e32 v4, 2, v10
	v_and_b32_e32 v2, 48, v10
	v_lshlrev_b32_e32 v0, 6, v0
	v_and_b32_e32 v4, 32, v4
	v_or_b32_e32 v3, v0, v2
	v_bitop3_b32 v0, v0, v4, v2 bitop3:0x36
	v_or_b32_e32 v206, s1, v0
	v_lshrrev_b32_e32 v0, 1, v11
	v_mul_lo_u32 v2, v13, s0
	s_mov_b32 s1, 0x2b000
	v_bitop3_b32 v4, v3, s15, v4 bitop3:0xde
	v_mad_u64_u32 v[2:3], s[4:5], v0, s1, v[2:3]
	v_or_b32_e32 v0, v2, v12
	v_add_lshl_u32 v2, v0, v14, 1
	v_mov_b32_e32 v3, v181
	s_mov_b64 s[4:5], 0x2b0180
	v_lshl_add_u64 v[186:187], v[2:3], 0, s[4:5]
	v_lshrrev_b32_e32 v0, 1, v15
	v_mul_lo_u32 v2, v16, s0
	v_mad_u64_u32 v[2:3], s[0:1], v0, s1, v[2:3]
	s_waitcnt vmcnt(6)
	s_cmpk_lt_u32 s14, 0x100
	v_or_b32_e32 v0, v2, v17
	s_cselect_b64 s[30:31], -1, 0
	v_add_lshl_u32 v2, v0, v18, 1
	v_mov_b32_e32 v3, v181
	s_add_i32 s78, 0, 0x10000
	s_add_i32 s79, 0, 0x14000
	s_ashr_i32 s76, s3, 31
	s_ashr_i32 s77, s2, 31
	v_lshl_add_u64 v[188:189], v[2:3], 0, s[4:5]
	v_mov_b64_e32 v[192:193], 0x3ff
	v_add_u32_e32 v207, s78, v206
	v_add_u32_e32 v208, s79, v206
	v_add_u32_e32 v209, 0, v4
	s_mov_b64 s[60:61], 0x100
	s_mov_b64 s[62:63], 0x180
	s_barrier
	s_branch .LBB0_320
	.p2align	6
.LBB0_318:
	s_mov_b64 s[4:5], 0
	.p2align	6

.LBB0_330:
	ds_read_b128 v[2:5], v207
	ds_read_b128 v[6:9], v207 offset:1024
	ds_read_b128 v[10:13], v207 offset:2048
	ds_read_b128 v[14:17], v207 offset:3072
	ds_read_b128 v[18:21], v208
	ds_read_b128 v[22:25], v208 offset:1024
	ds_read_b128 v[26:29], v208 offset:2048
	ds_read_b128 v[30:33], v208 offset:3072
	s_add_u32 s14, s66, 0x2b0080
	s_addc_u32 s15, s67, 0
	s_add_i32 s86, s11, 0xc000
	v_lshl_add_u64 v[66:67], s[14:15], 0, v[178:179]
	s_mov_b32 m0, s86
	s_add_i32 s87, s11, 0xe000
	ds_read_b128 v[34:37], v209
	ds_read_b128 v[38:41], v209 offset:1024
	ds_read_b128 v[42:45], v209 offset:2048
	ds_read_b128 v[46:49], v209 offset:3072
	ds_read_b128 v[50:53], v209 offset:4096
	ds_read_b128 v[54:57], v209 offset:5120
	ds_read_b128 v[58:61], v209 offset:6144
	ds_read_b128 v[62:65], v209 offset:7168
	global_load_lds_dwordx4 v[66:67], off
	v_lshl_add_u64 v[66:67], s[14:15], 0, v[182:183]
	s_mov_b32 m0, s87
	s_nop 0
	global_load_lds_dwordx4 v[66:67], off
	s_waitcnt vmcnt(8)
	s_waitcnt lgkmcnt(0)
	s_setprio 1
	s_barrier
	v_mfma_f32_16x16x32_bf16 v[90:93], v[2:5], v[58:61], 0
	v_mfma_f32_16x16x32_bf16 v[66:69], v[2:5], v[34:37], 0
	v_mfma_f32_16x16x32_bf16 v[70:73], v[10:13], v[34:37], 0
	v_mfma_f32_16x16x32_bf16 v[74:77], v[2:5], v[42:45], 0
	v_mfma_f32_16x16x32_bf16 v[78:81], v[10:13], v[42:45], 0
	v_mfma_f32_16x16x32_bf16 v[82:85], v[2:5], v[50:53], 0
	v_mfma_f32_16x16x32_bf16 v[86:89], v[10:13], v[50:53], 0
	v_mfma_f32_16x16x32_bf16 v[98:101], v[6:9], v[62:65], v[90:93]
	v_mfma_f32_16x16x32_bf16 v[90:93], v[10:13], v[58:61], 0
	v_mfma_f32_16x16x32_bf16 v[66:69], v[6:9], v[38:41], v[66:69]
	v_mfma_f32_16x16x32_bf16 v[70:73], v[14:17], v[38:41], v[70:73]
	v_mfma_f32_16x16x32_bf16 v[74:77], v[6:9], v[46:49], v[74:77]
	v_mfma_f32_16x16x32_bf16 v[78:81], v[14:17], v[46:49], v[78:81]
	v_mfma_f32_16x16x32_bf16 v[82:85], v[6:9], v[54:57], v[82:85]
	v_mfma_f32_16x16x32_bf16 v[86:89], v[14:17], v[54:57], v[86:89]
	v_mfma_f32_16x16x32_bf16 v[102:105], v[14:17], v[62:65], v[90:93]
	s_setprio 0
	s_setprio 1
	v_mfma_f32_16x16x32_bf16 v[90:93], v[18:21], v[34:37], 0
	v_mfma_f32_16x16x32_bf16 v[34:37], v[26:29], v[34:37], 0
	v_mfma_f32_16x16x32_bf16 v[114:117], v[22:25], v[38:41], v[90:93]
	v_mfma_f32_16x16x32_bf16 v[34:37], v[30:33], v[38:41], v[34:37]
	v_mfma_f32_16x16x32_bf16 v[38:41], v[18:21], v[42:45], 0
	v_mfma_f32_16x16x32_bf16 v[42:45], v[26:29], v[42:45], 0
	v_mfma_f32_16x16x32_bf16 v[38:41], v[22:25], v[46:49], v[38:41]
	v_mfma_f32_16x16x32_bf16 v[42:45], v[30:33], v[46:49], v[42:45]
	v_mfma_f32_16x16x32_bf16 v[46:49], v[18:21], v[50:53], 0
	v_mfma_f32_16x16x32_bf16 v[50:53], v[26:29], v[50:53], 0
	v_mfma_f32_16x16x32_bf16 v[46:49], v[22:25], v[54:57], v[46:49]
	v_mfma_f32_16x16x32_bf16 v[50:53], v[30:33], v[54:57], v[50:53]
	v_mfma_f32_16x16x32_bf16 v[54:57], v[18:21], v[58:61], 0
	v_mfma_f32_16x16x32_bf16 v[58:61], v[26:29], v[58:61], 0
	v_mfma_f32_16x16x32_bf16 v[54:57], v[22:25], v[62:65], v[54:57]
	v_mfma_f32_16x16x32_bf16 v[58:61], v[30:33], v[62:65], v[58:61]
	s_barrier
	s_setprio 0
	s_add_i32 s88, s78, s10
	v_lshl_add_u64 v[176:177], s[70:71], 0, v[180:181]
	s_add_i32 s84, s88, 0x2000
	v_lshl_add_u64 v[130:131], v[176:177], 0, s[60:61]
	s_mov_b32 m0, s88
	v_lshl_add_u64 v[250:251], s[70:71], 0, v[184:185]
	s_add_u32 s14, s70, 0x2b0100
	ds_read_b128 v[62:65], v209 offset:16384
	ds_read_b128 v[90:93], v209 offset:17408
	ds_read_b128 v[94:97], v209 offset:18432
	ds_read_b128 v[106:109], v209 offset:19456
	ds_read_b128 v[110:113], v209 offset:20480
	ds_read_b128 v[118:121], v209 offset:21504
	ds_read_b128 v[122:125], v209 offset:22528
	ds_read_b128 v[126:129], v209 offset:23552
	global_load_lds_dwordx4 v[130:131], off
	v_lshl_add_u64 v[130:131], v[250:251], 0, s[60:61]
	s_mov_b32 m0, s84
	s_addc_u32 s15, s71, 0
	s_add_i32 s85, s79, s10
	global_load_lds_dwordx4 v[130:131], off
	v_lshl_add_u64 v[130:131], s[14:15], 0, v[180:181]
	s_mov_b32 m0, s85
	s_add_i32 s46, s85, 0x2000
	global_load_lds_dwordx4 v[130:131], off
	v_lshl_add_u64 v[130:131], s[14:15], 0, v[184:185]
	s_mov_b32 m0, s46
	v_lshl_add_u64 v[252:253], s[66:67], 0, v[178:179]
	global_load_lds_dwordx4 v[130:131], off
	v_lshl_add_u64 v[130:131], v[252:253], 0, s[60:61]
	s_mov_b32 m0, s11
	v_lshl_add_u64 v[190:191], s[66:67], 0, v[182:183]
	global_load_lds_dwordx4 v[130:131], off
	v_lshl_add_u64 v[130:131], v[190:191], 0, s[60:61]
	s_mov_b32 m0, s12
	s_nop 0
	global_load_lds_dwordx4 v[130:131], off
	s_waitcnt vmcnt(8)
	s_waitcnt lgkmcnt(0)
	s_setprio 1
	s_barrier
	v_mfma_f32_16x16x32_bf16 v[130:133], v[2:5], v[62:65], 0
	v_mfma_f32_16x16x32_bf16 v[140:143], v[2:5], v[94:97], 0
	v_mfma_f32_16x16x32_bf16 v[148:151], v[2:5], v[110:113], 0
	v_mfma_f32_16x16x32_bf16 v[2:5], v[2:5], v[122:125], 0
	v_mfma_f32_16x16x32_bf16 v[132:135], v[6:9], v[90:93], v[130:133]
	v_mfma_f32_16x16x32_bf16 v[140:143], v[6:9], v[106:109], v[140:143]
	v_mfma_f32_16x16x32_bf16 v[148:151], v[6:9], v[118:121], v[148:151]
	v_mfma_f32_16x16x32_bf16 v[2:5], v[6:9], v[126:129], v[2:5]
	v_mfma_f32_16x16x32_bf16 v[6:9], v[10:13], v[122:125], 0
	v_mfma_f32_16x16x32_bf16 v[136:139], v[10:13], v[62:65], 0
	v_mfma_f32_16x16x32_bf16 v[144:147], v[10:13], v[94:97], 0
	v_mfma_f32_16x16x32_bf16 v[152:155], v[10:13], v[110:113], 0
	v_mfma_f32_16x16x32_bf16 v[6:9], v[14:17], v[126:129], v[6:9]
	v_mfma_f32_16x16x32_bf16 v[136:139], v[14:17], v[90:93], v[136:139]
	v_mfma_f32_16x16x32_bf16 v[144:147], v[14:17], v[106:109], v[144:147]
	v_mfma_f32_16x16x32_bf16 v[152:155], v[14:17], v[118:121], v[152:155]
	s_setprio 0
	s_setprio 1
	v_mfma_f32_16x16x32_bf16 v[10:13], v[18:21], v[62:65], 0
	v_mfma_f32_16x16x32_bf16 v[156:159], v[22:25], v[90:93], v[10:13]
	v_mfma_f32_16x16x32_bf16 v[10:13], v[26:29], v[62:65], 0
	v_mfma_f32_16x16x32_bf16 v[160:163], v[30:33], v[90:93], v[10:13]
	v_mfma_f32_16x16x32_bf16 v[10:13], v[18:21], v[94:97], 0
	v_mfma_f32_16x16x32_bf16 v[164:167], v[22:25], v[106:109], v[10:13]
	v_mfma_f32_16x16x32_bf16 v[10:13], v[26:29], v[94:97], 0
	v_mfma_f32_16x16x32_bf16 v[168:171], v[30:33], v[106:109], v[10:13]
	v_mfma_f32_16x16x32_bf16 v[10:13], v[18:21], v[110:113], 0
	v_mfma_f32_16x16x32_bf16 v[172:175], v[22:25], v[118:121], v[10:13]
	v_mfma_f32_16x16x32_bf16 v[10:13], v[26:29], v[110:113], 0
	v_mfma_f32_16x16x32_bf16 v[194:197], v[30:33], v[118:121], v[10:13]
	v_mfma_f32_16x16x32_bf16 v[10:13], v[18:21], v[122:125], 0
	v_mfma_f32_16x16x32_bf16 v[198:201], v[22:25], v[126:129], v[10:13]
	v_mfma_f32_16x16x32_bf16 v[10:13], v[26:29], v[122:125], 0
	v_mfma_f32_16x16x32_bf16 v[202:205], v[30:33], v[126:129], v[10:13]
	s_barrier
;     ...
;         for (int t = 2; t < nt; t += 2) PG8_KITER(t);
	s_setprio 0
	s_add_i32 s47, 0, 0x18000
	s_add_i32 s56, 0, 0x1c000
	v_add_u32_e32 v130, s47, v206
	v_add_u32_e32 v131, s56, v206
	s_nop 0
	ds_read_b128 v[10:13], v130
	ds_read_b128 v[14:17], v130 offset:1024
	ds_read_b128 v[18:21], v130 offset:2048
	ds_read_b128 v[22:25], v130 offset:3072
	ds_read_b128 v[210:213], v131
	ds_read_b128 v[214:217], v131 offset:1024
	ds_read_b128 v[218:221], v131 offset:2048
	ds_read_b128 v[222:225], v131 offset:3072
	s_add_u32 s14, s66, 0x2b0100
	s_addc_u32 s15, s67, 0
	s_mov_b32 m0, s13
	v_lshl_add_u64 v[90:91], s[14:15], 0, v[178:179]
	ds_read_b128 v[26:29], v209 offset:32768
	ds_read_b128 v[30:33], v209 offset:33792
	ds_read_b128 v[62:65], v209 offset:34816
	ds_read_b128 v[226:229], v209 offset:35840
	ds_read_b128 v[230:233], v209 offset:36864
	ds_read_b128 v[234:237], v209 offset:37888
	ds_read_b128 v[238:241], v209 offset:38912
	ds_read_b128 v[242:245], v209 offset:39936
	global_load_lds_dwordx4 v[90:91], off
	v_lshl_add_u64 v[90:91], s[14:15], 0, v[182:183]
	s_mov_b32 m0, s29
	s_nop 0
	global_load_lds_dwordx4 v[90:91], off
	s_waitcnt vmcnt(8)
	s_waitcnt lgkmcnt(0)
	s_setprio 1
	s_barrier
	v_mfma_f32_16x16x32_bf16 v[66:69], v[10:13], v[26:29], v[66:69]
	v_mfma_f32_16x16x32_bf16 v[122:125], v[14:17], v[30:33], v[66:69]
	v_mfma_f32_16x16x32_bf16 v[66:69], v[18:21], v[26:29], v[70:73]
	v_mfma_f32_16x16x32_bf16 v[118:121], v[22:25], v[30:33], v[66:69]
	v_mfma_f32_16x16x32_bf16 v[66:69], v[10:13], v[62:65], v[74:77]
	v_mfma_f32_16x16x32_bf16 v[110:113], v[14:17], v[226:229], v[66:69]
	v_mfma_f32_16x16x32_bf16 v[66:69], v[18:21], v[62:65], v[78:81]
	v_mfma_f32_16x16x32_bf16 v[106:109], v[22:25], v[226:229], v[66:69]
	v_mfma_f32_16x16x32_bf16 v[66:69], v[10:13], v[230:233], v[82:85]
	v_mfma_f32_16x16x32_bf16 v[94:97], v[14:17], v[234:237], v[66:69]
	v_mfma_f32_16x16x32_bf16 v[66:69], v[18:21], v[230:233], v[86:89]
	v_mfma_f32_16x16x32_bf16 v[90:93], v[22:25], v[234:237], v[66:69]
	v_mfma_f32_16x16x32_bf16 v[66:69], v[10:13], v[238:241], v[98:101]
	v_mfma_f32_16x16x32_bf16 v[78:81], v[14:17], v[242:245], v[66:69]
	v_mfma_f32_16x16x32_bf16 v[66:69], v[18:21], v[238:241], v[102:105]
	v_mfma_f32_16x16x32_bf16 v[74:77], v[22:25], v[242:245], v[66:69]
	s_setprio 0
	s_setprio 1
	v_mfma_f32_16x16x32_bf16 v[66:69], v[210:213], v[26:29], v[114:117]
	v_mfma_f32_16x16x32_bf16 v[26:29], v[218:221], v[26:29], v[34:37]
	v_mfma_f32_16x16x32_bf16 v[114:117], v[222:225], v[30:33], v[26:29]
	v_mfma_f32_16x16x32_bf16 v[26:29], v[210:213], v[62:65], v[38:41]
	v_mfma_f32_16x16x32_bf16 v[102:105], v[214:217], v[226:229], v[26:29]
	v_mfma_f32_16x16x32_bf16 v[26:29], v[218:221], v[62:65], v[42:45]
	v_mfma_f32_16x16x32_bf16 v[98:101], v[222:225], v[226:229], v[26:29]
	v_mfma_f32_16x16x32_bf16 v[26:29], v[210:213], v[230:233], v[46:49]
	v_mfma_f32_16x16x32_bf16 v[86:89], v[214:217], v[234:237], v[26:29]
	v_mfma_f32_16x16x32_bf16 v[26:29], v[218:221], v[230:233], v[50:53]
	v_mfma_f32_16x16x32_bf16 v[82:85], v[222:225], v[234:237], v[26:29]
	v_mfma_f32_16x16x32_bf16 v[26:29], v[210:213], v[238:241], v[54:57]
	v_mfma_f32_16x16x32_bf16 v[70:73], v[214:217], v[242:245], v[26:29]
	v_mfma_f32_16x16x32_bf16 v[26:29], v[218:221], v[238:241], v[58:61]
	v_mfma_f32_16x16x32_bf16 v[126:129], v[214:217], v[30:33], v[66:69]
	v_mfma_f32_16x16x32_bf16 v[66:69], v[222:225], v[242:245], v[26:29]
	s_barrier
	s_setprio 0
	s_add_i32 s47, s47, s10
	s_add_i32 s89, s47, 0x2000
	s_nop 1
	v_lshl_add_u64 v[26:27], v[176:177], 0, s[62:63]
	s_mov_b32 m0, s47
	s_add_u32 s14, s70, 0x2b0180
	ds_read_b128 v[34:37], v209 offset:49152
	ds_read_b128 v[38:41], v209 offset:50176
	ds_read_b128 v[226:229], v209 offset:51200
	ds_read_b128 v[230:233], v209 offset:52224
	ds_read_b128 v[234:237], v209 offset:53248
	ds_read_b128 v[238:241], v209 offset:54272
	ds_read_b128 v[242:245], v209 offset:55296
	ds_read_b128 v[246:249], v209 offset:56320
	global_load_lds_dwordx4 v[26:27], off
	v_lshl_add_u64 v[26:27], v[250:251], 0, s[62:63]
	s_mov_b32 m0, s89
	s_addc_u32 s15, s71, 0
	s_add_i32 s56, s56, s10
	global_load_lds_dwordx4 v[26:27], off
	v_lshl_add_u64 v[26:27], s[14:15], 0, v[180:181]
	s_mov_b32 m0, s56
	s_add_i32 s57, s56, 0x2000
	global_load_lds_dwordx4 v[26:27], off
	v_lshl_add_u64 v[26:27], s[14:15], 0, v[184:185]
	s_mov_b32 m0, s57
	s_nop 0
	global_load_lds_dwordx4 v[26:27], off
	v_lshl_add_u64 v[26:27], v[252:253], 0, s[62:63]
	s_mov_b32 m0, s58
	s_nop 0
	global_load_lds_dwordx4 v[26:27], off
	v_lshl_add_u64 v[26:27], v[190:191], 0, s[62:63]
	s_mov_b32 m0, s59
	s_nop 0
	global_load_lds_dwordx4 v[26:27], off
	s_waitcnt vmcnt(8)
	s_waitcnt lgkmcnt(0)
	s_setprio 1
	s_barrier
	v_mfma_f32_16x16x32_bf16 v[26:29], v[10:13], v[34:37], v[132:135]
	v_mfma_f32_16x16x32_bf16 v[58:61], v[14:17], v[38:41], v[26:29]
	v_mfma_f32_16x16x32_bf16 v[26:29], v[18:21], v[34:37], v[136:139]
	v_mfma_f32_16x16x32_bf16 v[54:57], v[22:25], v[38:41], v[26:29]
	v_mfma_f32_16x16x32_bf16 v[26:29], v[10:13], v[226:229], v[140:143]
	v_mfma_f32_16x16x32_bf16 v[46:49], v[14:17], v[230:233], v[26:29]
	v_mfma_f32_16x16x32_bf16 v[26:29], v[18:21], v[226:229], v[144:147]
	v_mfma_f32_16x16x32_bf16 v[42:45], v[22:25], v[230:233], v[26:29]
	v_mfma_f32_16x16x32_bf16 v[26:29], v[10:13], v[234:237], v[148:151]
	v_mfma_f32_16x16x32_bf16 v[2:5], v[10:13], v[242:245], v[2:5]
	v_mfma_f32_16x16x32_bf16 v[30:33], v[14:17], v[238:241], v[26:29]
	v_mfma_f32_16x16x32_bf16 v[26:29], v[18:21], v[234:237], v[152:155]
	v_mfma_f32_16x16x32_bf16 v[14:17], v[14:17], v[246:249], v[2:5]
	v_mfma_f32_16x16x32_bf16 v[2:5], v[18:21], v[242:245], v[6:9]
	v_mfma_f32_16x16x32_bf16 v[26:29], v[22:25], v[238:241], v[26:29]
	v_mfma_f32_16x16x32_bf16 v[10:13], v[22:25], v[246:249], v[2:5]
	s_setprio 0
	s_setprio 1
	v_mfma_f32_16x16x32_bf16 v[2:5], v[210:213], v[34:37], v[156:159]
	v_mfma_f32_16x16x32_bf16 v[62:65], v[214:217], v[38:41], v[2:5]
	v_mfma_f32_16x16x32_bf16 v[2:5], v[218:221], v[34:37], v[160:163]
	v_mfma_f32_16x16x32_bf16 v[50:53], v[222:225], v[38:41], v[2:5]
	v_mfma_f32_16x16x32_bf16 v[2:5], v[210:213], v[226:229], v[164:167]
	v_mfma_f32_16x16x32_bf16 v[38:41], v[214:217], v[230:233], v[2:5]
	v_mfma_f32_16x16x32_bf16 v[2:5], v[218:221], v[226:229], v[168:171]
	v_mfma_f32_16x16x32_bf16 v[34:37], v[222:225], v[230:233], v[2:5]
	v_mfma_f32_16x16x32_bf16 v[2:5], v[210:213], v[234:237], v[172:175]
	v_mfma_f32_16x16x32_bf16 v[22:25], v[214:217], v[238:241], v[2:5]
	v_mfma_f32_16x16x32_bf16 v[2:5], v[218:221], v[234:237], v[194:197]
	v_mfma_f32_16x16x32_bf16 v[18:21], v[222:225], v[238:241], v[2:5]
	v_mfma_f32_16x16x32_bf16 v[2:5], v[210:213], v[242:245], v[198:201]
	v_mfma_f32_16x16x32_bf16 v[6:9], v[214:217], v[246:249], v[2:5]
	v_mfma_f32_16x16x32_bf16 v[2:5], v[218:221], v[242:245], v[202:205]
	v_mfma_f32_16x16x32_bf16 v[2:5], v[222:225], v[246:249], v[2:5]
	s_barrier
	s_setprio 0
	s_add_u32 s90, s70, 0x200
	s_addc_u32 s14, s71, 0
	s_mov_b32 s15, 0
	.p2align	6

; #define PG8_STAGE(bufoff, gbase, voff) do { _Pragma("unroll") for (int _i = 0; _i < 2; ++_i) \
;         __builtin_amdgcn_global_load_lds((const unsigned*)((const char*)(gbase) + (voff)[_i]), (LAS unsigned*)(lds + (bufoff) + ldsw + _i * 8192), 16, 0, 0); } while (0)
; #define PG8_WAIT_V(n) asm volatile("s_waitcnt vmcnt(" #n ")" ::: "memory")
; #define PG8_BAR __builtin_amdgcn_s_barrier()
; #define PG8_TOUCH(p) asm volatile("global_load_dword %0, %1, off" : "+v"(pfd) : "v"(p) : "memory")
;     int tid = threadIdx.x; asm volatile("" : "+v"(tid));
;     const int wid = __builtin_amdgcn_readfirstlane(tid >> 6), lane = tid & 63, wr = wid >> 2, wc = wid & 3, fr = lane & 15, fq = lane >> 4;
;     const int K = g.K, nt = K / BK;
;     unsigned voffA[2], voffB[2];
; #pragma unroll
;     for (int i = 0; i < 2; ++i) { int R, C; stage_rc(tid * 16 + i * 8192, R, C); const int Rb = Epi::PERM ? ((R & ~31) + perm32(R & 31)) : R;
;         voffA[i] = (unsigned)(R * g.lda + C) * 2u; voffB[i] = (unsigned)(Rb * g.ldb + C) * 2u; }
;     const size_t kstep = (size_t)(BK * 2);
;     const size_t hstepA = (size_t)HALF * g.lda * 2, hstepB = (size_t)HALF * g.ldb * 2;
;     const unsigned ldsw = (unsigned)wid * 1024u;
;     const int aoff = lds_byte(wr * 64 + fr, fq * 8), boff = lds_byte(wc * 32 + fr, fq * 8);
;     ...
;     PG8_STAGE(PG8_SB(0, 0), cB, voffB); PG8_STAGE(PG8_SB(0, 1), cB + hstepB, voffB); PG8_STAGE(PG8_SA(0, 0), cA, voffA); PG8_STAGE(PG8_SA(0, 1), cA + hstepA, voffA);
;     if (wr == 1) PG8_BAR;
;     PG8_WAIT_V(2); PG8_BAR;
;     PG8_STAGE(PG8_SB(1, 0), cB + kstep, voffB); PG8_STAGE(PG8_SA(1, 0), cA + kstep, voffA); PG8_STAGE(PG8_SB(1, 1), cB + hstepB + kstep, voffB);
;     PG8_WAIT_V(6); PG8_BAR;
;     if constexpr (PF > 0) { const char* p0 = PG8_PFPTR(cA, cB) + (size_t)(2 + PF) * kstep; PG8_TOUCH(p0); }
;     for (;;) {
.LBB0_409:
	s_mov_b64 s[62:63], 0x80
	s_lshl_b32 s5, s5, 12
	s_add_i32 m0, s86, 0x18000
	v_lshl_add_u64 v[6:7], v[6:7], 0, s[62:63]
	s_lshl_b32 s1, s10, 13
	s_and_b32 s5, s5, 0x3000
	s_waitcnt vmcnt(2)
	s_barrier
	global_load_lds_dwordx4 v[6:7], off
	v_lshl_add_u64 v[4:5], v[4:5], 0, s[62:63]
	s_add_i32 m0, s86, 0x1a000
	s_add_i32 s96, s86, 0x8000
	s_add_i32 s97, s86, 0xa000
	global_load_lds_dwordx4 v[4:5], off
	v_lshl_add_u64 v[2:3], v[2:3], 0, s[62:63]
	s_mov_b32 m0, s96
	s_add_u32 s12, s6, 0x100080
	global_load_lds_dwordx4 v[2:3], off
	v_lshl_add_u64 v[2:3], v[8:9], 0, s[62:63]
	s_mov_b32 m0, s97
	s_addc_u32 s13, s7, 0
	global_load_lds_dwordx4 v[2:3], off
	s_add_i32 m0, s86, 0x1c000
	v_lshl_add_u64 v[2:3], s[12:13], 0, v[134:135]
	global_load_lds_dwordx4 v[2:3], off
	v_lshl_add_u64 v[2:3], s[12:13], 0, v[130:131]
	s_add_i32 m0, s86, 0x1e000
	v_and_b32_e32 v0, 15, v11
	global_load_lds_dwordx4 v[2:3], off
	v_lshlrev_b32_e32 v4, 2, v11
	v_and_b32_e32 v2, 48, v11
	v_lshlrev_b32_e32 v0, 6, v0
	v_and_b32_e32 v4, 32, v4
	v_or_b32_e32 v3, v0, v2
	v_bitop3_b32 v0, v0, v4, v2 bitop3:0x36
	v_or_b32_e32 v162, s5, v0
	v_lshlrev_b32_e32 v0, 16, v15
	v_and_b32_e32 v0, 0xfffe0000, v0
	v_bitop3_b32 v2, v3, s1, v4 bitop3:0xde
	v_lshl_add_u32 v0, v14, 13, v0
	v_and_b32_e32 v3, 1, v15
	v_lshl_or_b32 v0, v3, 6, v0
	v_lshl_add_u32 v140, v16, 1, v0
	v_lshlrev_b32_e32 v0, 16, v10
	v_and_b32_e32 v0, 0xfffe0000, v0
	s_waitcnt vmcnt(6)
	s_cmpk_lt_u32 s4, 0x100
	v_lshl_add_u32 v0, v12, 13, v0
	v_and_b32_e32 v3, 1, v10
	s_cselect_b64 s[64:65], -1, 0
	v_lshl_or_b32 v0, v3, 6, v0
	s_add_i32 s59, 0, 0x10000
	s_add_i32 s88, 0, 0x14000
	s_ashr_i32 s58, s3, 31
	v_mov_b32_e32 v141, v139
	v_lshl_add_u32 v142, v13, 1, v0
	v_mov_b32_e32 v143, v139
	v_mov_b64_e32 v[146:147], 0xbbf
	v_add_u32_e32 v163, s59, v162
	v_add_u32_e32 v164, s88, v162
	v_add_u32_e32 v165, 0, v2
	s_add_i32 s89, s86, 0xc000
	s_add_i32 s92, s86, 0xe000
	s_mov_b64 s[66:67], 0x100
	s_mov_b64 s[68:69], 0x180
	v_mov_b32_e32 v166, 0x358637bd
	s_mov_b32 s87, 0x800000
	s_movk_i32 s12, 0x5e00
	s_mov_b32 s70, 0x437f0000
	s_mov_b32 s13, 0
	s_barrier
	s_branch .LBB0_412
	.p2align	6

;     __host__ __device__ bool next(int i, Unit& u) const { if (!StaticOrder::next(i >> 1, u)) return false; u.seg = i & 1; return true; }
;     ...
;         const bool has_next = S.next(ui + 1, nxt);
;         const char* nA = has_next ? PG8_APTR(nxt) : cA; const char* nB = has_next ? PG8_BPTR(nxt) : cB;
;         const char* pfc = PG8_PFPTR(cA, cB); const char* pfn = PG8_PFPTR(nA, nB);
;         PG8_KITER(0);
.LBB0_414:
	s_ashr_i32 s75, s74, 31
	ds_read_b128 v[2:5], v163
	ds_read_b128 v[6:9], v163 offset:1024
	ds_read_b128 v[10:13], v163 offset:2048
	ds_read_b128 v[14:17], v163 offset:3072
	ds_read_b128 v[18:21], v164
	ds_read_b128 v[22:25], v164 offset:1024
	ds_read_b128 v[26:29], v164 offset:2048
	ds_read_b128 v[30:33], v164 offset:3072
	s_lshl_b64 s[14:15], s[74:75], 21
	s_add_u32 s76, s36, s14
	s_addc_u32 s77, s37, s15
	s_and_b64 s[14:15], s[4:5], exec
	s_cselect_b32 s1, s77, s81
	s_cselect_b32 s75, s76, s80
	s_and_b32 s18, s10, 0x7fffffff
	s_lshl_b64 s[14:15], s[18:19], 21
	s_add_u32 s78, s33, s14
	s_addc_u32 s79, s71, s15
	s_and_b64 s[14:15], s[4:5], exec
	s_cselect_b32 s18, s79, s7
	s_cselect_b32 vcc_lo, s78, s6
	s_add_u32 s14, s80, 0x100080
	s_addc_u32 s15, s81, 0
	s_mov_b32 m0, s89
	v_lshl_add_u64 v[66:67], s[14:15], 0, v[136:137]
	ds_read_b128 v[34:37], v165
	ds_read_b128 v[38:41], v165 offset:1024
	ds_read_b128 v[42:45], v165 offset:2048
	ds_read_b128 v[46:49], v165 offset:3072
	ds_read_b128 v[50:53], v165 offset:4096
	ds_read_b128 v[54:57], v165 offset:5120
	ds_read_b128 v[58:61], v165 offset:6144
	ds_read_b128 v[62:65], v165 offset:7168
	global_load_lds_dwordx4 v[66:67], off
	v_lshl_add_u64 v[66:67], s[14:15], 0, v[132:133]
	s_mov_b32 m0, s92
	s_nop 0
	global_load_lds_dwordx4 v[66:67], off
	s_waitcnt vmcnt(8)
	s_waitcnt lgkmcnt(0)
	s_setprio 1
	s_barrier
	v_mfma_f32_16x16x32_bf16 v[86:89], v[10:13], v[50:53], 0
	v_mfma_f32_16x16x32_bf16 v[90:93], v[14:17], v[54:57], v[86:89]
	v_mfma_f32_16x16x32_bf16 v[86:89], v[2:5], v[58:61], 0
	v_mfma_f32_16x16x32_bf16 v[66:69], v[2:5], v[34:37], 0
	v_mfma_f32_16x16x32_bf16 v[70:73], v[10:13], v[34:37], 0
	v_mfma_f32_16x16x32_bf16 v[74:77], v[2:5], v[42:45], 0
	v_mfma_f32_16x16x32_bf16 v[78:81], v[10:13], v[42:45], 0
	v_mfma_f32_16x16x32_bf16 v[82:85], v[2:5], v[50:53], 0
	v_mfma_f32_16x16x32_bf16 v[94:97], v[6:9], v[62:65], v[86:89]
	v_mfma_f32_16x16x32_bf16 v[86:89], v[10:13], v[58:61], 0
	v_mfma_f32_16x16x32_bf16 v[66:69], v[6:9], v[38:41], v[66:69]
	v_mfma_f32_16x16x32_bf16 v[70:73], v[14:17], v[38:41], v[70:73]
	v_mfma_f32_16x16x32_bf16 v[74:77], v[6:9], v[46:49], v[74:77]
	v_mfma_f32_16x16x32_bf16 v[78:81], v[14:17], v[46:49], v[78:81]
	v_mfma_f32_16x16x32_bf16 v[82:85], v[6:9], v[54:57], v[82:85]
	v_mfma_f32_16x16x32_bf16 v[106:109], v[14:17], v[62:65], v[86:89]
	s_setprio 0
	s_setprio 1
	v_mfma_f32_16x16x32_bf16 v[86:89], v[18:21], v[34:37], 0
	v_mfma_f32_16x16x32_bf16 v[34:37], v[26:29], v[34:37], 0
	v_mfma_f32_16x16x32_bf16 v[110:113], v[22:25], v[38:41], v[86:89]
	v_mfma_f32_16x16x32_bf16 v[34:37], v[30:33], v[38:41], v[34:37]
	v_mfma_f32_16x16x32_bf16 v[38:41], v[18:21], v[42:45], 0
	v_mfma_f32_16x16x32_bf16 v[42:45], v[26:29], v[42:45], 0
	v_mfma_f32_16x16x32_bf16 v[38:41], v[22:25], v[46:49], v[38:41]
	v_mfma_f32_16x16x32_bf16 v[42:45], v[30:33], v[46:49], v[42:45]
	v_mfma_f32_16x16x32_bf16 v[46:49], v[18:21], v[50:53], 0
	v_mfma_f32_16x16x32_bf16 v[50:53], v[26:29], v[50:53], 0
	v_mfma_f32_16x16x32_bf16 v[46:49], v[22:25], v[54:57], v[46:49]
	v_mfma_f32_16x16x32_bf16 v[50:53], v[30:33], v[54:57], v[50:53]
	v_mfma_f32_16x16x32_bf16 v[54:57], v[18:21], v[58:61], 0
	v_mfma_f32_16x16x32_bf16 v[58:61], v[26:29], v[58:61], 0
	v_mfma_f32_16x16x32_bf16 v[54:57], v[22:25], v[62:65], v[54:57]
	v_mfma_f32_16x16x32_bf16 v[58:61], v[30:33], v[62:65], v[58:61]
	s_barrier
	s_setprio 0
	s_add_i32 vcc_hi, s59, s29
	v_lshl_add_u64 v[248:249], s[6:7], 0, v[134:135]
	s_add_i32 s84, vcc_hi, 0x2000
	v_lshl_add_u64 v[148:149], v[248:249], 0, s[66:67]
	s_mov_b32 m0, vcc_hi
	v_lshl_add_u64 v[250:251], s[6:7], 0, v[130:131]
	s_add_u32 s14, s6, 0x100100
	ds_read_b128 v[62:65], v165 offset:16384
	ds_read_b128 v[86:89], v165 offset:17408
	ds_read_b128 v[98:101], v165 offset:18432
	ds_read_b128 v[102:105], v165 offset:19456
	ds_read_b128 v[114:117], v165 offset:20480
	ds_read_b128 v[118:121], v165 offset:21504
	ds_read_b128 v[122:125], v165 offset:22528
	ds_read_b128 v[126:129], v165 offset:23552
	global_load_lds_dwordx4 v[148:149], off
	v_lshl_add_u64 v[148:149], v[250:251], 0, s[66:67]
	s_mov_b32 m0, s84
	s_addc_u32 s15, s7, 0
	s_add_i32 s85, s88, s29
	global_load_lds_dwordx4 v[148:149], off
	v_lshl_add_u64 v[148:149], s[14:15], 0, v[134:135]
	s_mov_b32 m0, s85
	s_add_i32 s46, s85, 0x2000
	global_load_lds_dwordx4 v[148:149], off
	v_lshl_add_u64 v[148:149], s[14:15], 0, v[130:131]
	s_mov_b32 m0, s46
	v_lshl_add_u64 v[252:253], s[80:81], 0, v[136:137]
	global_load_lds_dwordx4 v[148:149], off
	v_lshl_add_u64 v[148:149], v[252:253], 0, s[66:67]
	s_mov_b32 m0, s86
	v_lshl_add_u64 v[144:145], s[80:81], 0, v[132:133]
	global_load_lds_dwordx4 v[148:149], off
	v_lshl_add_u64 v[148:149], v[144:145], 0, s[66:67]
	s_mov_b32 m0, s93
	s_nop 0
	global_load_lds_dwordx4 v[148:149], off
	s_waitcnt vmcnt(8)
	s_waitcnt lgkmcnt(0)
	s_setprio 1
	s_barrier
	v_mfma_f32_16x16x32_bf16 v[148:151], v[2:5], v[62:65], 0
	v_mfma_f32_16x16x32_bf16 v[158:161], v[2:5], v[98:101], 0
	v_mfma_f32_16x16x32_bf16 v[172:175], v[2:5], v[114:117], 0
	v_mfma_f32_16x16x32_bf16 v[2:5], v[2:5], v[122:125], 0
	v_mfma_f32_16x16x32_bf16 v[150:153], v[6:9], v[86:89], v[148:151]
	v_mfma_f32_16x16x32_bf16 v[158:161], v[6:9], v[102:105], v[158:161]
	v_mfma_f32_16x16x32_bf16 v[172:175], v[6:9], v[118:121], v[172:175]
	v_mfma_f32_16x16x32_bf16 v[2:5], v[6:9], v[126:129], v[2:5]
	v_mfma_f32_16x16x32_bf16 v[6:9], v[10:13], v[122:125], 0
	v_mfma_f32_16x16x32_bf16 v[154:157], v[10:13], v[62:65], 0
	v_mfma_f32_16x16x32_bf16 v[168:171], v[10:13], v[98:101], 0
	v_mfma_f32_16x16x32_bf16 v[176:179], v[10:13], v[114:117], 0
	v_mfma_f32_16x16x32_bf16 v[10:13], v[14:17], v[126:129], v[6:9]
	v_mfma_f32_16x16x32_bf16 v[154:157], v[14:17], v[86:89], v[154:157]
	v_mfma_f32_16x16x32_bf16 v[168:171], v[14:17], v[102:105], v[168:171]
	v_mfma_f32_16x16x32_bf16 v[176:179], v[14:17], v[118:121], v[176:179]
	s_setprio 0
	s_setprio 1
	v_mfma_f32_16x16x32_bf16 v[6:9], v[18:21], v[62:65], 0
	v_mfma_f32_16x16x32_bf16 v[14:17], v[22:25], v[86:89], v[6:9]
	v_mfma_f32_16x16x32_bf16 v[6:9], v[26:29], v[62:65], 0
	v_mfma_f32_16x16x32_bf16 v[180:183], v[30:33], v[86:89], v[6:9]
	v_mfma_f32_16x16x32_bf16 v[6:9], v[18:21], v[98:101], 0
	v_mfma_f32_16x16x32_bf16 v[184:187], v[22:25], v[102:105], v[6:9]
	v_mfma_f32_16x16x32_bf16 v[6:9], v[26:29], v[98:101], 0
	v_mfma_f32_16x16x32_bf16 v[188:191], v[30:33], v[102:105], v[6:9]
	v_mfma_f32_16x16x32_bf16 v[6:9], v[18:21], v[114:117], 0
	v_mfma_f32_16x16x32_bf16 v[192:195], v[22:25], v[118:121], v[6:9]
	v_mfma_f32_16x16x32_bf16 v[6:9], v[26:29], v[114:117], 0
	v_mfma_f32_16x16x32_bf16 v[196:199], v[30:33], v[118:121], v[6:9]
	v_mfma_f32_16x16x32_bf16 v[6:9], v[18:21], v[122:125], 0
	v_mfma_f32_16x16x32_bf16 v[200:203], v[22:25], v[126:129], v[6:9]
	v_mfma_f32_16x16x32_bf16 v[6:9], v[26:29], v[122:125], 0
	v_mfma_f32_16x16x32_bf16 v[204:207], v[30:33], v[126:129], v[6:9]
	s_barrier
	s_setprio 0
	s_add_i32 s47, 0, 0x18000
	s_add_i32 s56, 0, 0x1c000
	v_add_u32_e32 v138, s47, v162
	v_add_u32_e32 v148, s56, v162
	s_nop 0
	ds_read_b128 v[6:9], v138
	ds_read_b128 v[26:29], v138 offset:1024
	ds_read_b128 v[30:33], v138 offset:2048
	ds_read_b128 v[62:65], v138 offset:3072
	ds_read_b128 v[208:211], v148
	ds_read_b128 v[212:215], v148 offset:1024
	ds_read_b128 v[216:219], v148 offset:2048
	ds_read_b128 v[220:223], v148 offset:3072
	s_add_u32 s14, s80, 0x100100
	s_addc_u32 s15, s81, 0
	s_mov_b32 m0, s94
	v_lshl_add_u64 v[86:87], s[14:15], 0, v[136:137]
	ds_read_b128 v[18:21], v165 offset:32768
	ds_read_b128 v[22:25], v165 offset:33792
	ds_read_b128 v[224:227], v165 offset:34816
	ds_read_b128 v[228:231], v165 offset:35840
	ds_read_b128 v[232:235], v165 offset:36864
	ds_read_b128 v[236:239], v165 offset:37888
	ds_read_b128 v[240:243], v165 offset:38912
	ds_read_b128 v[244:247], v165 offset:39936
	global_load_lds_dwordx4 v[86:87], off
	v_lshl_add_u64 v[86:87], s[14:15], 0, v[132:133]
	s_mov_b32 m0, s95
	s_nop 0
	global_load_lds_dwordx4 v[86:87], off
	s_waitcnt vmcnt(8)
	s_waitcnt lgkmcnt(0)
	s_setprio 1
	s_barrier
	v_mfma_f32_16x16x32_bf16 v[66:69], v[6:9], v[18:21], v[66:69]
	v_mfma_f32_16x16x32_bf16 v[118:121], v[26:29], v[22:25], v[66:69]
	v_mfma_f32_16x16x32_bf16 v[66:69], v[30:33], v[18:21], v[70:73]
	v_mfma_f32_16x16x32_bf16 v[114:117], v[62:65], v[22:25], v[66:69]
	v_mfma_f32_16x16x32_bf16 v[66:69], v[6:9], v[224:227], v[74:77]
	v_mfma_f32_16x16x32_bf16 v[102:105], v[26:29], v[228:231], v[66:69]
	v_mfma_f32_16x16x32_bf16 v[66:69], v[30:33], v[224:227], v[78:81]
	v_mfma_f32_16x16x32_bf16 v[98:101], v[62:65], v[228:231], v[66:69]
	v_mfma_f32_16x16x32_bf16 v[66:69], v[6:9], v[232:235], v[82:85]
	v_mfma_f32_16x16x32_bf16 v[86:89], v[26:29], v[236:239], v[66:69]
	v_mfma_f32_16x16x32_bf16 v[66:69], v[30:33], v[232:235], v[90:93]
	v_mfma_f32_16x16x32_bf16 v[82:85], v[62:65], v[236:239], v[66:69]
	v_mfma_f32_16x16x32_bf16 v[66:69], v[6:9], v[240:243], v[94:97]
	v_mfma_f32_16x16x32_bf16 v[70:73], v[26:29], v[244:247], v[66:69]
	v_mfma_f32_16x16x32_bf16 v[66:69], v[30:33], v[240:243], v[106:109]
	v_mfma_f32_16x16x32_bf16 v[66:69], v[62:65], v[244:247], v[66:69]
	s_setprio 0
	s_setprio 1
	v_mfma_f32_16x16x32_bf16 v[74:77], v[208:211], v[18:21], v[110:113]
	v_mfma_f32_16x16x32_bf16 v[18:21], v[216:219], v[18:21], v[34:37]
	v_mfma_f32_16x16x32_bf16 v[122:125], v[220:223], v[22:25], v[18:21]
	v_mfma_f32_16x16x32_bf16 v[18:21], v[208:211], v[224:227], v[38:41]
	v_mfma_f32_16x16x32_bf16 v[110:113], v[212:215], v[228:231], v[18:21]
	v_mfma_f32_16x16x32_bf16 v[18:21], v[216:219], v[224:227], v[42:45]
	v_mfma_f32_16x16x32_bf16 v[106:109], v[220:223], v[228:231], v[18:21]
	v_mfma_f32_16x16x32_bf16 v[18:21], v[208:211], v[232:235], v[46:49]
	v_mfma_f32_16x16x32_bf16 v[94:97], v[212:215], v[236:239], v[18:21]
	v_mfma_f32_16x16x32_bf16 v[18:21], v[216:219], v[232:235], v[50:53]
	v_mfma_f32_16x16x32_bf16 v[90:93], v[220:223], v[236:239], v[18:21]
	v_mfma_f32_16x16x32_bf16 v[18:21], v[208:211], v[240:243], v[54:57]
	v_mfma_f32_16x16x32_bf16 v[78:81], v[212:215], v[244:247], v[18:21]
	v_mfma_f32_16x16x32_bf16 v[18:21], v[216:219], v[240:243], v[58:61]
	v_mfma_f32_16x16x32_bf16 v[126:129], v[212:215], v[22:25], v[74:77]
	v_mfma_f32_16x16x32_bf16 v[74:77], v[220:223], v[244:247], v[18:21]
	s_barrier
;     ...
;         for (int t = 2; t < nt; t += 2) PG8_KITER(t);
	s_setprio 0
	s_add_i32 s47, s47, s29
	s_add_i32 s91, s47, 0x2000
	s_nop 1
	v_lshl_add_u64 v[18:19], v[248:249], 0, s[68:69]
	s_mov_b32 m0, s47
	s_add_u32 s14, s6, 0x100180
	ds_read_b128 v[42:45], v165 offset:49152
	ds_read_b128 v[46:49], v165 offset:50176
	ds_read_b128 v[224:227], v165 offset:51200
	ds_read_b128 v[228:231], v165 offset:52224
	ds_read_b128 v[232:235], v165 offset:53248
	ds_read_b128 v[236:239], v165 offset:54272
	ds_read_b128 v[240:243], v165 offset:55296
	ds_read_b128 v[244:247], v165 offset:56320
	global_load_lds_dwordx4 v[18:19], off
	v_lshl_add_u64 v[18:19], v[250:251], 0, s[68:69]
	s_mov_b32 m0, s91
	s_addc_u32 s15, s7, 0
	s_add_i32 s56, s56, s29
	global_load_lds_dwordx4 v[18:19], off
	v_lshl_add_u64 v[18:19], s[14:15], 0, v[134:135]
	s_mov_b32 m0, s56
	s_add_i32 s57, s56, 0x2000
	global_load_lds_dwordx4 v[18:19], off
	v_lshl_add_u64 v[18:19], s[14:15], 0, v[130:131]
	s_mov_b32 m0, s57
	s_nop 0
	global_load_lds_dwordx4 v[18:19], off
	v_lshl_add_u64 v[18:19], v[252:253], 0, s[68:69]
	s_mov_b32 m0, s96
	s_nop 0
	global_load_lds_dwordx4 v[18:19], off
	v_lshl_add_u64 v[18:19], v[144:145], 0, s[68:69]
	s_mov_b32 m0, s97
	s_nop 0
	global_load_lds_dwordx4 v[18:19], off
	s_waitcnt vmcnt(8)
	s_waitcnt lgkmcnt(0)
	s_setprio 1
	s_barrier
	v_mfma_f32_16x16x32_bf16 v[18:21], v[6:9], v[42:45], v[150:153]
	v_mfma_f32_16x16x32_bf16 v[54:57], v[26:29], v[46:49], v[18:21]
	v_mfma_f32_16x16x32_bf16 v[18:21], v[30:33], v[42:45], v[154:157]
	v_mfma_f32_16x16x32_bf16 v[50:53], v[62:65], v[46:49], v[18:21]
	v_mfma_f32_16x16x32_bf16 v[18:21], v[6:9], v[224:227], v[158:161]
	v_mfma_f32_16x16x32_bf16 v[38:41], v[26:29], v[228:231], v[18:21]
	v_mfma_f32_16x16x32_bf16 v[18:21], v[30:33], v[224:227], v[168:171]
	v_mfma_f32_16x16x32_bf16 v[34:37], v[62:65], v[228:231], v[18:21]
	v_mfma_f32_16x16x32_bf16 v[18:21], v[6:9], v[232:235], v[172:175]
	v_mfma_f32_16x16x32_bf16 v[2:5], v[6:9], v[240:243], v[2:5]
	v_mfma_f32_16x16x32_bf16 v[22:25], v[26:29], v[236:239], v[18:21]
	v_mfma_f32_16x16x32_bf16 v[18:21], v[30:33], v[232:235], v[176:179]
	v_mfma_f32_16x16x32_bf16 v[6:9], v[26:29], v[244:247], v[2:5]
	v_mfma_f32_16x16x32_bf16 v[2:5], v[30:33], v[240:243], v[10:13]
	v_mfma_f32_16x16x32_bf16 v[18:21], v[62:65], v[236:239], v[18:21]
	v_mfma_f32_16x16x32_bf16 v[2:5], v[62:65], v[244:247], v[2:5]
	s_setprio 0
	s_setprio 1
	v_mfma_f32_16x16x32_bf16 v[10:13], v[208:211], v[42:45], v[14:17]
	v_mfma_f32_16x16x32_bf16 v[62:65], v[212:215], v[46:49], v[10:13]
	v_mfma_f32_16x16x32_bf16 v[10:13], v[216:219], v[42:45], v[180:183]
	v_mfma_f32_16x16x32_bf16 v[58:61], v[220:223], v[46:49], v[10:13]
	v_mfma_f32_16x16x32_bf16 v[10:13], v[208:211], v[224:227], v[184:187]
	v_mfma_f32_16x16x32_bf16 v[46:49], v[212:215], v[228:231], v[10:13]
	v_mfma_f32_16x16x32_bf16 v[10:13], v[216:219], v[224:227], v[188:191]
	v_mfma_f32_16x16x32_bf16 v[42:45], v[220:223], v[228:231], v[10:13]
	v_mfma_f32_16x16x32_bf16 v[10:13], v[208:211], v[232:235], v[192:195]
	v_mfma_f32_16x16x32_bf16 v[30:33], v[212:215], v[236:239], v[10:13]
	v_mfma_f32_16x16x32_bf16 v[10:13], v[216:219], v[232:235], v[196:199]
	v_mfma_f32_16x16x32_bf16 v[26:29], v[220:223], v[236:239], v[10:13]
	v_mfma_f32_16x16x32_bf16 v[10:13], v[208:211], v[240:243], v[200:203]
	v_mfma_f32_16x16x32_bf16 v[14:17], v[212:215], v[244:247], v[10:13]
	v_mfma_f32_16x16x32_bf16 v[10:13], v[216:219], v[240:243], v[204:207]
	v_mfma_f32_16x16x32_bf16 v[10:13], v[220:223], v[244:247], v[10:13]
	s_barrier
	s_setprio 0
	s_add_u32 s80, s80, 0x100180
	s_addc_u32 s81, s81, 0
	s_add_u32 s30, s6, 0x200
	s_addc_u32 s14, s7, 0
	s_mov_b32 s15, 0
	.p2align	6

; #define PG8_STAGE(bufoff, gbase, voff) do { _Pragma("unroll") for (int _i = 0; _i < 2; ++_i) \
;         __builtin_amdgcn_global_load_lds((const unsigned*)((const char*)(gbase) + (voff)[_i]), (LAS unsigned*)(lds + (bufoff) + ldsw + _i * 8192), 16, 0, 0); } while (0)
; #define PG8_WAIT_V(n) asm volatile("s_waitcnt vmcnt(" #n ")" ::: "memory")
; #define PG8_BAR __builtin_amdgcn_s_barrier()
; #define PG8_TOUCH(p) asm volatile("global_load_dword %0, %1, off" : "+v"(pfd) : "v"(p) : "memory")
;     int tid = threadIdx.x; asm volatile("" : "+v"(tid));
;     const int wid = __builtin_amdgcn_readfirstlane(tid >> 6), lane = tid & 63, wr = wid >> 2, wc = wid & 3, fr = lane & 15, fq = lane >> 4;
;     const int K = g.K, nt = K / BK;
;     unsigned voffA[2], voffB[2];
; #pragma unroll
;     for (int i = 0; i < 2; ++i) { int R, C; stage_rc(tid * 16 + i * 8192, R, C); const int Rb = Epi::PERM ? ((R & ~31) + perm32(R & 31)) : R;
;         voffA[i] = (unsigned)(R * g.lda + C) * 2u; voffB[i] = (unsigned)(Rb * g.ldb + C) * 2u; }
;     const size_t kstep = (size_t)(BK * 2);
;     const size_t hstepA = (size_t)HALF * g.lda * 2, hstepB = (size_t)HALF * g.ldb * 2;
;     const unsigned ldsw = (unsigned)wid * 1024u;
;     const int aoff = lds_byte(wr * 64 + fr, fq * 8), boff = lds_byte(wc * 32 + fr, fq * 8);
;     ...
;     PG8_STAGE(PG8_SB(0, 0), cB, voffB); PG8_STAGE(PG8_SB(0, 1), cB + hstepB, voffB); PG8_STAGE(PG8_SA(0, 0), cA, voffA); PG8_STAGE(PG8_SA(0, 1), cA + hstepA, voffA);
;     if (wr == 1) PG8_BAR;
;     PG8_WAIT_V(2); PG8_BAR;
;     PG8_STAGE(PG8_SB(1, 0), cB + kstep, voffB); PG8_STAGE(PG8_SA(1, 0), cA + kstep, voffA); PG8_STAGE(PG8_SB(1, 1), cB + hstepB + kstep, voffB);
;     PG8_WAIT_V(6); PG8_BAR;
;     if constexpr (PF > 0) { const char* p0 = PG8_PFPTR(cA, cB) + (size_t)(2 + PF) * kstep; PG8_TOUCH(p0); }
;     for (;;) {
; __global__ void __launch_bounds__(NWAVES * 64, 2) mk_fwd(Params P) {
;     ...
;         { pg8::Gemm g = pg8::mk_gemm(MN, WXKV, D, D, D); pg8::StaticOrder S; S.init(MMEM / 256, 1024 / 256, (int)gridDim.x, (int)((blockIdx.x + 64u) % (unsigned)(int)gridDim.x));
;           pg8::EpiF32Split E{XKV, 1024, 0x7fffffff, 30, 0, nullptr};
;           pg8::gemm_phase(LDSP, g, S, E); }
.LBB0_429:
	s_add_u32 s4, s34, 0x24100000
	s_addc_u32 s5, s35, 0
	s_lshl_b32 s6, s6, 12
	s_lshl_b32 s9, s7, 13
	s_and_b32 s15, s6, 0x3000
	s_mov_b64 s[6:7], 0x80
	s_add_i32 m0, s59, 0x18000
	v_lshl_add_u64 v[8:9], v[8:9], 0, s[6:7]
	s_waitcnt vmcnt(2)
	s_barrier
	global_load_lds_dwordx4 v[8:9], off
	v_lshl_add_u64 v[6:7], v[6:7], 0, s[6:7]
	s_add_i32 m0, s59, 0x1a000
	s_add_i32 s88, s59, 0x8000
	s_add_i32 s89, s59, 0xa000
	global_load_lds_dwordx4 v[6:7], off
	v_lshl_add_u64 v[2:3], v[2:3], 0, s[6:7]
	s_mov_b32 m0, s88
	s_add_u32 s16, s76, 0x100080
	global_load_lds_dwordx4 v[2:3], off
	v_lshl_add_u64 v[2:3], v[4:5], 0, s[6:7]
	s_mov_b32 m0, s89
	s_addc_u32 s17, s77, 0
	global_load_lds_dwordx4 v[2:3], off
	s_add_i32 m0, s59, 0x1c000
	v_lshl_add_u64 v[2:3], s[16:17], 0, v[132:133]
	global_load_lds_dwordx4 v[2:3], off
	v_lshl_add_u64 v[2:3], s[16:17], 0, v[130:131]
	s_add_i32 m0, s59, 0x1e000
	v_and_b32_e32 v0, 15, v13
	global_load_lds_dwordx4 v[2:3], off
	v_lshlrev_b32_e32 v4, 2, v13
	v_and_b32_e32 v2, 48, v13
	v_lshlrev_b32_e32 v0, 6, v0
	v_and_b32_e32 v4, 32, v4
	v_or_b32_e32 v3, v0, v2
	v_bitop3_b32 v0, v0, v4, v2 bitop3:0x36
	v_or_b32_e32 v140, s15, v0
	v_lshlrev_b32_e32 v0, 16, v15
	v_and_b32_e32 v0, 0xfffe0000, v0
	v_bitop3_b32 v2, v3, s9, v4 bitop3:0xde
	v_lshl_add_u32 v0, v14, 13, v0
	v_and_b32_e32 v3, 1, v15
	v_lshl_or_b32 v0, v3, 6, v0
	v_lshl_add_u32 v136, v16, 1, v0
	v_lshlrev_b32_e32 v0, 16, v10
	v_and_b32_e32 v0, 0xfffe0000, v0
	s_waitcnt vmcnt(6)
	s_cmpk_lt_u32 s14, 0x100
	v_lshl_add_u32 v0, v11, 13, v0
	v_and_b32_e32 v3, 1, v10
	s_cselect_b64 s[30:31], -1, 0
	v_lshl_or_b32 v0, v3, 6, v0
	s_add_i32 s91, 0, 0x10000
	s_add_i32 s92, 0, 0x14000
	s_mov_b32 s19, 0
	s_ashr_i32 s90, s3, 31
	v_mov_b32_e32 v137, v135
	v_lshl_add_u32 v138, v12, 1, v0
	v_mov_b32_e32 v139, v135
	v_add_u32_e32 v141, s91, v140
	v_add_u32_e32 v142, s92, v140
	v_add_u32_e32 v143, 0, v2
	s_mov_b64 s[62:63], 0x100
	s_mov_b64 s[64:65], 0x180
	s_mov_b32 s93, 0
	s_barrier
	s_branch .LBB0_432
	.p2align	6
.LBB0_430:
	s_mov_b64 s[8:9], 0
	.p2align	6

;     __host__ __device__ bool next(int i, Unit& u) const { if (!StaticOrder::next(i >> 1, u)) return false; u.seg = i & 1; return true; }
;     ...
;         const bool has_next = S.next(ui + 1, nxt);
;         const char* nA = has_next ? PG8_APTR(nxt) : cA; const char* nB = has_next ? PG8_BPTR(nxt) : cB;
;         const char* pfc = PG8_PFPTR(cA, cB); const char* pfn = PG8_PFPTR(nA, nB);
;         PG8_KITER(0);
.LBB0_434:
	s_ashr_i32 s67, s66, 31
	ds_read_b128 v[2:5], v141
	ds_read_b128 v[6:9], v141 offset:1024
	ds_read_b128 v[10:13], v141 offset:2048
	ds_read_b128 v[14:17], v141 offset:3072
	ds_read_b128 v[18:21], v142
	ds_read_b128 v[22:25], v142 offset:1024
	ds_read_b128 v[26:29], v142 offset:2048
	ds_read_b128 v[30:33], v142 offset:3072
	s_lshl_b64 s[14:15], s[66:67], 21
	s_add_u32 s70, s11, s14
	s_addc_u32 s71, s12, s15
	s_and_b64 s[14:15], s[68:69], exec
	s_cselect_b32 s9, s71, s79
	s_cselect_b32 s67, s70, s78
	s_and_b32 s18, s94, 0x7fffffff
	s_lshl_b64 s[14:15], s[18:19], 21
	s_add_u32 s74, s13, s14
	s_addc_u32 s75, s29, s15
	s_and_b64 s[14:15], s[68:69], exec
	s_cselect_b32 s18, s75, s77
	s_cselect_b32 s95, s74, s76
	s_add_u32 s14, s78, 0x100080
	s_addc_u32 s15, s79, 0
	s_add_i32 s96, s59, 0xc000
	v_lshl_add_u64 v[66:67], s[14:15], 0, v[132:133]
	s_mov_b32 m0, s96
	s_add_i32 s97, s59, 0xe000
	ds_read_b128 v[34:37], v143
	ds_read_b128 v[38:41], v143 offset:1024
	ds_read_b128 v[42:45], v143 offset:2048
	ds_read_b128 v[46:49], v143 offset:3072
	ds_read_b128 v[50:53], v143 offset:4096
	ds_read_b128 v[54:57], v143 offset:5120
	ds_read_b128 v[58:61], v143 offset:6144
	ds_read_b128 v[62:65], v143 offset:7168
	global_load_lds_dwordx4 v[66:67], off
	v_lshl_add_u64 v[66:67], s[14:15], 0, v[130:131]
	s_mov_b32 m0, s97
	s_nop 0
	global_load_lds_dwordx4 v[66:67], off
	s_waitcnt vmcnt(8)
	s_waitcnt lgkmcnt(0)
	s_setprio 1
	s_barrier
	v_mfma_f32_16x16x32_bf16 v[66:69], v[2:5], v[34:37], 0
	v_mfma_f32_16x16x32_bf16 v[70:73], v[10:13], v[34:37], 0
	v_mfma_f32_16x16x32_bf16 v[74:77], v[2:5], v[42:45], 0
	v_mfma_f32_16x16x32_bf16 v[78:81], v[10:13], v[42:45], 0
	v_mfma_f32_16x16x32_bf16 v[82:85], v[2:5], v[50:53], 0
	v_mfma_f32_16x16x32_bf16 v[86:89], v[10:13], v[50:53], 0
	v_mfma_f32_16x16x32_bf16 v[90:93], v[2:5], v[58:61], 0
	v_mfma_f32_16x16x32_bf16 v[94:97], v[10:13], v[58:61], 0
	v_mfma_f32_16x16x32_bf16 v[66:69], v[6:9], v[38:41], v[66:69]
	v_mfma_f32_16x16x32_bf16 v[70:73], v[14:17], v[38:41], v[70:73]
	v_mfma_f32_16x16x32_bf16 v[74:77], v[6:9], v[46:49], v[74:77]
	v_mfma_f32_16x16x32_bf16 v[78:81], v[14:17], v[46:49], v[78:81]
	v_mfma_f32_16x16x32_bf16 v[82:85], v[6:9], v[54:57], v[82:85]
	v_mfma_f32_16x16x32_bf16 v[86:89], v[14:17], v[54:57], v[86:89]
	v_mfma_f32_16x16x32_bf16 v[90:93], v[6:9], v[62:65], v[90:93]
	v_mfma_f32_16x16x32_bf16 v[94:97], v[14:17], v[62:65], v[94:97]
	s_setprio 0
	s_setprio 1
	v_mfma_f32_16x16x32_bf16 v[98:101], v[18:21], v[34:37], 0
	v_mfma_f32_16x16x32_bf16 v[34:37], v[26:29], v[34:37], 0
	v_mfma_f32_16x16x32_bf16 v[102:105], v[30:33], v[38:41], v[34:37]
	v_mfma_f32_16x16x32_bf16 v[34:37], v[18:21], v[42:45], 0
	v_mfma_f32_16x16x32_bf16 v[106:109], v[22:25], v[46:49], v[34:37]
	v_mfma_f32_16x16x32_bf16 v[34:37], v[26:29], v[42:45], 0
	v_mfma_f32_16x16x32_bf16 v[42:45], v[30:33], v[46:49], v[34:37]
	v_mfma_f32_16x16x32_bf16 v[34:37], v[18:21], v[50:53], 0
	v_mfma_f32_16x16x32_bf16 v[46:49], v[22:25], v[54:57], v[34:37]
	v_mfma_f32_16x16x32_bf16 v[34:37], v[26:29], v[50:53], 0
	v_mfma_f32_16x16x32_bf16 v[50:53], v[30:33], v[54:57], v[34:37]
	v_mfma_f32_16x16x32_bf16 v[34:37], v[18:21], v[58:61], 0
	v_mfma_f32_16x16x32_bf16 v[110:113], v[22:25], v[62:65], v[34:37]
	v_mfma_f32_16x16x32_bf16 v[34:37], v[26:29], v[58:61], 0
	v_mfma_f32_16x16x32_bf16 v[98:101], v[22:25], v[38:41], v[98:101]
	v_mfma_f32_16x16x32_bf16 v[58:61], v[30:33], v[62:65], v[34:37]
	s_barrier
	s_setprio 0
	s_add_i32 vcc_lo, s91, s33
	v_lshl_add_u64 v[246:247], s[76:77], 0, v[132:133]
	s_add_i32 s84, vcc_lo, 0x2000
	v_lshl_add_u64 v[144:145], v[246:247], 0, s[62:63]
	s_mov_b32 m0, vcc_lo
	v_lshl_add_u64 v[248:249], s[76:77], 0, v[130:131]
	s_add_u32 s14, s76, 0x100100
	ds_read_b128 v[34:37], v143 offset:16384
	ds_read_b128 v[38:41], v143 offset:17408
	ds_read_b128 v[54:57], v143 offset:18432
	ds_read_b128 v[62:65], v143 offset:19456
	ds_read_b128 v[114:117], v143 offset:20480
	ds_read_b128 v[118:121], v143 offset:21504
	ds_read_b128 v[122:125], v143 offset:22528
	ds_read_b128 v[126:129], v143 offset:23552
	global_load_lds_dwordx4 v[144:145], off
	v_lshl_add_u64 v[144:145], v[248:249], 0, s[62:63]
	s_mov_b32 m0, s84
	s_addc_u32 s15, s77, 0
	s_add_i32 s85, s92, s33
	global_load_lds_dwordx4 v[144:145], off
	v_lshl_add_u64 v[144:145], s[14:15], 0, v[132:133]
	s_mov_b32 m0, s85
	s_add_i32 s46, s85, 0x2000
	global_load_lds_dwordx4 v[144:145], off
	v_lshl_add_u64 v[144:145], s[14:15], 0, v[130:131]
	s_mov_b32 m0, s46
	v_lshl_add_u64 v[250:251], s[78:79], 0, v[132:133]
	global_load_lds_dwordx4 v[144:145], off
	v_lshl_add_u64 v[144:145], v[250:251], 0, s[62:63]
	s_mov_b32 m0, s59
	v_lshl_add_u64 v[252:253], s[78:79], 0, v[130:131]
	global_load_lds_dwordx4 v[144:145], off
	v_lshl_add_u64 v[144:145], v[252:253], 0, s[62:63]
	s_mov_b32 m0, s82
	s_nop 0
	global_load_lds_dwordx4 v[144:145], off
	s_waitcnt vmcnt(8)
	s_waitcnt lgkmcnt(0)
	s_setprio 1
	s_barrier
	v_mfma_f32_16x16x32_bf16 v[144:147], v[2:5], v[34:37], 0
	v_mfma_f32_16x16x32_bf16 v[154:157], v[2:5], v[54:57], 0
	v_mfma_f32_16x16x32_bf16 v[162:165], v[2:5], v[114:117], 0
	v_mfma_f32_16x16x32_bf16 v[2:5], v[2:5], v[122:125], 0
	v_mfma_f32_16x16x32_bf16 v[150:153], v[10:13], v[34:37], 0
	v_mfma_f32_16x16x32_bf16 v[158:161], v[10:13], v[54:57], 0
	v_mfma_f32_16x16x32_bf16 v[166:169], v[10:13], v[114:117], 0
	v_mfma_f32_16x16x32_bf16 v[170:173], v[6:9], v[126:129], v[2:5]
	v_mfma_f32_16x16x32_bf16 v[2:5], v[10:13], v[122:125], 0
	v_mfma_f32_16x16x32_bf16 v[146:149], v[6:9], v[38:41], v[144:147]
	v_mfma_f32_16x16x32_bf16 v[150:153], v[14:17], v[38:41], v[150:153]
	v_mfma_f32_16x16x32_bf16 v[154:157], v[6:9], v[62:65], v[154:157]
	v_mfma_f32_16x16x32_bf16 v[158:161], v[14:17], v[62:65], v[158:161]
	v_mfma_f32_16x16x32_bf16 v[162:165], v[6:9], v[118:121], v[162:165]
	v_mfma_f32_16x16x32_bf16 v[166:169], v[14:17], v[118:121], v[166:169]
	v_mfma_f32_16x16x32_bf16 v[174:177], v[14:17], v[126:129], v[2:5]
	s_setprio 0
	s_setprio 1
	v_mfma_f32_16x16x32_bf16 v[2:5], v[18:21], v[34:37], 0
	v_mfma_f32_16x16x32_bf16 v[178:181], v[22:25], v[38:41], v[2:5]
	v_mfma_f32_16x16x32_bf16 v[2:5], v[26:29], v[34:37], 0
	v_mfma_f32_16x16x32_bf16 v[182:185], v[30:33], v[38:41], v[2:5]
	v_mfma_f32_16x16x32_bf16 v[2:5], v[18:21], v[54:57], 0
	v_mfma_f32_16x16x32_bf16 v[186:189], v[22:25], v[62:65], v[2:5]
	v_mfma_f32_16x16x32_bf16 v[2:5], v[26:29], v[54:57], 0
	v_mfma_f32_16x16x32_bf16 v[190:193], v[30:33], v[62:65], v[2:5]
	v_mfma_f32_16x16x32_bf16 v[2:5], v[18:21], v[114:117], 0
	v_mfma_f32_16x16x32_bf16 v[194:197], v[22:25], v[118:121], v[2:5]
	v_mfma_f32_16x16x32_bf16 v[2:5], v[26:29], v[114:117], 0
	v_mfma_f32_16x16x32_bf16 v[198:201], v[30:33], v[118:121], v[2:5]
	v_mfma_f32_16x16x32_bf16 v[2:5], v[18:21], v[122:125], 0
	v_mfma_f32_16x16x32_bf16 v[202:205], v[22:25], v[126:129], v[2:5]
	v_mfma_f32_16x16x32_bf16 v[2:5], v[26:29], v[122:125], 0
	v_mfma_f32_16x16x32_bf16 v[206:209], v[30:33], v[126:129], v[2:5]
	s_barrier
	s_setprio 0
	s_add_i32 s47, 0, 0x18000
	s_add_i32 s56, 0, 0x1c000
	v_add_u32_e32 v134, s47, v140
	v_add_u32_e32 v144, s56, v140
	ds_read_b128 v[114:117], v134
	ds_read_b128 v[118:121], v134 offset:1024
	ds_read_b128 v[122:125], v134 offset:2048
	ds_read_b128 v[126:129], v134 offset:3072
	ds_read_b128 v[210:213], v144
	ds_read_b128 v[214:217], v144 offset:1024
	ds_read_b128 v[218:221], v144 offset:2048
	ds_read_b128 v[222:225], v144 offset:3072
	s_add_u32 s14, s78, 0x100100
	s_addc_u32 s15, s79, 0
	s_mov_b32 m0, s83
	v_lshl_add_u64 v[2:3], s[14:15], 0, v[132:133]
	ds_read_b128 v[26:29], v143 offset:32768
	ds_read_b128 v[30:33], v143 offset:33792
	ds_read_b128 v[62:65], v143 offset:34816
	ds_read_b128 v[226:229], v143 offset:35840
	ds_read_b128 v[230:233], v143 offset:36864
	ds_read_b128 v[234:237], v143 offset:37888
	ds_read_b128 v[238:241], v143 offset:38912
	ds_read_b128 v[242:245], v143 offset:39936
	global_load_lds_dwordx4 v[2:3], off
	v_lshl_add_u64 v[2:3], s[14:15], 0, v[130:131]
	s_mov_b32 m0, s86
	s_nop 0
	global_load_lds_dwordx4 v[2:3], off
	s_waitcnt vmcnt(8)
	s_waitcnt lgkmcnt(0)
	s_setprio 1
	s_barrier
	v_mfma_f32_16x16x32_bf16 v[2:5], v[114:117], v[26:29], v[66:69]
	v_mfma_f32_16x16x32_bf16 v[34:37], v[118:121], v[30:33], v[2:5]
	v_mfma_f32_16x16x32_bf16 v[2:5], v[122:125], v[26:29], v[70:73]
	v_mfma_f32_16x16x32_bf16 v[38:41], v[126:129], v[30:33], v[2:5]
	v_mfma_f32_16x16x32_bf16 v[2:5], v[114:117], v[62:65], v[74:77]
	v_mfma_f32_16x16x32_bf16 v[18:21], v[118:121], v[226:229], v[2:5]
	v_mfma_f32_16x16x32_bf16 v[2:5], v[122:125], v[62:65], v[78:81]
	v_mfma_f32_16x16x32_bf16 v[22:25], v[126:129], v[226:229], v[2:5]
	v_mfma_f32_16x16x32_bf16 v[2:5], v[114:117], v[230:233], v[82:85]
	v_mfma_f32_16x16x32_bf16 v[10:13], v[118:121], v[234:237], v[2:5]
	v_mfma_f32_16x16x32_bf16 v[2:5], v[122:125], v[230:233], v[86:89]
	v_mfma_f32_16x16x32_bf16 v[14:17], v[126:129], v[234:237], v[2:5]
	v_mfma_f32_16x16x32_bf16 v[2:5], v[114:117], v[238:241], v[90:93]
	v_mfma_f32_16x16x32_bf16 v[6:9], v[122:125], v[238:241], v[94:97]
	v_mfma_f32_16x16x32_bf16 v[2:5], v[118:121], v[242:245], v[2:5]
	v_mfma_f32_16x16x32_bf16 v[6:9], v[126:129], v[242:245], v[6:9]
	s_setprio 0
	s_setprio 1
	v_mfma_f32_16x16x32_bf16 v[54:57], v[210:213], v[26:29], v[98:101]
	v_mfma_f32_16x16x32_bf16 v[26:29], v[218:221], v[26:29], v[102:105]
	v_mfma_f32_16x16x32_bf16 v[70:73], v[222:225], v[30:33], v[26:29]
	v_mfma_f32_16x16x32_bf16 v[26:29], v[210:213], v[62:65], v[106:109]
	v_mfma_f32_16x16x32_bf16 v[66:69], v[214:217], v[30:33], v[54:57]
	v_mfma_f32_16x16x32_bf16 v[54:57], v[214:217], v[226:229], v[26:29]
	v_mfma_f32_16x16x32_bf16 v[26:29], v[218:221], v[62:65], v[42:45]
	v_mfma_f32_16x16x32_bf16 v[62:65], v[222:225], v[226:229], v[26:29]
	v_mfma_f32_16x16x32_bf16 v[26:29], v[210:213], v[230:233], v[46:49]
	v_mfma_f32_16x16x32_bf16 v[42:45], v[214:217], v[234:237], v[26:29]
	v_mfma_f32_16x16x32_bf16 v[26:29], v[218:221], v[230:233], v[50:53]
	v_mfma_f32_16x16x32_bf16 v[46:49], v[222:225], v[234:237], v[26:29]
	v_mfma_f32_16x16x32_bf16 v[26:29], v[210:213], v[238:241], v[110:113]
	v_mfma_f32_16x16x32_bf16 v[30:33], v[218:221], v[238:241], v[58:61]
	v_mfma_f32_16x16x32_bf16 v[26:29], v[214:217], v[242:245], v[26:29]
	v_mfma_f32_16x16x32_bf16 v[30:33], v[222:225], v[242:245], v[30:33]
	s_barrier
;     ...
;         for (int t = 2; t < nt; t += 2) PG8_KITER(t);
	s_setprio 0
	s_add_i32 s47, s47, s33
	s_add_i32 vcc_hi, s47, 0x2000
	v_lshl_add_u64 v[50:51], v[246:247], 0, s[64:65]
	s_mov_b32 m0, s47
	s_add_u32 s14, s76, 0x100180
	ds_read_b128 v[82:85], v143 offset:49152
	ds_read_b128 v[86:89], v143 offset:50176
	ds_read_b128 v[98:101], v143 offset:51200
	ds_read_b128 v[106:109], v143 offset:52224
	ds_read_b128 v[226:229], v143 offset:53248
	ds_read_b128 v[230:233], v143 offset:54272
	ds_read_b128 v[234:237], v143 offset:55296
	ds_read_b128 v[238:241], v143 offset:56320
	global_load_lds_dwordx4 v[50:51], off
	v_lshl_add_u64 v[50:51], v[248:249], 0, s[64:65]
	s_mov_b32 m0, vcc_hi
	s_addc_u32 s15, s77, 0
	s_add_i32 s56, s56, s33
	global_load_lds_dwordx4 v[50:51], off
	v_lshl_add_u64 v[50:51], s[14:15], 0, v[132:133]
	s_mov_b32 m0, s56
	s_add_i32 s57, s56, 0x2000
	global_load_lds_dwordx4 v[50:51], off
	v_lshl_add_u64 v[50:51], s[14:15], 0, v[130:131]
	s_mov_b32 m0, s57
	s_nop 0
	global_load_lds_dwordx4 v[50:51], off
	v_lshl_add_u64 v[50:51], v[250:251], 0, s[64:65]
	s_mov_b32 m0, s88
	s_nop 0
	global_load_lds_dwordx4 v[50:51], off
	v_lshl_add_u64 v[50:51], v[252:253], 0, s[64:65]
	s_mov_b32 m0, s89
	s_nop 0
	global_load_lds_dwordx4 v[50:51], off
	s_waitcnt vmcnt(8)
	s_waitcnt lgkmcnt(0)
	s_setprio 1
	s_barrier
	v_mfma_f32_16x16x32_bf16 v[50:53], v[114:117], v[82:85], v[146:149]
	v_mfma_f32_16x16x32_bf16 v[102:105], v[118:121], v[86:89], v[50:53]
	v_mfma_f32_16x16x32_bf16 v[50:53], v[122:125], v[82:85], v[150:153]
	v_mfma_f32_16x16x32_bf16 v[110:113], v[126:129], v[86:89], v[50:53]
	v_mfma_f32_16x16x32_bf16 v[50:53], v[114:117], v[98:101], v[154:157]
	v_mfma_f32_16x16x32_bf16 v[90:93], v[118:121], v[106:109], v[50:53]
	v_mfma_f32_16x16x32_bf16 v[50:53], v[122:125], v[98:101], v[158:161]
	v_mfma_f32_16x16x32_bf16 v[94:97], v[126:129], v[106:109], v[50:53]
	v_mfma_f32_16x16x32_bf16 v[50:53], v[114:117], v[226:229], v[162:165]
	v_mfma_f32_16x16x32_bf16 v[74:77], v[118:121], v[230:233], v[50:53]
	v_mfma_f32_16x16x32_bf16 v[50:53], v[122:125], v[226:229], v[166:169]
	v_mfma_f32_16x16x32_bf16 v[78:81], v[126:129], v[230:233], v[50:53]
	v_mfma_f32_16x16x32_bf16 v[50:53], v[114:117], v[234:237], v[170:173]
	v_mfma_f32_16x16x32_bf16 v[58:61], v[122:125], v[234:237], v[174:177]
	v_mfma_f32_16x16x32_bf16 v[50:53], v[118:121], v[238:241], v[50:53]
	v_mfma_f32_16x16x32_bf16 v[58:61], v[126:129], v[238:241], v[58:61]
	s_setprio 0
	s_setprio 1
	v_mfma_f32_16x16x32_bf16 v[114:117], v[210:213], v[82:85], v[178:181]
	v_mfma_f32_16x16x32_bf16 v[82:85], v[218:221], v[82:85], v[182:185]
	v_mfma_f32_16x16x32_bf16 v[126:129], v[222:225], v[86:89], v[82:85]
	v_mfma_f32_16x16x32_bf16 v[82:85], v[210:213], v[98:101], v[186:189]
	v_mfma_f32_16x16x32_bf16 v[122:125], v[214:217], v[86:89], v[114:117]
	v_mfma_f32_16x16x32_bf16 v[114:117], v[214:217], v[106:109], v[82:85]
	v_mfma_f32_16x16x32_bf16 v[82:85], v[218:221], v[98:101], v[190:193]
	v_mfma_f32_16x16x32_bf16 v[118:121], v[222:225], v[106:109], v[82:85]
	v_mfma_f32_16x16x32_bf16 v[82:85], v[210:213], v[226:229], v[194:197]
	v_mfma_f32_16x16x32_bf16 v[98:101], v[214:217], v[230:233], v[82:85]
	v_mfma_f32_16x16x32_bf16 v[82:85], v[218:221], v[226:229], v[198:201]
	v_mfma_f32_16x16x32_bf16 v[106:109], v[222:225], v[230:233], v[82:85]
	v_mfma_f32_16x16x32_bf16 v[82:85], v[210:213], v[234:237], v[202:205]
	v_mfma_f32_16x16x32_bf16 v[86:89], v[218:221], v[234:237], v[206:209]
	v_mfma_f32_16x16x32_bf16 v[82:85], v[214:217], v[238:241], v[82:85]
	v_mfma_f32_16x16x32_bf16 v[86:89], v[222:225], v[238:241], v[86:89]
	s_barrier
	s_setprio 0
	s_add_u32 s78, s78, 0x100180
	s_addc_u32 s79, s79, 0
	s_add_u32 s14, s76, 0x200
	s_addc_u32 s15, s77, 0
	s_mov_b32 s16, 0
	.p2align	6

;     __host__ __device__ bool next(int i, Unit& u) const { if (!StaticOrder::next(i >> 1, u)) return false; u.seg = i & 1; return true; }
; #define PG8_STAGE(bufoff, gbase, voff) do { _Pragma("unroll") for (int _i = 0; _i < 2; ++_i) \
;         __builtin_amdgcn_global_load_lds((const unsigned*)((const char*)(gbase) + (voff)[_i]), (LAS unsigned*)(lds + (bufoff) + ldsw + _i * 8192), 16, 0, 0); } while (0)
; #define PG8_WAIT_V(n) asm volatile("s_waitcnt vmcnt(" #n ")" ::: "memory")
; #define PG8_BAR __builtin_amdgcn_s_barrier()
; #define PG8_TOUCH(p) asm volatile("global_load_dword %0, %1, off" : "+v"(pfd) : "v"(p) : "memory")
;     ...
;     for (int i = 0; i < 2; ++i) { int R, C; stage_rc(tid * 16 + i * 8192, R, C); const int Rb = Epi::PERM ? ((R & ~31) + perm32(R & 31)) : R;
;         voffA[i] = (unsigned)(R * g.lda + C) * 2u; voffB[i] = (unsigned)(Rb * g.ldb + C) * 2u; }
;     const size_t kstep = (size_t)(BK * 2);
;     const size_t hstepA = (size_t)HALF * g.lda * 2, hstepB = (size_t)HALF * g.ldb * 2;
;     const unsigned ldsw = (unsigned)wid * 1024u;
;     const int aoff = lds_byte(wr * 64 + fr, fq * 8), boff = lds_byte(wc * 32 + fr, fq * 8);
;     ...
;     PG8_STAGE(PG8_SB(0, 0), cB, voffB); PG8_STAGE(PG8_SB(0, 1), cB + hstepB, voffB); PG8_STAGE(PG8_SA(0, 0), cA, voffA); PG8_STAGE(PG8_SA(0, 1), cA + hstepA, voffA);
;     if (wr == 1) PG8_BAR;
;     PG8_WAIT_V(2); PG8_BAR;
;     PG8_STAGE(PG8_SB(1, 0), cB + kstep, voffB); PG8_STAGE(PG8_SA(1, 0), cA + kstep, voffA); PG8_STAGE(PG8_SB(1, 1), cB + hstepB + kstep, voffB);
;     PG8_WAIT_V(6); PG8_BAR;
;     if constexpr (PF > 0) { const char* p0 = PG8_PFPTR(cA, cB) + (size_t)(2 + PF) * kstep; PG8_TOUCH(p0); }
;     for (;;) {
;         const bool has_next = S.next(ui + 1, nxt);
;         const char* nA = has_next ? PG8_APTR(nxt) : cA; const char* nB = has_next ? PG8_BPTR(nxt) : cB;
;         const char* pfc = PG8_PFPTR(cA, cB); const char* pfn = PG8_PFPTR(nA, nB);
.LBB0_638:
	s_lshl_b32 s8, s8, 12
	s_lshl_b32 s0, s9, 13
	s_and_b32 s16, s8, 0x3000
	s_mov_b64 s[8:9], 0x80
	s_add_i32 m0, s33, 0x18000
	v_lshl_add_u64 v[8:9], v[8:9], 0, s[8:9]
	s_waitcnt vmcnt(2)
	s_barrier
	global_load_lds_dwordx4 v[8:9], off
	v_lshl_add_u64 v[6:7], v[6:7], 0, s[8:9]
	s_add_i32 m0, s33, 0x1a000
	s_add_i32 s66, s33, 0x8000
	s_add_i32 s67, s33, 0xa000
	global_load_lds_dwordx4 v[6:7], off
	v_lshl_add_u64 v[2:3], v[2:3], 0, s[8:9]
	s_mov_b32 m0, s66
	s_add_u32 s14, s54, 0x40080
	global_load_lds_dwordx4 v[2:3], off
	v_lshl_add_u64 v[2:3], v[4:5], 0, s[8:9]
	s_mov_b32 m0, s67
	s_addc_u32 s15, s55, 0
	global_load_lds_dwordx4 v[2:3], off
	s_add_i32 m0, s33, 0x1c000
	v_lshl_add_u64 v[2:3], s[14:15], 0, v[134:135]
	global_load_lds_dwordx4 v[2:3], off
	v_lshl_add_u64 v[2:3], s[14:15], 0, v[130:131]
	s_add_i32 m0, s33, 0x1e000
	v_and_b32_e32 v0, 15, v10
	global_load_lds_dwordx4 v[2:3], off
	v_and_b32_e32 v2, 48, v10
	v_lshlrev_b32_e32 v0, 6, v0
	v_lshlrev_b32_e32 v4, 2, v10
	v_or_b32_e32 v3, v0, v2
	v_and_b32_e32 v4, 32, v4
	v_bitop3_b32 v0, v0, v4, v2 bitop3:0x36
	v_bitop3_b32 v2, v3, s0, v4 bitop3:0xde
	v_lshlrev_b32_e32 v3, 14, v14
	v_and_b32_e32 v3, 0xffff8000, v3
	v_lshl_add_u32 v3, v13, 11, v3
	v_and_b32_e32 v4, 1, v14
	v_lshl_or_b32 v3, v4, 6, v3
	v_lshl_add_u32 v138, v15, 1, v3
	v_lshlrev_b32_e32 v3, 14, v1
	v_and_b32_e32 v3, 0xffff8000, v3
	s_cmpk_lt_u32 s5, 0x100
	v_lshl_add_u32 v3, v11, 11, v3
	v_and_b32_e32 v1, 1, v1
	v_or_b32_e32 v0, s16, v0
	s_waitcnt vmcnt(6)
	s_cselect_b64 s[16:17], -1, 0
	v_lshl_or_b32 v1, v1, 6, v3
	s_add_i32 s72, 0, 0x10000
	s_add_i32 s74, 0, 0x14000
	s_add_i32 s76, 0, 0x18000
	s_add_i32 s78, 0, 0x1c000
	v_lshl_add_u32 v140, v12, 1, v1
	v_add_u32_e32 v1, s72, v0
	v_add_u32_e32 v150, s74, v0
	s_add_i32 s72, s72, s4
	s_add_i32 s74, s74, s4
	v_add_u32_e32 v152, s76, v0
	v_add_u32_e32 v153, s78, v0
	s_add_i32 s76, s76, s4
	s_add_i32 s78, s78, s4
	s_ashr_i32 s68, s3, 31
	v_mov_b32_e32 v139, v135
	v_mov_b32_e32 v141, v135
	v_add_u32_e32 v151, 0, v2
	s_add_i32 s69, s33, 0xc000
	s_add_i32 s70, s33, 0xe000
	s_mov_b64 s[18:19], 0x100
	s_mov_b64 s[20:21], 0x180
	s_movk_i32 s71, 0x1800
	s_add_i32 s73, s72, 0x2000
	s_add_i32 s75, s74, 0x2000
	s_add_i32 s77, s76, 0x2000
	s_add_i32 s79, s78, 0x2000
	s_mov_b32 s80, 0
	s_barrier
	s_branch .LBB0_641
	.p2align	6

;     __host__ __device__ bool next(int i, Unit& u) const { if (!StaticOrder::next(i >> 1, u)) return false; u.seg = i & 1; return true; }
;     ...
;         const bool has_next = S.next(ui + 1, nxt);
;         const char* nA = has_next ? PG8_APTR(nxt) : cA; const char* nB = has_next ? PG8_BPTR(nxt) : cB;
;         const char* pfc = PG8_PFPTR(cA, cB); const char* pfn = PG8_PFPTR(nA, nB);
.LBB0_643:
	s_ashr_i32 s23, s22, 31
	ds_read_b128 v[2:5], v1
	ds_read_b128 v[6:9], v1 offset:1024
	ds_read_b128 v[10:13], v1 offset:2048
	ds_read_b128 v[14:17], v1 offset:3072
	ds_read_b128 v[18:21], v150
	ds_read_b128 v[22:25], v150 offset:1024
	ds_read_b128 v[26:29], v150 offset:2048
	ds_read_b128 v[30:33], v150 offset:3072
	s_lshl_b64 s[14:15], s[22:23], 19
	s_add_u32 s28, s24, s14
	s_addc_u32 s29, s25, s15
	s_and_b64 s[14:15], s[4:5], exec
	s_cselect_b32 s23, s29, s63
	s_cselect_b32 s83, s28, s62
	s_and_b32 s0, s81, 0x7fffffff
	s_lshl_b64 s[14:15], s[0:1], 19
	s_add_u32 s30, s10, s14
	s_addc_u32 s31, s11, s15
	s_and_b64 s[14:15], s[4:5], exec
	s_cselect_b32 s0, s31, s55
	s_cselect_b32 s86, s30, s54
	s_add_u32 s14, s62, 0x40080
	s_addc_u32 s15, s63, 0
	s_mov_b32 m0, s69
	v_lshl_add_u64 v[66:67], s[14:15], 0, v[136:137]
	ds_read_b128 v[34:37], v151
	ds_read_b128 v[38:41], v151 offset:1024
	ds_read_b128 v[42:45], v151 offset:2048
	ds_read_b128 v[46:49], v151 offset:3072
	ds_read_b128 v[50:53], v151 offset:4096
	ds_read_b128 v[54:57], v151 offset:5120
	ds_read_b128 v[58:61], v151 offset:6144
	ds_read_b128 v[62:65], v151 offset:7168
	global_load_lds_dwordx4 v[66:67], off
	v_lshl_add_u64 v[66:67], s[14:15], 0, v[132:133]
	s_mov_b32 m0, s70
	s_nop 0
	global_load_lds_dwordx4 v[66:67], off
	s_waitcnt vmcnt(8)
	s_waitcnt lgkmcnt(0)
	s_setprio 1
	s_barrier
	v_mfma_f32_16x16x32_bf16 v[90:93], v[2:5], v[58:61], 0
	v_mfma_f32_16x16x32_bf16 v[66:69], v[2:5], v[34:37], 0
	v_mfma_f32_16x16x32_bf16 v[70:73], v[10:13], v[34:37], 0
	v_mfma_f32_16x16x32_bf16 v[74:77], v[2:5], v[42:45], 0
	v_mfma_f32_16x16x32_bf16 v[78:81], v[10:13], v[42:45], 0
	v_mfma_f32_16x16x32_bf16 v[82:85], v[2:5], v[50:53], 0
	v_mfma_f32_16x16x32_bf16 v[86:89], v[10:13], v[50:53], 0
	v_mfma_f32_16x16x32_bf16 v[94:97], v[6:9], v[62:65], v[90:93]
	v_mfma_f32_16x16x32_bf16 v[90:93], v[10:13], v[58:61], 0
	v_mfma_f32_16x16x32_bf16 v[66:69], v[6:9], v[38:41], v[66:69]
	v_mfma_f32_16x16x32_bf16 v[70:73], v[14:17], v[38:41], v[70:73]
	v_mfma_f32_16x16x32_bf16 v[74:77], v[6:9], v[46:49], v[74:77]
	v_mfma_f32_16x16x32_bf16 v[78:81], v[14:17], v[46:49], v[78:81]
	v_mfma_f32_16x16x32_bf16 v[82:85], v[6:9], v[54:57], v[82:85]
	v_mfma_f32_16x16x32_bf16 v[86:89], v[14:17], v[54:57], v[86:89]
	v_mfma_f32_16x16x32_bf16 v[102:105], v[14:17], v[62:65], v[90:93]
	s_setprio 0
	s_setprio 1
	v_mfma_f32_16x16x32_bf16 v[90:93], v[18:21], v[34:37], 0
	v_mfma_f32_16x16x32_bf16 v[34:37], v[26:29], v[34:37], 0
	v_mfma_f32_16x16x32_bf16 v[110:113], v[22:25], v[38:41], v[90:93]
	v_mfma_f32_16x16x32_bf16 v[34:37], v[30:33], v[38:41], v[34:37]
	v_mfma_f32_16x16x32_bf16 v[38:41], v[18:21], v[42:45], 0
	v_mfma_f32_16x16x32_bf16 v[42:45], v[26:29], v[42:45], 0
	v_mfma_f32_16x16x32_bf16 v[38:41], v[22:25], v[46:49], v[38:41]
	v_mfma_f32_16x16x32_bf16 v[42:45], v[30:33], v[46:49], v[42:45]
	v_mfma_f32_16x16x32_bf16 v[46:49], v[18:21], v[50:53], 0
	v_mfma_f32_16x16x32_bf16 v[50:53], v[26:29], v[50:53], 0
	v_mfma_f32_16x16x32_bf16 v[46:49], v[22:25], v[54:57], v[46:49]
	v_mfma_f32_16x16x32_bf16 v[54:57], v[30:33], v[54:57], v[50:53]
	v_mfma_f32_16x16x32_bf16 v[50:53], v[18:21], v[58:61], 0
	v_mfma_f32_16x16x32_bf16 v[146:149], v[22:25], v[62:65], v[50:53]
	v_mfma_f32_16x16x32_bf16 v[50:53], v[26:29], v[58:61], 0
	v_mfma_f32_16x16x32_bf16 v[154:157], v[30:33], v[62:65], v[50:53]
	s_barrier
	s_setprio 0
	v_lshl_add_u64 v[250:251], s[54:55], 0, v[134:135]
	s_mov_b32 m0, s72
	v_lshl_add_u64 v[122:123], v[250:251], 0, s[18:19]
	v_lshl_add_u64 v[252:253], s[54:55], 0, v[130:131]
	s_add_u32 s14, s54, 0x40100
	ds_read_b128 v[50:53], v151 offset:16384
	ds_read_b128 v[58:61], v151 offset:17408
	ds_read_b128 v[62:65], v151 offset:18432
	ds_read_b128 v[90:93], v151 offset:19456
	ds_read_b128 v[98:101], v151 offset:20480
	ds_read_b128 v[106:109], v151 offset:21504
	ds_read_b128 v[114:117], v151 offset:22528
	ds_read_b128 v[118:121], v151 offset:23552
	global_load_lds_dwordx4 v[122:123], off
	v_lshl_add_u64 v[122:123], v[252:253], 0, s[18:19]
	s_mov_b32 m0, s73
	s_addc_u32 s15, s55, 0
	global_load_lds_dwordx4 v[122:123], off
	v_lshl_add_u64 v[122:123], s[14:15], 0, v[134:135]
	s_mov_b32 m0, s74
	v_lshl_add_u64 v[142:143], s[62:63], 0, v[136:137]
	global_load_lds_dwordx4 v[122:123], off
	v_lshl_add_u64 v[122:123], s[14:15], 0, v[130:131]
	s_mov_b32 m0, s75
	v_lshl_add_u64 v[144:145], s[62:63], 0, v[132:133]
	global_load_lds_dwordx4 v[122:123], off
	v_lshl_add_u64 v[122:123], v[142:143], 0, s[18:19]
	s_mov_b32 m0, s33
	s_nop 0
	global_load_lds_dwordx4 v[122:123], off
	v_lshl_add_u64 v[122:123], v[144:145], 0, s[18:19]
	s_mov_b32 m0, s41
	s_nop 0
	global_load_lds_dwordx4 v[122:123], off
	s_waitcnt vmcnt(8)
	s_waitcnt lgkmcnt(0)
	s_setprio 1
	s_barrier
	v_mfma_f32_16x16x32_bf16 v[122:125], v[2:5], v[50:53], 0
	v_mfma_f32_16x16x32_bf16 v[158:161], v[6:9], v[58:61], v[122:125]
	v_mfma_f32_16x16x32_bf16 v[122:125], v[10:13], v[50:53], 0
	v_mfma_f32_16x16x32_bf16 v[162:165], v[14:17], v[58:61], v[122:125]
	v_mfma_f32_16x16x32_bf16 v[122:125], v[2:5], v[62:65], 0
	v_mfma_f32_16x16x32_bf16 v[166:169], v[6:9], v[90:93], v[122:125]
	v_mfma_f32_16x16x32_bf16 v[122:125], v[10:13], v[62:65], 0
	v_mfma_f32_16x16x32_bf16 v[170:173], v[14:17], v[90:93], v[122:125]
	v_mfma_f32_16x16x32_bf16 v[122:125], v[2:5], v[98:101], 0
	v_mfma_f32_16x16x32_bf16 v[2:5], v[2:5], v[114:117], 0
	v_mfma_f32_16x16x32_bf16 v[174:177], v[6:9], v[106:109], v[122:125]
	v_mfma_f32_16x16x32_bf16 v[2:5], v[6:9], v[118:121], v[2:5]
	v_mfma_f32_16x16x32_bf16 v[6:9], v[10:13], v[114:117], 0
	v_mfma_f32_16x16x32_bf16 v[122:125], v[10:13], v[98:101], 0
	v_mfma_f32_16x16x32_bf16 v[6:9], v[14:17], v[118:121], v[6:9]
	v_mfma_f32_16x16x32_bf16 v[178:181], v[14:17], v[106:109], v[122:125]
	s_setprio 0
	s_setprio 1
	v_mfma_f32_16x16x32_bf16 v[10:13], v[18:21], v[50:53], 0
	v_mfma_f32_16x16x32_bf16 v[14:17], v[22:25], v[58:61], v[10:13]
	v_mfma_f32_16x16x32_bf16 v[10:13], v[26:29], v[50:53], 0
	v_mfma_f32_16x16x32_bf16 v[182:185], v[30:33], v[58:61], v[10:13]
	v_mfma_f32_16x16x32_bf16 v[10:13], v[18:21], v[62:65], 0
	v_mfma_f32_16x16x32_bf16 v[186:189], v[22:25], v[90:93], v[10:13]
	v_mfma_f32_16x16x32_bf16 v[10:13], v[26:29], v[62:65], 0
	v_mfma_f32_16x16x32_bf16 v[190:193], v[30:33], v[90:93], v[10:13]
	v_mfma_f32_16x16x32_bf16 v[10:13], v[18:21], v[98:101], 0
	v_mfma_f32_16x16x32_bf16 v[194:197], v[22:25], v[106:109], v[10:13]
	v_mfma_f32_16x16x32_bf16 v[10:13], v[26:29], v[98:101], 0
	v_mfma_f32_16x16x32_bf16 v[198:201], v[30:33], v[106:109], v[10:13]
	v_mfma_f32_16x16x32_bf16 v[10:13], v[18:21], v[114:117], 0
	v_mfma_f32_16x16x32_bf16 v[202:205], v[22:25], v[118:121], v[10:13]
	v_mfma_f32_16x16x32_bf16 v[10:13], v[26:29], v[114:117], 0
	v_mfma_f32_16x16x32_bf16 v[206:209], v[30:33], v[118:121], v[10:13]
	s_barrier
	s_setprio 0
	s_nop 4
	ds_read_b128 v[10:13], v152
	ds_read_b128 v[22:25], v152 offset:1024
	ds_read_b128 v[30:33], v152 offset:2048
	ds_read_b128 v[210:213], v152 offset:3072
	ds_read_b128 v[214:217], v153
	ds_read_b128 v[218:221], v153 offset:1024
	ds_read_b128 v[222:225], v153 offset:2048
	ds_read_b128 v[226:229], v153 offset:3072
	s_add_u32 s14, s62, 0x40100
	s_addc_u32 s15, s63, 0
	s_mov_b32 m0, s58
	v_lshl_add_u64 v[50:51], s[14:15], 0, v[136:137]
	ds_read_b128 v[18:21], v151 offset:32768
	ds_read_b128 v[26:29], v151 offset:33792
	ds_read_b128 v[62:65], v151 offset:34816
	ds_read_b128 v[230:233], v151 offset:35840
	ds_read_b128 v[234:237], v151 offset:36864
	ds_read_b128 v[238:241], v151 offset:37888
	ds_read_b128 v[242:245], v151 offset:38912
	ds_read_b128 v[246:249], v151 offset:39936
	global_load_lds_dwordx4 v[50:51], off
	v_lshl_add_u64 v[50:51], s[14:15], 0, v[132:133]
	s_mov_b32 m0, s59
	s_nop 0
	global_load_lds_dwordx4 v[50:51], off
	s_waitcnt vmcnt(8)
	s_waitcnt lgkmcnt(0)
	s_setprio 1
	s_barrier
	v_mfma_f32_16x16x32_bf16 v[50:53], v[10:13], v[18:21], v[66:69]
	v_mfma_f32_16x16x32_bf16 v[122:125], v[22:25], v[26:29], v[50:53]
	v_mfma_f32_16x16x32_bf16 v[50:53], v[30:33], v[18:21], v[70:73]
	v_mfma_f32_16x16x32_bf16 v[114:117], v[210:213], v[26:29], v[50:53]
	v_mfma_f32_16x16x32_bf16 v[50:53], v[10:13], v[62:65], v[74:77]
	v_mfma_f32_16x16x32_bf16 v[106:109], v[22:25], v[230:233], v[50:53]
	v_mfma_f32_16x16x32_bf16 v[50:53], v[30:33], v[62:65], v[78:81]
	v_mfma_f32_16x16x32_bf16 v[98:101], v[210:213], v[230:233], v[50:53]
	v_mfma_f32_16x16x32_bf16 v[50:53], v[10:13], v[234:237], v[82:85]
	v_mfma_f32_16x16x32_bf16 v[90:93], v[22:25], v[238:241], v[50:53]
	v_mfma_f32_16x16x32_bf16 v[50:53], v[30:33], v[234:237], v[86:89]
	v_mfma_f32_16x16x32_bf16 v[82:85], v[210:213], v[238:241], v[50:53]
	v_mfma_f32_16x16x32_bf16 v[50:53], v[10:13], v[242:245], v[94:97]
	v_mfma_f32_16x16x32_bf16 v[58:61], v[22:25], v[246:249], v[50:53]
	v_mfma_f32_16x16x32_bf16 v[50:53], v[30:33], v[242:245], v[102:105]
	v_mfma_f32_16x16x32_bf16 v[50:53], v[210:213], v[246:249], v[50:53]
	s_setprio 0
	s_setprio 1
	v_mfma_f32_16x16x32_bf16 v[66:69], v[214:217], v[18:21], v[110:113]
	v_mfma_f32_16x16x32_bf16 v[18:21], v[222:225], v[18:21], v[34:37]
	v_mfma_f32_16x16x32_bf16 v[118:121], v[226:229], v[26:29], v[18:21]
	v_mfma_f32_16x16x32_bf16 v[18:21], v[214:217], v[62:65], v[38:41]
	v_mfma_f32_16x16x32_bf16 v[110:113], v[218:221], v[230:233], v[18:21]
	v_mfma_f32_16x16x32_bf16 v[18:21], v[222:225], v[62:65], v[42:45]
	v_mfma_f32_16x16x32_bf16 v[102:105], v[226:229], v[230:233], v[18:21]
	v_mfma_f32_16x16x32_bf16 v[18:21], v[214:217], v[234:237], v[46:49]
	v_mfma_f32_16x16x32_bf16 v[94:97], v[218:221], v[238:241], v[18:21]
	v_mfma_f32_16x16x32_bf16 v[18:21], v[222:225], v[234:237], v[54:57]
	v_mfma_f32_16x16x32_bf16 v[86:89], v[226:229], v[238:241], v[18:21]
	v_mfma_f32_16x16x32_bf16 v[18:21], v[214:217], v[242:245], v[146:149]
	v_mfma_f32_16x16x32_bf16 v[62:65], v[218:221], v[246:249], v[18:21]
	v_mfma_f32_16x16x32_bf16 v[18:21], v[222:225], v[242:245], v[154:157]
	v_mfma_f32_16x16x32_bf16 v[126:129], v[218:221], v[26:29], v[66:69]
	v_mfma_f32_16x16x32_bf16 v[54:57], v[226:229], v[246:249], v[18:21]
	s_barrier
;     ...
;         for (int t = 2; t < nt; t += 2) PG8_KITER(t);
	s_setprio 0
	s_mov_b32 m0, s76
	s_nop 2
	v_lshl_add_u64 v[18:19], v[250:251], 0, s[20:21]
	s_add_u32 s14, s54, 0x40180
	ds_read_b128 v[38:41], v151 offset:49152
	ds_read_b128 v[46:49], v151 offset:50176
	ds_read_b128 v[146:149], v151 offset:51200
	ds_read_b128 v[154:157], v151 offset:52224
	ds_read_b128 v[230:233], v151 offset:53248
	ds_read_b128 v[234:237], v151 offset:54272
	ds_read_b128 v[238:241], v151 offset:55296
	ds_read_b128 v[242:245], v151 offset:56320
	global_load_lds_dwordx4 v[18:19], off
	v_lshl_add_u64 v[18:19], v[252:253], 0, s[20:21]
	s_mov_b32 m0, s77
	s_addc_u32 s15, s55, 0
	global_load_lds_dwordx4 v[18:19], off
	v_lshl_add_u64 v[18:19], s[14:15], 0, v[134:135]
	s_mov_b32 m0, s78
	s_nop 0
	global_load_lds_dwordx4 v[18:19], off
	v_lshl_add_u64 v[18:19], s[14:15], 0, v[130:131]
	s_mov_b32 m0, s79
	s_nop 0
	global_load_lds_dwordx4 v[18:19], off
	v_lshl_add_u64 v[18:19], v[142:143], 0, s[20:21]
	s_mov_b32 m0, s66
	s_nop 0
	global_load_lds_dwordx4 v[18:19], off
	v_lshl_add_u64 v[18:19], v[144:145], 0, s[20:21]
	s_mov_b32 m0, s67
	s_nop 0
	global_load_lds_dwordx4 v[18:19], off
	s_waitcnt vmcnt(8)
	s_waitcnt lgkmcnt(0)
	s_setprio 1
	s_barrier
	v_mfma_f32_16x16x32_bf16 v[18:21], v[10:13], v[38:41], v[158:161]
	v_mfma_f32_16x16x32_bf16 v[74:77], v[22:25], v[46:49], v[18:21]
	v_mfma_f32_16x16x32_bf16 v[18:21], v[30:33], v[38:41], v[162:165]
	v_mfma_f32_16x16x32_bf16 v[66:69], v[210:213], v[46:49], v[18:21]
	v_mfma_f32_16x16x32_bf16 v[18:21], v[10:13], v[146:149], v[166:169]
	v_mfma_f32_16x16x32_bf16 v[42:45], v[22:25], v[154:157], v[18:21]
	v_mfma_f32_16x16x32_bf16 v[18:21], v[30:33], v[146:149], v[170:173]
	v_mfma_f32_16x16x32_bf16 v[34:37], v[210:213], v[154:157], v[18:21]
	v_mfma_f32_16x16x32_bf16 v[18:21], v[10:13], v[230:233], v[174:177]
	v_mfma_f32_16x16x32_bf16 v[2:5], v[10:13], v[238:241], v[2:5]
	v_mfma_f32_16x16x32_bf16 v[26:29], v[22:25], v[234:237], v[18:21]
	v_mfma_f32_16x16x32_bf16 v[18:21], v[30:33], v[230:233], v[178:181]
	v_mfma_f32_16x16x32_bf16 v[10:13], v[22:25], v[242:245], v[2:5]
	v_mfma_f32_16x16x32_bf16 v[2:5], v[30:33], v[238:241], v[6:9]
	v_mfma_f32_16x16x32_bf16 v[18:21], v[210:213], v[234:237], v[18:21]
	v_mfma_f32_16x16x32_bf16 v[2:5], v[210:213], v[242:245], v[2:5]
	s_setprio 0
	s_setprio 1
	v_mfma_f32_16x16x32_bf16 v[6:9], v[214:217], v[38:41], v[14:17]
	v_mfma_f32_16x16x32_bf16 v[78:81], v[218:221], v[46:49], v[6:9]
	v_mfma_f32_16x16x32_bf16 v[6:9], v[222:225], v[38:41], v[182:185]
	v_mfma_f32_16x16x32_bf16 v[70:73], v[226:229], v[46:49], v[6:9]
	v_mfma_f32_16x16x32_bf16 v[6:9], v[214:217], v[146:149], v[186:189]
	v_mfma_f32_16x16x32_bf16 v[46:49], v[218:221], v[154:157], v[6:9]
	v_mfma_f32_16x16x32_bf16 v[6:9], v[222:225], v[146:149], v[190:193]
	v_mfma_f32_16x16x32_bf16 v[38:41], v[226:229], v[154:157], v[6:9]
	v_mfma_f32_16x16x32_bf16 v[6:9], v[214:217], v[230:233], v[194:197]
	v_mfma_f32_16x16x32_bf16 v[30:33], v[218:221], v[234:237], v[6:9]
	v_mfma_f32_16x16x32_bf16 v[6:9], v[222:225], v[230:233], v[198:201]
	v_mfma_f32_16x16x32_bf16 v[22:25], v[226:229], v[234:237], v[6:9]
	v_mfma_f32_16x16x32_bf16 v[6:9], v[214:217], v[238:241], v[202:205]
	v_mfma_f32_16x16x32_bf16 v[14:17], v[218:221], v[242:245], v[6:9]
	v_mfma_f32_16x16x32_bf16 v[6:9], v[222:225], v[238:241], v[206:209]
	v_mfma_f32_16x16x32_bf16 v[6:9], v[226:229], v[242:245], v[6:9]
	s_barrier
	s_setprio 0
	s_add_u32 s62, s62, 0x40180
	s_addc_u32 s63, s63, 0
	s_add_u32 s14, s54, 0x200
	s_addc_u32 s15, s55, 0
	s_mov_b32 s26, 0
	.p2align	6

;     __host__ __device__ bool next(int i, Unit& u) const { if (!StaticOrder::next(i >> 1, u)) return false; u.seg = i & 1; return true; }
; #define PG8_STAGE(bufoff, gbase, voff) do { _Pragma("unroll") for (int _i = 0; _i < 2; ++_i) \
;         __builtin_amdgcn_global_load_lds((const unsigned*)((const char*)(gbase) + (voff)[_i]), (LAS unsigned*)(lds + (bufoff) + ldsw + _i * 8192), 16, 0, 0); } while (0)
; #define PG8_WAIT_V(n) asm volatile("s_waitcnt vmcnt(" #n ")" ::: "memory")
; #define PG8_BAR __builtin_amdgcn_s_barrier()
; #define PG8_TOUCH(p) asm volatile("global_load_dword %0, %1, off" : "+v"(pfd) : "v"(p) : "memory")
;     ...
;     for (int i = 0; i < 2; ++i) { int R, C; stage_rc(tid * 16 + i * 8192, R, C); const int Rb = Epi::PERM ? ((R & ~31) + perm32(R & 31)) : R;
;         voffA[i] = (unsigned)(R * g.lda + C) * 2u; voffB[i] = (unsigned)(Rb * g.ldb + C) * 2u; }
;     const size_t kstep = (size_t)(BK * 2);
;     const size_t hstepA = (size_t)HALF * g.lda * 2, hstepB = (size_t)HALF * g.ldb * 2;
;     const unsigned ldsw = (unsigned)wid * 1024u;
;     const int aoff = lds_byte(wr * 64 + fr, fq * 8), boff = lds_byte(wc * 32 + fr, fq * 8);
;     ...
;     PG8_STAGE(PG8_SB(0, 0), cB, voffB); PG8_STAGE(PG8_SB(0, 1), cB + hstepB, voffB); PG8_STAGE(PG8_SA(0, 0), cA, voffA); PG8_STAGE(PG8_SA(0, 1), cA + hstepA, voffA);
;     if (wr == 1) PG8_BAR;
;     PG8_WAIT_V(2); PG8_BAR;
;     PG8_STAGE(PG8_SB(1, 0), cB + kstep, voffB); PG8_STAGE(PG8_SA(1, 0), cA + kstep, voffA); PG8_STAGE(PG8_SB(1, 1), cB + hstepB + kstep, voffB);
;     PG8_WAIT_V(6); PG8_BAR;
;     if constexpr (PF > 0) { const char* p0 = PG8_PFPTR(cA, cB) + (size_t)(2 + PF) * kstep; PG8_TOUCH(p0); }
;     for (;;) {
;         const bool has_next = S.next(ui + 1, nxt);
;         const char* nA = has_next ? PG8_APTR(nxt) : cA; const char* nB = has_next ? PG8_BPTR(nxt) : cB;
;         const char* pfc = PG8_PFPTR(cA, cB); const char* pfn = PG8_PFPTR(nA, nB);
.LBB0_660:
	s_mov_b64 s[16:17], 0x80
	s_lshl_b32 s5, s5, 12
	s_add_i32 m0, s58, 0x18000
	v_lshl_add_u64 v[8:9], v[8:9], 0, s[16:17]
	s_lshl_b32 s0, s14, 13
	s_and_b32 s5, s5, 0x3000
	s_waitcnt vmcnt(2)
	s_barrier
	global_load_lds_dwordx4 v[8:9], off
	v_lshl_add_u64 v[6:7], v[6:7], 0, s[16:17]
	s_add_i32 m0, s58, 0x1a000
	s_add_i32 s69, s58, 0x8000
	s_add_i32 s70, s58, 0xa000
	global_load_lds_dwordx4 v[6:7], off
	v_lshl_add_u64 v[2:3], v[2:3], 0, s[16:17]
	s_mov_b32 m0, s69
	s_add_u32 s14, s6, 0x20080
	global_load_lds_dwordx4 v[2:3], off
	v_lshl_add_u64 v[2:3], v[4:5], 0, s[16:17]
	s_mov_b32 m0, s70
	s_addc_u32 s15, s7, 0
	global_load_lds_dwordx4 v[2:3], off
	s_add_i32 m0, s58, 0x1c000
	v_lshl_add_u64 v[2:3], s[14:15], 0, v[140:141]
	global_load_lds_dwordx4 v[2:3], off
	v_lshl_add_u64 v[2:3], s[14:15], 0, v[144:145]
	s_add_i32 m0, s58, 0x1e000
	v_and_b32_e32 v0, 15, v1
	global_load_lds_dwordx4 v[2:3], off
	v_and_b32_e32 v2, 48, v1
	v_lshlrev_b32_e32 v1, 2, v1
	v_lshlrev_b32_e32 v0, 6, v0
	v_and_b32_e32 v1, 32, v1
	v_or_b32_e32 v3, v0, v2
	v_bitop3_b32 v0, v0, v1, v2 bitop3:0x36
	v_bitop3_b32 v2, v3, s0, v1 bitop3:0xde
	v_or_b32_e32 v1, s5, v0
	v_lshlrev_b32_e32 v0, 13, v10
	v_and_b32_e32 v0, 0xffffc000, v0
	v_lshl_add_u32 v0, v11, 10, v0
	v_and_b32_e32 v3, 1, v10
	v_lshl_or_b32 v0, v3, 6, v0
	v_lshl_add_u32 v146, v12, 1, v0
	v_lshlrev_b32_e32 v0, 13, v13
	v_and_b32_e32 v0, 0xffffc000, v0
	s_waitcnt vmcnt(6)
	s_cmpk_lt_u32 s4, 0x100
	v_lshl_add_u32 v0, v14, 10, v0
	v_and_b32_e32 v3, 1, v13
	s_cselect_b64 s[18:19], -1, 0
	v_lshl_or_b32 v0, v3, 6, v0
	s_add_i32 s73, 0, 0x10000
	s_add_i32 s74, 0, 0x14000
	s_ashr_i32 s71, s3, 31
	s_ashr_i32 s72, s2, 31
	v_mov_b32_e32 v147, v141
	v_lshl_add_u32 v148, v15, 1, v0
	v_mov_b32_e32 v149, v141
	v_mov_b64_e32 v[152:153], 0x3ff
	v_add_u32_e32 v158, s73, v1
	v_add_u32_e32 v159, s74, v1
	v_add_u32_e32 v160, 0, v2
	s_mov_b64 s[20:21], 0x100
	s_mov_b64 s[22:23], 0x180
	v_mov_b32_e32 v161, 0x358637bd
	s_mov_b32 s75, 0x800000
	s_mov_b32 s76, 0
	s_barrier
	s_branch .LBB0_663
	.p2align	6

;     __host__ __device__ bool next(int i, Unit& u) const { if (!StaticOrder::next(i >> 1, u)) return false; u.seg = i & 1; return true; }
;     ...
;         const bool has_next = S.next(ui + 1, nxt);
;         const char* nA = has_next ? PG8_APTR(nxt) : cA; const char* nB = has_next ? PG8_BPTR(nxt) : cB;
;         const char* pfc = PG8_PFPTR(cA, cB); const char* pfn = PG8_PFPTR(nA, nB);
.LBB0_669:
	s_ashr_i32 s29, s28, 31
	ds_read_b128 v[2:5], v158
	ds_read_b128 v[6:9], v158 offset:1024
	ds_read_b128 v[10:13], v158 offset:2048
	ds_read_b128 v[14:17], v158 offset:3072
	ds_read_b128 v[18:21], v159
	ds_read_b128 v[22:25], v159 offset:1024
	ds_read_b128 v[26:29], v159 offset:2048
	ds_read_b128 v[30:33], v159 offset:3072
	s_lshl_b64 s[14:15], s[28:29], 18
	s_add_u32 s30, s10, s14
	s_addc_u32 s31, s11, s15
	s_and_b64 s[14:15], s[4:5], exec
	s_cselect_b32 s29, s31, s65
	s_cselect_b32 s79, s30, s64
	s_and_b32 s0, s77, 0x7fffffff
	s_lshl_b64 s[14:15], s[0:1], 18
	s_add_u32 s40, s12, s14
	s_addc_u32 s41, s13, s15
	s_and_b64 s[14:15], s[4:5], exec
	s_cselect_b32 s0, s41, s7
	s_cselect_b32 s80, s40, s6
	s_add_u32 s14, s64, 0x20080
	s_addc_u32 s15, s65, 0
	s_add_i32 s81, s58, 0xc000
	v_lshl_add_u64 v[66:67], s[14:15], 0, v[138:139]
	s_mov_b32 m0, s81
	s_add_i32 s82, s58, 0xe000
	ds_read_b128 v[34:37], v160
	ds_read_b128 v[38:41], v160 offset:1024
	ds_read_b128 v[42:45], v160 offset:2048
	ds_read_b128 v[46:49], v160 offset:3072
	ds_read_b128 v[50:53], v160 offset:4096
	ds_read_b128 v[54:57], v160 offset:5120
	ds_read_b128 v[58:61], v160 offset:6144
	ds_read_b128 v[62:65], v160 offset:7168
	global_load_lds_dwordx4 v[66:67], off
	v_lshl_add_u64 v[66:67], s[14:15], 0, v[142:143]
	s_mov_b32 m0, s82
	s_nop 0
	global_load_lds_dwordx4 v[66:67], off
	s_waitcnt vmcnt(8)
	s_waitcnt lgkmcnt(0)
	s_setprio 1
	s_barrier
	v_mfma_f32_16x16x32_bf16 v[90:93], v[2:5], v[58:61], 0
	v_mfma_f32_16x16x32_bf16 v[66:69], v[2:5], v[34:37], 0
	v_mfma_f32_16x16x32_bf16 v[70:73], v[10:13], v[34:37], 0
	v_mfma_f32_16x16x32_bf16 v[74:77], v[2:5], v[42:45], 0
	v_mfma_f32_16x16x32_bf16 v[78:81], v[10:13], v[42:45], 0
	v_mfma_f32_16x16x32_bf16 v[82:85], v[2:5], v[50:53], 0
	v_mfma_f32_16x16x32_bf16 v[86:89], v[10:13], v[50:53], 0
	v_mfma_f32_16x16x32_bf16 v[102:105], v[6:9], v[62:65], v[90:93]
	v_mfma_f32_16x16x32_bf16 v[90:93], v[10:13], v[58:61], 0
	v_mfma_f32_16x16x32_bf16 v[66:69], v[6:9], v[38:41], v[66:69]
	v_mfma_f32_16x16x32_bf16 v[70:73], v[14:17], v[38:41], v[70:73]
	v_mfma_f32_16x16x32_bf16 v[74:77], v[6:9], v[46:49], v[74:77]
	v_mfma_f32_16x16x32_bf16 v[78:81], v[14:17], v[46:49], v[78:81]
	v_mfma_f32_16x16x32_bf16 v[82:85], v[6:9], v[54:57], v[82:85]
	v_mfma_f32_16x16x32_bf16 v[86:89], v[14:17], v[54:57], v[86:89]
	v_mfma_f32_16x16x32_bf16 v[106:109], v[14:17], v[62:65], v[90:93]
	s_setprio 0
	s_setprio 1
	v_mfma_f32_16x16x32_bf16 v[90:93], v[18:21], v[34:37], 0
	v_mfma_f32_16x16x32_bf16 v[34:37], v[26:29], v[34:37], 0
	v_mfma_f32_16x16x32_bf16 v[122:125], v[22:25], v[38:41], v[90:93]
	v_mfma_f32_16x16x32_bf16 v[34:37], v[30:33], v[38:41], v[34:37]
	v_mfma_f32_16x16x32_bf16 v[38:41], v[18:21], v[42:45], 0
	v_mfma_f32_16x16x32_bf16 v[42:45], v[26:29], v[42:45], 0
	v_mfma_f32_16x16x32_bf16 v[38:41], v[22:25], v[46:49], v[38:41]
	v_mfma_f32_16x16x32_bf16 v[42:45], v[30:33], v[46:49], v[42:45]
	v_mfma_f32_16x16x32_bf16 v[46:49], v[18:21], v[50:53], 0
	v_mfma_f32_16x16x32_bf16 v[50:53], v[26:29], v[50:53], 0
	v_mfma_f32_16x16x32_bf16 v[46:49], v[22:25], v[54:57], v[46:49]
	v_mfma_f32_16x16x32_bf16 v[50:53], v[30:33], v[54:57], v[50:53]
	v_mfma_f32_16x16x32_bf16 v[54:57], v[18:21], v[58:61], 0
	v_mfma_f32_16x16x32_bf16 v[58:61], v[26:29], v[58:61], 0
	v_mfma_f32_16x16x32_bf16 v[54:57], v[22:25], v[62:65], v[54:57]
	v_mfma_f32_16x16x32_bf16 v[58:61], v[30:33], v[62:65], v[58:61]
	s_barrier
	s_setprio 0
	s_add_i32 s83, s73, s33
	v_lshl_add_u64 v[136:137], s[6:7], 0, v[140:141]
	s_add_i32 s84, s83, 0x2000
	v_lshl_add_u64 v[130:131], v[136:137], 0, s[20:21]
	s_mov_b32 m0, s83
	v_lshl_add_u64 v[250:251], s[6:7], 0, v[144:145]
	s_add_u32 s14, s6, 0x20100
	ds_read_b128 v[62:65], v160 offset:16384
	ds_read_b128 v[90:93], v160 offset:17408
	ds_read_b128 v[94:97], v160 offset:18432
	ds_read_b128 v[98:101], v160 offset:19456
	ds_read_b128 v[110:113], v160 offset:20480
	ds_read_b128 v[114:117], v160 offset:21504
	ds_read_b128 v[118:121], v160 offset:22528
	ds_read_b128 v[126:129], v160 offset:23552
	global_load_lds_dwordx4 v[130:131], off
	v_lshl_add_u64 v[130:131], v[250:251], 0, s[20:21]
	s_mov_b32 m0, s84
	s_addc_u32 s15, s7, 0
	s_add_i32 s85, s74, s33
	global_load_lds_dwordx4 v[130:131], off
	v_lshl_add_u64 v[130:131], s[14:15], 0, v[140:141]
	s_mov_b32 m0, s85
	s_add_i32 s46, s85, 0x2000
	global_load_lds_dwordx4 v[130:131], off
	v_lshl_add_u64 v[130:131], s[14:15], 0, v[144:145]
	s_mov_b32 m0, s46
	v_lshl_add_u64 v[252:253], s[64:65], 0, v[138:139]
	global_load_lds_dwordx4 v[130:131], off
	v_lshl_add_u64 v[130:131], v[252:253], 0, s[20:21]
	s_mov_b32 m0, s58
	v_lshl_add_u64 v[150:151], s[64:65], 0, v[142:143]
	global_load_lds_dwordx4 v[130:131], off
	v_lshl_add_u64 v[130:131], v[150:151], 0, s[20:21]
	s_mov_b32 m0, s59
	s_nop 0
	global_load_lds_dwordx4 v[130:131], off
	s_waitcnt vmcnt(8)
	s_waitcnt lgkmcnt(0)
	s_setprio 1
	s_barrier
	v_mfma_f32_16x16x32_bf16 v[130:133], v[2:5], v[62:65], 0
	v_mfma_f32_16x16x32_bf16 v[162:165], v[2:5], v[94:97], 0
	v_mfma_f32_16x16x32_bf16 v[170:173], v[2:5], v[110:113], 0
	v_mfma_f32_16x16x32_bf16 v[2:5], v[2:5], v[118:121], 0
	v_mfma_f32_16x16x32_bf16 v[132:135], v[6:9], v[90:93], v[130:133]
	v_mfma_f32_16x16x32_bf16 v[162:165], v[6:9], v[98:101], v[162:165]
	v_mfma_f32_16x16x32_bf16 v[170:173], v[6:9], v[114:117], v[170:173]
	v_mfma_f32_16x16x32_bf16 v[2:5], v[6:9], v[126:129], v[2:5]
	v_mfma_f32_16x16x32_bf16 v[6:9], v[10:13], v[118:121], 0
	v_mfma_f32_16x16x32_bf16 v[154:157], v[10:13], v[62:65], 0
	v_mfma_f32_16x16x32_bf16 v[166:169], v[10:13], v[94:97], 0
	v_mfma_f32_16x16x32_bf16 v[174:177], v[10:13], v[110:113], 0
	v_mfma_f32_16x16x32_bf16 v[6:9], v[14:17], v[126:129], v[6:9]
	v_mfma_f32_16x16x32_bf16 v[154:157], v[14:17], v[90:93], v[154:157]
	v_mfma_f32_16x16x32_bf16 v[166:169], v[14:17], v[98:101], v[166:169]
	v_mfma_f32_16x16x32_bf16 v[174:177], v[14:17], v[114:117], v[174:177]
	s_setprio 0
	s_setprio 1
	v_mfma_f32_16x16x32_bf16 v[10:13], v[18:21], v[62:65], 0
	v_mfma_f32_16x16x32_bf16 v[178:181], v[22:25], v[90:93], v[10:13]
	v_mfma_f32_16x16x32_bf16 v[10:13], v[26:29], v[62:65], 0
	v_mfma_f32_16x16x32_bf16 v[182:185], v[30:33], v[90:93], v[10:13]
	v_mfma_f32_16x16x32_bf16 v[10:13], v[18:21], v[94:97], 0
	v_mfma_f32_16x16x32_bf16 v[186:189], v[22:25], v[98:101], v[10:13]
	v_mfma_f32_16x16x32_bf16 v[10:13], v[26:29], v[94:97], 0
	v_mfma_f32_16x16x32_bf16 v[190:193], v[30:33], v[98:101], v[10:13]
	v_mfma_f32_16x16x32_bf16 v[10:13], v[18:21], v[110:113], 0
	v_mfma_f32_16x16x32_bf16 v[194:197], v[22:25], v[114:117], v[10:13]
	v_mfma_f32_16x16x32_bf16 v[10:13], v[26:29], v[110:113], 0
	v_mfma_f32_16x16x32_bf16 v[198:201], v[30:33], v[114:117], v[10:13]
	v_mfma_f32_16x16x32_bf16 v[10:13], v[18:21], v[118:121], 0
	v_mfma_f32_16x16x32_bf16 v[202:205], v[22:25], v[126:129], v[10:13]
	v_mfma_f32_16x16x32_bf16 v[10:13], v[26:29], v[118:121], 0
	v_mfma_f32_16x16x32_bf16 v[206:209], v[30:33], v[126:129], v[10:13]
	s_barrier
	s_setprio 0
	s_add_i32 s47, 0, 0x18000
	s_add_i32 s56, 0, 0x1c000
	v_add_u32_e32 v130, s47, v1
	v_add_u32_e32 v131, s56, v1
	s_nop 0
	ds_read_b128 v[10:13], v130
	ds_read_b128 v[14:17], v130 offset:1024
	ds_read_b128 v[18:21], v130 offset:2048
	ds_read_b128 v[22:25], v130 offset:3072
	ds_read_b128 v[210:213], v131
	ds_read_b128 v[214:217], v131 offset:1024
	ds_read_b128 v[218:221], v131 offset:2048
	ds_read_b128 v[222:225], v131 offset:3072
	s_add_u32 s14, s64, 0x20100
	s_addc_u32 s15, s65, 0
	s_mov_b32 m0, s63
	v_lshl_add_u64 v[90:91], s[14:15], 0, v[138:139]
	ds_read_b128 v[26:29], v160 offset:32768
	ds_read_b128 v[30:33], v160 offset:33792
	ds_read_b128 v[62:65], v160 offset:34816
	ds_read_b128 v[226:229], v160 offset:35840
	ds_read_b128 v[230:233], v160 offset:36864
	ds_read_b128 v[234:237], v160 offset:37888
	ds_read_b128 v[238:241], v160 offset:38912
	ds_read_b128 v[242:245], v160 offset:39936
	global_load_lds_dwordx4 v[90:91], off
	v_lshl_add_u64 v[90:91], s[14:15], 0, v[142:143]
	s_mov_b32 m0, s68
	s_nop 0
	global_load_lds_dwordx4 v[90:91], off
	s_waitcnt vmcnt(8)
	s_waitcnt lgkmcnt(0)
	s_setprio 1
	s_barrier
	v_mfma_f32_16x16x32_bf16 v[66:69], v[10:13], v[26:29], v[66:69]
	v_mfma_f32_16x16x32_bf16 v[118:121], v[14:17], v[30:33], v[66:69]
	v_mfma_f32_16x16x32_bf16 v[66:69], v[18:21], v[26:29], v[70:73]
	v_mfma_f32_16x16x32_bf16 v[114:117], v[22:25], v[30:33], v[66:69]
	v_mfma_f32_16x16x32_bf16 v[66:69], v[10:13], v[62:65], v[74:77]
	v_mfma_f32_16x16x32_bf16 v[110:113], v[14:17], v[226:229], v[66:69]
	v_mfma_f32_16x16x32_bf16 v[66:69], v[18:21], v[62:65], v[78:81]
	v_mfma_f32_16x16x32_bf16 v[98:101], v[22:25], v[226:229], v[66:69]
	v_mfma_f32_16x16x32_bf16 v[66:69], v[10:13], v[230:233], v[82:85]
	v_mfma_f32_16x16x32_bf16 v[94:97], v[14:17], v[234:237], v[66:69]
	v_mfma_f32_16x16x32_bf16 v[66:69], v[18:21], v[230:233], v[86:89]
	v_mfma_f32_16x16x32_bf16 v[90:93], v[22:25], v[234:237], v[66:69]
	v_mfma_f32_16x16x32_bf16 v[66:69], v[10:13], v[238:241], v[102:105]
	v_mfma_f32_16x16x32_bf16 v[78:81], v[14:17], v[242:245], v[66:69]
	v_mfma_f32_16x16x32_bf16 v[66:69], v[18:21], v[238:241], v[106:109]
	v_mfma_f32_16x16x32_bf16 v[70:73], v[22:25], v[242:245], v[66:69]
	s_setprio 0
	s_setprio 1
	v_mfma_f32_16x16x32_bf16 v[66:69], v[210:213], v[26:29], v[122:125]
	v_mfma_f32_16x16x32_bf16 v[26:29], v[218:221], v[26:29], v[34:37]
	v_mfma_f32_16x16x32_bf16 v[122:125], v[222:225], v[30:33], v[26:29]
	v_mfma_f32_16x16x32_bf16 v[26:29], v[210:213], v[62:65], v[38:41]
	v_mfma_f32_16x16x32_bf16 v[106:109], v[214:217], v[226:229], v[26:29]
	v_mfma_f32_16x16x32_bf16 v[26:29], v[218:221], v[62:65], v[42:45]
	v_mfma_f32_16x16x32_bf16 v[102:105], v[222:225], v[226:229], v[26:29]
	v_mfma_f32_16x16x32_bf16 v[26:29], v[210:213], v[230:233], v[46:49]
	v_mfma_f32_16x16x32_bf16 v[86:89], v[214:217], v[234:237], v[26:29]
	v_mfma_f32_16x16x32_bf16 v[26:29], v[218:221], v[230:233], v[50:53]
	v_mfma_f32_16x16x32_bf16 v[82:85], v[222:225], v[234:237], v[26:29]
	v_mfma_f32_16x16x32_bf16 v[26:29], v[210:213], v[238:241], v[54:57]
	v_mfma_f32_16x16x32_bf16 v[62:65], v[214:217], v[242:245], v[26:29]
	v_mfma_f32_16x16x32_bf16 v[26:29], v[218:221], v[238:241], v[58:61]
	v_mfma_f32_16x16x32_bf16 v[126:129], v[214:217], v[30:33], v[66:69]
	v_mfma_f32_16x16x32_bf16 v[58:61], v[222:225], v[242:245], v[26:29]
	s_barrier
;     ...
;         for (int t = 2; t < nt; t += 2) PG8_KITER(t);
	s_setprio 0
	s_add_i32 s47, s47, s33
	s_add_i32 s86, s47, 0x2000
	s_nop 1
	v_lshl_add_u64 v[26:27], v[136:137], 0, s[22:23]
	s_mov_b32 m0, s47
	s_add_u32 s14, s6, 0x20180
	ds_read_b128 v[34:37], v160 offset:49152
	ds_read_b128 v[38:41], v160 offset:50176
	ds_read_b128 v[226:229], v160 offset:51200
	ds_read_b128 v[230:233], v160 offset:52224
	ds_read_b128 v[234:237], v160 offset:53248
	ds_read_b128 v[238:241], v160 offset:54272
	ds_read_b128 v[242:245], v160 offset:55296
	ds_read_b128 v[246:249], v160 offset:56320
	global_load_lds_dwordx4 v[26:27], off
	v_lshl_add_u64 v[26:27], v[250:251], 0, s[22:23]
	s_mov_b32 m0, s86
	s_addc_u32 s15, s7, 0
	s_add_i32 s56, s56, s33
	global_load_lds_dwordx4 v[26:27], off
	v_lshl_add_u64 v[26:27], s[14:15], 0, v[140:141]
	s_mov_b32 m0, s56
	s_add_i32 s57, s56, 0x2000
	global_load_lds_dwordx4 v[26:27], off
	v_lshl_add_u64 v[26:27], s[14:15], 0, v[144:145]
	s_mov_b32 m0, s57
	s_nop 0
	global_load_lds_dwordx4 v[26:27], off
	v_lshl_add_u64 v[26:27], v[252:253], 0, s[22:23]
	s_mov_b32 m0, s69
	s_nop 0
	global_load_lds_dwordx4 v[26:27], off
	v_lshl_add_u64 v[26:27], v[150:151], 0, s[22:23]
	s_mov_b32 m0, s70
	s_nop 0
	global_load_lds_dwordx4 v[26:27], off
	s_waitcnt vmcnt(8)
	s_waitcnt lgkmcnt(0)
	s_setprio 1
	s_barrier
	v_mfma_f32_16x16x32_bf16 v[26:29], v[10:13], v[34:37], v[132:135]
	v_mfma_f32_16x16x32_bf16 v[74:77], v[14:17], v[38:41], v[26:29]
	v_mfma_f32_16x16x32_bf16 v[26:29], v[18:21], v[34:37], v[154:157]
	v_mfma_f32_16x16x32_bf16 v[66:69], v[22:25], v[38:41], v[26:29]
	v_mfma_f32_16x16x32_bf16 v[26:29], v[10:13], v[226:229], v[162:165]
	v_mfma_f32_16x16x32_bf16 v[46:49], v[14:17], v[230:233], v[26:29]
	v_mfma_f32_16x16x32_bf16 v[26:29], v[18:21], v[226:229], v[166:169]
	v_mfma_f32_16x16x32_bf16 v[42:45], v[22:25], v[230:233], v[26:29]
	v_mfma_f32_16x16x32_bf16 v[26:29], v[10:13], v[234:237], v[170:173]
	v_mfma_f32_16x16x32_bf16 v[2:5], v[10:13], v[242:245], v[2:5]
	v_mfma_f32_16x16x32_bf16 v[30:33], v[14:17], v[238:241], v[26:29]
	v_mfma_f32_16x16x32_bf16 v[26:29], v[18:21], v[234:237], v[174:177]
	v_mfma_f32_16x16x32_bf16 v[14:17], v[14:17], v[246:249], v[2:5]
	v_mfma_f32_16x16x32_bf16 v[2:5], v[18:21], v[242:245], v[6:9]
	v_mfma_f32_16x16x32_bf16 v[26:29], v[22:25], v[238:241], v[26:29]
	v_mfma_f32_16x16x32_bf16 v[10:13], v[22:25], v[246:249], v[2:5]
	s_setprio 0
	s_setprio 1
	v_mfma_f32_16x16x32_bf16 v[2:5], v[210:213], v[34:37], v[178:181]
	v_mfma_f32_16x16x32_bf16 v[54:57], v[214:217], v[38:41], v[2:5]
	v_mfma_f32_16x16x32_bf16 v[2:5], v[218:221], v[34:37], v[182:185]
	v_mfma_f32_16x16x32_bf16 v[50:53], v[222:225], v[38:41], v[2:5]
	v_mfma_f32_16x16x32_bf16 v[2:5], v[210:213], v[226:229], v[186:189]
	v_mfma_f32_16x16x32_bf16 v[38:41], v[214:217], v[230:233], v[2:5]
	v_mfma_f32_16x16x32_bf16 v[2:5], v[218:221], v[226:229], v[190:193]
	v_mfma_f32_16x16x32_bf16 v[34:37], v[222:225], v[230:233], v[2:5]
	v_mfma_f32_16x16x32_bf16 v[2:5], v[210:213], v[234:237], v[194:197]
	v_mfma_f32_16x16x32_bf16 v[22:25], v[214:217], v[238:241], v[2:5]
	v_mfma_f32_16x16x32_bf16 v[2:5], v[218:221], v[234:237], v[198:201]
	v_mfma_f32_16x16x32_bf16 v[18:21], v[222:225], v[238:241], v[2:5]
	v_mfma_f32_16x16x32_bf16 v[2:5], v[210:213], v[242:245], v[202:205]
	v_mfma_f32_16x16x32_bf16 v[6:9], v[214:217], v[246:249], v[2:5]
	v_mfma_f32_16x16x32_bf16 v[2:5], v[218:221], v[242:245], v[206:209]
	v_mfma_f32_16x16x32_bf16 v[2:5], v[222:225], v[246:249], v[2:5]
	s_barrier
	s_setprio 0
	s_add_u32 s64, s64, 0x20180
	s_addc_u32 s65, s65, 0
	s_add_u32 s14, s6, 0x200
	s_addc_u32 s15, s7, 0
	s_mov_b32 s26, 0
	.p2align	6

;     __host__ __device__ bool next(int i, Unit& u) const { if (!StaticOrder::next(i >> 1, u)) return false; u.seg = i & 1; return true; }
; #define PG8_STAGE(bufoff, gbase, voff) do { _Pragma("unroll") for (int _i = 0; _i < 2; ++_i) \
;         __builtin_amdgcn_global_load_lds((const unsigned*)((const char*)(gbase) + (voff)[_i]), (LAS unsigned*)(lds + (bufoff) + ldsw + _i * 8192), 16, 0, 0); } while (0)
; #define PG8_WAIT_V(n) asm volatile("s_waitcnt vmcnt(" #n ")" ::: "memory")
; #define PG8_BAR __builtin_amdgcn_s_barrier()
; #define PG8_TOUCH(p) asm volatile("global_load_dword %0, %1, off" : "+v"(pfd) : "v"(p) : "memory")
;     ...
;     for (int i = 0; i < 2; ++i) { int R, C; stage_rc(tid * 16 + i * 8192, R, C); const int Rb = Epi::PERM ? ((R & ~31) + perm32(R & 31)) : R;
;         voffA[i] = (unsigned)(R * g.lda + C) * 2u; voffB[i] = (unsigned)(Rb * g.ldb + C) * 2u; }
;     const size_t kstep = (size_t)(BK * 2);
;     const size_t hstepA = (size_t)HALF * g.lda * 2, hstepB = (size_t)HALF * g.ldb * 2;
;     const unsigned ldsw = (unsigned)wid * 1024u;
;     const int aoff = lds_byte(wr * 64 + fr, fq * 8), boff = lds_byte(wc * 32 + fr, fq * 8);
;     ...
;     PG8_STAGE(PG8_SB(0, 0), cB, voffB); PG8_STAGE(PG8_SB(0, 1), cB + hstepB, voffB); PG8_STAGE(PG8_SA(0, 0), cA, voffA); PG8_STAGE(PG8_SA(0, 1), cA + hstepA, voffA);
;     if (wr == 1) PG8_BAR;
;     PG8_WAIT_V(2); PG8_BAR;
;     PG8_STAGE(PG8_SB(1, 0), cB + kstep, voffB); PG8_STAGE(PG8_SA(1, 0), cA + kstep, voffA); PG8_STAGE(PG8_SB(1, 1), cB + hstepB + kstep, voffB);
;     PG8_WAIT_V(6); PG8_BAR;
;     if constexpr (PF > 0) { const char* p0 = PG8_PFPTR(cA, cB) + (size_t)(2 + PF) * kstep; PG8_TOUCH(p0); }
;     for (;;) {
;         const bool has_next = S.next(ui + 1, nxt);
;         const char* nA = has_next ? PG8_APTR(nxt) : cA; const char* nB = has_next ? PG8_BPTR(nxt) : cB;
;         const char* pfc = PG8_PFPTR(cA, cB); const char* pfn = PG8_PFPTR(nA, nB);
.LBB0_702:
	s_mov_b64 s[8:9], 0x80
	s_lshl_b32 s0, s0, 12
	s_add_i32 m0, s59, 0x18000
	v_lshl_add_u64 v[8:9], v[8:9], 0, s[8:9]
	s_lshl_b32 s5, s1, 13
	s_and_b32 s14, s0, 0x3000
	s_waitcnt vmcnt(2)
	s_barrier
	global_load_lds_dwordx4 v[8:9], off
	v_lshl_add_u64 v[4:5], v[4:5], 0, s[8:9]
	s_add_i32 m0, s59, 0x1a000
	s_add_i32 s69, s59, 0x8000
	s_add_i32 s70, s59, 0xa000
	global_load_lds_dwordx4 v[4:5], off
	v_lshl_add_u64 v[2:3], v[2:3], 0, s[8:9]
	s_mov_b32 m0, s69
	s_add_u32 s0, s50, 0x80080
	global_load_lds_dwordx4 v[2:3], off
	v_lshl_add_u64 v[2:3], v[6:7], 0, s[8:9]
	s_mov_b32 m0, s70
	s_addc_u32 s1, s51, 0
	global_load_lds_dwordx4 v[2:3], off
	s_add_i32 m0, s59, 0x1c000
	v_lshl_add_u64 v[2:3], s[0:1], 0, v[148:149]
	global_load_lds_dwordx4 v[2:3], off
	v_lshl_add_u64 v[2:3], s[0:1], 0, v[152:153]
	s_add_i32 m0, s59, 0x1e000
	v_and_b32_e32 v0, 15, v1
	global_load_lds_dwordx4 v[2:3], off
	v_and_b32_e32 v2, 48, v1
	v_lshlrev_b32_e32 v1, 2, v1
	v_lshlrev_b32_e32 v0, 6, v0
	v_and_b32_e32 v1, 32, v1
	v_or_b32_e32 v3, v0, v2
	v_bitop3_b32 v0, v0, v1, v2 bitop3:0x36
	v_bitop3_b32 v2, v3, s5, v1 bitop3:0xde
	v_or_b32_e32 v1, s14, v0
	v_lshlrev_b32_e32 v0, 15, v10
	v_and_b32_e32 v0, 0xffff0000, v0
	v_lshl_add_u32 v0, v11, 12, v0
	v_and_b32_e32 v3, 1, v10
	v_lshl_or_b32 v0, v3, 6, v0
	v_lshl_add_u32 v154, v12, 1, v0
	v_lshlrev_b32_e32 v0, 15, v13
	v_and_b32_e32 v0, 0xffff0000, v0
	s_waitcnt vmcnt(6)
	s_cmpk_lt_u32 s4, 0x100
	v_lshl_add_u32 v0, v14, 12, v0
	v_and_b32_e32 v3, 1, v13
	s_cselect_b64 s[16:17], -1, 0
	v_lshl_or_b32 v0, v3, 6, v0
	s_add_i32 s72, 0, 0x10000
	s_add_i32 s73, 0, 0x14000
	s_ashr_i32 s71, s3, 31
	v_mov_b32_e32 v155, v149
	v_lshl_add_u32 v156, v15, 1, v0
	v_mov_b32_e32 v157, v149
	v_mov_b64_e32 v[160:161], 0x1ff
	v_add_u32_e32 v164, s72, v1
	v_add_u32_e32 v165, s73, v1
	v_add_u32_e32 v166, 0, v2
	s_mov_b64 s[18:19], 0x100
	s_mov_b64 s[20:21], 0x180
	s_mov_b32 s74, 0xb0000
	s_barrier
	s_branch .LBB0_705
	.p2align	6

.LBB0_715:
	ds_read_b128 v[2:5], v164
	ds_read_b128 v[6:9], v164 offset:1024
	ds_read_b128 v[10:13], v164 offset:2048
	ds_read_b128 v[14:17], v164 offset:3072
	ds_read_b128 v[18:21], v165
	ds_read_b128 v[22:25], v165 offset:1024
	ds_read_b128 v[26:29], v165 offset:2048
	ds_read_b128 v[30:33], v165 offset:3072
	s_add_u32 s14, s62, 0x80080
	s_addc_u32 s15, s63, 0
	s_add_i32 s23, s59, 0xc000
	v_lshl_add_u64 v[66:67], s[14:15], 0, v[146:147]
	s_mov_b32 m0, s23
	s_add_i32 s77, s59, 0xe000
	ds_read_b128 v[34:37], v166
	ds_read_b128 v[38:41], v166 offset:1024
	ds_read_b128 v[42:45], v166 offset:2048
	ds_read_b128 v[46:49], v166 offset:3072
	ds_read_b128 v[50:53], v166 offset:4096
	ds_read_b128 v[54:57], v166 offset:5120
	ds_read_b128 v[58:61], v166 offset:6144
	ds_read_b128 v[62:65], v166 offset:7168
	global_load_lds_dwordx4 v[66:67], off
	v_lshl_add_u64 v[66:67], s[14:15], 0, v[150:151]
	s_mov_b32 m0, s77
	s_nop 0
	global_load_lds_dwordx4 v[66:67], off
	s_waitcnt vmcnt(8)
	s_waitcnt lgkmcnt(0)
	s_setprio 1
	s_barrier
	v_mfma_f32_16x16x32_bf16 v[86:89], v[10:13], v[50:53], 0
	v_mfma_f32_16x16x32_bf16 v[106:109], v[14:17], v[54:57], v[86:89]
	v_mfma_f32_16x16x32_bf16 v[86:89], v[2:5], v[58:61], 0
	v_mfma_f32_16x16x32_bf16 v[66:69], v[2:5], v[34:37], 0
	v_mfma_f32_16x16x32_bf16 v[70:73], v[10:13], v[34:37], 0
	v_mfma_f32_16x16x32_bf16 v[74:77], v[2:5], v[42:45], 0
	v_mfma_f32_16x16x32_bf16 v[78:81], v[10:13], v[42:45], 0
	v_mfma_f32_16x16x32_bf16 v[82:85], v[2:5], v[50:53], 0
	v_mfma_f32_16x16x32_bf16 v[110:113], v[6:9], v[62:65], v[86:89]
	v_mfma_f32_16x16x32_bf16 v[86:89], v[10:13], v[58:61], 0
	v_mfma_f32_16x16x32_bf16 v[66:69], v[6:9], v[38:41], v[66:69]
	v_mfma_f32_16x16x32_bf16 v[70:73], v[14:17], v[38:41], v[70:73]
	v_mfma_f32_16x16x32_bf16 v[74:77], v[6:9], v[46:49], v[74:77]
	v_mfma_f32_16x16x32_bf16 v[78:81], v[14:17], v[46:49], v[78:81]
	v_mfma_f32_16x16x32_bf16 v[82:85], v[6:9], v[54:57], v[82:85]
	v_mfma_f32_16x16x32_bf16 v[114:117], v[14:17], v[62:65], v[86:89]
	s_setprio 0
	s_setprio 1
	v_mfma_f32_16x16x32_bf16 v[86:89], v[18:21], v[34:37], 0
	v_mfma_f32_16x16x32_bf16 v[34:37], v[26:29], v[34:37], 0
	v_mfma_f32_16x16x32_bf16 v[118:121], v[22:25], v[38:41], v[86:89]
	v_mfma_f32_16x16x32_bf16 v[34:37], v[30:33], v[38:41], v[34:37]
	v_mfma_f32_16x16x32_bf16 v[38:41], v[18:21], v[42:45], 0
	v_mfma_f32_16x16x32_bf16 v[42:45], v[26:29], v[42:45], 0
	v_mfma_f32_16x16x32_bf16 v[38:41], v[22:25], v[46:49], v[38:41]
	v_mfma_f32_16x16x32_bf16 v[42:45], v[30:33], v[46:49], v[42:45]
	v_mfma_f32_16x16x32_bf16 v[46:49], v[18:21], v[50:53], 0
	v_mfma_f32_16x16x32_bf16 v[50:53], v[26:29], v[50:53], 0
	v_mfma_f32_16x16x32_bf16 v[46:49], v[22:25], v[54:57], v[46:49]
	v_mfma_f32_16x16x32_bf16 v[50:53], v[30:33], v[54:57], v[50:53]
	v_mfma_f32_16x16x32_bf16 v[54:57], v[18:21], v[58:61], 0
	v_mfma_f32_16x16x32_bf16 v[58:61], v[26:29], v[58:61], 0
	v_mfma_f32_16x16x32_bf16 v[54:57], v[22:25], v[62:65], v[54:57]
	v_mfma_f32_16x16x32_bf16 v[58:61], v[30:33], v[62:65], v[58:61]
	s_barrier
	s_setprio 0
	s_add_i32 s78, s72, s58
	v_lshl_add_u64 v[144:145], s[50:51], 0, v[148:149]
	s_add_i32 s79, s78, 0x2000
	v_lshl_add_u64 v[130:131], v[144:145], 0, s[18:19]
	s_mov_b32 m0, s78
	v_lshl_add_u64 v[162:163], s[50:51], 0, v[152:153]
	s_add_u32 s14, s50, 0x80100
	ds_read_b128 v[62:65], v166 offset:16384
	ds_read_b128 v[86:89], v166 offset:17408
	ds_read_b128 v[90:93], v166 offset:18432
	ds_read_b128 v[94:97], v166 offset:19456
	ds_read_b128 v[98:101], v166 offset:20480
	ds_read_b128 v[102:105], v166 offset:21504
	ds_read_b128 v[122:125], v166 offset:22528
	ds_read_b128 v[126:129], v166 offset:23552
	global_load_lds_dwordx4 v[130:131], off
	v_lshl_add_u64 v[130:131], v[162:163], 0, s[18:19]
	s_mov_b32 m0, s79
	s_addc_u32 s15, s51, 0
	s_add_i32 s80, s73, s58
	global_load_lds_dwordx4 v[130:131], off
	v_lshl_add_u64 v[130:131], s[14:15], 0, v[148:149]
	s_mov_b32 m0, s80
	s_add_i32 s46, s80, 0x2000
	global_load_lds_dwordx4 v[130:131], off
	v_lshl_add_u64 v[130:131], s[14:15], 0, v[152:153]
	s_mov_b32 m0, s46
	v_lshl_add_u64 v[252:253], s[62:63], 0, v[146:147]
	global_load_lds_dwordx4 v[130:131], off
	v_lshl_add_u64 v[130:131], v[252:253], 0, s[18:19]
	s_mov_b32 m0, s59
	v_lshl_add_u64 v[158:159], s[62:63], 0, v[150:151]
	global_load_lds_dwordx4 v[130:131], off
	v_lshl_add_u64 v[130:131], v[158:159], 0, s[18:19]
	s_mov_b32 m0, s31
	s_nop 0
	global_load_lds_dwordx4 v[130:131], off
	s_waitcnt vmcnt(8)
	s_waitcnt lgkmcnt(0)
	s_setprio 1
	s_barrier
	v_mfma_f32_16x16x32_bf16 v[130:133], v[2:5], v[62:65], 0
	v_mfma_f32_16x16x32_bf16 v[140:143], v[2:5], v[90:93], 0
	v_mfma_f32_16x16x32_bf16 v[172:175], v[2:5], v[98:101], 0
	v_mfma_f32_16x16x32_bf16 v[2:5], v[2:5], v[122:125], 0
	v_mfma_f32_16x16x32_bf16 v[132:135], v[6:9], v[86:89], v[130:133]
	v_mfma_f32_16x16x32_bf16 v[140:143], v[6:9], v[94:97], v[140:143]
	v_mfma_f32_16x16x32_bf16 v[172:175], v[6:9], v[102:105], v[172:175]
	v_mfma_f32_16x16x32_bf16 v[2:5], v[6:9], v[126:129], v[2:5]
	v_mfma_f32_16x16x32_bf16 v[6:9], v[10:13], v[122:125], 0
	v_mfma_f32_16x16x32_bf16 v[136:139], v[10:13], v[62:65], 0
	v_mfma_f32_16x16x32_bf16 v[168:171], v[10:13], v[90:93], 0
	v_mfma_f32_16x16x32_bf16 v[176:179], v[10:13], v[98:101], 0
	v_mfma_f32_16x16x32_bf16 v[6:9], v[14:17], v[126:129], v[6:9]
	v_mfma_f32_16x16x32_bf16 v[136:139], v[14:17], v[86:89], v[136:139]
	v_mfma_f32_16x16x32_bf16 v[168:171], v[14:17], v[94:97], v[168:171]
	v_mfma_f32_16x16x32_bf16 v[176:179], v[14:17], v[102:105], v[176:179]
	s_setprio 0
	s_setprio 1
	v_mfma_f32_16x16x32_bf16 v[10:13], v[18:21], v[62:65], 0
	v_mfma_f32_16x16x32_bf16 v[180:183], v[22:25], v[86:89], v[10:13]
	v_mfma_f32_16x16x32_bf16 v[10:13], v[26:29], v[62:65], 0
	v_mfma_f32_16x16x32_bf16 v[184:187], v[30:33], v[86:89], v[10:13]
	v_mfma_f32_16x16x32_bf16 v[10:13], v[18:21], v[90:93], 0
	v_mfma_f32_16x16x32_bf16 v[188:191], v[22:25], v[94:97], v[10:13]
	v_mfma_f32_16x16x32_bf16 v[10:13], v[26:29], v[90:93], 0
	v_mfma_f32_16x16x32_bf16 v[192:195], v[30:33], v[94:97], v[10:13]
	v_mfma_f32_16x16x32_bf16 v[10:13], v[18:21], v[98:101], 0
	v_mfma_f32_16x16x32_bf16 v[196:199], v[22:25], v[102:105], v[10:13]
	v_mfma_f32_16x16x32_bf16 v[10:13], v[26:29], v[98:101], 0
	v_mfma_f32_16x16x32_bf16 v[200:203], v[30:33], v[102:105], v[10:13]
	v_mfma_f32_16x16x32_bf16 v[10:13], v[18:21], v[122:125], 0
	v_mfma_f32_16x16x32_bf16 v[204:207], v[22:25], v[126:129], v[10:13]
	v_mfma_f32_16x16x32_bf16 v[10:13], v[26:29], v[122:125], 0
	v_mfma_f32_16x16x32_bf16 v[208:211], v[30:33], v[126:129], v[10:13]
	s_barrier
;     ...
;         for (int t = 2; t < nt; t += 2) PG8_KITER(t);
	s_setprio 0
	s_add_i32 s47, 0, 0x18000
	s_add_i32 s56, 0, 0x1c000
	v_add_u32_e32 v130, s47, v1
	v_add_u32_e32 v131, s56, v1
	s_nop 0
	ds_read_b128 v[10:13], v130
	ds_read_b128 v[14:17], v130 offset:1024
	ds_read_b128 v[18:21], v130 offset:2048
	ds_read_b128 v[22:25], v130 offset:3072
	ds_read_b128 v[212:215], v131
	ds_read_b128 v[216:219], v131 offset:1024
	ds_read_b128 v[220:223], v131 offset:2048
	ds_read_b128 v[224:227], v131 offset:3072
	s_add_u32 s14, s62, 0x80100
	s_addc_u32 s15, s63, 0
	s_mov_b32 m0, s66
	v_lshl_add_u64 v[62:63], s[14:15], 0, v[146:147]
	ds_read_b128 v[26:29], v166 offset:32768
	ds_read_b128 v[30:33], v166 offset:33792
	ds_read_b128 v[228:231], v166 offset:34816
	ds_read_b128 v[232:235], v166 offset:35840
	ds_read_b128 v[236:239], v166 offset:36864
	ds_read_b128 v[240:243], v166 offset:37888
	ds_read_b128 v[244:247], v166 offset:38912
	ds_read_b128 v[248:251], v166 offset:39936
	global_load_lds_dwordx4 v[62:63], off
	v_lshl_add_u64 v[62:63], s[14:15], 0, v[150:151]
	s_mov_b32 m0, s67
	s_nop 0
	global_load_lds_dwordx4 v[62:63], off
	s_waitcnt vmcnt(8)
	s_waitcnt lgkmcnt(0)
	s_setprio 1
	s_barrier
	v_mfma_f32_16x16x32_bf16 v[62:65], v[10:13], v[26:29], v[66:69]
	v_mfma_f32_16x16x32_bf16 v[102:105], v[14:17], v[30:33], v[62:65]
	v_mfma_f32_16x16x32_bf16 v[62:65], v[18:21], v[26:29], v[70:73]
	v_mfma_f32_16x16x32_bf16 v[98:101], v[22:25], v[30:33], v[62:65]
	v_mfma_f32_16x16x32_bf16 v[62:65], v[10:13], v[228:231], v[74:77]
	v_mfma_f32_16x16x32_bf16 v[94:97], v[14:17], v[232:235], v[62:65]
	v_mfma_f32_16x16x32_bf16 v[62:65], v[18:21], v[228:231], v[78:81]
	v_mfma_f32_16x16x32_bf16 v[90:93], v[22:25], v[232:235], v[62:65]
	v_mfma_f32_16x16x32_bf16 v[62:65], v[10:13], v[236:239], v[82:85]
	v_mfma_f32_16x16x32_bf16 v[86:89], v[14:17], v[240:243], v[62:65]
	v_mfma_f32_16x16x32_bf16 v[62:65], v[18:21], v[236:239], v[106:109]
	v_mfma_f32_16x16x32_bf16 v[82:85], v[22:25], v[240:243], v[62:65]
	v_mfma_f32_16x16x32_bf16 v[62:65], v[10:13], v[244:247], v[110:113]
	v_mfma_f32_16x16x32_bf16 v[78:81], v[14:17], v[248:251], v[62:65]
	v_mfma_f32_16x16x32_bf16 v[62:65], v[18:21], v[244:247], v[114:117]
	v_mfma_f32_16x16x32_bf16 v[62:65], v[22:25], v[248:251], v[62:65]
	s_setprio 0
	s_setprio 1
	v_mfma_f32_16x16x32_bf16 v[66:69], v[212:215], v[26:29], v[118:121]
	v_mfma_f32_16x16x32_bf16 v[26:29], v[220:223], v[26:29], v[34:37]
	v_mfma_f32_16x16x32_bf16 v[122:125], v[224:227], v[30:33], v[26:29]
	v_mfma_f32_16x16x32_bf16 v[26:29], v[212:215], v[228:231], v[38:41]
	v_mfma_f32_16x16x32_bf16 v[118:121], v[216:219], v[232:235], v[26:29]
	v_mfma_f32_16x16x32_bf16 v[26:29], v[220:223], v[228:231], v[42:45]
	v_mfma_f32_16x16x32_bf16 v[114:117], v[224:227], v[232:235], v[26:29]
	v_mfma_f32_16x16x32_bf16 v[26:29], v[212:215], v[236:239], v[46:49]
	v_mfma_f32_16x16x32_bf16 v[110:113], v[216:219], v[240:243], v[26:29]
	v_mfma_f32_16x16x32_bf16 v[26:29], v[220:223], v[236:239], v[50:53]
	v_mfma_f32_16x16x32_bf16 v[106:109], v[224:227], v[240:243], v[26:29]
	v_mfma_f32_16x16x32_bf16 v[26:29], v[212:215], v[244:247], v[54:57]
	v_mfma_f32_16x16x32_bf16 v[54:57], v[216:219], v[248:251], v[26:29]
	v_mfma_f32_16x16x32_bf16 v[26:29], v[220:223], v[244:247], v[58:61]
	v_mfma_f32_16x16x32_bf16 v[126:129], v[216:219], v[30:33], v[66:69]
	v_mfma_f32_16x16x32_bf16 v[50:53], v[224:227], v[248:251], v[26:29]
	s_barrier
	s_setprio 0
	s_add_i32 s47, s47, s58
	s_add_i32 s81, s47, 0x2000
	s_nop 1
	v_lshl_add_u64 v[26:27], v[144:145], 0, s[20:21]
	s_mov_b32 m0, s47
	s_add_u32 s14, s50, 0x80180
	ds_read_b128 v[34:37], v166 offset:49152
	ds_read_b128 v[38:41], v166 offset:50176
	ds_read_b128 v[228:231], v166 offset:51200
	ds_read_b128 v[232:235], v166 offset:52224
	ds_read_b128 v[236:239], v166 offset:53248
	ds_read_b128 v[240:243], v166 offset:54272
	ds_read_b128 v[244:247], v166 offset:55296
	ds_read_b128 v[248:251], v166 offset:56320
	global_load_lds_dwordx4 v[26:27], off
	v_lshl_add_u64 v[26:27], v[162:163], 0, s[20:21]
	s_mov_b32 m0, s81
	s_addc_u32 s15, s51, 0
	s_add_i32 s56, s56, s58
	global_load_lds_dwordx4 v[26:27], off
	v_lshl_add_u64 v[26:27], s[14:15], 0, v[148:149]
	s_mov_b32 m0, s56
	s_add_i32 s57, s56, 0x2000
	global_load_lds_dwordx4 v[26:27], off
	v_lshl_add_u64 v[26:27], s[14:15], 0, v[152:153]
	s_mov_b32 m0, s57
	s_nop 0
	global_load_lds_dwordx4 v[26:27], off
	v_lshl_add_u64 v[26:27], v[252:253], 0, s[20:21]
	s_mov_b32 m0, s69
	s_nop 0
	global_load_lds_dwordx4 v[26:27], off
	v_lshl_add_u64 v[26:27], v[158:159], 0, s[20:21]
	s_mov_b32 m0, s70
	s_nop 0
	global_load_lds_dwordx4 v[26:27], off
	s_waitcnt vmcnt(8)
	s_waitcnt lgkmcnt(0)
	s_setprio 1
	s_barrier
	v_mfma_f32_16x16x32_bf16 v[26:29], v[10:13], v[34:37], v[132:135]
	v_mfma_f32_16x16x32_bf16 v[74:77], v[14:17], v[38:41], v[26:29]
	v_mfma_f32_16x16x32_bf16 v[26:29], v[18:21], v[34:37], v[136:139]
	v_mfma_f32_16x16x32_bf16 v[70:73], v[22:25], v[38:41], v[26:29]
	v_mfma_f32_16x16x32_bf16 v[26:29], v[10:13], v[228:231], v[140:143]
	v_mfma_f32_16x16x32_bf16 v[46:49], v[14:17], v[232:235], v[26:29]
	v_mfma_f32_16x16x32_bf16 v[26:29], v[18:21], v[228:231], v[168:171]
	v_mfma_f32_16x16x32_bf16 v[42:45], v[22:25], v[232:235], v[26:29]
	v_mfma_f32_16x16x32_bf16 v[26:29], v[10:13], v[236:239], v[172:175]
	v_mfma_f32_16x16x32_bf16 v[2:5], v[10:13], v[244:247], v[2:5]
	v_mfma_f32_16x16x32_bf16 v[30:33], v[14:17], v[240:243], v[26:29]
	v_mfma_f32_16x16x32_bf16 v[26:29], v[18:21], v[236:239], v[176:179]
	v_mfma_f32_16x16x32_bf16 v[14:17], v[14:17], v[248:251], v[2:5]
	v_mfma_f32_16x16x32_bf16 v[2:5], v[18:21], v[244:247], v[6:9]
	v_mfma_f32_16x16x32_bf16 v[26:29], v[22:25], v[240:243], v[26:29]
	v_mfma_f32_16x16x32_bf16 v[10:13], v[22:25], v[248:251], v[2:5]
	s_setprio 0
	s_setprio 1
	v_mfma_f32_16x16x32_bf16 v[2:5], v[212:215], v[34:37], v[180:183]
	v_mfma_f32_16x16x32_bf16 v[66:69], v[216:219], v[38:41], v[2:5]
	v_mfma_f32_16x16x32_bf16 v[2:5], v[220:223], v[34:37], v[184:187]
	v_mfma_f32_16x16x32_bf16 v[58:61], v[224:227], v[38:41], v[2:5]
	v_mfma_f32_16x16x32_bf16 v[2:5], v[212:215], v[228:231], v[188:191]
	v_mfma_f32_16x16x32_bf16 v[38:41], v[216:219], v[232:235], v[2:5]
	v_mfma_f32_16x16x32_bf16 v[2:5], v[220:223], v[228:231], v[192:195]
	v_mfma_f32_16x16x32_bf16 v[34:37], v[224:227], v[232:235], v[2:5]
	v_mfma_f32_16x16x32_bf16 v[2:5], v[212:215], v[236:239], v[196:199]
	v_mfma_f32_16x16x32_bf16 v[22:25], v[216:219], v[240:243], v[2:5]
	v_mfma_f32_16x16x32_bf16 v[2:5], v[220:223], v[236:239], v[200:203]
	v_mfma_f32_16x16x32_bf16 v[18:21], v[224:227], v[240:243], v[2:5]
	v_mfma_f32_16x16x32_bf16 v[2:5], v[212:215], v[244:247], v[204:207]
	v_mfma_f32_16x16x32_bf16 v[6:9], v[216:219], v[248:251], v[2:5]
	v_mfma_f32_16x16x32_bf16 v[2:5], v[220:223], v[244:247], v[208:211]
	v_mfma_f32_16x16x32_bf16 v[2:5], v[224:227], v[248:251], v[2:5]
	s_barrier
	s_setprio 0
	s_add_u32 s62, s62, 0x80180
	s_addc_u32 s63, s63, 0
	s_add_u32 s14, s50, 0x200
	s_addc_u32 s15, s51, 0
	s_mov_b32 s26, 0
	.p2align	6

; __global__ void __launch_bounds__(NWAVES * 64, 2) mk_fwd(Params P) {
;     ...
;         for (int item = vcu_; item < 512; item += (int)gridDim.x) {
;             const int bh = item >> 4, x = item & 15, b = bh >> 4, h = bh & 15;
; #pragma unroll 1
;             for (int half = 0; half < 2; ++half) {
;                 const int qb = half ? x : 31 - x;
;                 const size_t row0 = (size_t)b * SEQ + (size_t)qb * 256;
.LBB0_780:
	s_ashr_i32 s0, s33, 8
	s_and_b32 s78, s33, 15
	s_bfe_u32 s8, s33, 0x40004
	s_ashr_i32 s1, s0, 31
	s_xor_b32 s79, s78, 31
	s_lshl_b64 s[50:51], s[0:1], 13
	s_mul_i32 s4, s8, 0x180
	s_add_u32 s4, s42, s4
	s_addc_u32 s5, s43, 0
	s_lshl_b64 s[6:7], s[0:1], 26
	s_add_u32 s6, s54, s6
	s_addc_u32 s7, s55, s7
	s_lshl_b32 s9, s8, 8
	s_lshl_b32 s8, s8, 9
	s_add_u32 s16, s6, s8
	s_addc_u32 s6, s7, 0
	s_lshl_b64 s[0:1], s[0:1], 20
	s_add_u32 s20, s68, s0
	s_addc_u32 s0, s69, s1
	s_add_u32 s28, s16, 0x100
	s_addc_u32 s1, s6, 0
	s_add_u32 s80, s70, s9
	s_addc_u32 s81, s71, 0
	s_and_b32 s29, s1, 0xffff
	s_and_b32 s17, s6, 0xffff
	s_and_b32 s21, s0, 0xffff
	v_mov_b64_e32 v[184:185], s[4:5]
	s_mov_b64 s[6:7], -1
	s_branch .LBB0_782
	.p2align	6

; #define KLOAD(k0) do { const unsigned sk_ = (unsigned)(k0) * (unsigned)ldk * 2u; ks0 = BLD(rsK, okl, sk_); ks1 = BLD(rsK, okl + 64u * (unsigned)ldk, sk_); \
;     if constexpr (DK == 192) kr0 = BLD(rsR, orl, (unsigned)(k0) * (unsigned)ldkr * 2u); } while (0)
; #define VLOAD(k0) do { const unsigned sv_ = (unsigned)(k0) * (unsigned)ldv * 2u; vs0 = BLD(rsV, ovl, sv_); vs1 = BLD(rsV, ovl + 64u * (unsigned)ldv, sv_); } while (0)
; #define KWRITE(boff) do { const int kc = sc * 2; *(bf16x8*)(K_lds + (boff) + ATT_KSWZ(sr, kc, KROW)) = ks0; *(bf16x8*)(K_lds + (boff) + ATT_KSWZ(32 + sr, kc, KROW)) = ks1; \
;     if constexpr (DK == 192) *(bf16x8*)(K_lds + (boff) + ATT_KSWZ(rr, 256 + rc * 2, KROW)) = kr0; } while (0)
; #define VWRITE(boff) do { *(bf16x8*)(V_lds + (boff) + vst0) = vs0; *(bf16x8*)(V_lds + (boff) + vst1) = vs1; } while (0)
; #define VMWAIT() asm volatile("s_waitcnt vmcnt(0)" ::: "memory")
; #define PPBAR() do { ATT_SBAR(); asm volatile("s_waitcnt lgkmcnt(0)" ::: "memory"); __builtin_amdgcn_s_barrier(); asm volatile("" ::: "memory"); ATT_SBAR(); } while (0)
; template <int DK, bool CAUSAL> ...
;     ...
;     f32x16 p0, p1; float mn, al; bf16x8 pa0, pa1, pa2, pa3;
;     KLOAD(KVBLK); { const bf16x8 t0 = ks0, t1 = ks1, t2 = kr0;
;       KLOAD(0); VLOAD(0); VMWAIT(); KWRITE(0); VWRITE(0);
;       ks0 = t0; ks1 = t1; if constexpr (DK == 192) kr0 = t2; KWRITE(SHM_K); }
;     PPBAR();
;     { const int kt0 = 1 + half, vt0 = half; if (kt0 < NT) KLOAD(kt0 * KVBLK); if (vt0 < NT) VLOAD(vt0 * KVBLK); }
;     if (half == 1) PPBAR();
.LBB0_817:
	v_add_f32_e32 v0, v200, v204
	v_fmac_f32_e32 v0, 0, v199
	v_add_f32_e32 v199, v66, v67
	v_fmac_f32_e32 v199, v0, v206
	s_waitcnt lgkmcnt(0)
	s_barrier
	s_lshl_b32 s0, s11, 14
	s_and_b32 s1, s0, 0x4000
	s_lshl_b32 s83, s82, 5
	s_add_i32 s59, s1, 0
	s_bitcmp1_b32 s10, 8
	s_cselect_b32 s1, 0x6400, 0
	s_cselect_b32 s6, 0, 0x6400
	s_add_i32 s87, s1, 0
	s_lshl_b32 s1, s11, 19
	s_add_i32 s88, s1, 0x280000
	s_lshl_b32 s1, s11, 13
	v_or_b32_e32 v200, s83, v201
	s_mov_b32 s86, 2
	v_cmp_gt_u32_e64 s[4:5], 32, v202
	v_lshl_add_u32 v201, v201, 2, s13
	s_add_i32 s82, s6, 0
	s_add_i32 s89, s1, 0xa000
	s_sub_i32 s58, 0xff, s58
	s_sub_i32 s90, 0, s90
	s_add_i32 s91, s0, 0xc000
	s_branch .LBB0_819
	.p2align	6

;     __host__ __device__ bool next(int i, Unit& u) const { if (!StaticOrder::next(i >> 1, u)) return false; u.seg = i & 1; return true; }
; #define PG8_STAGE(bufoff, gbase, voff) do { _Pragma("unroll") for (int _i = 0; _i < 2; ++_i) \
;         __builtin_amdgcn_global_load_lds((const unsigned*)((const char*)(gbase) + (voff)[_i]), (LAS unsigned*)(lds + (bufoff) + ldsw + _i * 8192), 16, 0, 0); } while (0)
; #define PG8_WAIT_V(n) asm volatile("s_waitcnt vmcnt(" #n ")" ::: "memory")
; #define PG8_BAR __builtin_amdgcn_s_barrier()
; #define PG8_TOUCH(p) asm volatile("global_load_dword %0, %1, off" : "+v"(pfd) : "v"(p) : "memory")
;     ...
;     f32x4 acc[2][2][4][2];
; #pragma unroll
;     for (int a = 0; a < 2; ++a)
; #pragma unroll
;         for (int b = 0; b < 2; ++b)
; #pragma unroll
;             for (int m = 0; m < 4; ++m)
; #pragma unroll
;                 for (int n = 0; n < 2; ++n) acc[a][b][m][n] = (f32x4){0.f, 0.f, 0.f, 0.f};
;     ...
;     PG8_STAGE(PG8_SB(0, 0), cB, voffB); PG8_STAGE(PG8_SB(0, 1), cB + hstepB, voffB); PG8_STAGE(PG8_SA(0, 0), cA, voffA); PG8_STAGE(PG8_SA(0, 1), cA + hstepA, voffA);
;     if (wr == 1) PG8_BAR;
;     PG8_WAIT_V(2); PG8_BAR;
;     PG8_STAGE(PG8_SB(1, 0), cB + kstep, voffB); PG8_STAGE(PG8_SA(1, 0), cA + kstep, voffA); PG8_STAGE(PG8_SB(1, 1), cB + hstepB + kstep, voffB);
;     PG8_WAIT_V(6); PG8_BAR;
;     if constexpr (PF > 0) { const char* p0 = PG8_PFPTR(cA, cB) + (size_t)(2 + PF) * kstep; PG8_TOUCH(p0); }
;     for (;;) {
;         const bool has_next = S.next(ui + 1, nxt);
;         const char* nA = has_next ? PG8_APTR(nxt) : cA; const char* nB = has_next ? PG8_BPTR(nxt) : cB;
;         const char* pfc = PG8_PFPTR(cA, cB); const char* pfn = PG8_PFPTR(nA, nB);
.LBB0_916:
	s_add_u32 s73, s34, 0x54e00000
	s_addc_u32 s74, s35, 0
	v_and_b32_e32 v0, 15, v1
	s_add_u32 s75, s34, 0x17d00000
	v_and_b32_e32 v16, 48, v1
	v_lshlrev_b32_e32 v0, 6, v0
	v_lshlrev_b32_e32 v1, 2, v1
	s_addc_u32 s76, s35, 0
	v_or_b32_e32 v17, v0, v16
	s_lshl_b32 s0, s6, 13
	v_and_b32_e32 v1, 32, v1
	s_mov_b64 s[16:17], 0x80
	v_bitop3_b32 v0, v0, v1, v16 bitop3:0x36
	v_bitop3_b32 v16, v17, s0, v1 bitop3:0xde
	s_lshl_b32 s0, s5, 12
	s_add_i32 m0, s69, 0x18000
	v_lshl_add_u64 v[8:9], v[8:9], 0, s[16:17]
	s_and_b32 s0, s0, 0x3000
	s_waitcnt vmcnt(2)
	s_barrier
	global_load_lds_dwordx4 v[8:9], off
	v_lshl_add_u64 v[4:5], v[4:5], 0, s[16:17]
	s_add_i32 m0, s69, 0x1a000
	s_add_i32 s77, s69, 0x8000
	s_add_i32 s78, s69, 0xa000
	global_load_lds_dwordx4 v[4:5], off
	v_lshl_add_u64 v[2:3], v[2:3], 0, s[16:17]
	s_mov_b32 m0, s77
	s_add_u32 s6, s50, 0x80080
	global_load_lds_dwordx4 v[2:3], off
	v_lshl_add_u64 v[2:3], v[6:7], 0, s[16:17]
	s_mov_b32 m0, s78
	s_addc_u32 s7, s51, 0
	global_load_lds_dwordx4 v[2:3], off
	s_add_i32 m0, s69, 0x1c000
	v_lshl_add_u64 v[2:3], s[6:7], 0, v[152:153]
	global_load_lds_dwordx4 v[2:3], off
	v_lshl_add_u64 v[2:3], s[6:7], 0, v[156:157]
	s_add_i32 m0, s69, 0x1e000
	v_or_b32_e32 v1, s0, v0
	global_load_lds_dwordx4 v[2:3], off
	v_lshlrev_b32_e32 v0, 15, v10
	v_and_b32_e32 v0, 0xffff0000, v0
	v_lshl_add_u32 v0, v11, 12, v0
	v_and_b32_e32 v2, 1, v10
	v_lshl_or_b32 v0, v2, 6, v0
	v_lshl_add_u32 v160, v12, 1, v0
	v_lshlrev_b32_e32 v0, 15, v13
	v_and_b32_e32 v0, 0xffff0000, v0
	s_waitcnt vmcnt(6)
	s_cmpk_lt_u32 s4, 0x100
	v_lshl_add_u32 v0, v14, 12, v0
	v_and_b32_e32 v2, 1, v13
	s_cselect_b64 s[18:19], -1, 0
	s_add_u32 s20, s34, 0x5d200000
	v_lshl_or_b32 v0, v2, 6, v0
	s_addc_u32 s21, s35, 0
	v_mov_b32_e32 v161, v159
	v_lshl_add_u32 v162, v15, 1, v0
	v_mov_b32_e32 v163, v159
	v_mov_b64_e32 v[164:165], 0x400
	v_mov_b64_e32 v[166:167], 0x3ff
	s_add_i32 s79, 0, 0x10000
	s_add_i32 s80, 0, 0x14000
	s_mov_b64 s[22:23], 0x100
	s_mov_b64 s[28:29], 0x180
	s_mov_b64 s[30:31], 0xa0000
	s_mov_b64 s[38:39], 0xb0000
	v_add_u32_e32 v172, 0, v16
	s_mov_b32 s10, 0
	s_mov_b32 s81, 0
	v_mov_b32_e32 v2, v159
	v_mov_b32_e32 v3, v159
	v_mov_b32_e32 v4, v159
	v_mov_b32_e32 v5, v159
	v_mov_b32_e32 v6, v159
	v_mov_b32_e32 v7, v159
	v_mov_b32_e32 v8, v159
	v_mov_b32_e32 v9, v159
	v_mov_b32_e32 v10, v159
	v_mov_b32_e32 v11, v159
	v_mov_b32_e32 v12, v159
	v_mov_b32_e32 v13, v159
	v_mov_b32_e32 v14, v159
	v_mov_b32_e32 v15, v159
	v_mov_b32_e32 v16, v159
	v_mov_b32_e32 v17, v159
	v_mov_b32_e32 v18, v159
	v_mov_b32_e32 v19, v159
	v_mov_b32_e32 v20, v159
	v_mov_b32_e32 v21, v159
	v_mov_b32_e32 v22, v159
	v_mov_b32_e32 v23, v159
	v_mov_b32_e32 v24, v159
	v_mov_b32_e32 v25, v159
	v_mov_b32_e32 v26, v159
	v_mov_b32_e32 v27, v159
	v_mov_b32_e32 v28, v159
	v_mov_b32_e32 v29, v159
	v_mov_b32_e32 v30, v159
	v_mov_b32_e32 v31, v159
	v_mov_b32_e32 v32, v159
	v_mov_b32_e32 v33, v159
	v_mov_b32_e32 v34, v159
	v_mov_b32_e32 v35, v159
	v_mov_b32_e32 v36, v159
	v_mov_b32_e32 v37, v159
	v_mov_b32_e32 v38, v159
	v_mov_b32_e32 v39, v159
	v_mov_b32_e32 v40, v159
	v_mov_b32_e32 v41, v159
	v_mov_b32_e32 v42, v159
	v_mov_b32_e32 v43, v159
	v_mov_b32_e32 v44, v159
	v_mov_b32_e32 v45, v159
	v_mov_b32_e32 v46, v159
	v_mov_b32_e32 v47, v159
	v_mov_b32_e32 v48, v159
	v_mov_b32_e32 v49, v159
	v_mov_b32_e32 v50, v159
	v_mov_b32_e32 v51, v159
	v_mov_b32_e32 v52, v159
	v_mov_b32_e32 v53, v159
	v_mov_b32_e32 v54, v159
	v_mov_b32_e32 v55, v159
	v_mov_b32_e32 v56, v159
	v_mov_b32_e32 v57, v159
	v_mov_b32_e32 v58, v159
	v_mov_b32_e32 v59, v159
	v_mov_b32_e32 v60, v159
	v_mov_b32_e32 v61, v159
	v_mov_b32_e32 v62, v159
	v_mov_b32_e32 v63, v159
	v_mov_b32_e32 v64, v159
	v_mov_b32_e32 v65, v159
	v_mov_b32_e32 v66, v159
	v_mov_b32_e32 v67, v159
	v_mov_b32_e32 v68, v159
	v_mov_b32_e32 v69, v159
	v_mov_b32_e32 v70, v159
	v_mov_b32_e32 v71, v159
	v_mov_b32_e32 v72, v159
	v_mov_b32_e32 v73, v159
	v_mov_b32_e32 v74, v159
	v_mov_b32_e32 v75, v159
	v_mov_b32_e32 v76, v159
	v_mov_b32_e32 v77, v159
	v_mov_b32_e32 v78, v159
	v_mov_b32_e32 v79, v159
	v_mov_b32_e32 v80, v159
	v_mov_b32_e32 v81, v159
	v_mov_b32_e32 v82, v159
	v_mov_b32_e32 v83, v159
	v_mov_b32_e32 v84, v159
	v_mov_b32_e32 v85, v159
	v_mov_b32_e32 v86, v159
	v_mov_b32_e32 v87, v159
	v_mov_b32_e32 v88, v159
	v_mov_b32_e32 v89, v159
	v_mov_b32_e32 v90, v159
	v_mov_b32_e32 v91, v159
	v_mov_b32_e32 v92, v159
	v_mov_b32_e32 v93, v159
	v_mov_b32_e32 v94, v159
	v_mov_b32_e32 v95, v159
	v_mov_b32_e32 v96, v159
	v_mov_b32_e32 v97, v159
	v_mov_b32_e32 v98, v159
	v_mov_b32_e32 v99, v159
	v_mov_b32_e32 v100, v159
	v_mov_b32_e32 v101, v159
	v_mov_b32_e32 v102, v159
	v_mov_b32_e32 v103, v159
	v_mov_b32_e32 v104, v159
	v_mov_b32_e32 v105, v159
	v_mov_b32_e32 v106, v159
	v_mov_b32_e32 v107, v159
	v_mov_b32_e32 v108, v159
	v_mov_b32_e32 v109, v159
	v_mov_b32_e32 v110, v159
	v_mov_b32_e32 v111, v159
	v_mov_b32_e32 v112, v159
	v_mov_b32_e32 v113, v159
	v_mov_b32_e32 v114, v159
	v_mov_b32_e32 v115, v159
	v_mov_b32_e32 v116, v159
	v_mov_b32_e32 v117, v159
	v_mov_b32_e32 v118, v159
	v_mov_b32_e32 v119, v159
	v_mov_b32_e32 v120, v159
	v_mov_b32_e32 v121, v159
	v_mov_b32_e32 v122, v159
	v_mov_b32_e32 v123, v159
	v_mov_b32_e32 v124, v159
	v_mov_b32_e32 v125, v159
	v_mov_b32_e32 v126, v159
	v_mov_b32_e32 v127, v159
	v_mov_b32_e32 v128, v159
	v_mov_b32_e32 v129, v159
	s_barrier
	s_branch .LBB0_919
	.p2align	6

.LBB0_929:
	v_add_u32_e32 v130, s79, v1
	v_add_u32_e32 v131, s80, v1
	ds_read_b128 v[132:135], v130
	ds_read_b128 v[136:139], v130 offset:1024
	ds_read_b128 v[140:143], v130 offset:2048
	ds_read_b128 v[144:147], v130 offset:3072
	ds_read_b128 v[168:171], v131
	ds_read_b128 v[174:177], v131 offset:1024
	ds_read_b128 v[178:181], v131 offset:2048
	ds_read_b128 v[182:185], v131 offset:3072
	s_add_u32 s12, s62, 0x80080
	s_addc_u32 s13, s63, 0
	s_add_i32 s0, s69, 0xc000
	v_lshl_add_u64 v[148:149], s[12:13], 0, v[150:151]
	s_mov_b32 m0, s0
	s_add_i32 s11, s69, 0xe000
	ds_read_b128 v[186:189], v172
	ds_read_b128 v[190:193], v172 offset:1024
	ds_read_b128 v[194:197], v172 offset:2048
	ds_read_b128 v[198:201], v172 offset:3072
	ds_read_b128 v[202:205], v172 offset:4096
	ds_read_b128 v[206:209], v172 offset:5120
	ds_read_b128 v[210:213], v172 offset:6144
	ds_read_b128 v[214:217], v172 offset:7168
	global_load_lds_dwordx4 v[148:149], off
	v_lshl_add_u64 v[148:149], s[12:13], 0, v[154:155]
	s_mov_b32 m0, s11
	s_nop 0
	global_load_lds_dwordx4 v[148:149], off
	s_waitcnt vmcnt(8)
	s_waitcnt lgkmcnt(0)
	s_setprio 1
	s_barrier
	v_mfma_f32_16x16x32_bf16 v[126:129], v[132:135], v[186:189], v[126:129]
	v_mfma_f32_16x16x32_bf16 v[122:125], v[140:143], v[186:189], v[122:125]
	v_mfma_f32_16x16x32_bf16 v[118:121], v[132:135], v[194:197], v[118:121]
	v_mfma_f32_16x16x32_bf16 v[114:117], v[140:143], v[194:197], v[114:117]
	v_mfma_f32_16x16x32_bf16 v[110:113], v[132:135], v[202:205], v[110:113]
	v_mfma_f32_16x16x32_bf16 v[106:109], v[140:143], v[202:205], v[106:109]
	v_mfma_f32_16x16x32_bf16 v[102:105], v[132:135], v[210:213], v[102:105]
	v_mfma_f32_16x16x32_bf16 v[98:101], v[140:143], v[210:213], v[98:101]
	v_mfma_f32_16x16x32_bf16 v[126:129], v[136:139], v[190:193], v[126:129]
	v_mfma_f32_16x16x32_bf16 v[122:125], v[144:147], v[190:193], v[122:125]
	v_mfma_f32_16x16x32_bf16 v[118:121], v[136:139], v[198:201], v[118:121]
	v_mfma_f32_16x16x32_bf16 v[114:117], v[144:147], v[198:201], v[114:117]
	v_mfma_f32_16x16x32_bf16 v[110:113], v[136:139], v[206:209], v[110:113]
	v_mfma_f32_16x16x32_bf16 v[106:109], v[144:147], v[206:209], v[106:109]
	v_mfma_f32_16x16x32_bf16 v[102:105], v[136:139], v[214:217], v[102:105]
	v_mfma_f32_16x16x32_bf16 v[98:101], v[144:147], v[214:217], v[98:101]
	s_setprio 0
	s_setprio 1
	v_mfma_f32_16x16x32_bf16 v[94:97], v[168:171], v[186:189], v[94:97]
	v_mfma_f32_16x16x32_bf16 v[90:93], v[178:181], v[186:189], v[90:93]
	v_mfma_f32_16x16x32_bf16 v[86:89], v[168:171], v[194:197], v[86:89]
	v_mfma_f32_16x16x32_bf16 v[82:85], v[178:181], v[194:197], v[82:85]
	v_mfma_f32_16x16x32_bf16 v[78:81], v[168:171], v[202:205], v[78:81]
	v_mfma_f32_16x16x32_bf16 v[74:77], v[178:181], v[202:205], v[74:77]
	v_mfma_f32_16x16x32_bf16 v[70:73], v[168:171], v[210:213], v[70:73]
	v_mfma_f32_16x16x32_bf16 v[66:69], v[178:181], v[210:213], v[66:69]
	v_mfma_f32_16x16x32_bf16 v[94:97], v[174:177], v[190:193], v[94:97]
	v_mfma_f32_16x16x32_bf16 v[90:93], v[182:185], v[190:193], v[90:93]
	v_mfma_f32_16x16x32_bf16 v[86:89], v[174:177], v[198:201], v[86:89]
	v_mfma_f32_16x16x32_bf16 v[82:85], v[182:185], v[198:201], v[82:85]
	v_mfma_f32_16x16x32_bf16 v[78:81], v[174:177], v[206:209], v[78:81]
	v_mfma_f32_16x16x32_bf16 v[74:77], v[182:185], v[206:209], v[74:77]
	v_mfma_f32_16x16x32_bf16 v[70:73], v[174:177], v[214:217], v[70:73]
	v_mfma_f32_16x16x32_bf16 v[66:69], v[182:185], v[214:217], v[66:69]
	s_barrier
	s_setprio 0
	s_add_i32 s12, s79, s68
	v_lshl_add_u64 v[218:219], s[50:51], 0, v[152:153]
	s_add_i32 s13, s12, 0x2000
	v_lshl_add_u64 v[148:149], v[218:219], 0, s[22:23]
	s_mov_b32 m0, s12
	v_lshl_add_u64 v[220:221], s[50:51], 0, v[156:157]
	s_add_u32 s14, s50, 0x80100
	ds_read_b128 v[186:189], v172 offset:16384
	ds_read_b128 v[190:193], v172 offset:17408
	ds_read_b128 v[194:197], v172 offset:18432
	ds_read_b128 v[198:201], v172 offset:19456
	ds_read_b128 v[202:205], v172 offset:20480
	ds_read_b128 v[206:209], v172 offset:21504
	ds_read_b128 v[210:213], v172 offset:22528
	ds_read_b128 v[214:217], v172 offset:23552
	global_load_lds_dwordx4 v[148:149], off
	v_lshl_add_u64 v[148:149], v[220:221], 0, s[22:23]
	s_mov_b32 m0, s13
	s_addc_u32 s15, s51, 0
	s_add_i32 s43, s80, s68
	global_load_lds_dwordx4 v[148:149], off
	v_lshl_add_u64 v[148:149], s[14:15], 0, v[152:153]
	s_mov_b32 m0, s43
	s_add_i32 s46, s43, 0x2000
	global_load_lds_dwordx4 v[148:149], off
	v_lshl_add_u64 v[148:149], s[14:15], 0, v[156:157]
	s_mov_b32 m0, s46
	v_lshl_add_u64 v[222:223], s[62:63], 0, v[150:151]
	global_load_lds_dwordx4 v[148:149], off
	v_lshl_add_u64 v[148:149], v[222:223], 0, s[22:23]
	s_mov_b32 m0, s69
	v_lshl_add_u64 v[224:225], s[62:63], 0, v[154:155]
	global_load_lds_dwordx4 v[148:149], off
	v_lshl_add_u64 v[148:149], v[224:225], 0, s[22:23]
	s_mov_b32 m0, s70
	s_nop 0
	global_load_lds_dwordx4 v[148:149], off
	s_waitcnt vmcnt(8)
	s_waitcnt lgkmcnt(0)
	s_setprio 1
	s_barrier
	v_mfma_f32_16x16x32_bf16 v[62:65], v[132:135], v[186:189], v[62:65]
	v_mfma_f32_16x16x32_bf16 v[58:61], v[140:143], v[186:189], v[58:61]
	v_mfma_f32_16x16x32_bf16 v[54:57], v[132:135], v[194:197], v[54:57]
	v_mfma_f32_16x16x32_bf16 v[50:53], v[140:143], v[194:197], v[50:53]
	v_mfma_f32_16x16x32_bf16 v[46:49], v[132:135], v[202:205], v[46:49]
	v_mfma_f32_16x16x32_bf16 v[42:45], v[140:143], v[202:205], v[42:45]
	v_mfma_f32_16x16x32_bf16 v[38:41], v[132:135], v[210:213], v[38:41]
	v_mfma_f32_16x16x32_bf16 v[34:37], v[140:143], v[210:213], v[34:37]
	v_mfma_f32_16x16x32_bf16 v[62:65], v[136:139], v[190:193], v[62:65]
	v_mfma_f32_16x16x32_bf16 v[58:61], v[144:147], v[190:193], v[58:61]
	v_mfma_f32_16x16x32_bf16 v[54:57], v[136:139], v[198:201], v[54:57]
	v_mfma_f32_16x16x32_bf16 v[50:53], v[144:147], v[198:201], v[50:53]
	v_mfma_f32_16x16x32_bf16 v[46:49], v[136:139], v[206:209], v[46:49]
	v_mfma_f32_16x16x32_bf16 v[42:45], v[144:147], v[206:209], v[42:45]
	v_mfma_f32_16x16x32_bf16 v[38:41], v[136:139], v[214:217], v[38:41]
	v_mfma_f32_16x16x32_bf16 v[34:37], v[144:147], v[214:217], v[34:37]
	s_setprio 0
	s_setprio 1
	v_mfma_f32_16x16x32_bf16 v[30:33], v[168:171], v[186:189], v[30:33]
	v_mfma_f32_16x16x32_bf16 v[26:29], v[178:181], v[186:189], v[26:29]
	v_mfma_f32_16x16x32_bf16 v[22:25], v[168:171], v[194:197], v[22:25]
	v_mfma_f32_16x16x32_bf16 v[18:21], v[178:181], v[194:197], v[18:21]
	v_mfma_f32_16x16x32_bf16 v[14:17], v[168:171], v[202:205], v[14:17]
	v_mfma_f32_16x16x32_bf16 v[10:13], v[178:181], v[202:205], v[10:13]
	v_mfma_f32_16x16x32_bf16 v[6:9], v[168:171], v[210:213], v[6:9]
	v_mfma_f32_16x16x32_bf16 v[2:5], v[178:181], v[210:213], v[2:5]
	v_mfma_f32_16x16x32_bf16 v[30:33], v[174:177], v[190:193], v[30:33]
	v_mfma_f32_16x16x32_bf16 v[26:29], v[182:185], v[190:193], v[26:29]
	v_mfma_f32_16x16x32_bf16 v[22:25], v[174:177], v[198:201], v[22:25]
	v_mfma_f32_16x16x32_bf16 v[18:21], v[182:185], v[198:201], v[18:21]
	v_mfma_f32_16x16x32_bf16 v[14:17], v[174:177], v[206:209], v[14:17]
	v_mfma_f32_16x16x32_bf16 v[10:13], v[182:185], v[206:209], v[10:13]
	v_mfma_f32_16x16x32_bf16 v[6:9], v[174:177], v[214:217], v[6:9]
	v_mfma_f32_16x16x32_bf16 v[2:5], v[182:185], v[214:217], v[2:5]
	s_barrier
	s_setprio 0
	s_add_i32 s47, 0, 0x18000
	s_add_i32 s55, 0, 0x1c000
	v_add_u32_e32 v132, s47, v1
	v_add_u32_e32 v133, s55, v1
	ds_read_b128 v[134:137], v132
	ds_read_b128 v[138:141], v132 offset:1024
	ds_read_b128 v[142:145], v132 offset:2048
	ds_read_b128 v[146:149], v132 offset:3072
	ds_read_b128 v[168:171], v133
	ds_read_b128 v[174:177], v133 offset:1024
	ds_read_b128 v[178:181], v133 offset:2048
	ds_read_b128 v[182:185], v133 offset:3072
	s_add_u32 s14, s62, 0x80100
	s_addc_u32 s15, s63, 0
	s_mov_b32 m0, s71
	v_lshl_add_u64 v[226:227], s[14:15], 0, v[150:151]
	ds_read_b128 v[186:189], v172 offset:32768
	ds_read_b128 v[190:193], v172 offset:33792
	ds_read_b128 v[194:197], v172 offset:34816
	ds_read_b128 v[198:201], v172 offset:35840
	ds_read_b128 v[202:205], v172 offset:36864
	ds_read_b128 v[206:209], v172 offset:37888
	ds_read_b128 v[210:213], v172 offset:38912
	ds_read_b128 v[214:217], v172 offset:39936
	global_load_lds_dwordx4 v[226:227], off
	v_lshl_add_u64 v[226:227], s[14:15], 0, v[154:155]
	s_mov_b32 m0, s72
	s_nop 0
	global_load_lds_dwordx4 v[226:227], off
	s_waitcnt vmcnt(8)
	s_waitcnt lgkmcnt(0)
	s_setprio 1
	s_barrier
	v_mfma_f32_16x16x32_bf16 v[126:129], v[134:137], v[186:189], v[126:129]
	v_mfma_f32_16x16x32_bf16 v[122:125], v[142:145], v[186:189], v[122:125]
	v_mfma_f32_16x16x32_bf16 v[118:121], v[134:137], v[194:197], v[118:121]
	v_mfma_f32_16x16x32_bf16 v[114:117], v[142:145], v[194:197], v[114:117]
	v_mfma_f32_16x16x32_bf16 v[110:113], v[134:137], v[202:205], v[110:113]
	v_mfma_f32_16x16x32_bf16 v[106:109], v[142:145], v[202:205], v[106:109]
	v_mfma_f32_16x16x32_bf16 v[102:105], v[134:137], v[210:213], v[102:105]
	v_mfma_f32_16x16x32_bf16 v[98:101], v[142:145], v[210:213], v[98:101]
	v_mfma_f32_16x16x32_bf16 v[126:129], v[138:141], v[190:193], v[126:129]
	v_mfma_f32_16x16x32_bf16 v[122:125], v[146:149], v[190:193], v[122:125]
	v_mfma_f32_16x16x32_bf16 v[118:121], v[138:141], v[198:201], v[118:121]
	v_mfma_f32_16x16x32_bf16 v[114:117], v[146:149], v[198:201], v[114:117]
	v_mfma_f32_16x16x32_bf16 v[110:113], v[138:141], v[206:209], v[110:113]
	v_mfma_f32_16x16x32_bf16 v[106:109], v[146:149], v[206:209], v[106:109]
	v_mfma_f32_16x16x32_bf16 v[102:105], v[138:141], v[214:217], v[102:105]
	v_mfma_f32_16x16x32_bf16 v[98:101], v[146:149], v[214:217], v[98:101]
	s_setprio 0
	s_setprio 1
	v_mfma_f32_16x16x32_bf16 v[94:97], v[168:171], v[186:189], v[94:97]
	v_mfma_f32_16x16x32_bf16 v[90:93], v[178:181], v[186:189], v[90:93]
	v_mfma_f32_16x16x32_bf16 v[86:89], v[168:171], v[194:197], v[86:89]
	v_mfma_f32_16x16x32_bf16 v[82:85], v[178:181], v[194:197], v[82:85]
	v_mfma_f32_16x16x32_bf16 v[78:81], v[168:171], v[202:205], v[78:81]
	v_mfma_f32_16x16x32_bf16 v[74:77], v[178:181], v[202:205], v[74:77]
	v_mfma_f32_16x16x32_bf16 v[70:73], v[168:171], v[210:213], v[70:73]
	v_mfma_f32_16x16x32_bf16 v[66:69], v[178:181], v[210:213], v[66:69]
	v_mfma_f32_16x16x32_bf16 v[94:97], v[174:177], v[190:193], v[94:97]
	v_mfma_f32_16x16x32_bf16 v[90:93], v[182:185], v[190:193], v[90:93]
	v_mfma_f32_16x16x32_bf16 v[86:89], v[174:177], v[198:201], v[86:89]
	v_mfma_f32_16x16x32_bf16 v[82:85], v[182:185], v[198:201], v[82:85]
	v_mfma_f32_16x16x32_bf16 v[78:81], v[174:177], v[206:209], v[78:81]
	v_mfma_f32_16x16x32_bf16 v[74:77], v[182:185], v[206:209], v[74:77]
	v_mfma_f32_16x16x32_bf16 v[70:73], v[174:177], v[214:217], v[70:73]
	v_mfma_f32_16x16x32_bf16 v[66:69], v[182:185], v[214:217], v[66:69]
	s_barrier
;     ...
;         for (int t = 2; t < nt; t += 2) PG8_KITER(t);
	s_setprio 0
	s_add_i32 s47, s47, s68
	s_add_i32 s53, s47, 0x2000
	v_lshl_add_u64 v[218:219], v[218:219], 0, s[28:29]
	s_mov_b32 m0, s47
	s_add_u32 s14, s50, 0x80180
	ds_read_b128 v[186:189], v172 offset:49152
	ds_read_b128 v[190:193], v172 offset:50176
	ds_read_b128 v[194:197], v172 offset:51200
	ds_read_b128 v[198:201], v172 offset:52224
	ds_read_b128 v[202:205], v172 offset:53248
	ds_read_b128 v[206:209], v172 offset:54272
	ds_read_b128 v[210:213], v172 offset:55296
	ds_read_b128 v[214:217], v172 offset:56320
	global_load_lds_dwordx4 v[218:219], off
	v_lshl_add_u64 v[218:219], v[220:221], 0, s[28:29]
	s_mov_b32 m0, s53
	s_addc_u32 s15, s51, 0
	s_add_i32 s55, s55, s68
	global_load_lds_dwordx4 v[218:219], off
	v_lshl_add_u64 v[218:219], s[14:15], 0, v[152:153]
	s_mov_b32 m0, s55
	s_add_i32 s56, s55, 0x2000
	global_load_lds_dwordx4 v[218:219], off
	v_lshl_add_u64 v[218:219], s[14:15], 0, v[156:157]
	s_mov_b32 m0, s56
	s_nop 0
	global_load_lds_dwordx4 v[218:219], off
	v_lshl_add_u64 v[218:219], v[222:223], 0, s[28:29]
	s_mov_b32 m0, s77
	s_nop 0
	global_load_lds_dwordx4 v[218:219], off
	v_lshl_add_u64 v[218:219], v[224:225], 0, s[28:29]
	s_mov_b32 m0, s78
	s_nop 0
	global_load_lds_dwordx4 v[218:219], off
	s_waitcnt vmcnt(8)
	s_waitcnt lgkmcnt(0)
	s_setprio 1
	s_barrier
	v_mfma_f32_16x16x32_bf16 v[62:65], v[134:137], v[186:189], v[62:65]
	v_mfma_f32_16x16x32_bf16 v[58:61], v[142:145], v[186:189], v[58:61]
	v_mfma_f32_16x16x32_bf16 v[54:57], v[134:137], v[194:197], v[54:57]
	v_mfma_f32_16x16x32_bf16 v[50:53], v[142:145], v[194:197], v[50:53]
	v_mfma_f32_16x16x32_bf16 v[46:49], v[134:137], v[202:205], v[46:49]
	v_mfma_f32_16x16x32_bf16 v[42:45], v[142:145], v[202:205], v[42:45]
	v_mfma_f32_16x16x32_bf16 v[38:41], v[134:137], v[210:213], v[38:41]
	v_mfma_f32_16x16x32_bf16 v[34:37], v[142:145], v[210:213], v[34:37]
	v_mfma_f32_16x16x32_bf16 v[62:65], v[138:141], v[190:193], v[62:65]
	v_mfma_f32_16x16x32_bf16 v[58:61], v[146:149], v[190:193], v[58:61]
	v_mfma_f32_16x16x32_bf16 v[54:57], v[138:141], v[198:201], v[54:57]
	v_mfma_f32_16x16x32_bf16 v[50:53], v[146:149], v[198:201], v[50:53]
	v_mfma_f32_16x16x32_bf16 v[46:49], v[138:141], v[206:209], v[46:49]
	v_mfma_f32_16x16x32_bf16 v[42:45], v[146:149], v[206:209], v[42:45]
	v_mfma_f32_16x16x32_bf16 v[38:41], v[138:141], v[214:217], v[38:41]
	v_mfma_f32_16x16x32_bf16 v[34:37], v[146:149], v[214:217], v[34:37]
	s_setprio 0
	s_setprio 1
	v_mfma_f32_16x16x32_bf16 v[30:33], v[168:171], v[186:189], v[30:33]
	v_mfma_f32_16x16x32_bf16 v[26:29], v[178:181], v[186:189], v[26:29]
	v_mfma_f32_16x16x32_bf16 v[22:25], v[168:171], v[194:197], v[22:25]
	v_mfma_f32_16x16x32_bf16 v[18:21], v[178:181], v[194:197], v[18:21]
	v_mfma_f32_16x16x32_bf16 v[14:17], v[168:171], v[202:205], v[14:17]
	v_mfma_f32_16x16x32_bf16 v[10:13], v[178:181], v[202:205], v[10:13]
	v_mfma_f32_16x16x32_bf16 v[6:9], v[168:171], v[210:213], v[6:9]
	v_mfma_f32_16x16x32_bf16 v[2:5], v[178:181], v[210:213], v[2:5]
	v_mfma_f32_16x16x32_bf16 v[30:33], v[174:177], v[190:193], v[30:33]
	v_mfma_f32_16x16x32_bf16 v[26:29], v[182:185], v[190:193], v[26:29]
	v_mfma_f32_16x16x32_bf16 v[22:25], v[174:177], v[198:201], v[22:25]
	v_mfma_f32_16x16x32_bf16 v[18:21], v[182:185], v[198:201], v[18:21]
	v_mfma_f32_16x16x32_bf16 v[14:17], v[174:177], v[206:209], v[14:17]
	v_mfma_f32_16x16x32_bf16 v[10:13], v[182:185], v[206:209], v[10:13]
	v_mfma_f32_16x16x32_bf16 v[6:9], v[174:177], v[214:217], v[6:9]
	v_mfma_f32_16x16x32_bf16 v[2:5], v[182:185], v[214:217], v[2:5]
	s_barrier
	s_setprio 0
	s_add_u32 s62, s62, 0x80180
	s_addc_u32 s63, s63, 0
	s_add_u32 s14, s50, 0x200
	s_addc_u32 s15, s51, 0
	s_mov_b32 s26, 0
	.p2align	6

;     __host__ __device__ bool next(int i, Unit& u) const { if (!StaticOrder::next(i >> 1, u)) return false; u.seg = i & 1; return true; }
; #define PG8_STAGE(bufoff, gbase, voff) do { _Pragma("unroll") for (int _i = 0; _i < 2; ++_i) \
;         __builtin_amdgcn_global_load_lds((const unsigned*)((const char*)(gbase) + (voff)[_i]), (LAS unsigned*)(lds + (bufoff) + ldsw + _i * 8192), 16, 0, 0); } while (0)
; #define PG8_WAIT_V(n) asm volatile("s_waitcnt vmcnt(" #n ")" ::: "memory")
; #define PG8_BAR __builtin_amdgcn_s_barrier()
; #define PG8_TOUCH(p) asm volatile("global_load_dword %0, %1, off" : "+v"(pfd) : "v"(p) : "memory")
;     ...
;     for (int i = 0; i < 2; ++i) { int R, C; stage_rc(tid * 16 + i * 8192, R, C); const int Rb = Epi::PERM ? ((R & ~31) + perm32(R & 31)) : R;
;         voffA[i] = (unsigned)(R * g.lda + C) * 2u; voffB[i] = (unsigned)(Rb * g.ldb + C) * 2u; }
;     const size_t kstep = (size_t)(BK * 2);
;     const size_t hstepA = (size_t)HALF * g.lda * 2, hstepB = (size_t)HALF * g.ldb * 2;
;     const unsigned ldsw = (unsigned)wid * 1024u;
;     const int aoff = lds_byte(wr * 64 + fr, fq * 8), boff = lds_byte(wc * 32 + fr, fq * 8);
;     ...
;     PG8_STAGE(PG8_SB(0, 0), cB, voffB); PG8_STAGE(PG8_SB(0, 1), cB + hstepB, voffB); PG8_STAGE(PG8_SA(0, 0), cA, voffA); PG8_STAGE(PG8_SA(0, 1), cA + hstepA, voffA);
;     if (wr == 1) PG8_BAR;
;     PG8_WAIT_V(2); PG8_BAR;
;     PG8_STAGE(PG8_SB(1, 0), cB + kstep, voffB); PG8_STAGE(PG8_SA(1, 0), cA + kstep, voffA); PG8_STAGE(PG8_SB(1, 1), cB + hstepB + kstep, voffB);
;     PG8_WAIT_V(6); PG8_BAR;
;     if constexpr (PF > 0) { const char* p0 = PG8_PFPTR(cA, cB) + (size_t)(2 + PF) * kstep; PG8_TOUCH(p0); }
;     for (;;) {
;         const bool has_next = S.next(ui + 1, nxt);
;         const char* nA = has_next ? PG8_APTR(nxt) : cA; const char* nB = has_next ? PG8_BPTR(nxt) : cB;
;         const char* pfc = PG8_PFPTR(cA, cB); const char* pfn = PG8_PFPTR(nA, nB);
.LBB0_1004:
	s_mov_b64 s[16:17], 0x80
	s_lshl_b32 s5, s5, 12
	s_add_i32 m0, s13, 0x18000
	v_lshl_add_u64 v[8:9], v[8:9], 0, s[16:17]
	s_lshl_b32 s0, s14, 13
	s_and_b32 s5, s5, 0x3000
	s_waitcnt vmcnt(2)
	s_barrier
	global_load_lds_dwordx4 v[8:9], off
	v_lshl_add_u64 v[6:7], v[6:7], 0, s[16:17]
	s_add_i32 m0, s13, 0x1a000
	s_add_i32 s54, s13, 0x8000
	s_add_i32 s55, s13, 0xa000
	global_load_lds_dwordx4 v[6:7], off
	v_lshl_add_u64 v[2:3], v[2:3], 0, s[16:17]
	s_mov_b32 m0, s54
	s_add_u32 s14, s42, 0x100080
	global_load_lds_dwordx4 v[2:3], off
	v_lshl_add_u64 v[2:3], v[4:5], 0, s[16:17]
	s_mov_b32 m0, s55
	s_addc_u32 s15, s43, 0
	global_load_lds_dwordx4 v[2:3], off
	s_add_i32 m0, s13, 0x1c000
	v_lshl_add_u64 v[2:3], s[14:15], 0, v[156:157]
	global_load_lds_dwordx4 v[2:3], off
	v_lshl_add_u64 v[2:3], s[14:15], 0, v[160:161]
	s_add_i32 m0, s13, 0x1e000
	v_and_b32_e32 v0, 15, v1
	global_load_lds_dwordx4 v[2:3], off
	v_and_b32_e32 v2, 48, v1
	v_lshlrev_b32_e32 v1, 2, v1
	v_lshlrev_b32_e32 v0, 6, v0
	v_and_b32_e32 v1, 32, v1
	v_or_b32_e32 v3, v0, v2
	v_bitop3_b32 v0, v0, v1, v2 bitop3:0x36
	v_bitop3_b32 v2, v3, s0, v1 bitop3:0xde
	v_or_b32_e32 v1, s5, v0
	v_lshlrev_b32_e32 v0, 16, v10
	v_and_b32_e32 v0, 0xfffe0000, v0
	v_lshl_add_u32 v0, v11, 13, v0
	v_and_b32_e32 v3, 1, v10
	v_lshl_or_b32 v0, v3, 6, v0
	v_lshl_add_u32 v162, v12, 1, v0
	v_lshlrev_b32_e32 v0, 16, v13
	s_cmpk_lt_u32 s4, 0x100
	v_and_b32_e32 v0, 0xfffe0000, v0
	s_waitcnt vmcnt(6)
	s_cselect_b64 s[18:19], -1, 0
	v_lshl_add_u32 v0, v14, 13, v0
	v_and_b32_e32 v3, 1, v13
	s_add_i32 s63, 0, 0x10000
	v_lshl_or_b32 v0, v3, 6, v0
	v_add_u32_e32 v182, s63, v1
	s_add_i32 s60, 0, 0x14000
	s_add_i32 s63, s63, s12
	s_ashr_i32 s58, s3, 31
	s_ashr_i32 s59, s2, 31
	v_mov_b32_e32 v163, v157
	v_lshl_add_u32 v164, v15, 1, v0
	v_mov_b32_e32 v165, v157
	v_mov_b64_e32 v[168:169], 0x3ff
	v_add_u32_e32 v183, s60, v1
	v_add_u32_e32 v184, 0, v2
	s_mov_b64 s[20:21], 0x100
	s_mov_b64 s[22:23], 0x180
	s_add_i32 s61, s13, 0xc000
	s_add_i32 s62, s13, 0xe000
	s_add_i32 s64, s63, 0x2000
	s_mov_b32 s65, 0
	s_barrier
	s_branch .LBB0_1007
	.p2align	6

;     __host__ __device__ bool next(int i, Unit& u) const { if (!StaticOrder::next(i >> 1, u)) return false; u.seg = i & 1; return true; }
;     ...
;         const bool has_next = S.next(ui + 1, nxt);
;         const char* nA = has_next ? PG8_APTR(nxt) : cA; const char* nB = has_next ? PG8_BPTR(nxt) : cB;
;         const char* pfc = PG8_PFPTR(cA, cB); const char* pfn = PG8_PFPTR(nA, nB);
.LBB0_1013:
	s_ashr_i32 s29, s28, 31
	ds_read_b128 v[2:5], v182
	ds_read_b128 v[6:9], v182 offset:1024
	ds_read_b128 v[10:13], v182 offset:2048
	ds_read_b128 v[14:17], v182 offset:3072
	ds_read_b128 v[18:21], v183
	ds_read_b128 v[22:25], v183 offset:1024
	ds_read_b128 v[26:29], v183 offset:2048
	ds_read_b128 v[30:33], v183 offset:3072
	s_lshl_b64 s[14:15], s[28:29], 21
	s_add_u32 s30, s24, s14
	s_addc_u32 s31, s25, s15
	s_and_b64 s[14:15], s[4:5], exec
	s_cselect_b32 s29, s31, s49
	s_cselect_b32 s41, s30, s48
	s_and_b32 s0, s66, 0x7fffffff
	s_lshl_b64 s[14:15], s[0:1], 21
	s_add_u32 s38, s10, s14
	s_addc_u32 s39, s11, s15
	s_and_b64 s[14:15], s[4:5], exec
	s_cselect_b32 s0, s39, s43
	s_cselect_b32 s68, s38, s42
	s_add_u32 s14, s48, 0x100080
	s_addc_u32 s15, s49, 0
	s_mov_b32 m0, s61
	v_lshl_add_u64 v[66:67], s[14:15], 0, v[154:155]
	ds_read_b128 v[34:37], v184
	ds_read_b128 v[38:41], v184 offset:1024
	ds_read_b128 v[42:45], v184 offset:2048
	ds_read_b128 v[46:49], v184 offset:3072
	ds_read_b128 v[50:53], v184 offset:4096
	ds_read_b128 v[54:57], v184 offset:5120
	ds_read_b128 v[58:61], v184 offset:6144
	ds_read_b128 v[62:65], v184 offset:7168
	global_load_lds_dwordx4 v[66:67], off
	v_lshl_add_u64 v[66:67], s[14:15], 0, v[158:159]
	s_mov_b32 m0, s62
	s_nop 0
	global_load_lds_dwordx4 v[66:67], off
	s_waitcnt vmcnt(8)
	s_waitcnt lgkmcnt(0)
	s_setprio 1
	s_barrier
	v_mfma_f32_16x16x32_bf16 v[90:93], v[2:5], v[58:61], 0
	v_mfma_f32_16x16x32_bf16 v[66:69], v[2:5], v[34:37], 0
	v_mfma_f32_16x16x32_bf16 v[70:73], v[10:13], v[34:37], 0
	v_mfma_f32_16x16x32_bf16 v[74:77], v[2:5], v[42:45], 0
	v_mfma_f32_16x16x32_bf16 v[78:81], v[10:13], v[42:45], 0
	v_mfma_f32_16x16x32_bf16 v[82:85], v[2:5], v[50:53], 0
	v_mfma_f32_16x16x32_bf16 v[86:89], v[10:13], v[50:53], 0
	v_mfma_f32_16x16x32_bf16 v[98:101], v[6:9], v[62:65], v[90:93]
	v_mfma_f32_16x16x32_bf16 v[90:93], v[10:13], v[58:61], 0
	v_mfma_f32_16x16x32_bf16 v[66:69], v[6:9], v[38:41], v[66:69]
	v_mfma_f32_16x16x32_bf16 v[70:73], v[14:17], v[38:41], v[70:73]
	v_mfma_f32_16x16x32_bf16 v[74:77], v[6:9], v[46:49], v[74:77]
	v_mfma_f32_16x16x32_bf16 v[78:81], v[14:17], v[46:49], v[78:81]
	v_mfma_f32_16x16x32_bf16 v[82:85], v[6:9], v[54:57], v[82:85]
	v_mfma_f32_16x16x32_bf16 v[86:89], v[14:17], v[54:57], v[86:89]
	v_mfma_f32_16x16x32_bf16 v[102:105], v[14:17], v[62:65], v[90:93]
	s_setprio 0
	s_setprio 1
	v_mfma_f32_16x16x32_bf16 v[90:93], v[18:21], v[34:37], 0
	v_mfma_f32_16x16x32_bf16 v[34:37], v[26:29], v[34:37], 0
	v_mfma_f32_16x16x32_bf16 v[114:117], v[22:25], v[38:41], v[90:93]
	v_mfma_f32_16x16x32_bf16 v[34:37], v[30:33], v[38:41], v[34:37]
	v_mfma_f32_16x16x32_bf16 v[38:41], v[18:21], v[42:45], 0
	v_mfma_f32_16x16x32_bf16 v[42:45], v[26:29], v[42:45], 0
	v_mfma_f32_16x16x32_bf16 v[38:41], v[22:25], v[46:49], v[38:41]
	v_mfma_f32_16x16x32_bf16 v[42:45], v[30:33], v[46:49], v[42:45]
	v_mfma_f32_16x16x32_bf16 v[46:49], v[18:21], v[50:53], 0
	v_mfma_f32_16x16x32_bf16 v[50:53], v[26:29], v[50:53], 0
	v_mfma_f32_16x16x32_bf16 v[46:49], v[22:25], v[54:57], v[46:49]
	v_mfma_f32_16x16x32_bf16 v[50:53], v[30:33], v[54:57], v[50:53]
	v_mfma_f32_16x16x32_bf16 v[54:57], v[18:21], v[58:61], 0
	v_mfma_f32_16x16x32_bf16 v[58:61], v[26:29], v[58:61], 0
	v_mfma_f32_16x16x32_bf16 v[54:57], v[22:25], v[62:65], v[54:57]
	v_mfma_f32_16x16x32_bf16 v[58:61], v[30:33], v[62:65], v[58:61]
	s_barrier
	s_setprio 0
	v_lshl_add_u64 v[152:153], s[42:43], 0, v[156:157]
	s_mov_b32 m0, s63
	v_lshl_add_u64 v[130:131], v[152:153], 0, s[20:21]
	v_lshl_add_u64 v[250:251], s[42:43], 0, v[160:161]
	s_add_u32 s14, s42, 0x100100
	ds_read_b128 v[62:65], v184 offset:16384
	ds_read_b128 v[90:93], v184 offset:17408
	ds_read_b128 v[94:97], v184 offset:18432
	ds_read_b128 v[106:109], v184 offset:19456
	ds_read_b128 v[110:113], v184 offset:20480
	ds_read_b128 v[118:121], v184 offset:21504
	ds_read_b128 v[122:125], v184 offset:22528
	ds_read_b128 v[126:129], v184 offset:23552
	global_load_lds_dwordx4 v[130:131], off
	v_lshl_add_u64 v[130:131], v[250:251], 0, s[20:21]
	s_mov_b32 m0, s64
	s_addc_u32 s15, s43, 0
	s_add_i32 s69, s60, s12
	global_load_lds_dwordx4 v[130:131], off
	v_lshl_add_u64 v[130:131], s[14:15], 0, v[156:157]
	s_mov_b32 m0, s69
	s_add_i32 s46, s69, 0x2000
	global_load_lds_dwordx4 v[130:131], off
	v_lshl_add_u64 v[130:131], s[14:15], 0, v[160:161]
	s_mov_b32 m0, s46
	v_lshl_add_u64 v[252:253], s[48:49], 0, v[154:155]
	global_load_lds_dwordx4 v[130:131], off
	v_lshl_add_u64 v[130:131], v[252:253], 0, s[20:21]
	s_mov_b32 m0, s13
	v_lshl_add_u64 v[166:167], s[48:49], 0, v[158:159]
	global_load_lds_dwordx4 v[130:131], off
	v_lshl_add_u64 v[130:131], v[166:167], 0, s[20:21]
	s_mov_b32 m0, s33
	s_nop 0
	global_load_lds_dwordx4 v[130:131], off
	s_waitcnt vmcnt(8)
	s_waitcnt lgkmcnt(0)
	s_setprio 1
	s_barrier
	v_mfma_f32_16x16x32_bf16 v[130:133], v[2:5], v[62:65], 0
	v_mfma_f32_16x16x32_bf16 v[140:143], v[2:5], v[94:97], 0
	v_mfma_f32_16x16x32_bf16 v[148:151], v[2:5], v[110:113], 0
	v_mfma_f32_16x16x32_bf16 v[2:5], v[2:5], v[122:125], 0
	v_mfma_f32_16x16x32_bf16 v[132:135], v[6:9], v[90:93], v[130:133]
	v_mfma_f32_16x16x32_bf16 v[140:143], v[6:9], v[106:109], v[140:143]
	v_mfma_f32_16x16x32_bf16 v[148:151], v[6:9], v[118:121], v[148:151]
	v_mfma_f32_16x16x32_bf16 v[2:5], v[6:9], v[126:129], v[2:5]
	v_mfma_f32_16x16x32_bf16 v[6:9], v[10:13], v[122:125], 0
	v_mfma_f32_16x16x32_bf16 v[136:139], v[10:13], v[62:65], 0
	v_mfma_f32_16x16x32_bf16 v[144:147], v[10:13], v[94:97], 0
	v_mfma_f32_16x16x32_bf16 v[170:173], v[10:13], v[110:113], 0
	v_mfma_f32_16x16x32_bf16 v[6:9], v[14:17], v[126:129], v[6:9]
	v_mfma_f32_16x16x32_bf16 v[136:139], v[14:17], v[90:93], v[136:139]
	v_mfma_f32_16x16x32_bf16 v[144:147], v[14:17], v[106:109], v[144:147]
	v_mfma_f32_16x16x32_bf16 v[170:173], v[14:17], v[118:121], v[170:173]
	s_setprio 0
	s_setprio 1
	v_mfma_f32_16x16x32_bf16 v[10:13], v[18:21], v[62:65], 0
	v_mfma_f32_16x16x32_bf16 v[174:177], v[22:25], v[90:93], v[10:13]
	v_mfma_f32_16x16x32_bf16 v[10:13], v[26:29], v[62:65], 0
	v_mfma_f32_16x16x32_bf16 v[178:181], v[30:33], v[90:93], v[10:13]
	v_mfma_f32_16x16x32_bf16 v[10:13], v[18:21], v[94:97], 0
	v_mfma_f32_16x16x32_bf16 v[186:189], v[22:25], v[106:109], v[10:13]
	v_mfma_f32_16x16x32_bf16 v[10:13], v[26:29], v[94:97], 0
	v_mfma_f32_16x16x32_bf16 v[190:193], v[30:33], v[106:109], v[10:13]
	v_mfma_f32_16x16x32_bf16 v[10:13], v[18:21], v[110:113], 0
	v_mfma_f32_16x16x32_bf16 v[194:197], v[22:25], v[118:121], v[10:13]
	v_mfma_f32_16x16x32_bf16 v[10:13], v[26:29], v[110:113], 0
	v_mfma_f32_16x16x32_bf16 v[198:201], v[30:33], v[118:121], v[10:13]
	v_mfma_f32_16x16x32_bf16 v[10:13], v[18:21], v[122:125], 0
	v_mfma_f32_16x16x32_bf16 v[202:205], v[22:25], v[126:129], v[10:13]
	v_mfma_f32_16x16x32_bf16 v[10:13], v[26:29], v[122:125], 0
	v_mfma_f32_16x16x32_bf16 v[206:209], v[30:33], v[126:129], v[10:13]
	s_barrier
	s_setprio 0
	s_add_i32 s47, 0, 0x18000
	s_add_i32 s56, 0, 0x1c000
	v_add_u32_e32 v130, s47, v1
	v_add_u32_e32 v131, s56, v1
	s_nop 0
	ds_read_b128 v[10:13], v130
	ds_read_b128 v[14:17], v130 offset:1024
	ds_read_b128 v[18:21], v130 offset:2048
	ds_read_b128 v[22:25], v130 offset:3072
	ds_read_b128 v[210:213], v131
	ds_read_b128 v[214:217], v131 offset:1024
	ds_read_b128 v[218:221], v131 offset:2048
	ds_read_b128 v[222:225], v131 offset:3072
	s_add_u32 s14, s48, 0x100100
	s_addc_u32 s15, s49, 0
	s_mov_b32 m0, s52
	v_lshl_add_u64 v[90:91], s[14:15], 0, v[154:155]
	ds_read_b128 v[26:29], v184 offset:32768
	ds_read_b128 v[30:33], v184 offset:33792
	ds_read_b128 v[62:65], v184 offset:34816
	ds_read_b128 v[226:229], v184 offset:35840
	ds_read_b128 v[230:233], v184 offset:36864
	ds_read_b128 v[234:237], v184 offset:37888
	ds_read_b128 v[238:241], v184 offset:38912
	ds_read_b128 v[242:245], v184 offset:39936
	global_load_lds_dwordx4 v[90:91], off
	v_lshl_add_u64 v[90:91], s[14:15], 0, v[158:159]
	s_mov_b32 m0, s53
	s_nop 0
	global_load_lds_dwordx4 v[90:91], off
	s_waitcnt vmcnt(8)
	s_waitcnt lgkmcnt(0)
	s_setprio 1
	s_barrier
	v_mfma_f32_16x16x32_bf16 v[66:69], v[10:13], v[26:29], v[66:69]
	v_mfma_f32_16x16x32_bf16 v[122:125], v[14:17], v[30:33], v[66:69]
	v_mfma_f32_16x16x32_bf16 v[66:69], v[18:21], v[26:29], v[70:73]
	v_mfma_f32_16x16x32_bf16 v[118:121], v[22:25], v[30:33], v[66:69]
	v_mfma_f32_16x16x32_bf16 v[66:69], v[10:13], v[62:65], v[74:77]
	v_mfma_f32_16x16x32_bf16 v[110:113], v[14:17], v[226:229], v[66:69]
	v_mfma_f32_16x16x32_bf16 v[66:69], v[18:21], v[62:65], v[78:81]
	v_mfma_f32_16x16x32_bf16 v[106:109], v[22:25], v[226:229], v[66:69]
	v_mfma_f32_16x16x32_bf16 v[66:69], v[10:13], v[230:233], v[82:85]
	v_mfma_f32_16x16x32_bf16 v[94:97], v[14:17], v[234:237], v[66:69]
	v_mfma_f32_16x16x32_bf16 v[66:69], v[18:21], v[230:233], v[86:89]
	v_mfma_f32_16x16x32_bf16 v[90:93], v[22:25], v[234:237], v[66:69]
	v_mfma_f32_16x16x32_bf16 v[66:69], v[10:13], v[238:241], v[98:101]
	v_mfma_f32_16x16x32_bf16 v[78:81], v[14:17], v[242:245], v[66:69]
	v_mfma_f32_16x16x32_bf16 v[66:69], v[18:21], v[238:241], v[102:105]
	v_mfma_f32_16x16x32_bf16 v[74:77], v[22:25], v[242:245], v[66:69]
	s_setprio 0
	s_setprio 1
	v_mfma_f32_16x16x32_bf16 v[66:69], v[210:213], v[26:29], v[114:117]
	v_mfma_f32_16x16x32_bf16 v[26:29], v[218:221], v[26:29], v[34:37]
	v_mfma_f32_16x16x32_bf16 v[114:117], v[222:225], v[30:33], v[26:29]
	v_mfma_f32_16x16x32_bf16 v[26:29], v[210:213], v[62:65], v[38:41]
	v_mfma_f32_16x16x32_bf16 v[102:105], v[214:217], v[226:229], v[26:29]
	v_mfma_f32_16x16x32_bf16 v[26:29], v[218:221], v[62:65], v[42:45]
	v_mfma_f32_16x16x32_bf16 v[98:101], v[222:225], v[226:229], v[26:29]
	v_mfma_f32_16x16x32_bf16 v[26:29], v[210:213], v[230:233], v[46:49]
	v_mfma_f32_16x16x32_bf16 v[86:89], v[214:217], v[234:237], v[26:29]
	v_mfma_f32_16x16x32_bf16 v[26:29], v[218:221], v[230:233], v[50:53]
	v_mfma_f32_16x16x32_bf16 v[82:85], v[222:225], v[234:237], v[26:29]
	v_mfma_f32_16x16x32_bf16 v[26:29], v[210:213], v[238:241], v[54:57]
	v_mfma_f32_16x16x32_bf16 v[70:73], v[214:217], v[242:245], v[26:29]
	v_mfma_f32_16x16x32_bf16 v[26:29], v[218:221], v[238:241], v[58:61]
	v_mfma_f32_16x16x32_bf16 v[126:129], v[214:217], v[30:33], v[66:69]
	v_mfma_f32_16x16x32_bf16 v[66:69], v[222:225], v[242:245], v[26:29]
	s_barrier
;     ...
;         for (int t = 2; t < nt; t += 2) PG8_KITER(t);
	s_setprio 0
	s_add_i32 s47, s47, s12
	s_add_i32 s70, s47, 0x2000
	s_nop 1
	v_lshl_add_u64 v[26:27], v[152:153], 0, s[22:23]
	s_mov_b32 m0, s47
	s_add_u32 s14, s42, 0x100180
	ds_read_b128 v[34:37], v184 offset:49152
	ds_read_b128 v[38:41], v184 offset:50176
	ds_read_b128 v[226:229], v184 offset:51200
	ds_read_b128 v[230:233], v184 offset:52224
	ds_read_b128 v[234:237], v184 offset:53248
	ds_read_b128 v[238:241], v184 offset:54272
	ds_read_b128 v[242:245], v184 offset:55296
	ds_read_b128 v[246:249], v184 offset:56320
	global_load_lds_dwordx4 v[26:27], off
	v_lshl_add_u64 v[26:27], v[250:251], 0, s[22:23]
	s_mov_b32 m0, s70
	s_addc_u32 s15, s43, 0
	s_add_i32 s56, s56, s12
	global_load_lds_dwordx4 v[26:27], off
	v_lshl_add_u64 v[26:27], s[14:15], 0, v[156:157]
	s_mov_b32 m0, s56
	s_add_i32 s57, s56, 0x2000
	global_load_lds_dwordx4 v[26:27], off
	v_lshl_add_u64 v[26:27], s[14:15], 0, v[160:161]
	s_mov_b32 m0, s57
	s_nop 0
	global_load_lds_dwordx4 v[26:27], off
	v_lshl_add_u64 v[26:27], v[252:253], 0, s[22:23]
	s_mov_b32 m0, s54
	s_nop 0
	global_load_lds_dwordx4 v[26:27], off
	v_lshl_add_u64 v[26:27], v[166:167], 0, s[22:23]
	s_mov_b32 m0, s55
	s_nop 0
	global_load_lds_dwordx4 v[26:27], off
	s_waitcnt vmcnt(8)
	s_waitcnt lgkmcnt(0)
	s_setprio 1
	s_barrier
	v_mfma_f32_16x16x32_bf16 v[26:29], v[10:13], v[34:37], v[132:135]
	v_mfma_f32_16x16x32_bf16 v[58:61], v[14:17], v[38:41], v[26:29]
	v_mfma_f32_16x16x32_bf16 v[26:29], v[18:21], v[34:37], v[136:139]
	v_mfma_f32_16x16x32_bf16 v[54:57], v[22:25], v[38:41], v[26:29]
	v_mfma_f32_16x16x32_bf16 v[26:29], v[10:13], v[226:229], v[140:143]
	v_mfma_f32_16x16x32_bf16 v[46:49], v[14:17], v[230:233], v[26:29]
	v_mfma_f32_16x16x32_bf16 v[26:29], v[18:21], v[226:229], v[144:147]
	v_mfma_f32_16x16x32_bf16 v[42:45], v[22:25], v[230:233], v[26:29]
	v_mfma_f32_16x16x32_bf16 v[26:29], v[10:13], v[234:237], v[148:151]
	v_mfma_f32_16x16x32_bf16 v[2:5], v[10:13], v[242:245], v[2:5]
	v_mfma_f32_16x16x32_bf16 v[30:33], v[14:17], v[238:241], v[26:29]
	v_mfma_f32_16x16x32_bf16 v[26:29], v[18:21], v[234:237], v[170:173]
	v_mfma_f32_16x16x32_bf16 v[14:17], v[14:17], v[246:249], v[2:5]
	v_mfma_f32_16x16x32_bf16 v[2:5], v[18:21], v[242:245], v[6:9]
	v_mfma_f32_16x16x32_bf16 v[26:29], v[22:25], v[238:241], v[26:29]
	v_mfma_f32_16x16x32_bf16 v[10:13], v[22:25], v[246:249], v[2:5]
	s_setprio 0
	s_setprio 1
	v_mfma_f32_16x16x32_bf16 v[2:5], v[210:213], v[34:37], v[174:177]
	v_mfma_f32_16x16x32_bf16 v[62:65], v[214:217], v[38:41], v[2:5]
	v_mfma_f32_16x16x32_bf16 v[2:5], v[218:221], v[34:37], v[178:181]
	v_mfma_f32_16x16x32_bf16 v[50:53], v[222:225], v[38:41], v[2:5]
	v_mfma_f32_16x16x32_bf16 v[2:5], v[210:213], v[226:229], v[186:189]
	v_mfma_f32_16x16x32_bf16 v[38:41], v[214:217], v[230:233], v[2:5]
	v_mfma_f32_16x16x32_bf16 v[2:5], v[218:221], v[226:229], v[190:193]
	v_mfma_f32_16x16x32_bf16 v[34:37], v[222:225], v[230:233], v[2:5]
	v_mfma_f32_16x16x32_bf16 v[2:5], v[210:213], v[234:237], v[194:197]
	v_mfma_f32_16x16x32_bf16 v[22:25], v[214:217], v[238:241], v[2:5]
	v_mfma_f32_16x16x32_bf16 v[2:5], v[218:221], v[234:237], v[198:201]
	v_mfma_f32_16x16x32_bf16 v[18:21], v[222:225], v[238:241], v[2:5]
	v_mfma_f32_16x16x32_bf16 v[2:5], v[210:213], v[242:245], v[202:205]
	v_mfma_f32_16x16x32_bf16 v[6:9], v[214:217], v[246:249], v[2:5]
	v_mfma_f32_16x16x32_bf16 v[2:5], v[218:221], v[242:245], v[206:209]
	v_mfma_f32_16x16x32_bf16 v[2:5], v[222:225], v[246:249], v[2:5]
	s_barrier
	s_setprio 0
	s_add_u32 s48, s48, 0x100180
	s_addc_u32 s49, s49, 0
	s_add_u32 s14, s42, 0x200
	s_addc_u32 s15, s43, 0
	s_mov_b32 s26, 0
	.p2align	6

;     __host__ __device__ bool next(int i, Unit& u) const { if (!StaticOrder::next(i >> 1, u)) return false; u.seg = i & 1; return true; }
; #define PG8_STAGE(bufoff, gbase, voff) do { _Pragma("unroll") for (int _i = 0; _i < 2; ++_i) \
;         __builtin_amdgcn_global_load_lds((const unsigned*)((const char*)(gbase) + (voff)[_i]), (LAS unsigned*)(lds + (bufoff) + ldsw + _i * 8192), 16, 0, 0); } while (0)
; #define PG8_WAIT_V(n) asm volatile("s_waitcnt vmcnt(" #n ")" ::: "memory")
; #define PG8_BAR __builtin_amdgcn_s_barrier()
; #define PG8_TOUCH(p) asm volatile("global_load_dword %0, %1, off" : "+v"(pfd) : "v"(p) : "memory")
;     ...
;     for (int i = 0; i < 2; ++i) { int R, C; stage_rc(tid * 16 + i * 8192, R, C); const int Rb = Epi::PERM ? ((R & ~31) + perm32(R & 31)) : R;
;         voffA[i] = (unsigned)(R * g.lda + C) * 2u; voffB[i] = (unsigned)(Rb * g.ldb + C) * 2u; }
;     const size_t kstep = (size_t)(BK * 2);
;     const size_t hstepA = (size_t)HALF * g.lda * 2, hstepB = (size_t)HALF * g.ldb * 2;
;     const unsigned ldsw = (unsigned)wid * 1024u;
;     const int aoff = lds_byte(wr * 64 + fr, fq * 8), boff = lds_byte(wc * 32 + fr, fq * 8);
;     ...
;     PG8_STAGE(PG8_SB(0, 0), cB, voffB); PG8_STAGE(PG8_SB(0, 1), cB + hstepB, voffB); PG8_STAGE(PG8_SA(0, 0), cA, voffA); PG8_STAGE(PG8_SA(0, 1), cA + hstepA, voffA);
;     if (wr == 1) PG8_BAR;
;     PG8_WAIT_V(2); PG8_BAR;
;     PG8_STAGE(PG8_SB(1, 0), cB + kstep, voffB); PG8_STAGE(PG8_SA(1, 0), cA + kstep, voffA); PG8_STAGE(PG8_SB(1, 1), cB + hstepB + kstep, voffB);
;     PG8_WAIT_V(6); PG8_BAR;
;     if constexpr (PF > 0) { const char* p0 = PG8_PFPTR(cA, cB) + (size_t)(2 + PF) * kstep; PG8_TOUCH(p0); }
;     for (;;) {
;         const bool has_next = S.next(ui + 1, nxt);
;         const char* nA = has_next ? PG8_APTR(nxt) : cA; const char* nB = has_next ? PG8_BPTR(nxt) : cB;
;         const char* pfc = PG8_PFPTR(cA, cB); const char* pfn = PG8_PFPTR(nA, nB);
.LBB0_1096:
	s_mov_b64 s[16:17], 0x80
	s_lshl_b32 s0, s0, 12
	s_add_i32 m0, s33, 0x18000
	v_lshl_add_u64 v[8:9], v[8:9], 0, s[16:17]
	s_lshl_b32 s5, s1, 13
	s_and_b32 s14, s0, 0x3000
	s_waitcnt vmcnt(2)
	s_barrier
	global_load_lds_dwordx4 v[8:9], off
	v_lshl_add_u64 v[6:7], v[6:7], 0, s[16:17]
	s_add_i32 m0, s33, 0x1a000
	s_add_i32 s61, s33, 0x8000
	s_add_i32 s62, s33, 0xa000
	global_load_lds_dwordx4 v[6:7], off
	v_lshl_add_u64 v[2:3], v[2:3], 0, s[16:17]
	s_mov_b32 m0, s61
	s_add_u32 s0, s52, 0x100080
	global_load_lds_dwordx4 v[2:3], off
	v_lshl_add_u64 v[2:3], v[4:5], 0, s[16:17]
	s_mov_b32 m0, s62
	s_addc_u32 s1, s53, 0
	global_load_lds_dwordx4 v[2:3], off
	s_add_i32 m0, s33, 0x1c000
	v_lshl_add_u64 v[2:3], s[0:1], 0, v[130:131]
	global_load_lds_dwordx4 v[2:3], off
	v_lshl_add_u64 v[2:3], s[0:1], 0, v[132:133]
	s_add_i32 m0, s33, 0x1e000
	v_and_b32_e32 v0, 15, v1
	global_load_lds_dwordx4 v[2:3], off
	v_and_b32_e32 v2, 48, v1
	v_lshlrev_b32_e32 v1, 2, v1
	v_lshlrev_b32_e32 v0, 6, v0
	v_and_b32_e32 v1, 32, v1
	v_or_b32_e32 v3, v0, v2
	v_bitop3_b32 v0, v0, v1, v2 bitop3:0x36
	v_bitop3_b32 v2, v3, s5, v1 bitop3:0xde
	v_or_b32_e32 v1, s14, v0
	v_lshlrev_b32_e32 v0, 16, v10
	v_and_b32_e32 v0, 0xfffe0000, v0
	v_lshl_add_u32 v0, v11, 13, v0
	v_and_b32_e32 v3, 1, v10
	v_lshl_or_b32 v0, v3, 6, v0
	v_lshl_add_u32 v136, v12, 1, v0
	v_lshlrev_b32_e32 v0, 16, v13
	v_and_b32_e32 v0, 0xfffe0000, v0
	s_waitcnt vmcnt(6)
	s_cmpk_lt_u32 s4, 0x100
	v_lshl_add_u32 v0, v14, 13, v0
	v_and_b32_e32 v3, 1, v13
	s_cselect_b64 s[18:19], -1, 0
	v_lshl_or_b32 v0, v3, 6, v0
	s_add_i32 s64, 0, 0x10000
	s_add_i32 s65, 0, 0x14000
	s_ashr_i32 s63, s3, 31
	v_mov_b32_e32 v137, v135
	v_lshl_add_u32 v138, v15, 1, v0
	v_mov_b32_e32 v139, v135
	s_mov_b64 s[20:21], 0x100
	v_mov_b64_e32 v[140:141], 0x100
	v_mov_b64_e32 v[142:143], 0xff
	v_add_u32_e32 v148, s64, v1
	v_add_u32_e32 v149, s65, v1
	v_add_u32_e32 v150, 0, v2
	s_mov_b64 s[22:23], 0x180
	v_mov_b32_e32 v151, 0x358637bd
	s_mov_b32 s66, 0x800000
	s_mov_b64 s[24:25], 0x40000
	s_mov_b32 s67, 0x40000
	s_mov_b64 s[28:29], 0x48000
	s_mov_b32 s68, 0x48000
	s_mov_b64 s[30:31], 0x50000
	s_mov_b32 s69, 0x50000
	s_mov_b64 s[38:39], 0x58000
	s_mov_b32 s70, 0x58000
	s_barrier
	s_branch .LBB0_1099
	.p2align	6

.LBB0_1109:
	ds_read_b128 v[2:5], v148
	ds_read_b128 v[6:9], v148 offset:1024
	ds_read_b128 v[10:13], v148 offset:2048
	ds_read_b128 v[14:17], v148 offset:3072
	ds_read_b128 v[18:21], v149
	ds_read_b128 v[22:25], v149 offset:1024
	ds_read_b128 v[26:29], v149 offset:2048
	ds_read_b128 v[30:33], v149 offset:3072
	s_add_u32 s0, s54, 0x100080
	s_addc_u32 s1, s55, 0
	s_add_i32 s41, s33, 0xc000
	v_lshl_add_u64 v[66:67], s[0:1], 0, v[130:131]
	s_mov_b32 m0, s41
	s_add_i32 s73, s33, 0xe000
	ds_read_b128 v[34:37], v150
	ds_read_b128 v[38:41], v150 offset:1024
	ds_read_b128 v[42:45], v150 offset:2048
	ds_read_b128 v[46:49], v150 offset:3072
	ds_read_b128 v[50:53], v150 offset:4096
	ds_read_b128 v[54:57], v150 offset:5120
	ds_read_b128 v[58:61], v150 offset:6144
	ds_read_b128 v[62:65], v150 offset:7168
	global_load_lds_dwordx4 v[66:67], off
	v_lshl_add_u64 v[66:67], s[0:1], 0, v[132:133]
	s_mov_b32 m0, s73
	s_nop 0
	global_load_lds_dwordx4 v[66:67], off
	s_waitcnt vmcnt(8)
	s_waitcnt lgkmcnt(0)
	s_setprio 1
	s_barrier
	v_mfma_f32_16x16x32_bf16 v[86:89], v[10:13], v[50:53], 0
	v_mfma_f32_16x16x32_bf16 v[90:93], v[14:17], v[54:57], v[86:89]
	v_mfma_f32_16x16x32_bf16 v[86:89], v[2:5], v[58:61], 0
	v_mfma_f32_16x16x32_bf16 v[66:69], v[2:5], v[34:37], 0
	v_mfma_f32_16x16x32_bf16 v[70:73], v[10:13], v[34:37], 0
	v_mfma_f32_16x16x32_bf16 v[74:77], v[2:5], v[42:45], 0
	v_mfma_f32_16x16x32_bf16 v[78:81], v[10:13], v[42:45], 0
	v_mfma_f32_16x16x32_bf16 v[82:85], v[2:5], v[50:53], 0
	v_mfma_f32_16x16x32_bf16 v[94:97], v[6:9], v[62:65], v[86:89]
	v_mfma_f32_16x16x32_bf16 v[86:89], v[10:13], v[58:61], 0
	v_mfma_f32_16x16x32_bf16 v[66:69], v[6:9], v[38:41], v[66:69]
	v_mfma_f32_16x16x32_bf16 v[70:73], v[14:17], v[38:41], v[70:73]
	v_mfma_f32_16x16x32_bf16 v[74:77], v[6:9], v[46:49], v[74:77]
	v_mfma_f32_16x16x32_bf16 v[78:81], v[14:17], v[46:49], v[78:81]
	v_mfma_f32_16x16x32_bf16 v[82:85], v[6:9], v[54:57], v[82:85]
	v_mfma_f32_16x16x32_bf16 v[106:109], v[14:17], v[62:65], v[86:89]
	s_setprio 0
	s_setprio 1
	v_mfma_f32_16x16x32_bf16 v[86:89], v[18:21], v[34:37], 0
	v_mfma_f32_16x16x32_bf16 v[34:37], v[26:29], v[34:37], 0
	v_mfma_f32_16x16x32_bf16 v[110:113], v[22:25], v[38:41], v[86:89]
	v_mfma_f32_16x16x32_bf16 v[34:37], v[30:33], v[38:41], v[34:37]
	v_mfma_f32_16x16x32_bf16 v[38:41], v[18:21], v[42:45], 0
	v_mfma_f32_16x16x32_bf16 v[42:45], v[26:29], v[42:45], 0
	v_mfma_f32_16x16x32_bf16 v[38:41], v[22:25], v[46:49], v[38:41]
	v_mfma_f32_16x16x32_bf16 v[42:45], v[30:33], v[46:49], v[42:45]
	v_mfma_f32_16x16x32_bf16 v[46:49], v[18:21], v[50:53], 0
	v_mfma_f32_16x16x32_bf16 v[50:53], v[26:29], v[50:53], 0
	v_mfma_f32_16x16x32_bf16 v[46:49], v[22:25], v[54:57], v[46:49]
	v_mfma_f32_16x16x32_bf16 v[50:53], v[30:33], v[54:57], v[50:53]
	v_mfma_f32_16x16x32_bf16 v[54:57], v[18:21], v[58:61], 0
	v_mfma_f32_16x16x32_bf16 v[152:155], v[22:25], v[62:65], v[54:57]
	v_mfma_f32_16x16x32_bf16 v[54:57], v[26:29], v[58:61], 0
	v_mfma_f32_16x16x32_bf16 v[58:61], v[30:33], v[62:65], v[54:57]
	s_barrier
	s_setprio 0
	s_add_i32 s74, s64, s13
	v_lshl_add_u64 v[146:147], s[52:53], 0, v[130:131]
	s_add_i32 s75, s74, 0x2000
	v_lshl_add_u64 v[126:127], v[146:147], 0, s[20:21]
	s_mov_b32 m0, s74
	v_lshl_add_u64 v[248:249], s[52:53], 0, v[132:133]
	s_add_u32 s0, s52, 0x100100
	ds_read_b128 v[54:57], v150 offset:16384
	ds_read_b128 v[62:65], v150 offset:17408
	ds_read_b128 v[86:89], v150 offset:18432
	ds_read_b128 v[98:101], v150 offset:19456
	ds_read_b128 v[102:105], v150 offset:20480
	ds_read_b128 v[114:117], v150 offset:21504
	ds_read_b128 v[118:121], v150 offset:22528
	ds_read_b128 v[122:125], v150 offset:23552
	global_load_lds_dwordx4 v[126:127], off
	v_lshl_add_u64 v[126:127], v[248:249], 0, s[20:21]
	s_mov_b32 m0, s75
	s_addc_u32 s1, s53, 0
	s_add_i32 s76, s65, s13
	global_load_lds_dwordx4 v[126:127], off
	v_lshl_add_u64 v[126:127], s[0:1], 0, v[130:131]
	s_mov_b32 m0, s76
	s_add_i32 s46, s76, 0x2000
	global_load_lds_dwordx4 v[126:127], off
	v_lshl_add_u64 v[126:127], s[0:1], 0, v[132:133]
	s_mov_b32 m0, s46
	v_lshl_add_u64 v[250:251], s[54:55], 0, v[130:131]
	global_load_lds_dwordx4 v[126:127], off
	v_lshl_add_u64 v[126:127], v[250:251], 0, s[20:21]
	s_mov_b32 m0, s33
	v_lshl_add_u64 v[252:253], s[54:55], 0, v[132:133]
	global_load_lds_dwordx4 v[126:127], off
	v_lshl_add_u64 v[126:127], v[252:253], 0, s[20:21]
	s_mov_b32 m0, s51
	s_nop 0
	global_load_lds_dwordx4 v[126:127], off
	s_waitcnt vmcnt(8)
	s_waitcnt lgkmcnt(0)
	s_setprio 1
	s_barrier
	v_mfma_f32_16x16x32_bf16 v[126:129], v[2:5], v[54:57], 0
	v_mfma_f32_16x16x32_bf16 v[156:159], v[6:9], v[62:65], v[126:129]
	v_mfma_f32_16x16x32_bf16 v[126:129], v[10:13], v[54:57], 0
	v_mfma_f32_16x16x32_bf16 v[160:163], v[14:17], v[62:65], v[126:129]
	v_mfma_f32_16x16x32_bf16 v[126:129], v[2:5], v[86:89], 0
	v_mfma_f32_16x16x32_bf16 v[164:167], v[6:9], v[98:101], v[126:129]
	v_mfma_f32_16x16x32_bf16 v[126:129], v[10:13], v[86:89], 0
	v_mfma_f32_16x16x32_bf16 v[168:171], v[14:17], v[98:101], v[126:129]
	v_mfma_f32_16x16x32_bf16 v[126:129], v[2:5], v[102:105], 0
	v_mfma_f32_16x16x32_bf16 v[2:5], v[2:5], v[118:121], 0
	v_mfma_f32_16x16x32_bf16 v[172:175], v[6:9], v[114:117], v[126:129]
	v_mfma_f32_16x16x32_bf16 v[2:5], v[6:9], v[122:125], v[2:5]
	v_mfma_f32_16x16x32_bf16 v[6:9], v[10:13], v[118:121], 0
	v_mfma_f32_16x16x32_bf16 v[126:129], v[10:13], v[102:105], 0
	v_mfma_f32_16x16x32_bf16 v[10:13], v[14:17], v[122:125], v[6:9]
	v_mfma_f32_16x16x32_bf16 v[176:179], v[14:17], v[114:117], v[126:129]
	s_setprio 0
	s_setprio 1
	v_mfma_f32_16x16x32_bf16 v[6:9], v[18:21], v[54:57], 0
	v_mfma_f32_16x16x32_bf16 v[14:17], v[22:25], v[62:65], v[6:9]
	v_mfma_f32_16x16x32_bf16 v[6:9], v[26:29], v[54:57], 0
	v_mfma_f32_16x16x32_bf16 v[180:183], v[30:33], v[62:65], v[6:9]
	v_mfma_f32_16x16x32_bf16 v[6:9], v[18:21], v[86:89], 0
	v_mfma_f32_16x16x32_bf16 v[184:187], v[22:25], v[98:101], v[6:9]
	v_mfma_f32_16x16x32_bf16 v[6:9], v[26:29], v[86:89], 0
	v_mfma_f32_16x16x32_bf16 v[188:191], v[30:33], v[98:101], v[6:9]
	v_mfma_f32_16x16x32_bf16 v[6:9], v[18:21], v[102:105], 0
	v_mfma_f32_16x16x32_bf16 v[192:195], v[22:25], v[114:117], v[6:9]
	v_mfma_f32_16x16x32_bf16 v[6:9], v[26:29], v[102:105], 0
	v_mfma_f32_16x16x32_bf16 v[196:199], v[30:33], v[114:117], v[6:9]
	v_mfma_f32_16x16x32_bf16 v[6:9], v[18:21], v[118:121], 0
	v_mfma_f32_16x16x32_bf16 v[200:203], v[22:25], v[122:125], v[6:9]
	v_mfma_f32_16x16x32_bf16 v[6:9], v[26:29], v[118:121], 0
	v_mfma_f32_16x16x32_bf16 v[204:207], v[30:33], v[122:125], v[6:9]
	s_barrier
;     ...
;         for (int t = 2; t < nt; t += 2) PG8_KITER(t);
	s_setprio 0
	s_add_i32 s47, 0, 0x18000
	s_add_i32 s56, 0, 0x1c000
	v_add_u32_e32 v134, s47, v1
	v_add_u32_e32 v144, s56, v1
	s_nop 0
	ds_read_b128 v[6:9], v134
	ds_read_b128 v[18:21], v134 offset:1024
	ds_read_b128 v[30:33], v134 offset:2048
	ds_read_b128 v[208:211], v134 offset:3072
	ds_read_b128 v[212:215], v144
	ds_read_b128 v[216:219], v144 offset:1024
	ds_read_b128 v[220:223], v144 offset:2048
	ds_read_b128 v[224:227], v144 offset:3072
	s_add_u32 s0, s54, 0x100100
	s_addc_u32 s1, s55, 0
	s_mov_b32 m0, s58
	v_lshl_add_u64 v[54:55], s[0:1], 0, v[130:131]
	ds_read_b128 v[22:25], v150 offset:32768
	ds_read_b128 v[26:29], v150 offset:33792
	ds_read_b128 v[62:65], v150 offset:34816
	ds_read_b128 v[228:231], v150 offset:35840
	ds_read_b128 v[232:235], v150 offset:36864
	ds_read_b128 v[236:239], v150 offset:37888
	ds_read_b128 v[240:243], v150 offset:38912
	ds_read_b128 v[244:247], v150 offset:39936
	global_load_lds_dwordx4 v[54:55], off
	v_lshl_add_u64 v[54:55], s[0:1], 0, v[132:133]
	s_mov_b32 m0, s59
	s_nop 0
	global_load_lds_dwordx4 v[54:55], off
	s_waitcnt vmcnt(8)
	s_waitcnt lgkmcnt(0)
	s_setprio 1
	s_barrier
	v_mfma_f32_16x16x32_bf16 v[54:57], v[6:9], v[22:25], v[66:69]
	v_mfma_f32_16x16x32_bf16 v[118:121], v[18:21], v[26:29], v[54:57]
	v_mfma_f32_16x16x32_bf16 v[54:57], v[30:33], v[22:25], v[70:73]
	v_mfma_f32_16x16x32_bf16 v[114:117], v[208:211], v[26:29], v[54:57]
	v_mfma_f32_16x16x32_bf16 v[54:57], v[6:9], v[62:65], v[74:77]
	v_mfma_f32_16x16x32_bf16 v[102:105], v[18:21], v[228:231], v[54:57]
	v_mfma_f32_16x16x32_bf16 v[54:57], v[30:33], v[62:65], v[78:81]
	v_mfma_f32_16x16x32_bf16 v[98:101], v[208:211], v[228:231], v[54:57]
	v_mfma_f32_16x16x32_bf16 v[54:57], v[6:9], v[232:235], v[82:85]
	v_mfma_f32_16x16x32_bf16 v[86:89], v[18:21], v[236:239], v[54:57]
	v_mfma_f32_16x16x32_bf16 v[54:57], v[30:33], v[232:235], v[90:93]
	v_mfma_f32_16x16x32_bf16 v[82:85], v[208:211], v[236:239], v[54:57]
	v_mfma_f32_16x16x32_bf16 v[54:57], v[6:9], v[240:243], v[94:97]
	v_mfma_f32_16x16x32_bf16 v[74:77], v[18:21], v[244:247], v[54:57]
	v_mfma_f32_16x16x32_bf16 v[54:57], v[30:33], v[240:243], v[106:109]
	v_mfma_f32_16x16x32_bf16 v[54:57], v[208:211], v[244:247], v[54:57]
	s_setprio 0
	s_setprio 1
	v_mfma_f32_16x16x32_bf16 v[66:69], v[212:215], v[22:25], v[110:113]
	v_mfma_f32_16x16x32_bf16 v[22:25], v[220:223], v[22:25], v[34:37]
	v_mfma_f32_16x16x32_bf16 v[122:125], v[224:227], v[26:29], v[22:25]
	v_mfma_f32_16x16x32_bf16 v[22:25], v[212:215], v[62:65], v[38:41]
	v_mfma_f32_16x16x32_bf16 v[110:113], v[216:219], v[228:231], v[22:25]
	v_mfma_f32_16x16x32_bf16 v[22:25], v[220:223], v[62:65], v[42:45]
	v_mfma_f32_16x16x32_bf16 v[106:109], v[224:227], v[228:231], v[22:25]
	v_mfma_f32_16x16x32_bf16 v[22:25], v[212:215], v[232:235], v[46:49]
	v_mfma_f32_16x16x32_bf16 v[94:97], v[216:219], v[236:239], v[22:25]
	v_mfma_f32_16x16x32_bf16 v[22:25], v[220:223], v[232:235], v[50:53]
	v_mfma_f32_16x16x32_bf16 v[90:93], v[224:227], v[236:239], v[22:25]
	v_mfma_f32_16x16x32_bf16 v[22:25], v[212:215], v[240:243], v[152:155]
	v_mfma_f32_16x16x32_bf16 v[70:73], v[216:219], v[244:247], v[22:25]
	v_mfma_f32_16x16x32_bf16 v[22:25], v[220:223], v[240:243], v[58:61]
	v_mfma_f32_16x16x32_bf16 v[126:129], v[216:219], v[26:29], v[66:69]
	v_mfma_f32_16x16x32_bf16 v[50:53], v[224:227], v[244:247], v[22:25]
	s_barrier
	s_setprio 0
	s_add_i32 s47, s47, s13
	s_add_i32 s77, s47, 0x2000
	s_nop 1
	v_lshl_add_u64 v[22:23], v[146:147], 0, s[22:23]
	s_mov_b32 m0, s47
	s_add_u32 s0, s52, 0x100180
	ds_read_b128 v[34:37], v150 offset:49152
	ds_read_b128 v[46:49], v150 offset:50176
	ds_read_b128 v[152:155], v150 offset:51200
	ds_read_b128 v[228:231], v150 offset:52224
	ds_read_b128 v[232:235], v150 offset:53248
	ds_read_b128 v[236:239], v150 offset:54272
	ds_read_b128 v[240:243], v150 offset:55296
	ds_read_b128 v[244:247], v150 offset:56320
	global_load_lds_dwordx4 v[22:23], off
	v_lshl_add_u64 v[22:23], v[248:249], 0, s[22:23]
	s_mov_b32 m0, s77
	s_addc_u32 s1, s53, 0
	s_add_i32 s56, s56, s13
	global_load_lds_dwordx4 v[22:23], off
	v_lshl_add_u64 v[22:23], s[0:1], 0, v[130:131]
	s_mov_b32 m0, s56
	s_add_i32 s57, s56, 0x2000
	global_load_lds_dwordx4 v[22:23], off
	v_lshl_add_u64 v[22:23], s[0:1], 0, v[132:133]
	s_mov_b32 m0, s57
	s_nop 0
	global_load_lds_dwordx4 v[22:23], off
	v_lshl_add_u64 v[22:23], v[250:251], 0, s[22:23]
	s_mov_b32 m0, s61
	s_nop 0
	global_load_lds_dwordx4 v[22:23], off
	v_lshl_add_u64 v[22:23], v[252:253], 0, s[22:23]
	s_mov_b32 m0, s62
	s_nop 0
	global_load_lds_dwordx4 v[22:23], off
	s_waitcnt vmcnt(8)
	s_waitcnt lgkmcnt(0)
	s_setprio 1
	s_barrier
	v_mfma_f32_16x16x32_bf16 v[22:25], v[6:9], v[34:37], v[156:159]
	v_mfma_f32_16x16x32_bf16 v[66:69], v[18:21], v[46:49], v[22:25]
	v_mfma_f32_16x16x32_bf16 v[22:25], v[30:33], v[34:37], v[160:163]
	v_mfma_f32_16x16x32_bf16 v[62:65], v[208:211], v[46:49], v[22:25]
	v_mfma_f32_16x16x32_bf16 v[22:25], v[6:9], v[152:155], v[164:167]
	v_mfma_f32_16x16x32_bf16 v[42:45], v[18:21], v[228:231], v[22:25]
	v_mfma_f32_16x16x32_bf16 v[22:25], v[30:33], v[152:155], v[168:171]
	v_mfma_f32_16x16x32_bf16 v[38:41], v[208:211], v[228:231], v[22:25]
	v_mfma_f32_16x16x32_bf16 v[22:25], v[6:9], v[232:235], v[172:175]
	v_mfma_f32_16x16x32_bf16 v[2:5], v[6:9], v[240:243], v[2:5]
	v_mfma_f32_16x16x32_bf16 v[26:29], v[18:21], v[236:239], v[22:25]
	v_mfma_f32_16x16x32_bf16 v[22:25], v[30:33], v[232:235], v[176:179]
	v_mfma_f32_16x16x32_bf16 v[6:9], v[18:21], v[244:247], v[2:5]
	v_mfma_f32_16x16x32_bf16 v[2:5], v[30:33], v[240:243], v[10:13]
	v_mfma_f32_16x16x32_bf16 v[22:25], v[208:211], v[236:239], v[22:25]
	v_mfma_f32_16x16x32_bf16 v[2:5], v[208:211], v[244:247], v[2:5]
	s_setprio 0
	s_setprio 1
	v_mfma_f32_16x16x32_bf16 v[10:13], v[212:215], v[34:37], v[14:17]
	v_mfma_f32_16x16x32_bf16 v[78:81], v[216:219], v[46:49], v[10:13]
	v_mfma_f32_16x16x32_bf16 v[10:13], v[220:223], v[34:37], v[180:183]
	v_mfma_f32_16x16x32_bf16 v[58:61], v[224:227], v[46:49], v[10:13]
	v_mfma_f32_16x16x32_bf16 v[10:13], v[212:215], v[152:155], v[184:187]
	v_mfma_f32_16x16x32_bf16 v[46:49], v[216:219], v[228:231], v[10:13]
	v_mfma_f32_16x16x32_bf16 v[10:13], v[220:223], v[152:155], v[188:191]
	v_mfma_f32_16x16x32_bf16 v[34:37], v[224:227], v[228:231], v[10:13]
	v_mfma_f32_16x16x32_bf16 v[10:13], v[212:215], v[232:235], v[192:195]
	v_mfma_f32_16x16x32_bf16 v[30:33], v[216:219], v[236:239], v[10:13]
	v_mfma_f32_16x16x32_bf16 v[10:13], v[220:223], v[232:235], v[196:199]
	v_mfma_f32_16x16x32_bf16 v[18:21], v[224:227], v[236:239], v[10:13]
	v_mfma_f32_16x16x32_bf16 v[10:13], v[212:215], v[240:243], v[200:203]
	v_mfma_f32_16x16x32_bf16 v[14:17], v[216:219], v[244:247], v[10:13]
	v_mfma_f32_16x16x32_bf16 v[10:13], v[220:223], v[240:243], v[204:207]
	v_mfma_f32_16x16x32_bf16 v[10:13], v[224:227], v[244:247], v[10:13]
	s_barrier
	s_setprio 0
	s_add_u32 s0, s54, 0x100180
	s_addc_u32 s1, s55, 0
	s_add_u32 s14, s52, 0x200
	s_addc_u32 s15, s53, 0
	s_mov_b32 s26, 0
	.p2align	6

; #define PHASE_IDS() int tid_ = threadIdx.x; asm volatile("" : "+v"(tid_)); const int lane = tid_ & 63, wave_ = __builtin_amdgcn_readfirstlane(tid_ >> 6); \
;     const int G_ = gridDim.x, vcu_ = (G_ % 8 == 0) ? ((int)blockIdx.x % 8) * (G_ / 8) + (int)blockIdx.x / 8 : (int)blockIdx.x, gw = vcu_ * NWAVES + wave_, NGW = G_ * NWAVES; (void)gw; (void)NGW; (void)lane; (void)vcu_; (void)wave_
; __global__ void __launch_bounds__(NWAVES * 64, 2) mk_fwd(Params P) {
;     ...
;         PHASE_IDS();
;         const int r32 = lane & 31, hi5 = lane >> 5; const float* gxq = P.in[I_XQN];
;         for (int item = vcu_; item < 256; item += (int)gridDim.x) {
;             const int bh = item >> 5, qb = item & 31, b = bh >> 2, h = bh & 3;
;             const size_t row0 = (size_t)b * SEQ + (size_t)qb * 256;
;             bf16x8 qr[8];
;             { const float* q0 = XQP + (row0 + wave_ * 32 + r32) * 512 + h * 128 + hi5 * 8; const float* q1 = q0 + (size_t)M * 512;
.LBB0_1172:
	s_ashr_i32 s0, s0, 1
	s_andn2_b32 s0, s0, 31
	s_ashr_i32 s1, s0, 31
	v_readlane_b32 s12, v255, 0
	s_add_u32 s11, s34, 0x24300000
	v_readlane_b32 s13, v255, 1
	s_addc_u32 s12, s35, 0
	v_lshrrev_b32_e32 v0, 2, v1
	s_add_u32 s13, s34, 0x24380000
	v_and_b32_e32 v4, 8, v0
	s_addc_u32 s33, s35, 0
	v_mov_b32_e32 v3, 0
	v_lshlrev_b32_e32 v2, 2, v4
	v_readlane_b32 s14, v255, 2
	v_readlane_b32 s15, v255, 3
	v_readlane_b32 s16, v255, 4
	v_readlane_b32 s17, v255, 5
	v_readlane_b32 s18, v255, 6
	v_readlane_b32 s19, v255, 7
	v_readlane_b32 s20, v255, 8
	v_readlane_b32 s21, v255, 9
	v_readlane_b32 s22, v255, 10
	v_readlane_b32 s23, v255, 11
	v_readlane_b32 s24, v255, 12
	v_readlane_b32 s25, v255, 13
	s_add_u32 s52, s34, 0x28400000
	v_and_or_b32 v148, v1, 31, s0
	v_mov_b32_e32 v149, s1
	v_lshl_add_u64 v[150:151], s[14:15], 0, v[2:3]
	s_addc_u32 s53, s35, 0
	s_mov_b32 s1, 0
	v_lshlrev_b32_e32 v152, 2, v4
	v_mov_b32_e32 v153, v3
	s_mov_b64 s[14:15], 0x2000000
	s_brev_b32 s54, 64
	s_mov_b64 s[16:17], 0x2000040
	s_mov_b64 s[18:19], 0x2000080
	s_mov_b64 s[20:21], 0x20000c0
	s_mov_b64 s[22:23], 0x2000100
	s_mov_b64 s[24:25], 0x2000140
	s_mov_b64 s[28:29], 0x2000180
	s_mov_b64 s[30:31], 0x20001c0
	v_mov_b32_e32 v1, 0x358637bd
	s_mov_b32 s55, 0x800000
	s_add_i32 s58, 0, 0x10800
	s_movk_i32 s59, 0x110
	s_mov_b64 s[38:39], 0x20000
	s_mov_b64 s[40:41], 0x28000
	s_mov_b32 s60, 0x41380000
	s_movk_i32 s61, 0x2000
	s_movk_i32 s62, 0x4000
	s_movk_i32 s63, 0x6000
	v_readlane_b32 s26, v255, 14
	v_readlane_b32 s27, v255, 15
	s_branch .LBB0_1174
	.p2align	6

; __global__ void __launch_bounds__(NWAVES * 64, 2) mk_fwd(Params P) {
;     ...
;         for (int item = vcu_; item < 256; item += (int)gridDim.x) {
;             const int bh = item >> 5, qb = item & 31, b = bh >> 2, h = bh & 3;
;             const size_t row0 = (size_t)b * SEQ + (size_t)qb * 256;
;             bf16x8 qr[8];
;             { const float* q0 = XQP + (row0 + wave_ * 32 + r32) * 512 + h * 128 + hi5 * 8; const float* q1 = q0 + (size_t)M * 512;
;               f32x4 qa[8], qbv[8]; float s = 0.f;
; #pragma unroll
;               for (int d0 = 0; d0 < 8; ++d0) { qa[d0] = *(const f32x4*)(q0 + d0 * 16) + *(const f32x4*)(q1 + d0 * 16); qbv[d0] = *(const f32x4*)(q0 + d0 * 16 + 4) + *(const f32x4*)(q1 + d0 * 16 + 4);
;                   s += (qa[d0].x * qa[d0].x + qa[d0].y * qa[d0].y) + (qa[d0].z * qa[d0].z + qa[d0].w * qa[d0].w) + (qbv[d0].x * qbv[d0].x + qbv[d0].y * qbv[d0].y) + (qbv[d0].z * qbv[d0].z + qbv[d0].w * qbv[d0].w); }
.LBB0_1174:
	s_ashr_i32 s4, s10, 7
	s_ashr_i32 s5, s4, 31
	s_lshl_b32 s0, s10, 8
	s_lshl_b64 s[42:43], s[4:5], 13
	s_and_b32 s0, s0, 0x1f00
	s_or_b32 s42, s42, s0
	v_lshl_add_u64 v[4:5], s[42:43], 0, v[148:149]
	s_lshl_b32 s0, s10, 2
	v_lshlrev_b64 v[4:5], 11, v[4:5]
	s_and_b32 s64, s0, 0x180
	v_lshl_add_u64 v[4:5], s[44:45], 0, v[4:5]
	s_lshl_b32 s0, s64, 2
	v_lshl_add_u64 v[4:5], v[4:5], 0, s[0:1]
	v_lshl_add_u64 v[36:37], v[4:5], 0, v[152:153]
	v_add_co_u32_e32 v38, vcc, s54, v36
	v_lshl_add_u64 v[16:17], v[36:37], 0, s[14:15]
	s_nop 0
	v_addc_co_u32_e32 v39, vcc, 0, v37, vcc
	global_load_dwordx4 v[4:7], v[36:37], off offset:16
	global_load_dwordx4 v[8:11], v[36:37], off
	global_load_dwordx4 v[12:15], v[38:39], off
	s_nop 0
	global_load_dwordx4 v[16:19], v[16:17], off offset:16
	s_nop 0
	global_load_dwordx4 v[20:23], v[36:37], off offset:80
	global_load_dwordx4 v[24:27], v[36:37], off offset:64
	v_lshl_add_u64 v[32:33], v[36:37], 0, s[16:17]
	global_load_dwordx4 v[28:31], v[38:39], off offset:64
	s_nop 0
	global_load_dwordx4 v[32:35], v[32:33], off offset:16
	s_nop 0
	global_load_dwordx4 v[40:43], v[36:37], off offset:144
	global_load_dwordx4 v[44:47], v[36:37], off offset:128
	global_load_dwordx4 v[48:51], v[38:39], off offset:128
	v_lshl_add_u64 v[52:53], v[36:37], 0, s[18:19]
	v_lshl_add_u64 v[68:69], v[36:37], 0, s[20:21]
	global_load_dwordx4 v[52:55], v[52:53], off offset:16
	s_nop 0
	global_load_dwordx4 v[56:59], v[36:37], off offset:208
	global_load_dwordx4 v[60:63], v[36:37], off offset:192
	global_load_dwordx4 v[64:67], v[38:39], off offset:192
	s_nop 0
	global_load_dwordx4 v[68:71], v[68:69], off offset:16
	s_nop 0
	global_load_dwordx4 v[72:75], v[36:37], off offset:272
	global_load_dwordx4 v[76:79], v[36:37], off offset:256
	global_load_dwordx4 v[80:83], v[38:39], off offset:256
	v_lshl_add_u64 v[84:85], v[36:37], 0, s[22:23]
	global_load_dwordx4 v[84:87], v[84:85], off offset:16
	s_nop 0
	global_load_dwordx4 v[88:91], v[36:37], off offset:336
	global_load_dwordx4 v[92:95], v[36:37], off offset:320
	v_lshl_add_u64 v[112:113], v[36:37], 0, s[24:25]
	v_lshl_add_u64 v[128:129], v[36:37], 0, s[28:29]
	global_load_dwordx4 v[96:99], v[36:37], off offset:400
	global_load_dwordx4 v[100:103], v[36:37], off offset:384
	global_load_dwordx4 v[104:107], v[36:37], off offset:464
	global_load_dwordx4 v[108:111], v[36:37], off offset:448
	v_lshl_add_u64 v[36:37], v[36:37], 0, s[30:31]
	global_load_dwordx4 v[112:115], v[112:113], off offset:16
	s_nop 0
	global_load_dwordx4 v[116:119], v[38:39], off offset:320
	global_load_dwordx4 v[120:123], v[38:39], off offset:384
	global_load_dwordx4 v[124:127], v[38:39], off offset:448
	s_nop 0
	global_load_dwordx4 v[128:131], v[128:129], off offset:16
	s_nop 0
	global_load_dwordx4 v[132:135], v[36:37], off offset:16
	s_lshl_b64 s[4:5], s[4:5], 18
	s_add_u32 s0, s11, s4
	s_addc_u32 s7, s12, s5
	s_lshl_b32 s8, s64, 1
	s_add_u32 s6, s0, s8
	s_addc_u32 s7, s7, 0
	v_mov_b32_e32 v166, v254
	s_add_u32 s0, s13, s4
	s_addc_u32 s4, s33, s5
	s_add_u32 s26, s0, s8
	s_addc_u32 s27, s4, 0
	v_mov_b32_e32 v182, 0xf149f2ca
	s_mov_b64 s[8:9], -1
	s_mov_b32 s0, 0
	v_mov_b32_e32 v178, 0
	s_waitcnt vmcnt(28)
	v_pk_add_f32 v[140:141], v[6:7], v[18:19]
	v_pk_add_f32 v[136:137], v[10:11], v[14:15]
	v_pk_add_f32 v[138:139], v[8:9], v[12:13]
	s_waitcnt vmcnt(25)
	v_pk_add_f32 v[144:145], v[26:27], v[30:31]
	v_pk_add_f32 v[146:147], v[24:25], v[28:29]
	v_pk_add_f32 v[142:143], v[4:5], v[16:17]
	s_waitcnt vmcnt(24)
	v_pk_add_f32 v[38:39], v[20:21], v[32:33]
	v_mov_b32_e32 v6, v139
	v_mov_b32_e32 v7, v147
	v_mov_b32_e32 v10, v137
	v_mov_b32_e32 v11, v145
	v_pk_add_f32 v[36:37], v[22:23], v[34:35]
	v_mov_b32_e32 v4, v138
	v_mov_b32_e32 v5, v146
	v_mov_b32_e32 v8, v136
	v_mov_b32_e32 v9, v144
	v_mov_b32_e32 v14, v143
	v_mov_b32_e32 v15, v39
	v_pk_mul_f32 v[6:7], v[6:7], v[6:7]
	v_pk_mul_f32 v[10:11], v[10:11], v[10:11]
	v_mov_b32_e32 v12, v142
	v_mov_b32_e32 v13, v38
	v_mov_b32_e32 v18, v141
	v_mov_b32_e32 v19, v37
	v_pk_mul_f32 v[14:15], v[14:15], v[14:15]
	v_pk_fma_f32 v[4:5], v[4:5], v[4:5], v[6:7]
	v_pk_fma_f32 v[6:7], v[8:9], v[8:9], v[10:11]
	v_mov_b32_e32 v16, v140
	v_mov_b32_e32 v17, v36
	v_pk_mul_f32 v[18:19], v[18:19], v[18:19]
	v_pk_fma_f32 v[8:9], v[12:13], v[12:13], v[14:15]
	v_pk_add_f32 v[4:5], v[4:5], v[6:7]
	s_waitcnt vmcnt(21)
	v_pk_add_f32 v[24:25], v[46:47], v[50:51]
	v_pk_add_f32 v[26:27], v[44:45], v[48:49]
	v_pk_fma_f32 v[10:11], v[16:17], v[16:17], v[18:19]
	v_pk_add_f32 v[4:5], v[8:9], v[4:5]
	v_pk_mul_f32 v[8:9], v[26:27], v[26:27]
	v_pk_add_f32 v[6:7], v[10:11], v[4:5]
	v_pk_mul_f32 v[4:5], v[24:25], v[24:25]
	s_waitcnt vmcnt(20)
	v_pk_add_f32 v[20:21], v[42:43], v[54:55]
	v_pk_add_f32 v[22:23], v[40:41], v[52:53]
	v_pk_mov_b32 v[10:11], v[8:9], v[4:5] op_sel:[1,0]
	v_mov_b32_e32 v9, v5
	v_pk_add_f32 v[4:5], v[10:11], v[8:9]
	v_pk_mul_f32 v[8:9], v[20:21], v[20:21]
	v_pk_mul_f32 v[10:11], v[22:23], v[22:23]
	v_mov_b32_e32 v12, v8
	v_mov_b32_e32 v13, v10
	v_mov_b32_e32 v10, v9
	s_waitcnt vmcnt(16)
	v_pk_add_f32 v[30:31], v[56:57], v[68:69]
	s_waitcnt vmcnt(13)
	v_pk_add_f32 v[18:19], v[76:77], v[80:81]
	v_pk_add_f32 v[8:9], v[12:13], v[10:11]
	v_pk_add_f32 v[34:35], v[60:61], v[64:65]
	v_mov_b32_e32 v12, v31
	v_mov_b32_e32 v13, v19
	v_pk_add_f32 v[32:33], v[62:63], v[66:67]
	v_mov_b32_e32 v10, v30
	v_mov_b32_e32 v11, v18
	v_pk_mul_f32 v[12:13], v[12:13], v[12:13]
	v_mul_f32_e32 v0, v35, v35
	v_pk_add_f32 v[16:17], v[78:79], v[82:83]
	v_pk_fma_f32 v[10:11], v[10:11], v[10:11], v[12:13]
	v_pk_fma_f32 v[12:13], v[34:35], v[34:35], v[0:1] op_sel_hi:[1,1,0]
	v_mul_f32_e32 v0, v33, v33
	v_mul_f32_e32 v2, v16, v16
	v_mul_f32_e32 v42, v17, v17
	v_pk_fma_f32 v[40:41], v[32:33], v[32:33], v[0:1] op_sel_hi:[1,1,0]
	v_pk_add_f32 v[28:29], v[58:59], v[70:71]
	s_waitcnt vmcnt(12)
; __device__ __forceinline__ unsigned cvt_pk_bf16(float lo, float hi) { unsigned r; asm volatile("v_cvt_pk_bf16_f32 %0, %1, %2" : "=v"(r) : "v"(lo), "v"(hi)); return r; }
; __device__ __forceinline__ float xsum32(float s) { auto r = __builtin_amdgcn_permlane32_swap(__float_as_uint(s), __float_as_uint(s), false, false); return __uint_as_float(r[0]) + __uint_as_float(r[1]); }
; __global__ void __launch_bounds__(NWAVES * 64, 2) mk_fwd(Params P) {
;     ...
;                   s += (qa[d0].x * qa[d0].x + qa[d0].y * qa[d0].y) + (qa[d0].z * qa[d0].z + qa[d0].w * qa[d0].w) + (qbv[d0].x * qbv[d0].x + qbv[d0].y * qbv[d0].y) + (qbv[d0].z * qbv[d0].z + qbv[d0].w * qbv[d0].w); }
;               s = xsum32(s);
;               const float rstd = rsqrtf(s * (1.f / 128.f) + EPS) * XSCALE;
; #pragma unroll
;               for (int d0 = 0; d0 < 8; ++d0) { const float* gp = gxq + d0 * 16 + hi5 * 8; const f32x4 g0 = *(const f32x4*)gp, g1 = *(const f32x4*)(gp + 4);
;                   const f32x4 a = qa[d0] * rstd * g0, c = qbv[d0] * rstd * g1; u32x4 w; w.x = cvt_pk_bf16(a.x, a.y); w.y = cvt_pk_bf16(a.z, a.w); w.z = cvt_pk_bf16(c.x, c.y); w.w = cvt_pk_bf16(c.z, c.w);
;                   qr[d0] = __builtin_bit_cast(bf16x8, w); } }
	v_pk_add_f32 v[14:15], v[72:73], v[84:85]
	v_mov_b32_e32 v13, v2
	v_mov_b32_e32 v41, v42
	v_pk_add_f32 v[12:13], v[12:13], v[40:41]
	v_mov_b32_e32 v40, v29
	v_mov_b32_e32 v41, v15
	v_pk_mul_f32 v[48:49], v[40:41], v[40:41]
	global_load_dwordx4 v[40:43], v[150:151], off offset:16
	global_load_dwordx4 v[44:47], v[150:151], off
	v_pk_add_f32 v[4:5], v[4:5], v[4:5] op_sel:[0,1] op_sel_hi:[1,0]
	v_pk_add_f32 v[10:11], v[10:11], v[12:13]
	v_pk_add_f32 v[4:5], v[8:9], v[4:5] op_sel:[1,0] op_sel_hi:[0,1]
	v_pk_add_f32 v[8:9], v[8:9], v[4:5]
	v_pk_add_f32 v[4:5], v[74:75], v[86:87]
	v_mov_b32_e32 v12, v28
	v_mul_f32_e32 v50, v4, v4
	v_mov_b32_e32 v13, v14
	v_pk_add_f32 v[6:7], v[6:7], v[6:7] op_sel:[0,1] op_sel_hi:[1,0]
	v_mul_f32_e32 v9, v5, v5
	v_pk_fma_f32 v[12:13], v[12:13], v[12:13], v[48:49]
	v_mov_b32_e32 v7, v50
	v_pk_add_f32 v[10:11], v[12:13], v[10:11]
	v_pk_add_f32 v[6:7], v[6:7], v[8:9]
	s_waitcnt vmcnt(6)
	v_pk_add_f32 v[50:51], v[94:95], v[118:119]
	v_pk_add_f32 v[52:53], v[92:93], v[116:117]
	v_pk_add_f32 v[48:49], v[6:7], v[10:11]
	v_pk_mul_f32 v[6:7], v[50:51], v[50:51]
	v_pk_mul_f32 v[8:9], v[52:53], v[52:53]
	v_pk_add_f32 v[54:55], v[90:91], v[114:115]
	v_pk_add_f32 v[56:57], v[88:89], v[112:113]
	v_pk_mov_b32 v[10:11], v[8:9], v[6:7] op_sel:[1,0]
	v_mov_b32_e32 v9, v7
	v_pk_add_f32 v[6:7], v[10:11], v[8:9]
	v_pk_mul_f32 v[8:9], v[54:55], v[54:55]
	v_pk_mul_f32 v[10:11], v[56:57], v[56:57]
	v_mov_b32_e32 v12, v8
	v_mov_b32_e32 v13, v10
	v_mov_b32_e32 v10, v9
	v_pk_add_f32 v[8:9], v[12:13], v[10:11]
	s_waitcnt vmcnt(3)
	v_pk_add_f32 v[66:67], v[96:97], v[128:129]
	v_pk_add_f32 v[10:11], v[108:109], v[124:125]
	v_pk_add_f32 v[6:7], v[6:7], v[6:7] op_sel:[0,1] op_sel_hi:[1,0]
	v_pk_add_f32 v[62:63], v[100:101], v[120:121]
	v_mov_b32_e32 v70, v67
	v_mov_b32_e32 v71, v11
	v_pk_add_f32 v[6:7], v[8:9], v[6:7] op_sel:[1,0] op_sel_hi:[0,1]
	v_pk_add_f32 v[60:61], v[102:103], v[122:123]
	v_mov_b32_e32 v68, v66
	v_mov_b32_e32 v69, v10
	v_pk_mul_f32 v[70:71], v[70:71], v[70:71]
	v_mul_f32_e32 v0, v63, v63
	v_pk_add_f32 v[58:59], v[8:9], v[6:7]
	v_pk_add_f32 v[6:7], v[110:111], v[126:127]
	v_pk_fma_f32 v[68:69], v[68:69], v[68:69], v[70:71]
	v_pk_fma_f32 v[70:71], v[62:63], v[62:63], v[0:1] op_sel_hi:[1,1,0]
	v_mul_f32_e32 v0, v61, v61
	v_mul_f32_e32 v2, v6, v6
	v_mul_f32_e32 v74, v7, v7
	v_pk_fma_f32 v[72:73], v[60:61], v[60:61], v[0:1] op_sel_hi:[1,1,0]
	v_pk_add_f32 v[64:65], v[98:99], v[130:131]
	s_waitcnt vmcnt(2)
	v_pk_add_f32 v[12:13], v[104:105], v[132:133]
	v_mov_b32_e32 v71, v2
	v_mov_b32_e32 v73, v74
	v_pk_add_f32 v[8:9], v[106:107], v[134:135]
	v_pk_add_f32 v[70:71], v[70:71], v[72:73]
	v_mov_b32_e32 v72, v65
	v_mov_b32_e32 v73, v13
	v_mul_f32_e32 v75, v8, v8
	v_pk_add_f32 v[68:69], v[68:69], v[70:71]
	v_mov_b32_e32 v70, v64
	v_mov_b32_e32 v71, v12
	v_pk_mul_f32 v[72:73], v[72:73], v[72:73]
	v_pk_add_f32 v[48:49], v[48:49], v[48:49] op_sel:[0,1] op_sel_hi:[1,0]
	v_mul_f32_e32 v59, v9, v9
	v_pk_fma_f32 v[70:71], v[70:71], v[70:71], v[72:73]
	v_mov_b32_e32 v49, v75
	v_pk_add_f32 v[68:69], v[70:71], v[68:69]
	v_pk_add_f32 v[48:49], v[48:49], v[58:59]
	s_nop 0
	v_pk_add_f32 v[48:49], v[48:49], v[68:69]
	s_nop 0
	v_pk_add_f32 v[48:49], v[48:49], v[48:49] op_sel:[0,1] op_sel_hi:[1,0]
	s_nop 0
	v_mov_b32_e32 v0, v48
	s_nop 1
	v_permlane32_swap_b32_e32 v48, v0
	v_add_f32_e32 v0, v48, v0
	v_fmamk_f32 v0, v0, 0x3c000000, v1
	v_mul_f32_e32 v2, 0x4b800000, v0
	v_cmp_gt_f32_e32 vcc, s55, v0
	s_nop 1
	v_cndmask_b32_e32 v0, v0, v2, vcc
	v_rsq_f32_e32 v0, v0
	s_nop 0
	v_mul_f32_e32 v2, 0x45800000, v0
	v_cndmask_b32_e32 v0, v0, v2, vcc
	v_mul_f32_e32 v2, 0x3e0293ee, v0
	v_pk_mul_f32 v[48:49], v[2:3], v[138:139] op_sel_hi:[0,1]
	v_pk_mul_f32 v[58:59], v[2:3], v[136:137] op_sel_hi:[0,1]
	s_waitcnt vmcnt(0)
	v_pk_mul_f32 v[46:47], v[46:47], v[58:59]
	v_pk_mul_f32 v[44:45], v[44:45], v[48:49]
	v_pk_mul_f32 v[48:49], v[2:3], v[142:143] op_sel_hi:[0,1]
	v_pk_mul_f32 v[58:59], v[2:3], v[140:141] op_sel_hi:[0,1]
	v_pk_mul_f32 v[42:43], v[42:43], v[58:59]
	v_pk_mul_f32 v[40:41], v[40:41], v[48:49]
	v_cvt_pk_bf16_f32 v100, v44, v45
	v_cvt_pk_bf16_f32 v101, v46, v47
	v_pk_mul_f32 v[48:49], v[2:3], v[146:147] op_sel_hi:[0,1]
	v_cvt_pk_bf16_f32 v102, v40, v41
	v_cvt_pk_bf16_f32 v103, v42, v43
	global_load_dwordx4 v[40:43], v[150:151], off offset:64
	global_load_dwordx4 v[44:47], v[150:151], off offset:80
	v_pk_mul_f32 v[58:59], v[2:3], v[144:145] op_sel_hi:[0,1]
	v_pk_mul_f32 v[38:39], v[2:3], v[38:39] op_sel_hi:[0,1]
	v_pk_mul_f32 v[36:37], v[2:3], v[36:37] op_sel_hi:[0,1]
	v_pk_mul_f32 v[26:27], v[2:3], v[26:27] op_sel_hi:[0,1]
	v_pk_mul_f32 v[24:25], v[2:3], v[24:25] op_sel_hi:[0,1]
	v_pk_mul_f32 v[22:23], v[2:3], v[22:23] op_sel_hi:[0,1]
	v_pk_mul_f32 v[20:21], v[2:3], v[20:21] op_sel_hi:[0,1]
	v_pk_mul_f32 v[34:35], v[2:3], v[34:35] op_sel_hi:[0,1]
	v_pk_mul_f32 v[32:33], v[2:3], v[32:33] op_sel_hi:[0,1]
	v_pk_mul_f32 v[30:31], v[2:3], v[30:31] op_sel_hi:[0,1]
	v_pk_mul_f32 v[28:29], v[2:3], v[28:29] op_sel_hi:[0,1]
	v_pk_mul_f32 v[18:19], v[2:3], v[18:19] op_sel_hi:[0,1]
	v_pk_mul_f32 v[16:17], v[2:3], v[16:17] op_sel_hi:[0,1]
	v_pk_mul_f32 v[14:15], v[2:3], v[14:15] op_sel_hi:[0,1]
	v_pk_mul_f32 v[4:5], v[2:3], v[4:5] op_sel_hi:[0,1]
	v_pk_mul_f32 v[10:11], v[2:3], v[10:11] op_sel_hi:[0,1]
	v_pk_mul_f32 v[6:7], v[2:3], v[6:7] op_sel_hi:[0,1]
	v_pk_mul_f32 v[12:13], v[2:3], v[12:13] op_sel_hi:[0,1]
	v_pk_mul_f32 v[8:9], v[2:3], v[8:9] op_sel_hi:[0,1]
	s_waitcnt vmcnt(1)
	v_pk_mul_f32 v[42:43], v[42:43], v[58:59]
	v_pk_mul_f32 v[40:41], v[40:41], v[48:49]
	s_waitcnt vmcnt(0)
; __device__ __forceinline__ unsigned cvt_pk_bf16(float lo, float hi) { unsigned r; asm volatile("v_cvt_pk_bf16_f32 %0, %1, %2" : "=v"(r) : "v"(lo), "v"(hi)); return r; }
; __global__ void __launch_bounds__(NWAVES * 64, 2) mk_fwd(Params P) {
;     ...
; #pragma unroll
;               for (int d0 = 0; d0 < 8; ++d0) { const float* gp = gxq + d0 * 16 + hi5 * 8; const f32x4 g0 = *(const f32x4*)gp, g1 = *(const f32x4*)(gp + 4);
;                   const f32x4 a = qa[d0] * rstd * g0, c = qbv[d0] * rstd * g1; u32x4 w; w.x = cvt_pk_bf16(a.x, a.y); w.y = cvt_pk_bf16(a.z, a.w); w.z = cvt_pk_bf16(c.x, c.y); w.w = cvt_pk_bf16(c.z, c.w);
;                   qr[d0] = __builtin_bit_cast(bf16x8, w); } }
	v_pk_mul_f32 v[36:37], v[46:47], v[36:37]
	v_pk_mul_f32 v[38:39], v[44:45], v[38:39]
	v_cvt_pk_bf16_f32 v104, v40, v41
	v_cvt_pk_bf16_f32 v105, v42, v43
	s_nop 0
	v_cvt_pk_bf16_f32 v106, v38, v39
	v_cvt_pk_bf16_f32 v107, v36, v37
	global_load_dwordx4 v[36:39], v[150:151], off offset:128
	global_load_dwordx4 v[40:43], v[150:151], off offset:144
	s_waitcnt vmcnt(1)
	v_pk_mul_f32 v[24:25], v[38:39], v[24:25]
	v_pk_mul_f32 v[26:27], v[36:37], v[26:27]
	s_waitcnt vmcnt(0)
	v_pk_mul_f32 v[20:21], v[42:43], v[20:21]
	v_pk_mul_f32 v[22:23], v[40:41], v[22:23]
	v_cvt_pk_bf16_f32 v108, v26, v27
	v_cvt_pk_bf16_f32 v109, v24, v25
	s_nop 0
	v_cvt_pk_bf16_f32 v110, v22, v23
	v_cvt_pk_bf16_f32 v111, v20, v21
	global_load_dwordx4 v[20:23], v[150:151], off offset:192
	global_load_dwordx4 v[24:27], v[150:151], off offset:208
	s_waitcnt vmcnt(1)
	v_pk_mul_f32 v[22:23], v[22:23], v[32:33]
	v_pk_mul_f32 v[20:21], v[20:21], v[34:35]
	s_waitcnt vmcnt(0)
	v_pk_mul_f32 v[26:27], v[26:27], v[28:29]
	v_pk_mul_f32 v[24:25], v[24:25], v[30:31]
	v_cvt_pk_bf16_f32 v112, v20, v21
	v_cvt_pk_bf16_f32 v113, v22, v23
	s_nop 0
	v_cvt_pk_bf16_f32 v114, v24, v25
	v_cvt_pk_bf16_f32 v115, v26, v27
	global_load_dwordx4 v[20:23], v[150:151], off offset:256
	global_load_dwordx4 v[24:27], v[150:151], off offset:272
	s_waitcnt vmcnt(1)
	v_pk_mul_f32 v[16:17], v[22:23], v[16:17]
	v_pk_mul_f32 v[18:19], v[20:21], v[18:19]
	s_waitcnt vmcnt(0)
	v_pk_mul_f32 v[14:15], v[24:25], v[14:15]
	v_pk_mul_f32 v[4:5], v[26:27], v[4:5]
	v_cvt_pk_bf16_f32 v116, v18, v19
	v_cvt_pk_bf16_f32 v117, v16, v17
	v_cvt_pk_bf16_f32 v118, v14, v15
	v_pk_mul_f32 v[22:23], v[2:3], v[50:51] op_sel_hi:[0,1]
	v_cvt_pk_bf16_f32 v119, v4, v5
	global_load_dwordx4 v[14:17], v[150:151], off offset:320
	global_load_dwordx4 v[18:21], v[150:151], off offset:336
	v_pk_mul_f32 v[4:5], v[2:3], v[52:53] op_sel_hi:[0,1]
	v_pk_mul_f32 v[24:25], v[2:3], v[56:57] op_sel_hi:[0,1]
	v_pk_mul_f32 v[26:27], v[2:3], v[54:55] op_sel_hi:[0,1]
	s_waitcnt vmcnt(1)
	v_pk_mul_f32 v[16:17], v[16:17], v[22:23]
	v_pk_mul_f32 v[4:5], v[14:15], v[4:5]
	s_waitcnt vmcnt(0)
	v_pk_mul_f32 v[14:15], v[20:21], v[26:27]
	v_pk_mul_f32 v[18:19], v[18:19], v[24:25]
	v_cvt_pk_bf16_f32 v120, v4, v5
	v_cvt_pk_bf16_f32 v121, v16, v17
	v_pk_mul_f32 v[4:5], v[2:3], v[62:63] op_sel_hi:[0,1]
	v_cvt_pk_bf16_f32 v122, v18, v19
	v_cvt_pk_bf16_f32 v123, v14, v15
	global_load_dwordx4 v[14:17], v[150:151], off offset:384
	global_load_dwordx4 v[18:21], v[150:151], off offset:400
	v_pk_mul_f32 v[22:23], v[2:3], v[60:61] op_sel_hi:[0,1]
	v_pk_mul_f32 v[24:25], v[2:3], v[66:67] op_sel_hi:[0,1]
	v_pk_mul_f32 v[26:27], v[2:3], v[64:65] op_sel_hi:[0,1]
	s_waitcnt vmcnt(1)
	v_pk_mul_f32 v[16:17], v[16:17], v[22:23]
	v_pk_mul_f32 v[4:5], v[14:15], v[4:5]
	s_waitcnt vmcnt(0)
	v_pk_mul_f32 v[14:15], v[20:21], v[26:27]
	v_pk_mul_f32 v[18:19], v[18:19], v[24:25]
	v_cvt_pk_bf16_f32 v124, v4, v5
	v_cvt_pk_bf16_f32 v125, v16, v17
	v_mov_b32_e32 v4, v3
	v_cvt_pk_bf16_f32 v126, v18, v19
	v_cvt_pk_bf16_f32 v127, v14, v15
	global_load_dwordx4 v[14:17], v[150:151], off offset:448
	global_load_dwordx4 v[18:21], v[150:151], off offset:464
	v_mov_b32_e32 v5, v3
	s_waitcnt vmcnt(1)
	v_pk_mul_f32 v[6:7], v[16:17], v[6:7]
	v_pk_mul_f32 v[10:11], v[14:15], v[10:11]
	s_waitcnt vmcnt(0)
; __device__ __forceinline__ int v_st(int k, int c) { const int kk = (k & ~0xC) | ((k & 4) << 1) | ((k & 8) >> 1); return ((kk >> 3) * 4 + (c >> 5)) * 512 + ((kk & 7) * 32 + (c & 31)) * 2; }
; __device__ __forceinline__ int v_rd_base(int lane) { return ((lane & 3) << 3) | (((lane >> 2) & 3) << 6) | (((lane >> 4) & 1) << 5) | (((lane >> 5) & 1) << 8); }
; #define SLOAD(k0) do { vs0 = *(const bf16x8*)(V + (size_t)((k0) + sr) * ldv + sc); vs1 = *(const bf16x8*)(V + (size_t)((k0) + 32 + sr) * ldv + sc); \
;     ks0 = *(const bf16x8*)(Kn + (size_t)((k0) + sr) * ldk + sc); ks1 = *(const bf16x8*)(Kn + (size_t)((k0) + 32 + sr) * ldk + sc); \
;     if constexpr (DK == 192) kr0 = *(const bf16x8*)(Kr + (size_t)((k0) + rr) * ldkr + rc); } while (0)
; #define SWRITE(b) do { *(bf16x8*)(V_lds + (b) * SHM_V + vst0) = vs0; *(bf16x8*)(V_lds + (b) * SHM_V + vst1) = vs1; const int kc = sc * 2; \
;     *(bf16x8*)(K_lds + (b) * SHM_K + ATT_KSWZ(sr, kc, KROW)) = ks0; *(bf16x8*)(K_lds + (b) * SHM_K + ATT_KSWZ(32 + sr, kc, KROW)) = ks1; \
;     if constexpr (DK == 192) *(bf16x8*)(K_lds + (b) * SHM_K + ATT_KSWZ(rr, 256 + rc * 2, KROW)) = kr0; } while (0)
; #define SWAIT() asm volatile("s_waitcnt vmcnt(0)" ::: "memory")
; template <int DK, bool CAUSAL> ...
;     ...
;     int tid = threadIdx.x; asm volatile("" : "+v"(tid));
;     const int wid = tid >> 6, lane = tid & 63, r32 = lane & 31, hi = lane >> 5;
;     char* V_lds = lds; char* K_lds = lds + 2 * SHM_V;
;     float* wsf = (float*)(lds + 2 * SHM_V + 2 * SHM_K) + wid * 64; float* li_l = wsf; float* al_l = wsf + 32;
;     float m_reg = -1e30f, l_reg = 0; f32x16 o[4] = {};
;     const int sr = tid >> 4, sc = (tid & 15) * 8, vst0 = v_st(sr, sc), vst1 = v_st(32 + sr, sc);
;     const int rr = tid >> 3, rc = (tid & 7) * 8;
;     const int vb0 = (int)(uintptr_t)V_lds + v_rd_base(lane);
;     bf16x8 vs0, vs1, ks0, ks1, kr0;
;     ...
;     f32x16 p0, p1; float mn, al; bf16x8 pa0, pa1, pa2, pa3;
;     SLOAD(0); SWAIT(); SWRITE(0); __syncthreads();
	v_pk_mul_f32 v[8:9], v[20:21], v[8:9]
	v_pk_mul_f32 v[12:13], v[18:19], v[12:13]
	v_cvt_pk_bf16_f32 v128, v10, v11
	v_cvt_pk_bf16_f32 v129, v6, v7
	v_mov_b32_e32 v16, v3
	v_cvt_pk_bf16_f32 v130, v12, v13
	v_cvt_pk_bf16_f32 v131, v8, v9
	v_mov_b32_e32 v17, v3
	v_ashrrev_i32_e32 v18, 4, v166
	v_lshlrev_b32_e32 v0, 3, v166
	v_add_u32_e32 v20, 32, v18
	v_ashrrev_i32_e32 v19, 31, v18
	v_and_b32_e32 v2, 0x78, v0
	v_lshlrev_b64 v[22:23], 10, v[18:19]
	v_ashrrev_i32_e32 v21, 31, v20
	v_lshlrev_b32_e32 v2, 1, v2
	v_lshl_add_u64 v[6:7], s[26:27], 0, v[22:23]
	v_lshlrev_b64 v[8:9], 10, v[20:21]
	v_lshl_add_u64 v[10:11], s[6:7], 0, v[22:23]
	v_lshl_add_u64 v[6:7], v[6:7], 0, v[2:3]
	v_lshl_add_u64 v[12:13], s[26:27], 0, v[8:9]
	v_lshl_add_u64 v[8:9], s[6:7], 0, v[8:9]
	v_lshl_add_u64 v[10:11], v[10:11], 0, v[2:3]
	v_lshl_add_u64 v[12:13], v[12:13], 0, v[2:3]
	v_lshl_add_u64 v[8:9], v[8:9], 0, v[2:3]
	global_load_dwordx4 v[68:71], v[6:7], off
	global_load_dwordx4 v[72:75], v[12:13], off
	global_load_dwordx4 v[76:79], v[10:11], off
	global_load_dwordx4 v[80:83], v[8:9], off
	v_and_b32_e32 v21, 0x3fffffc0, v166
	v_and_b32_e32 v19, 63, v166
	v_lshlrev_b32_e32 v24, 4, v166
	v_lshl_add_u32 v169, v21, 2, s58
	v_and_b32_e32 v21, 0xfffff0, v18
	v_lshlrev_b32_e32 v26, 1, v18
	v_lshrrev_b32_e32 v27, 1, v18
	v_and_b32_e32 v28, 3, v18
	v_lshlrev_b32_e32 v29, 3, v19
	v_and_b32_e32 v24, 0xc0, v24
	v_cmp_gt_u32_e64 s[4:5], 32, v19
	v_and_or_b32 v19, v26, 8, v21
	v_and_b32_e32 v26, 0xfffff0, v20
	v_lshlrev_b32_e32 v20, 1, v20
	v_bfe_u32 v168, v166, 5, 1
	v_lshlrev_b32_e32 v25, 1, v166
	v_add_u32_e32 v171, 64, v18
	v_add_u32_e32 v172, 0x60, v18
	v_and_or_b32 v21, v27, 4, v28
	v_and_or_b32 v24, v29, 24, v24
	v_and_b32_e32 v27, 0x100, v29
	v_lshrrev_b32_e32 v29, 1, v19
	v_and_or_b32 v26, v20, 8, v26
	v_mad_u64_u32 v[18:19], s[46:47], v18, s59, v[2:3]
	v_and_b32_e32 v167, 31, v166
	v_bfe_u32 v0, v0, 5, 2
	v_and_b32_e32 v25, 32, v25
	v_lshlrev_b32_e32 v170, 4, v168
	v_lshrrev_b32_e32 v19, 1, v26
	v_mad_u32_u24 v28, v167, s59, v170
	v_lshlrev_b32_e32 v84, 6, v21
	v_and_b32_e32 v85, 48, v2
	v_or3_b32 v24, v24, v25, v27
	v_lshl_add_u64 v[154:155], s[26:27], 0, v[2:3]
	v_lshl_add_u64 v[156:157], s[6:7], 0, v[2:3]
	v_lshl_add_u64 v[20:21], v[22:23], 0, s[38:39]
	v_lshl_add_u64 v[22:23], v[22:23], 0, s[40:41]
	v_or_b32_e32 v2, v29, v0
	v_or_b32_e32 v0, v19, v0
	v_mov_b32_e32 v6, v3
	v_mov_b32_e32 v7, v3
	v_mov_b32_e32 v8, v3
	v_mov_b32_e32 v9, v3
	v_mov_b32_e32 v10, v3
	v_mov_b32_e32 v11, v3
	v_mov_b32_e32 v12, v3
	v_mov_b32_e32 v13, v3
	v_mov_b32_e32 v14, v3
	v_mov_b32_e32 v15, v3
	v_add_u32_e32 v174, 0, v28
	v_add_u32_e32 v175, 0, v18
	v_lshl_add_u64 v[158:159], v[154:155], 0, v[20:21]
	v_lshl_add_u64 v[160:161], v[154:155], 0, v[22:23]
	v_lshl_add_u64 v[162:163], v[156:157], 0, v[20:21]
	v_lshl_add_u64 v[164:165], v[156:157], 0, v[22:23]
	v_add_u32_e32 v176, 0, v24
	v_lshlrev_b32_e32 v18, 9, v2
	v_mov_b32_e32 v2, v3
	v_lshlrev_b32_e32 v0, 9, v0
	s_waitcnt vmcnt(0)
	v_mov_b64_e32 v[66:67], v[16:17]
	v_mov_b64_e32 v[50:51], v[16:17]
	v_mov_b64_e32 v[34:35], v[16:17]
	v_or3_b32 v86, v18, v84, v85
	v_mov_b64_e32 v[64:65], v[14:15]
	v_mov_b64_e32 v[62:63], v[12:13]
	v_mov_b64_e32 v[60:61], v[10:11]
	v_mov_b64_e32 v[58:59], v[8:9]
	v_mov_b64_e32 v[56:57], v[6:7]
	v_mov_b64_e32 v[54:55], v[4:5]
	v_mov_b64_e32 v[52:53], v[2:3]
	v_mov_b64_e32 v[48:49], v[14:15]
	v_mov_b64_e32 v[46:47], v[12:13]
	v_mov_b64_e32 v[44:45], v[10:11]
	v_mov_b64_e32 v[42:43], v[8:9]
	v_mov_b64_e32 v[40:41], v[6:7]
	v_mov_b64_e32 v[38:39], v[4:5]
	v_mov_b64_e32 v[36:37], v[2:3]
	v_mov_b64_e32 v[32:33], v[14:15]
	v_mov_b64_e32 v[30:31], v[12:13]
	v_mov_b64_e32 v[28:29], v[10:11]
	v_mov_b64_e32 v[26:27], v[8:9]
	v_mov_b64_e32 v[24:25], v[6:7]
	v_mov_b64_e32 v[22:23], v[4:5]
	v_mov_b64_e32 v[20:21], v[2:3]
	v_mov_b64_e32 v[18:19], v[16:17]
	v_or3_b32 v0, v0, v84, v85
	v_lshl_add_u32 v173, v167, 2, v169
	v_mov_b64_e32 v[16:17], v[14:15]
	v_mov_b64_e32 v[14:15], v[12:13]
	v_mov_b64_e32 v[12:13], v[10:11]
	v_mov_b64_e32 v[10:11], v[8:9]
	v_mov_b64_e32 v[8:9], v[6:7]
	v_mov_b64_e32 v[6:7], v[4:5]
	v_mov_b64_e32 v[4:5], v[2:3]
	v_add_u32_e32 v2, 0, v86
	v_add_u32_e32 v177, 0, v0
	s_waitcnt vmcnt(3)
	ds_write_b128 v2, v[68:71]
	s_waitcnt vmcnt(2)
	ds_write_b128 v177, v[72:75]
	s_waitcnt vmcnt(1)
	ds_write_b128 v175, v[76:79] offset:32768
	s_waitcnt vmcnt(0)
	ds_write_b128 v175, v[80:83] offset:41472
	s_waitcnt lgkmcnt(0)
	s_barrier
	s_branch .LBB0_1176
	.p2align	6

; #define PG8_STAGE(bufoff, gbase, voff) do { _Pragma("unroll") for (int _i = 0; _i < 2; ++_i) \
;         __builtin_amdgcn_global_load_lds((const unsigned*)((const char*)(gbase) + (voff)[_i]), (LAS unsigned*)(lds + (bufoff) + ldsw + _i * 8192), 16, 0, 0); } while (0)
; #define PG8_WAIT_V(n) asm volatile("s_waitcnt vmcnt(" #n ")" ::: "memory")
; #define PG8_BAR __builtin_amdgcn_s_barrier()
; #define PG8_TOUCH(p) asm volatile("global_load_dword %0, %1, off" : "+v"(pfd) : "v"(p) : "memory")
;     ...
;     for (int i = 0; i < 2; ++i) { int R, C; stage_rc(tid * 16 + i * 8192, R, C); const int Rb = Epi::PERM ? ((R & ~31) + perm32(R & 31)) : R;
;         voffA[i] = (unsigned)(R * g.lda + C) * 2u; voffB[i] = (unsigned)(Rb * g.ldb + C) * 2u; }
;     const size_t kstep = (size_t)(BK * 2);
;     const size_t hstepA = (size_t)HALF * g.lda * 2, hstepB = (size_t)HALF * g.ldb * 2;
;     const unsigned ldsw = (unsigned)wid * 1024u;
;     const int aoff = lds_byte(wr * 64 + fr, fq * 8), boff = lds_byte(wc * 32 + fr, fq * 8);
;     ...
;     PG8_STAGE(PG8_SB(0, 0), cB, voffB); PG8_STAGE(PG8_SB(0, 1), cB + hstepB, voffB); PG8_STAGE(PG8_SA(0, 0), cA, voffA); PG8_STAGE(PG8_SA(0, 1), cA + hstepA, voffA);
;     if (wr == 1) PG8_BAR;
;     PG8_WAIT_V(2); PG8_BAR;
;     PG8_STAGE(PG8_SB(1, 0), cB + kstep, voffB); PG8_STAGE(PG8_SA(1, 0), cA + kstep, voffA); PG8_STAGE(PG8_SB(1, 1), cB + hstepB + kstep, voffB);
;     PG8_WAIT_V(6); PG8_BAR;
;     if constexpr (PF > 0) { const char* p0 = PG8_PFPTR(cA, cB) + (size_t)(2 + PF) * kstep; PG8_TOUCH(p0); }
.LBB0_1251:
	s_lshl_b32 s0, s14, 13
	s_mov_b64 s[14:15], 0x80
	s_lshl_b32 s5, s5, 12
	s_add_i32 m0, s48, 0x18000
	v_lshl_add_u64 v[8:9], v[8:9], 0, s[14:15]
	s_and_b32 s5, s5, 0x3000
	s_waitcnt vmcnt(2)
	s_barrier
	global_load_lds_dwordx4 v[8:9], off
	v_lshl_add_u64 v[6:7], v[6:7], 0, s[14:15]
	s_add_i32 m0, s48, 0x1a000
	s_add_i32 s52, s48, 0x8000
	s_add_i32 s53, s48, 0xa000
	global_load_lds_dwordx4 v[6:7], off
	v_lshl_add_u64 v[2:3], v[2:3], 0, s[14:15]
	s_mov_b32 m0, s52
	s_add_u32 s16, s38, 0x20080
	global_load_lds_dwordx4 v[2:3], off
	v_lshl_add_u64 v[2:3], v[4:5], 0, s[14:15]
	s_mov_b32 m0, s53
	s_addc_u32 s17, s39, 0
	global_load_lds_dwordx4 v[2:3], off
	s_add_i32 m0, s48, 0x1c000
	v_lshl_add_u64 v[2:3], s[16:17], 0, v[156:157]
	global_load_lds_dwordx4 v[2:3], off
	v_lshl_add_u64 v[2:3], s[16:17], 0, v[160:161]
	s_add_i32 m0, s48, 0x1e000
	v_and_b32_e32 v0, 15, v1
	global_load_lds_dwordx4 v[2:3], off
	v_and_b32_e32 v2, 48, v1
	v_lshlrev_b32_e32 v1, 2, v1
	v_lshlrev_b32_e32 v0, 6, v0
	v_and_b32_e32 v1, 32, v1
	v_or_b32_e32 v3, v0, v2
	v_bitop3_b32 v0, v0, v1, v2 bitop3:0x36
	v_bitop3_b32 v2, v3, s0, v1 bitop3:0xde
	v_or_b32_e32 v1, s5, v0
	v_lshlrev_b32_e32 v0, 13, v10
	v_and_b32_e32 v0, 0xffffc000, v0
	v_lshl_add_u32 v0, v11, 10, v0
	v_and_b32_e32 v3, 1, v10
	v_lshl_or_b32 v0, v3, 6, v0
	v_lshl_add_u32 v162, v12, 1, v0
	v_lshlrev_b32_e32 v0, 13, v13
	s_cmpk_lt_u32 s4, 0x100
	v_and_b32_e32 v0, 0xffffc000, v0
	s_waitcnt vmcnt(6)
	s_cselect_b64 s[16:17], -1, 0
	v_lshl_add_u32 v0, v14, 10, v0
	v_and_b32_e32 v3, 1, v13
	s_add_i32 s61, 0, 0x10000
	v_lshl_or_b32 v0, v3, 6, v0
	v_add_u32_e32 v182, s61, v1
	s_add_i32 s58, 0, 0x14000
	s_add_i32 s61, s61, s33
	s_ashr_i32 s54, s3, 31
	s_ashr_i32 s55, s2, 31
	v_mov_b32_e32 v163, v157
	v_lshl_add_u32 v164, v15, 1, v0
	v_mov_b32_e32 v165, v157
	v_mov_b64_e32 v[168:169], 0x3ff
	v_add_u32_e32 v183, s58, v1
	v_add_u32_e32 v184, 0, v2
	s_mov_b64 s[18:19], 0x100
	s_mov_b64 s[20:21], 0x180
	s_add_i32 s59, s48, 0xc000
	s_add_i32 s60, s48, 0xe000
	s_add_i32 s62, s61, 0x2000
	s_mov_b32 s63, 0
	s_barrier
	s_branch .LBB0_1254
	.p2align	6

;     __host__ __device__ bool next(int i, Unit& u) const { if (!StaticOrder::next(i >> 1, u)) return false; u.seg = i & 1; return true; }
;     ...
;         const bool has_next = S.next(ui + 1, nxt);
;         const char* nA = has_next ? PG8_APTR(nxt) : cA; const char* nB = has_next ? PG8_BPTR(nxt) : cB;
.LBB0_1260:
	s_ashr_i32 s23, s22, 31
	ds_read_b128 v[2:5], v182
	ds_read_b128 v[6:9], v182 offset:1024
	ds_read_b128 v[10:13], v182 offset:2048
	ds_read_b128 v[14:17], v182 offset:3072
	ds_read_b128 v[18:21], v183
	ds_read_b128 v[22:25], v183 offset:1024
	ds_read_b128 v[26:29], v183 offset:2048
	ds_read_b128 v[30:33], v183 offset:3072
	s_lshl_b64 s[24:25], s[22:23], 18
	s_add_u32 s24, s10, s24
	s_addc_u32 s25, s11, s25
	s_and_b64 s[26:27], s[4:5], exec
	s_cselect_b32 s23, s25, s41
	s_cselect_b32 s31, s24, s40
	s_and_b32 s0, s64, 0x7fffffff
	s_lshl_b64 s[26:27], s[0:1], 18
	s_add_u32 s28, s12, s26
	s_addc_u32 s29, s13, s27
	s_and_b64 s[26:27], s[4:5], exec
	s_cselect_b32 s0, s29, s39
	s_cselect_b32 s66, s28, s38
	s_add_u32 s26, s40, 0x20080
	s_addc_u32 s27, s41, 0
	s_mov_b32 m0, s59
	v_lshl_add_u64 v[66:67], s[26:27], 0, v[154:155]
	ds_read_b128 v[34:37], v184
	ds_read_b128 v[38:41], v184 offset:1024
	ds_read_b128 v[42:45], v184 offset:2048
	ds_read_b128 v[46:49], v184 offset:3072
	ds_read_b128 v[50:53], v184 offset:4096
	ds_read_b128 v[54:57], v184 offset:5120
	ds_read_b128 v[58:61], v184 offset:6144
	ds_read_b128 v[62:65], v184 offset:7168
	global_load_lds_dwordx4 v[66:67], off
	v_lshl_add_u64 v[66:67], s[26:27], 0, v[158:159]
	s_mov_b32 m0, s60
	s_nop 0
	global_load_lds_dwordx4 v[66:67], off
	s_waitcnt vmcnt(8)
	s_waitcnt lgkmcnt(0)
	s_setprio 1
	s_barrier
	v_mfma_f32_16x16x32_bf16 v[90:93], v[2:5], v[58:61], 0
	v_mfma_f32_16x16x32_bf16 v[66:69], v[2:5], v[34:37], 0
	v_mfma_f32_16x16x32_bf16 v[70:73], v[10:13], v[34:37], 0
	v_mfma_f32_16x16x32_bf16 v[74:77], v[2:5], v[42:45], 0
	v_mfma_f32_16x16x32_bf16 v[78:81], v[10:13], v[42:45], 0
	v_mfma_f32_16x16x32_bf16 v[82:85], v[2:5], v[50:53], 0
	v_mfma_f32_16x16x32_bf16 v[86:89], v[10:13], v[50:53], 0
	v_mfma_f32_16x16x32_bf16 v[98:101], v[6:9], v[62:65], v[90:93]
	v_mfma_f32_16x16x32_bf16 v[90:93], v[10:13], v[58:61], 0
	v_mfma_f32_16x16x32_bf16 v[66:69], v[6:9], v[38:41], v[66:69]
	v_mfma_f32_16x16x32_bf16 v[70:73], v[14:17], v[38:41], v[70:73]
	v_mfma_f32_16x16x32_bf16 v[74:77], v[6:9], v[46:49], v[74:77]
	v_mfma_f32_16x16x32_bf16 v[78:81], v[14:17], v[46:49], v[78:81]
	v_mfma_f32_16x16x32_bf16 v[82:85], v[6:9], v[54:57], v[82:85]
	v_mfma_f32_16x16x32_bf16 v[86:89], v[14:17], v[54:57], v[86:89]
	v_mfma_f32_16x16x32_bf16 v[102:105], v[14:17], v[62:65], v[90:93]
	s_setprio 0
	s_setprio 1
	v_mfma_f32_16x16x32_bf16 v[90:93], v[18:21], v[34:37], 0
	v_mfma_f32_16x16x32_bf16 v[34:37], v[26:29], v[34:37], 0
	v_mfma_f32_16x16x32_bf16 v[114:117], v[22:25], v[38:41], v[90:93]
	v_mfma_f32_16x16x32_bf16 v[34:37], v[30:33], v[38:41], v[34:37]
	v_mfma_f32_16x16x32_bf16 v[38:41], v[18:21], v[42:45], 0
	v_mfma_f32_16x16x32_bf16 v[42:45], v[26:29], v[42:45], 0
	v_mfma_f32_16x16x32_bf16 v[38:41], v[22:25], v[46:49], v[38:41]
	v_mfma_f32_16x16x32_bf16 v[42:45], v[30:33], v[46:49], v[42:45]
	v_mfma_f32_16x16x32_bf16 v[46:49], v[18:21], v[50:53], 0
	v_mfma_f32_16x16x32_bf16 v[50:53], v[26:29], v[50:53], 0
	v_mfma_f32_16x16x32_bf16 v[46:49], v[22:25], v[54:57], v[46:49]
	v_mfma_f32_16x16x32_bf16 v[50:53], v[30:33], v[54:57], v[50:53]
	v_mfma_f32_16x16x32_bf16 v[54:57], v[18:21], v[58:61], 0
	v_mfma_f32_16x16x32_bf16 v[58:61], v[26:29], v[58:61], 0
	v_mfma_f32_16x16x32_bf16 v[54:57], v[22:25], v[62:65], v[54:57]
	v_mfma_f32_16x16x32_bf16 v[58:61], v[30:33], v[62:65], v[58:61]
	s_barrier
	s_setprio 0
	v_lshl_add_u64 v[152:153], s[38:39], 0, v[156:157]
	s_mov_b32 m0, s61
	v_lshl_add_u64 v[130:131], v[152:153], 0, s[18:19]
	v_lshl_add_u64 v[250:251], s[38:39], 0, v[160:161]
	s_add_u32 s26, s38, 0x20100
	ds_read_b128 v[62:65], v184 offset:16384
	ds_read_b128 v[90:93], v184 offset:17408
	ds_read_b128 v[94:97], v184 offset:18432
	ds_read_b128 v[106:109], v184 offset:19456
	ds_read_b128 v[110:113], v184 offset:20480
	ds_read_b128 v[118:121], v184 offset:21504
	ds_read_b128 v[122:125], v184 offset:22528
	ds_read_b128 v[126:129], v184 offset:23552
	global_load_lds_dwordx4 v[130:131], off
	v_lshl_add_u64 v[130:131], v[250:251], 0, s[18:19]
	s_mov_b32 m0, s62
	s_addc_u32 s27, s39, 0
	s_add_i32 s67, s58, s33
	global_load_lds_dwordx4 v[130:131], off
	v_lshl_add_u64 v[130:131], s[26:27], 0, v[156:157]
	s_mov_b32 m0, s67
	s_add_i32 s46, s67, 0x2000
	global_load_lds_dwordx4 v[130:131], off
	v_lshl_add_u64 v[130:131], s[26:27], 0, v[160:161]
	s_mov_b32 m0, s46
	v_lshl_add_u64 v[252:253], s[40:41], 0, v[154:155]
	global_load_lds_dwordx4 v[130:131], off
	v_lshl_add_u64 v[130:131], v[252:253], 0, s[18:19]
	s_mov_b32 m0, s48
	v_lshl_add_u64 v[166:167], s[40:41], 0, v[158:159]
	global_load_lds_dwordx4 v[130:131], off
	v_lshl_add_u64 v[130:131], v[166:167], 0, s[18:19]
	s_mov_b32 m0, s49
	s_nop 0
	global_load_lds_dwordx4 v[130:131], off
	s_waitcnt vmcnt(8)
	s_waitcnt lgkmcnt(0)
	s_setprio 1
	s_barrier
	v_mfma_f32_16x16x32_bf16 v[130:133], v[2:5], v[62:65], 0
	v_mfma_f32_16x16x32_bf16 v[140:143], v[2:5], v[94:97], 0
	v_mfma_f32_16x16x32_bf16 v[148:151], v[2:5], v[110:113], 0
	v_mfma_f32_16x16x32_bf16 v[2:5], v[2:5], v[122:125], 0
	v_mfma_f32_16x16x32_bf16 v[132:135], v[6:9], v[90:93], v[130:133]
	v_mfma_f32_16x16x32_bf16 v[140:143], v[6:9], v[106:109], v[140:143]
	v_mfma_f32_16x16x32_bf16 v[148:151], v[6:9], v[118:121], v[148:151]
	v_mfma_f32_16x16x32_bf16 v[2:5], v[6:9], v[126:129], v[2:5]
	v_mfma_f32_16x16x32_bf16 v[6:9], v[10:13], v[122:125], 0
	v_mfma_f32_16x16x32_bf16 v[136:139], v[10:13], v[62:65], 0
	v_mfma_f32_16x16x32_bf16 v[144:147], v[10:13], v[94:97], 0
	v_mfma_f32_16x16x32_bf16 v[170:173], v[10:13], v[110:113], 0
	v_mfma_f32_16x16x32_bf16 v[6:9], v[14:17], v[126:129], v[6:9]
	v_mfma_f32_16x16x32_bf16 v[136:139], v[14:17], v[90:93], v[136:139]
	v_mfma_f32_16x16x32_bf16 v[144:147], v[14:17], v[106:109], v[144:147]
	v_mfma_f32_16x16x32_bf16 v[170:173], v[14:17], v[118:121], v[170:173]
	s_setprio 0
	s_setprio 1
	v_mfma_f32_16x16x32_bf16 v[10:13], v[18:21], v[62:65], 0
	v_mfma_f32_16x16x32_bf16 v[174:177], v[22:25], v[90:93], v[10:13]
	v_mfma_f32_16x16x32_bf16 v[10:13], v[26:29], v[62:65], 0
	v_mfma_f32_16x16x32_bf16 v[178:181], v[30:33], v[90:93], v[10:13]
	v_mfma_f32_16x16x32_bf16 v[10:13], v[18:21], v[94:97], 0
	v_mfma_f32_16x16x32_bf16 v[186:189], v[22:25], v[106:109], v[10:13]
	v_mfma_f32_16x16x32_bf16 v[10:13], v[26:29], v[94:97], 0
	v_mfma_f32_16x16x32_bf16 v[190:193], v[30:33], v[106:109], v[10:13]
	v_mfma_f32_16x16x32_bf16 v[10:13], v[18:21], v[110:113], 0
	v_mfma_f32_16x16x32_bf16 v[194:197], v[22:25], v[118:121], v[10:13]
	v_mfma_f32_16x16x32_bf16 v[10:13], v[26:29], v[110:113], 0
	v_mfma_f32_16x16x32_bf16 v[198:201], v[30:33], v[118:121], v[10:13]
	v_mfma_f32_16x16x32_bf16 v[10:13], v[18:21], v[122:125], 0
	v_mfma_f32_16x16x32_bf16 v[202:205], v[22:25], v[126:129], v[10:13]
	v_mfma_f32_16x16x32_bf16 v[10:13], v[26:29], v[122:125], 0
	v_mfma_f32_16x16x32_bf16 v[206:209], v[30:33], v[126:129], v[10:13]
	s_barrier
	s_setprio 0
	s_add_i32 s47, 0, 0x18000
	s_add_i32 s56, 0, 0x1c000
	v_add_u32_e32 v130, s47, v1
	v_add_u32_e32 v131, s56, v1
	s_nop 0
	ds_read_b128 v[10:13], v130
	ds_read_b128 v[14:17], v130 offset:1024
	ds_read_b128 v[18:21], v130 offset:2048
	ds_read_b128 v[22:25], v130 offset:3072
	ds_read_b128 v[210:213], v131
	ds_read_b128 v[214:217], v131 offset:1024
	ds_read_b128 v[218:221], v131 offset:2048
	ds_read_b128 v[222:225], v131 offset:3072
	s_add_u32 s26, s40, 0x20100
	s_addc_u32 s27, s41, 0
	s_mov_b32 m0, s50
	v_lshl_add_u64 v[90:91], s[26:27], 0, v[154:155]
	ds_read_b128 v[26:29], v184 offset:32768
	ds_read_b128 v[30:33], v184 offset:33792
	ds_read_b128 v[62:65], v184 offset:34816
	ds_read_b128 v[226:229], v184 offset:35840
	ds_read_b128 v[230:233], v184 offset:36864
	ds_read_b128 v[234:237], v184 offset:37888
	ds_read_b128 v[238:241], v184 offset:38912
	ds_read_b128 v[242:245], v184 offset:39936
	global_load_lds_dwordx4 v[90:91], off
	v_lshl_add_u64 v[90:91], s[26:27], 0, v[158:159]
	s_mov_b32 m0, s51
	s_nop 0
	global_load_lds_dwordx4 v[90:91], off
	s_waitcnt vmcnt(8)
	s_waitcnt lgkmcnt(0)
	s_setprio 1
	s_barrier
	v_mfma_f32_16x16x32_bf16 v[66:69], v[10:13], v[26:29], v[66:69]
	v_mfma_f32_16x16x32_bf16 v[122:125], v[14:17], v[30:33], v[66:69]
	v_mfma_f32_16x16x32_bf16 v[66:69], v[18:21], v[26:29], v[70:73]
	v_mfma_f32_16x16x32_bf16 v[118:121], v[22:25], v[30:33], v[66:69]
	v_mfma_f32_16x16x32_bf16 v[66:69], v[10:13], v[62:65], v[74:77]
	v_mfma_f32_16x16x32_bf16 v[110:113], v[14:17], v[226:229], v[66:69]
	v_mfma_f32_16x16x32_bf16 v[66:69], v[18:21], v[62:65], v[78:81]
	v_mfma_f32_16x16x32_bf16 v[106:109], v[22:25], v[226:229], v[66:69]
	v_mfma_f32_16x16x32_bf16 v[66:69], v[10:13], v[230:233], v[82:85]
	v_mfma_f32_16x16x32_bf16 v[94:97], v[14:17], v[234:237], v[66:69]
	v_mfma_f32_16x16x32_bf16 v[66:69], v[18:21], v[230:233], v[86:89]
	v_mfma_f32_16x16x32_bf16 v[90:93], v[22:25], v[234:237], v[66:69]
	v_mfma_f32_16x16x32_bf16 v[66:69], v[10:13], v[238:241], v[98:101]
	v_mfma_f32_16x16x32_bf16 v[78:81], v[14:17], v[242:245], v[66:69]
	v_mfma_f32_16x16x32_bf16 v[66:69], v[18:21], v[238:241], v[102:105]
	v_mfma_f32_16x16x32_bf16 v[74:77], v[22:25], v[242:245], v[66:69]
	s_setprio 0
	s_setprio 1
	v_mfma_f32_16x16x32_bf16 v[66:69], v[210:213], v[26:29], v[114:117]
	v_mfma_f32_16x16x32_bf16 v[26:29], v[218:221], v[26:29], v[34:37]
	v_mfma_f32_16x16x32_bf16 v[114:117], v[222:225], v[30:33], v[26:29]
	v_mfma_f32_16x16x32_bf16 v[26:29], v[210:213], v[62:65], v[38:41]
	v_mfma_f32_16x16x32_bf16 v[102:105], v[214:217], v[226:229], v[26:29]
	v_mfma_f32_16x16x32_bf16 v[26:29], v[218:221], v[62:65], v[42:45]
	v_mfma_f32_16x16x32_bf16 v[98:101], v[222:225], v[226:229], v[26:29]
	v_mfma_f32_16x16x32_bf16 v[26:29], v[210:213], v[230:233], v[46:49]
	v_mfma_f32_16x16x32_bf16 v[86:89], v[214:217], v[234:237], v[26:29]
	v_mfma_f32_16x16x32_bf16 v[26:29], v[218:221], v[230:233], v[50:53]
	v_mfma_f32_16x16x32_bf16 v[82:85], v[222:225], v[234:237], v[26:29]
	v_mfma_f32_16x16x32_bf16 v[26:29], v[210:213], v[238:241], v[54:57]
	v_mfma_f32_16x16x32_bf16 v[70:73], v[214:217], v[242:245], v[26:29]
	v_mfma_f32_16x16x32_bf16 v[26:29], v[218:221], v[238:241], v[58:61]
	v_mfma_f32_16x16x32_bf16 v[126:129], v[214:217], v[30:33], v[66:69]
	v_mfma_f32_16x16x32_bf16 v[66:69], v[222:225], v[242:245], v[26:29]
	s_barrier
;     ...
;         PG8_KITER(0);
;         for (int t = 2; t < nt; t += 2) PG8_KITER(t);
	s_setprio 0
	s_add_i32 s47, s47, s33
	s_add_i32 s68, s47, 0x2000
	s_nop 1
	v_lshl_add_u64 v[26:27], v[152:153], 0, s[20:21]
	s_mov_b32 m0, s47
	s_add_u32 s26, s38, 0x20180
	ds_read_b128 v[34:37], v184 offset:49152
	ds_read_b128 v[38:41], v184 offset:50176
	ds_read_b128 v[226:229], v184 offset:51200
	ds_read_b128 v[230:233], v184 offset:52224
	ds_read_b128 v[234:237], v184 offset:53248
	ds_read_b128 v[238:241], v184 offset:54272
	ds_read_b128 v[242:245], v184 offset:55296
	ds_read_b128 v[246:249], v184 offset:56320
	global_load_lds_dwordx4 v[26:27], off
	v_lshl_add_u64 v[26:27], v[250:251], 0, s[20:21]
	s_mov_b32 m0, s68
	s_addc_u32 s27, s39, 0
	s_add_i32 s56, s56, s33
	global_load_lds_dwordx4 v[26:27], off
	v_lshl_add_u64 v[26:27], s[26:27], 0, v[156:157]
	s_mov_b32 m0, s56
	s_add_i32 s57, s56, 0x2000
	global_load_lds_dwordx4 v[26:27], off
	v_lshl_add_u64 v[26:27], s[26:27], 0, v[160:161]
	s_mov_b32 m0, s57
	s_nop 0
	global_load_lds_dwordx4 v[26:27], off
	v_lshl_add_u64 v[26:27], v[252:253], 0, s[20:21]
	s_mov_b32 m0, s52
	s_nop 0
	global_load_lds_dwordx4 v[26:27], off
	v_lshl_add_u64 v[26:27], v[166:167], 0, s[20:21]
	s_mov_b32 m0, s53
	s_nop 0
	global_load_lds_dwordx4 v[26:27], off
	s_waitcnt vmcnt(8)
	s_waitcnt lgkmcnt(0)
	s_setprio 1
	s_barrier
	v_mfma_f32_16x16x32_bf16 v[26:29], v[10:13], v[34:37], v[132:135]
	v_mfma_f32_16x16x32_bf16 v[58:61], v[14:17], v[38:41], v[26:29]
	v_mfma_f32_16x16x32_bf16 v[26:29], v[18:21], v[34:37], v[136:139]
	v_mfma_f32_16x16x32_bf16 v[54:57], v[22:25], v[38:41], v[26:29]
	v_mfma_f32_16x16x32_bf16 v[26:29], v[10:13], v[226:229], v[140:143]
	v_mfma_f32_16x16x32_bf16 v[46:49], v[14:17], v[230:233], v[26:29]
	v_mfma_f32_16x16x32_bf16 v[26:29], v[18:21], v[226:229], v[144:147]
	v_mfma_f32_16x16x32_bf16 v[42:45], v[22:25], v[230:233], v[26:29]
	v_mfma_f32_16x16x32_bf16 v[26:29], v[10:13], v[234:237], v[148:151]
	v_mfma_f32_16x16x32_bf16 v[2:5], v[10:13], v[242:245], v[2:5]
	v_mfma_f32_16x16x32_bf16 v[30:33], v[14:17], v[238:241], v[26:29]
	v_mfma_f32_16x16x32_bf16 v[26:29], v[18:21], v[234:237], v[170:173]
	v_mfma_f32_16x16x32_bf16 v[14:17], v[14:17], v[246:249], v[2:5]
	v_mfma_f32_16x16x32_bf16 v[2:5], v[18:21], v[242:245], v[6:9]
	v_mfma_f32_16x16x32_bf16 v[26:29], v[22:25], v[238:241], v[26:29]
	v_mfma_f32_16x16x32_bf16 v[10:13], v[22:25], v[246:249], v[2:5]
	s_setprio 0
	s_setprio 1
	v_mfma_f32_16x16x32_bf16 v[2:5], v[210:213], v[34:37], v[174:177]
	v_mfma_f32_16x16x32_bf16 v[62:65], v[214:217], v[38:41], v[2:5]
	v_mfma_f32_16x16x32_bf16 v[2:5], v[218:221], v[34:37], v[178:181]
	v_mfma_f32_16x16x32_bf16 v[50:53], v[222:225], v[38:41], v[2:5]
	v_mfma_f32_16x16x32_bf16 v[2:5], v[210:213], v[226:229], v[186:189]
	v_mfma_f32_16x16x32_bf16 v[38:41], v[214:217], v[230:233], v[2:5]
	v_mfma_f32_16x16x32_bf16 v[2:5], v[218:221], v[226:229], v[190:193]
	v_mfma_f32_16x16x32_bf16 v[34:37], v[222:225], v[230:233], v[2:5]
	v_mfma_f32_16x16x32_bf16 v[2:5], v[210:213], v[234:237], v[194:197]
	v_mfma_f32_16x16x32_bf16 v[22:25], v[214:217], v[238:241], v[2:5]
	v_mfma_f32_16x16x32_bf16 v[2:5], v[218:221], v[234:237], v[198:201]
	v_mfma_f32_16x16x32_bf16 v[18:21], v[222:225], v[238:241], v[2:5]
	v_mfma_f32_16x16x32_bf16 v[2:5], v[210:213], v[242:245], v[202:205]
	v_mfma_f32_16x16x32_bf16 v[6:9], v[214:217], v[246:249], v[2:5]
	v_mfma_f32_16x16x32_bf16 v[2:5], v[218:221], v[242:245], v[206:209]
	v_mfma_f32_16x16x32_bf16 v[2:5], v[222:225], v[246:249], v[2:5]
	s_barrier
	s_setprio 0
	s_add_u32 s40, s40, 0x20180
	s_addc_u32 s41, s41, 0
	s_add_u32 s26, s38, 0x200
	s_addc_u32 s27, s39, 0
	s_mov_b32 s69, 0
	.p2align	6

; #define PG8_STAGE(bufoff, gbase, voff) do { _Pragma("unroll") for (int _i = 0; _i < 2; ++_i) \
;         __builtin_amdgcn_global_load_lds((const unsigned*)((const char*)(gbase) + (voff)[_i]), (LAS unsigned*)(lds + (bufoff) + ldsw + _i * 8192), 16, 0, 0); } while (0)
; #define PG8_WAIT_V(n) asm volatile("s_waitcnt vmcnt(" #n ")" ::: "memory")
; #define PG8_BAR __builtin_amdgcn_s_barrier()
; #define PG8_TOUCH(p) asm volatile("global_load_dword %0, %1, off" : "+v"(pfd) : "v"(p) : "memory")
;     ...
;     for (int i = 0; i < 2; ++i) { int R, C; stage_rc(tid * 16 + i * 8192, R, C); const int Rb = Epi::PERM ? ((R & ~31) + perm32(R & 31)) : R;
;         voffA[i] = (unsigned)(R * g.lda + C) * 2u; voffB[i] = (unsigned)(Rb * g.ldb + C) * 2u; }
;     const size_t kstep = (size_t)(BK * 2);
;     const size_t hstepA = (size_t)HALF * g.lda * 2, hstepB = (size_t)HALF * g.ldb * 2;
;     const unsigned ldsw = (unsigned)wid * 1024u;
;     const int aoff = lds_byte(wr * 64 + fr, fq * 8), boff = lds_byte(wc * 32 + fr, fq * 8);
;     ...
;     PG8_STAGE(PG8_SB(0, 0), cB, voffB); PG8_STAGE(PG8_SB(0, 1), cB + hstepB, voffB); PG8_STAGE(PG8_SA(0, 0), cA, voffA); PG8_STAGE(PG8_SA(0, 1), cA + hstepA, voffA);
;     if (wr == 1) PG8_BAR;
;     PG8_WAIT_V(2); PG8_BAR;
;     PG8_STAGE(PG8_SB(1, 0), cB + kstep, voffB); PG8_STAGE(PG8_SA(1, 0), cA + kstep, voffA); PG8_STAGE(PG8_SB(1, 1), cB + hstepB + kstep, voffB);
;     PG8_WAIT_V(6); PG8_BAR;
;     if constexpr (PF > 0) { const char* p0 = PG8_PFPTR(cA, cB) + (size_t)(2 + PF) * kstep; PG8_TOUCH(p0); }
.LBB0_1339:
	s_lshl_b32 s1, s16, 13
	s_mov_b64 s[16:17], 0x80
	s_lshl_b32 s5, s5, 12
	s_add_i32 m0, s13, 0x18000
	v_lshl_add_u64 v[8:9], v[8:9], 0, s[16:17]
	s_and_b32 s5, s5, 0x3000
	s_waitcnt vmcnt(2)
	s_barrier
	global_load_lds_dwordx4 v[8:9], off
	v_lshl_add_u64 v[6:7], v[6:7], 0, s[16:17]
	s_add_i32 m0, s13, 0x1a000
	s_add_i32 s50, s13, 0x8000
	s_add_i32 s51, s13, 0xa000
	global_load_lds_dwordx4 v[6:7], off
	v_lshl_add_u64 v[2:3], v[2:3], 0, s[16:17]
	s_mov_b32 m0, s50
	s_add_u32 s18, s38, 0x100080
	global_load_lds_dwordx4 v[2:3], off
	v_lshl_add_u64 v[2:3], v[4:5], 0, s[16:17]
	s_mov_b32 m0, s51
	s_addc_u32 s19, s39, 0
	global_load_lds_dwordx4 v[2:3], off
	s_add_i32 m0, s13, 0x1c000
	v_lshl_add_u64 v[2:3], s[18:19], 0, v[134:135]
	global_load_lds_dwordx4 v[2:3], off
	v_lshl_add_u64 v[2:3], s[18:19], 0, v[130:131]
	s_add_i32 m0, s13, 0x1e000
	v_and_b32_e32 v0, 15, v1
	global_load_lds_dwordx4 v[2:3], off
	v_and_b32_e32 v2, 48, v1
	v_lshlrev_b32_e32 v1, 2, v1
	v_lshlrev_b32_e32 v0, 6, v0
	v_and_b32_e32 v1, 32, v1
	v_or_b32_e32 v3, v0, v2
	v_bitop3_b32 v0, v0, v1, v2 bitop3:0x36
	v_bitop3_b32 v2, v3, s1, v1 bitop3:0xde
	v_or_b32_e32 v155, s5, v0
	v_lshlrev_b32_e32 v0, 16, v14
	v_lshlrev_b32_e32 v3, 16, v10
	s_cmpk_lt_u32 s4, 0x100
	v_and_b32_e32 v0, 0xfffe0000, v0
	v_and_b32_e32 v3, 0xfffe0000, v3
	s_waitcnt vmcnt(6)
	s_cselect_b64 s[18:19], -1, 0
	v_lshl_add_u32 v0, v13, 13, v0
	v_and_b32_e32 v1, 1, v14
	v_lshl_add_u32 v3, v11, 13, v3
	v_and_b32_e32 v4, 1, v10
	s_add_i32 s59, 0, 0x10000
	s_add_i32 s61, 0, 0x14000
	v_lshl_or_b32 v0, v1, 6, v0
	v_lshl_or_b32 v3, v4, 6, v3
	v_add_u32_e32 v150, s59, v155
	v_add_u32_e32 v151, s61, v155
	s_add_i32 s59, s59, s10
	s_add_i32 s61, s61, s10
	s_add_i32 s63, 0, 0x18000
	s_ashr_i32 s52, s3, 31
	v_lshl_add_u32 v0, v15, 1, v0
	v_mov_b32_e32 v1, v135
	v_lshl_add_u32 v140, v12, 1, v3
	v_mov_b32_e32 v141, v135
	v_add_u32_e32 v152, 0, v2
	s_add_i32 s53, s13, 0xc000
	s_add_i32 s54, s13, 0xe000
	s_mov_b64 s[20:21], 0x100
	s_mov_b64 s[22:23], 0x180
	v_mov_b32_e32 v153, 0x358637bd
	s_mov_b32 s55, 0x800000
	s_movk_i32 s58, 0x5600
	s_add_i32 s60, s59, 0x2000
	s_add_i32 s62, s61, 0x2000
	v_add_u32_e32 v154, s63, v155
	s_mov_b32 s64, 0
	s_barrier
	s_branch .LBB0_1342
	.p2align	6

;     __host__ __device__ bool next(int i, Unit& u) const { if (!StaticOrder::next(i >> 1, u)) return false; u.seg = i & 1; return true; }
;     ...
;         const bool has_next = S.next(ui + 1, nxt);
;         const char* nA = has_next ? PG8_APTR(nxt) : cA; const char* nB = has_next ? PG8_BPTR(nxt) : cB;
.LBB0_1344:
	s_ashr_i32 s25, s24, 31
	ds_read_b128 v[2:5], v150
	ds_read_b128 v[6:9], v150 offset:1024
	ds_read_b128 v[10:13], v150 offset:2048
	ds_read_b128 v[14:17], v150 offset:3072
	ds_read_b128 v[18:21], v151
	ds_read_b128 v[22:25], v151 offset:1024
	ds_read_b128 v[26:29], v151 offset:2048
	ds_read_b128 v[30:33], v151 offset:3072
	s_lshl_b64 s[26:27], s[24:25], 21
	s_add_u32 s28, s36, s26
	s_addc_u32 s29, s37, s27
	s_and_b64 s[26:27], s[4:5], exec
	s_cselect_b32 s1, s29, s41
	s_cselect_b32 s25, s28, s40
	s_and_b32 s8, s65, 0x7fffffff
	s_lshl_b64 s[26:27], s[8:9], 21
	s_add_u32 s30, s96, s26
	s_addc_u32 s31, s97, s27
	s_and_b64 s[26:27], s[4:5], exec
	s_cselect_b32 s8, s31, s39
	s_cselect_b32 s67, s30, s38
	s_add_u32 s26, s40, 0x100080
	s_addc_u32 s27, s41, 0
	s_mov_b32 m0, s53
	v_lshl_add_u64 v[66:67], s[26:27], 0, v[136:137]
	ds_read_b128 v[34:37], v152
	ds_read_b128 v[38:41], v152 offset:1024
	ds_read_b128 v[42:45], v152 offset:2048
	ds_read_b128 v[46:49], v152 offset:3072
	ds_read_b128 v[50:53], v152 offset:4096
	ds_read_b128 v[54:57], v152 offset:5120
	ds_read_b128 v[58:61], v152 offset:6144
	ds_read_b128 v[62:65], v152 offset:7168
	global_load_lds_dwordx4 v[66:67], off
	v_lshl_add_u64 v[66:67], s[26:27], 0, v[132:133]
	s_mov_b32 m0, s54
	s_nop 0
	global_load_lds_dwordx4 v[66:67], off
	s_waitcnt vmcnt(8)
	s_waitcnt lgkmcnt(0)
	s_setprio 1
	s_barrier
	v_mfma_f32_16x16x32_bf16 v[86:89], v[10:13], v[50:53], 0
	v_mfma_f32_16x16x32_bf16 v[90:93], v[14:17], v[54:57], v[86:89]
	v_mfma_f32_16x16x32_bf16 v[86:89], v[2:5], v[58:61], 0
	v_mfma_f32_16x16x32_bf16 v[66:69], v[2:5], v[34:37], 0
	v_mfma_f32_16x16x32_bf16 v[70:73], v[10:13], v[34:37], 0
	v_mfma_f32_16x16x32_bf16 v[74:77], v[2:5], v[42:45], 0
	v_mfma_f32_16x16x32_bf16 v[78:81], v[10:13], v[42:45], 0
	v_mfma_f32_16x16x32_bf16 v[82:85], v[2:5], v[50:53], 0
	v_mfma_f32_16x16x32_bf16 v[94:97], v[6:9], v[62:65], v[86:89]
	v_mfma_f32_16x16x32_bf16 v[86:89], v[10:13], v[58:61], 0
	v_mfma_f32_16x16x32_bf16 v[66:69], v[6:9], v[38:41], v[66:69]
	v_mfma_f32_16x16x32_bf16 v[70:73], v[14:17], v[38:41], v[70:73]
	v_mfma_f32_16x16x32_bf16 v[74:77], v[6:9], v[46:49], v[74:77]
	v_mfma_f32_16x16x32_bf16 v[78:81], v[14:17], v[46:49], v[78:81]
	v_mfma_f32_16x16x32_bf16 v[82:85], v[6:9], v[54:57], v[82:85]
	v_mfma_f32_16x16x32_bf16 v[106:109], v[14:17], v[62:65], v[86:89]
	s_setprio 0
	s_setprio 1
	v_mfma_f32_16x16x32_bf16 v[86:89], v[18:21], v[34:37], 0
	v_mfma_f32_16x16x32_bf16 v[34:37], v[26:29], v[34:37], 0
	v_mfma_f32_16x16x32_bf16 v[110:113], v[22:25], v[38:41], v[86:89]
	v_mfma_f32_16x16x32_bf16 v[34:37], v[30:33], v[38:41], v[34:37]
	v_mfma_f32_16x16x32_bf16 v[38:41], v[18:21], v[42:45], 0
	v_mfma_f32_16x16x32_bf16 v[42:45], v[26:29], v[42:45], 0
	v_mfma_f32_16x16x32_bf16 v[38:41], v[22:25], v[46:49], v[38:41]
	v_mfma_f32_16x16x32_bf16 v[42:45], v[30:33], v[46:49], v[42:45]
	v_mfma_f32_16x16x32_bf16 v[46:49], v[18:21], v[50:53], 0
	v_mfma_f32_16x16x32_bf16 v[50:53], v[26:29], v[50:53], 0
	v_mfma_f32_16x16x32_bf16 v[46:49], v[22:25], v[54:57], v[46:49]
	v_mfma_f32_16x16x32_bf16 v[50:53], v[30:33], v[54:57], v[50:53]
	v_mfma_f32_16x16x32_bf16 v[54:57], v[18:21], v[58:61], 0
	v_mfma_f32_16x16x32_bf16 v[58:61], v[26:29], v[58:61], 0
	v_mfma_f32_16x16x32_bf16 v[54:57], v[22:25], v[62:65], v[54:57]
	v_mfma_f32_16x16x32_bf16 v[58:61], v[30:33], v[62:65], v[58:61]
	s_barrier
	s_setprio 0
	v_lshl_add_u64 v[252:253], s[38:39], 0, v[134:135]
	s_mov_b32 m0, s59
	v_lshl_add_u64 v[146:147], v[252:253], 0, s[20:21]
	v_lshl_add_u64 v[142:143], s[38:39], 0, v[130:131]
	s_add_u32 s26, s38, 0x100100
	ds_read_b128 v[62:65], v152 offset:16384
	ds_read_b128 v[86:89], v152 offset:17408
	ds_read_b128 v[98:101], v152 offset:18432
	ds_read_b128 v[102:105], v152 offset:19456
	ds_read_b128 v[114:117], v152 offset:20480
	ds_read_b128 v[118:121], v152 offset:21504
	ds_read_b128 v[122:125], v152 offset:22528
	ds_read_b128 v[126:129], v152 offset:23552
	global_load_lds_dwordx4 v[146:147], off
	v_lshl_add_u64 v[146:147], v[142:143], 0, s[20:21]
	s_mov_b32 m0, s60
	s_addc_u32 s27, s39, 0
	global_load_lds_dwordx4 v[146:147], off
	v_lshl_add_u64 v[146:147], s[26:27], 0, v[134:135]
	s_mov_b32 m0, s61
	v_lshl_add_u64 v[144:145], s[40:41], 0, v[136:137]
	global_load_lds_dwordx4 v[146:147], off
	v_lshl_add_u64 v[146:147], s[26:27], 0, v[130:131]
	s_mov_b32 m0, s62
	v_lshl_add_u64 v[138:139], s[40:41], 0, v[132:133]
	global_load_lds_dwordx4 v[146:147], off
	v_lshl_add_u64 v[146:147], v[144:145], 0, s[20:21]
	s_mov_b32 m0, s13
	s_nop 0
	global_load_lds_dwordx4 v[146:147], off
	v_lshl_add_u64 v[146:147], v[138:139], 0, s[20:21]
	s_mov_b32 m0, s33
	s_nop 0
	global_load_lds_dwordx4 v[146:147], off
	s_waitcnt vmcnt(8)
	s_waitcnt lgkmcnt(0)
	s_setprio 1
	s_barrier
	v_mfma_f32_16x16x32_bf16 v[146:149], v[2:5], v[62:65], 0
	v_mfma_f32_16x16x32_bf16 v[156:159], v[6:9], v[86:89], v[146:149]
	v_mfma_f32_16x16x32_bf16 v[146:149], v[10:13], v[62:65], 0
	v_mfma_f32_16x16x32_bf16 v[160:163], v[14:17], v[86:89], v[146:149]
	v_mfma_f32_16x16x32_bf16 v[146:149], v[2:5], v[98:101], 0
	v_mfma_f32_16x16x32_bf16 v[164:167], v[6:9], v[102:105], v[146:149]
	v_mfma_f32_16x16x32_bf16 v[146:149], v[10:13], v[98:101], 0
	v_mfma_f32_16x16x32_bf16 v[168:171], v[14:17], v[102:105], v[146:149]
	v_mfma_f32_16x16x32_bf16 v[146:149], v[2:5], v[114:117], 0
	v_mfma_f32_16x16x32_bf16 v[2:5], v[2:5], v[122:125], 0
	v_mfma_f32_16x16x32_bf16 v[172:175], v[6:9], v[118:121], v[146:149]
	v_mfma_f32_16x16x32_bf16 v[2:5], v[6:9], v[126:129], v[2:5]
	v_mfma_f32_16x16x32_bf16 v[6:9], v[10:13], v[122:125], 0
	v_mfma_f32_16x16x32_bf16 v[146:149], v[10:13], v[114:117], 0
	v_mfma_f32_16x16x32_bf16 v[10:13], v[14:17], v[126:129], v[6:9]
	v_mfma_f32_16x16x32_bf16 v[176:179], v[14:17], v[118:121], v[146:149]
	s_setprio 0
	s_setprio 1
	v_mfma_f32_16x16x32_bf16 v[6:9], v[18:21], v[62:65], 0
	v_mfma_f32_16x16x32_bf16 v[14:17], v[22:25], v[86:89], v[6:9]
	v_mfma_f32_16x16x32_bf16 v[6:9], v[26:29], v[62:65], 0
	v_mfma_f32_16x16x32_bf16 v[180:183], v[30:33], v[86:89], v[6:9]
	v_mfma_f32_16x16x32_bf16 v[6:9], v[18:21], v[98:101], 0
	v_mfma_f32_16x16x32_bf16 v[184:187], v[22:25], v[102:105], v[6:9]
	v_mfma_f32_16x16x32_bf16 v[6:9], v[26:29], v[98:101], 0
	v_mfma_f32_16x16x32_bf16 v[188:191], v[30:33], v[102:105], v[6:9]
	v_mfma_f32_16x16x32_bf16 v[6:9], v[18:21], v[114:117], 0
	v_mfma_f32_16x16x32_bf16 v[192:195], v[22:25], v[118:121], v[6:9]
	v_mfma_f32_16x16x32_bf16 v[6:9], v[26:29], v[114:117], 0
	v_mfma_f32_16x16x32_bf16 v[196:199], v[30:33], v[118:121], v[6:9]
	v_mfma_f32_16x16x32_bf16 v[6:9], v[18:21], v[122:125], 0
	v_mfma_f32_16x16x32_bf16 v[200:203], v[22:25], v[126:129], v[6:9]
	v_mfma_f32_16x16x32_bf16 v[6:9], v[26:29], v[122:125], 0
	v_mfma_f32_16x16x32_bf16 v[204:207], v[30:33], v[126:129], v[6:9]
	s_barrier
	s_setprio 0
	s_add_i32 s56, 0, 0x1c000
	v_add_u32_e32 v146, s56, v155
	s_nop 2
	ds_read_b128 v[6:9], v154
	ds_read_b128 v[26:29], v154 offset:1024
	ds_read_b128 v[30:33], v154 offset:2048
	ds_read_b128 v[208:211], v154 offset:3072
	ds_read_b128 v[212:215], v146
	ds_read_b128 v[216:219], v146 offset:1024
	ds_read_b128 v[220:223], v146 offset:2048
	ds_read_b128 v[224:227], v146 offset:3072
	s_add_u32 s26, s40, 0x100100
	s_addc_u32 s27, s41, 0
	s_mov_b32 m0, s48
	v_lshl_add_u64 v[62:63], s[26:27], 0, v[136:137]
	ds_read_b128 v[18:21], v152 offset:32768
	ds_read_b128 v[22:25], v152 offset:33792
	ds_read_b128 v[228:231], v152 offset:34816
	ds_read_b128 v[232:235], v152 offset:35840
	ds_read_b128 v[236:239], v152 offset:36864
	ds_read_b128 v[240:243], v152 offset:37888
	ds_read_b128 v[244:247], v152 offset:38912
	ds_read_b128 v[248:251], v152 offset:39936
	global_load_lds_dwordx4 v[62:63], off
	v_lshl_add_u64 v[62:63], s[26:27], 0, v[132:133]
	s_mov_b32 m0, s49
	s_nop 0
	global_load_lds_dwordx4 v[62:63], off
	s_waitcnt vmcnt(8)
	s_waitcnt lgkmcnt(0)
	s_setprio 1
	s_barrier
	v_mfma_f32_16x16x32_bf16 v[62:65], v[6:9], v[18:21], v[66:69]
	v_mfma_f32_16x16x32_bf16 v[118:121], v[26:29], v[22:25], v[62:65]
	v_mfma_f32_16x16x32_bf16 v[62:65], v[30:33], v[18:21], v[70:73]
	v_mfma_f32_16x16x32_bf16 v[114:117], v[208:211], v[22:25], v[62:65]
	v_mfma_f32_16x16x32_bf16 v[62:65], v[6:9], v[228:231], v[74:77]
	v_mfma_f32_16x16x32_bf16 v[102:105], v[26:29], v[232:235], v[62:65]
	v_mfma_f32_16x16x32_bf16 v[62:65], v[30:33], v[228:231], v[78:81]
	v_mfma_f32_16x16x32_bf16 v[98:101], v[208:211], v[232:235], v[62:65]
	v_mfma_f32_16x16x32_bf16 v[62:65], v[6:9], v[236:239], v[82:85]
	v_mfma_f32_16x16x32_bf16 v[86:89], v[26:29], v[240:243], v[62:65]
	v_mfma_f32_16x16x32_bf16 v[62:65], v[30:33], v[236:239], v[90:93]
	v_mfma_f32_16x16x32_bf16 v[82:85], v[208:211], v[240:243], v[62:65]
	v_mfma_f32_16x16x32_bf16 v[62:65], v[6:9], v[244:247], v[94:97]
	v_mfma_f32_16x16x32_bf16 v[66:69], v[26:29], v[248:251], v[62:65]
	v_mfma_f32_16x16x32_bf16 v[62:65], v[30:33], v[244:247], v[106:109]
	v_mfma_f32_16x16x32_bf16 v[62:65], v[208:211], v[248:251], v[62:65]
	s_setprio 0
	s_setprio 1
	v_mfma_f32_16x16x32_bf16 v[70:73], v[212:215], v[18:21], v[110:113]
	v_mfma_f32_16x16x32_bf16 v[18:21], v[220:223], v[18:21], v[34:37]
	v_mfma_f32_16x16x32_bf16 v[122:125], v[224:227], v[22:25], v[18:21]
	v_mfma_f32_16x16x32_bf16 v[18:21], v[212:215], v[228:231], v[38:41]
	v_mfma_f32_16x16x32_bf16 v[110:113], v[216:219], v[232:235], v[18:21]
	v_mfma_f32_16x16x32_bf16 v[18:21], v[220:223], v[228:231], v[42:45]
	v_mfma_f32_16x16x32_bf16 v[106:109], v[224:227], v[232:235], v[18:21]
	v_mfma_f32_16x16x32_bf16 v[18:21], v[212:215], v[236:239], v[46:49]
	v_mfma_f32_16x16x32_bf16 v[94:97], v[216:219], v[240:243], v[18:21]
	v_mfma_f32_16x16x32_bf16 v[18:21], v[220:223], v[236:239], v[50:53]
	v_mfma_f32_16x16x32_bf16 v[90:93], v[224:227], v[240:243], v[18:21]
	v_mfma_f32_16x16x32_bf16 v[18:21], v[212:215], v[244:247], v[54:57]
	v_mfma_f32_16x16x32_bf16 v[78:81], v[216:219], v[248:251], v[18:21]
	v_mfma_f32_16x16x32_bf16 v[18:21], v[220:223], v[244:247], v[58:61]
	v_mfma_f32_16x16x32_bf16 v[126:129], v[216:219], v[22:25], v[70:73]
	v_mfma_f32_16x16x32_bf16 v[74:77], v[224:227], v[248:251], v[18:21]
	s_barrier
;     ...
;         PG8_KITER(0);
;         for (int t = 2; t < nt; t += 2) PG8_KITER(t);
	s_setprio 0
	s_add_i32 s46, s63, s10
	s_add_i32 s47, s46, 0x2000
	s_nop 1
	v_lshl_add_u64 v[18:19], v[252:253], 0, s[22:23]
	s_mov_b32 m0, s46
	s_add_u32 s26, s38, 0x100180
	ds_read_b128 v[42:45], v152 offset:49152
	ds_read_b128 v[46:49], v152 offset:50176
	ds_read_b128 v[228:231], v152 offset:51200
	ds_read_b128 v[232:235], v152 offset:52224
	ds_read_b128 v[236:239], v152 offset:53248
	ds_read_b128 v[240:243], v152 offset:54272
	ds_read_b128 v[244:247], v152 offset:55296
	ds_read_b128 v[248:251], v152 offset:56320
	global_load_lds_dwordx4 v[18:19], off
	v_lshl_add_u64 v[18:19], v[142:143], 0, s[22:23]
	s_mov_b32 m0, s47
	s_addc_u32 s27, s39, 0
	s_add_i32 s56, s56, s10
	global_load_lds_dwordx4 v[18:19], off
	v_lshl_add_u64 v[18:19], s[26:27], 0, v[134:135]
	s_mov_b32 m0, s56
	s_add_i32 s57, s56, 0x2000
	global_load_lds_dwordx4 v[18:19], off
	v_lshl_add_u64 v[18:19], s[26:27], 0, v[130:131]
	s_mov_b32 m0, s57
	s_nop 0
	global_load_lds_dwordx4 v[18:19], off
	v_lshl_add_u64 v[18:19], v[144:145], 0, s[22:23]
	s_mov_b32 m0, s50
	s_nop 0
	global_load_lds_dwordx4 v[18:19], off
	v_lshl_add_u64 v[18:19], v[138:139], 0, s[22:23]
	s_mov_b32 m0, s51
	s_nop 0
	global_load_lds_dwordx4 v[18:19], off
	s_waitcnt vmcnt(8)
	s_waitcnt lgkmcnt(0)
	s_setprio 1
	s_barrier
	v_mfma_f32_16x16x32_bf16 v[18:21], v[6:9], v[42:45], v[156:159]
	v_mfma_f32_16x16x32_bf16 v[54:57], v[26:29], v[46:49], v[18:21]
	v_mfma_f32_16x16x32_bf16 v[18:21], v[30:33], v[42:45], v[160:163]
	v_mfma_f32_16x16x32_bf16 v[50:53], v[208:211], v[46:49], v[18:21]
	v_mfma_f32_16x16x32_bf16 v[18:21], v[6:9], v[228:231], v[164:167]
	v_mfma_f32_16x16x32_bf16 v[38:41], v[26:29], v[232:235], v[18:21]
	v_mfma_f32_16x16x32_bf16 v[18:21], v[30:33], v[228:231], v[168:171]
	v_mfma_f32_16x16x32_bf16 v[34:37], v[208:211], v[232:235], v[18:21]
	v_mfma_f32_16x16x32_bf16 v[18:21], v[6:9], v[236:239], v[172:175]
	v_mfma_f32_16x16x32_bf16 v[2:5], v[6:9], v[244:247], v[2:5]
	v_mfma_f32_16x16x32_bf16 v[22:25], v[26:29], v[240:243], v[18:21]
	v_mfma_f32_16x16x32_bf16 v[18:21], v[30:33], v[236:239], v[176:179]
	v_mfma_f32_16x16x32_bf16 v[6:9], v[26:29], v[248:251], v[2:5]
	v_mfma_f32_16x16x32_bf16 v[2:5], v[30:33], v[244:247], v[10:13]
	v_mfma_f32_16x16x32_bf16 v[18:21], v[208:211], v[240:243], v[18:21]
	v_mfma_f32_16x16x32_bf16 v[2:5], v[208:211], v[248:251], v[2:5]
	s_setprio 0
	s_setprio 1
	v_mfma_f32_16x16x32_bf16 v[10:13], v[212:215], v[42:45], v[14:17]
	v_mfma_f32_16x16x32_bf16 v[70:73], v[216:219], v[46:49], v[10:13]
	v_mfma_f32_16x16x32_bf16 v[10:13], v[220:223], v[42:45], v[180:183]
	v_mfma_f32_16x16x32_bf16 v[58:61], v[224:227], v[46:49], v[10:13]
	v_mfma_f32_16x16x32_bf16 v[10:13], v[212:215], v[228:231], v[184:187]
	v_mfma_f32_16x16x32_bf16 v[46:49], v[216:219], v[232:235], v[10:13]
	v_mfma_f32_16x16x32_bf16 v[10:13], v[220:223], v[228:231], v[188:191]
	v_mfma_f32_16x16x32_bf16 v[42:45], v[224:227], v[232:235], v[10:13]
	v_mfma_f32_16x16x32_bf16 v[10:13], v[212:215], v[236:239], v[192:195]
	v_mfma_f32_16x16x32_bf16 v[30:33], v[216:219], v[240:243], v[10:13]
	v_mfma_f32_16x16x32_bf16 v[10:13], v[220:223], v[236:239], v[196:199]
	v_mfma_f32_16x16x32_bf16 v[26:29], v[224:227], v[240:243], v[10:13]
	v_mfma_f32_16x16x32_bf16 v[10:13], v[212:215], v[244:247], v[200:203]
	v_mfma_f32_16x16x32_bf16 v[14:17], v[216:219], v[248:251], v[10:13]
	v_mfma_f32_16x16x32_bf16 v[10:13], v[220:223], v[244:247], v[204:207]
	v_mfma_f32_16x16x32_bf16 v[10:13], v[224:227], v[248:251], v[10:13]
	s_barrier
	s_setprio 0
	s_add_u32 s40, s40, 0x100180
	s_addc_u32 s41, s41, 0
	s_add_u32 s26, s38, 0x200
	s_addc_u32 s27, s39, 0
	s_mov_b32 s68, 0
	.p2align	6

; #define PG8_STAGE(bufoff, gbase, voff) do { _Pragma("unroll") for (int _i = 0; _i < 2; ++_i) \
;         __builtin_amdgcn_global_load_lds((const unsigned*)((const char*)(gbase) + (voff)[_i]), (LAS unsigned*)(lds + (bufoff) + ldsw + _i * 8192), 16, 0, 0); } while (0)
; #define PG8_WAIT_V(n) asm volatile("s_waitcnt vmcnt(" #n ")" ::: "memory")
; #define PG8_BAR __builtin_amdgcn_s_barrier()
; #define PG8_TOUCH(p) asm volatile("global_load_dword %0, %1, off" : "+v"(pfd) : "v"(p) : "memory")
;     ...
;     for (int i = 0; i < 2; ++i) { int R, C; stage_rc(tid * 16 + i * 8192, R, C); const int Rb = Epi::PERM ? ((R & ~31) + perm32(R & 31)) : R;
;         voffA[i] = (unsigned)(R * g.lda + C) * 2u; voffB[i] = (unsigned)(Rb * g.ldb + C) * 2u; }
;     const size_t kstep = (size_t)(BK * 2);
;     const size_t hstepA = (size_t)HALF * g.lda * 2, hstepB = (size_t)HALF * g.ldb * 2;
;     const unsigned ldsw = (unsigned)wid * 1024u;
;     const int aoff = lds_byte(wr * 64 + fr, fq * 8), boff = lds_byte(wc * 32 + fr, fq * 8);
;     ...
;     PG8_STAGE(PG8_SB(0, 0), cB, voffB); PG8_STAGE(PG8_SB(0, 1), cB + hstepB, voffB); PG8_STAGE(PG8_SA(0, 0), cA, voffA); PG8_STAGE(PG8_SA(0, 1), cA + hstepA, voffA);
;     if (wr == 1) PG8_BAR;
;     PG8_WAIT_V(2); PG8_BAR;
;     PG8_STAGE(PG8_SB(1, 0), cB + kstep, voffB); PG8_STAGE(PG8_SA(1, 0), cA + kstep, voffA); PG8_STAGE(PG8_SB(1, 1), cB + hstepB + kstep, voffB);
;     PG8_WAIT_V(6); PG8_BAR;
;     if constexpr (PF > 0) { const char* p0 = PG8_PFPTR(cA, cB) + (size_t)(2 + PF) * kstep; PG8_TOUCH(p0); }
.LBB0_1411:
	s_mov_b64 s[8:9], 0x80
	s_lshl_b32 s1, s1, 12
	s_add_i32 m0, s28, 0x18000
	v_lshl_add_u64 v[8:9], v[8:9], 0, s[8:9]
	s_lshl_b32 s5, s5, 13
	s_and_b32 s1, s1, 0x3000
	s_waitcnt vmcnt(2)
	s_barrier
	global_load_lds_dwordx4 v[8:9], off
	v_lshl_add_u64 v[6:7], v[6:7], 0, s[8:9]
	s_add_i32 m0, s28, 0x1a000
	s_add_i32 s34, s28, 0x8000
	s_add_i32 s35, s28, 0xa000
	global_load_lds_dwordx4 v[6:7], off
	v_lshl_add_u64 v[2:3], v[2:3], 0, s[8:9]
	s_mov_b32 m0, s34
	s_add_u32 s10, s20, 0x2b0080
	global_load_lds_dwordx4 v[2:3], off
	v_lshl_add_u64 v[2:3], v[4:5], 0, s[8:9]
	s_mov_b32 m0, s35
	s_addc_u32 s11, s21, 0
	global_load_lds_dwordx4 v[2:3], off
	s_add_i32 m0, s28, 0x1c000
	v_lshl_add_u64 v[2:3], s[10:11], 0, v[132:133]
	global_load_lds_dwordx4 v[2:3], off
	v_lshl_add_u64 v[2:3], s[10:11], 0, v[136:137]
	s_add_i32 m0, s28, 0x1e000
	v_and_b32_e32 v0, 15, v1
	global_load_lds_dwordx4 v[2:3], off
	v_and_b32_e32 v2, 48, v1
	v_lshlrev_b32_e32 v1, 2, v1
	v_lshlrev_b32_e32 v0, 6, v0
	v_and_b32_e32 v1, 32, v1
	v_or_b32_e32 v3, v0, v2
	v_bitop3_b32 v0, v0, v1, v2 bitop3:0x36
	v_bitop3_b32 v4, v3, s5, v1 bitop3:0xde
	v_or_b32_e32 v1, s1, v0
	v_lshrrev_b32_e32 v2, 1, v10
	v_mul_lo_u32 v0, v12, s0
	s_mov_b32 s1, 0x2b000
	s_cmpk_lt_u32 s4, 0x100
	v_mad_u64_u32 v[2:3], s[4:5], v2, s1, v[0:1]
	v_or_b32_e32 v0, v2, v11
	v_add_lshl_u32 v2, v0, v13, 1
	v_mov_b32_e32 v3, v133
	s_mov_b64 s[4:5], 0x2b0180
	v_lshl_add_u64 v[138:139], v[2:3], 0, s[4:5]
	v_lshrrev_b32_e32 v2, 1, v14
	v_mul_lo_u32 v0, v15, s0
	v_mad_u64_u32 v[2:3], s[0:1], v2, s1, v[0:1]
	s_waitcnt vmcnt(6)
	v_or_b32_e32 v0, v2, v16
	s_cselect_b64 s[10:11], -1, 0
	v_add_lshl_u32 v2, v0, v17, 1
	v_mov_b32_e32 v3, v133
	s_add_i32 s39, 0, 0x10000
	s_add_i32 s40, 0, 0x14000
	s_ashr_i32 s38, s3, 31
	v_lshl_add_u64 v[140:141], v[2:3], 0, s[4:5]
	v_mov_b64_e32 v[144:145], 0x3ff
	v_add_u32_e32 v152, s39, v1
	v_add_u32_e32 v153, s40, v1
	v_add_u32_e32 v154, 0, v4
	s_mov_b64 s[12:13], 0x100
	s_mov_b64 s[14:15], 0x180
	s_barrier
	s_branch .LBB0_1414
	.p2align	6

;     __host__ __device__ bool next(int i, Unit& u) const { if (!StaticOrder::next(i >> 1, u)) return false; u.seg = i & 1; return true; }
;     ...
;         const bool has_next = S.next(ui + 1, nxt);
;         const char* nA = has_next ? PG8_APTR(nxt) : cA; const char* nB = has_next ? PG8_BPTR(nxt) : cB;
.LBB0_1424:
	ds_read_b128 v[2:5], v152
	ds_read_b128 v[6:9], v152 offset:1024
	ds_read_b128 v[10:13], v152 offset:2048
	ds_read_b128 v[14:17], v152 offset:3072
	ds_read_b128 v[18:21], v153
	ds_read_b128 v[22:25], v153 offset:1024
	ds_read_b128 v[26:29], v153 offset:2048
	ds_read_b128 v[30:33], v153 offset:3072
	s_add_u32 s22, s18, 0x2b0080
	s_addc_u32 s23, s19, 0
	s_add_i32 s49, s28, 0xc000
	v_lshl_add_u64 v[66:67], s[22:23], 0, v[130:131]
	s_mov_b32 m0, s49
	s_add_i32 s50, s28, 0xe000
	ds_read_b128 v[34:37], v154
	ds_read_b128 v[38:41], v154 offset:1024
	ds_read_b128 v[42:45], v154 offset:2048
	ds_read_b128 v[46:49], v154 offset:3072
	ds_read_b128 v[50:53], v154 offset:4096
	ds_read_b128 v[54:57], v154 offset:5120
	ds_read_b128 v[58:61], v154 offset:6144
	ds_read_b128 v[62:65], v154 offset:7168
	global_load_lds_dwordx4 v[66:67], off
	v_lshl_add_u64 v[66:67], s[22:23], 0, v[134:135]
	s_mov_b32 m0, s50
	s_nop 0
	global_load_lds_dwordx4 v[66:67], off
	s_waitcnt vmcnt(8)
	s_waitcnt lgkmcnt(0)
	s_setprio 1
	s_barrier
	v_mfma_f32_16x16x32_bf16 v[90:93], v[2:5], v[58:61], 0
	v_mfma_f32_16x16x32_bf16 v[66:69], v[2:5], v[34:37], 0
	v_mfma_f32_16x16x32_bf16 v[70:73], v[10:13], v[34:37], 0
	v_mfma_f32_16x16x32_bf16 v[74:77], v[2:5], v[42:45], 0
	v_mfma_f32_16x16x32_bf16 v[78:81], v[10:13], v[42:45], 0
	v_mfma_f32_16x16x32_bf16 v[82:85], v[2:5], v[50:53], 0
	v_mfma_f32_16x16x32_bf16 v[86:89], v[10:13], v[50:53], 0
	v_mfma_f32_16x16x32_bf16 v[98:101], v[6:9], v[62:65], v[90:93]
	v_mfma_f32_16x16x32_bf16 v[90:93], v[10:13], v[58:61], 0
	v_mfma_f32_16x16x32_bf16 v[66:69], v[6:9], v[38:41], v[66:69]
	v_mfma_f32_16x16x32_bf16 v[70:73], v[14:17], v[38:41], v[70:73]
	v_mfma_f32_16x16x32_bf16 v[74:77], v[6:9], v[46:49], v[74:77]
	v_mfma_f32_16x16x32_bf16 v[78:81], v[14:17], v[46:49], v[78:81]
	v_mfma_f32_16x16x32_bf16 v[82:85], v[6:9], v[54:57], v[82:85]
	v_mfma_f32_16x16x32_bf16 v[86:89], v[14:17], v[54:57], v[86:89]
	v_mfma_f32_16x16x32_bf16 v[102:105], v[14:17], v[62:65], v[90:93]
	s_setprio 0
	s_setprio 1
	v_mfma_f32_16x16x32_bf16 v[90:93], v[18:21], v[34:37], 0
	v_mfma_f32_16x16x32_bf16 v[34:37], v[26:29], v[34:37], 0
	v_mfma_f32_16x16x32_bf16 v[114:117], v[22:25], v[38:41], v[90:93]
	v_mfma_f32_16x16x32_bf16 v[34:37], v[30:33], v[38:41], v[34:37]
	v_mfma_f32_16x16x32_bf16 v[38:41], v[18:21], v[42:45], 0
	v_mfma_f32_16x16x32_bf16 v[42:45], v[26:29], v[42:45], 0
	v_mfma_f32_16x16x32_bf16 v[38:41], v[22:25], v[46:49], v[38:41]
	v_mfma_f32_16x16x32_bf16 v[42:45], v[30:33], v[46:49], v[42:45]
	v_mfma_f32_16x16x32_bf16 v[46:49], v[18:21], v[50:53], 0
	v_mfma_f32_16x16x32_bf16 v[50:53], v[26:29], v[50:53], 0
	v_mfma_f32_16x16x32_bf16 v[46:49], v[22:25], v[54:57], v[46:49]
	v_mfma_f32_16x16x32_bf16 v[50:53], v[30:33], v[54:57], v[50:53]
	v_mfma_f32_16x16x32_bf16 v[54:57], v[18:21], v[58:61], 0
	v_mfma_f32_16x16x32_bf16 v[58:61], v[26:29], v[58:61], 0
	v_mfma_f32_16x16x32_bf16 v[54:57], v[22:25], v[62:65], v[54:57]
	v_mfma_f32_16x16x32_bf16 v[58:61], v[30:33], v[62:65], v[58:61]
	s_barrier
	s_setprio 0
	s_add_i32 s51, s39, s25
	v_lshl_add_u64 v[248:249], s[20:21], 0, v[132:133]
	s_add_i32 s52, s51, 0x2000
	v_lshl_add_u64 v[146:147], v[248:249], 0, s[12:13]
	s_mov_b32 m0, s51
	v_lshl_add_u64 v[250:251], s[20:21], 0, v[136:137]
	s_add_u32 s22, s20, 0x2b0100
	ds_read_b128 v[62:65], v154 offset:16384
	ds_read_b128 v[90:93], v154 offset:17408
	ds_read_b128 v[94:97], v154 offset:18432
	ds_read_b128 v[106:109], v154 offset:19456
	ds_read_b128 v[110:113], v154 offset:20480
	ds_read_b128 v[118:121], v154 offset:21504
	ds_read_b128 v[122:125], v154 offset:22528
	ds_read_b128 v[126:129], v154 offset:23552
	global_load_lds_dwordx4 v[146:147], off
	v_lshl_add_u64 v[146:147], v[250:251], 0, s[12:13]
	s_mov_b32 m0, s52
	s_addc_u32 s23, s21, 0
	s_add_i32 s46, s40, s25
	global_load_lds_dwordx4 v[146:147], off
	v_lshl_add_u64 v[146:147], s[22:23], 0, v[132:133]
	s_mov_b32 m0, s46
	s_add_i32 s47, s46, 0x2000
	global_load_lds_dwordx4 v[146:147], off
	v_lshl_add_u64 v[146:147], s[22:23], 0, v[136:137]
	s_mov_b32 m0, s47
	v_lshl_add_u64 v[252:253], s[18:19], 0, v[130:131]
	global_load_lds_dwordx4 v[146:147], off
	v_lshl_add_u64 v[146:147], v[252:253], 0, s[12:13]
	s_mov_b32 m0, s28
	v_lshl_add_u64 v[142:143], s[18:19], 0, v[134:135]
	global_load_lds_dwordx4 v[146:147], off
	v_lshl_add_u64 v[146:147], v[142:143], 0, s[12:13]
	s_mov_b32 m0, s29
	s_nop 0
	global_load_lds_dwordx4 v[146:147], off
	s_waitcnt vmcnt(8)
	s_waitcnt lgkmcnt(0)
	s_setprio 1
	s_barrier
	v_mfma_f32_16x16x32_bf16 v[146:149], v[2:5], v[62:65], 0
	v_mfma_f32_16x16x32_bf16 v[160:163], v[2:5], v[94:97], 0
	v_mfma_f32_16x16x32_bf16 v[168:171], v[2:5], v[110:113], 0
	v_mfma_f32_16x16x32_bf16 v[2:5], v[2:5], v[122:125], 0
	v_mfma_f32_16x16x32_bf16 v[148:151], v[6:9], v[90:93], v[146:149]
	v_mfma_f32_16x16x32_bf16 v[160:163], v[6:9], v[106:109], v[160:163]
	v_mfma_f32_16x16x32_bf16 v[168:171], v[6:9], v[118:121], v[168:171]
	v_mfma_f32_16x16x32_bf16 v[2:5], v[6:9], v[126:129], v[2:5]
	v_mfma_f32_16x16x32_bf16 v[6:9], v[10:13], v[122:125], 0
	v_mfma_f32_16x16x32_bf16 v[156:159], v[10:13], v[62:65], 0
	v_mfma_f32_16x16x32_bf16 v[164:167], v[10:13], v[94:97], 0
	v_mfma_f32_16x16x32_bf16 v[172:175], v[10:13], v[110:113], 0
	v_mfma_f32_16x16x32_bf16 v[6:9], v[14:17], v[126:129], v[6:9]
	v_mfma_f32_16x16x32_bf16 v[156:159], v[14:17], v[90:93], v[156:159]
	v_mfma_f32_16x16x32_bf16 v[164:167], v[14:17], v[106:109], v[164:167]
	v_mfma_f32_16x16x32_bf16 v[172:175], v[14:17], v[118:121], v[172:175]
	s_setprio 0
	s_setprio 1
	v_mfma_f32_16x16x32_bf16 v[10:13], v[18:21], v[62:65], 0
	v_mfma_f32_16x16x32_bf16 v[176:179], v[22:25], v[90:93], v[10:13]
	v_mfma_f32_16x16x32_bf16 v[10:13], v[26:29], v[62:65], 0
	v_mfma_f32_16x16x32_bf16 v[180:183], v[30:33], v[90:93], v[10:13]
	v_mfma_f32_16x16x32_bf16 v[10:13], v[18:21], v[94:97], 0
	v_mfma_f32_16x16x32_bf16 v[184:187], v[22:25], v[106:109], v[10:13]
	v_mfma_f32_16x16x32_bf16 v[10:13], v[26:29], v[94:97], 0
	v_mfma_f32_16x16x32_bf16 v[188:191], v[30:33], v[106:109], v[10:13]
	v_mfma_f32_16x16x32_bf16 v[10:13], v[18:21], v[110:113], 0
	v_mfma_f32_16x16x32_bf16 v[192:195], v[22:25], v[118:121], v[10:13]
	v_mfma_f32_16x16x32_bf16 v[10:13], v[26:29], v[110:113], 0
	v_mfma_f32_16x16x32_bf16 v[196:199], v[30:33], v[118:121], v[10:13]
	v_mfma_f32_16x16x32_bf16 v[10:13], v[18:21], v[122:125], 0
	v_mfma_f32_16x16x32_bf16 v[200:203], v[22:25], v[126:129], v[10:13]
	v_mfma_f32_16x16x32_bf16 v[10:13], v[26:29], v[122:125], 0
	v_mfma_f32_16x16x32_bf16 v[204:207], v[30:33], v[126:129], v[10:13]
	s_barrier
;     ...
;         PG8_KITER(0);
;         for (int t = 2; t < nt; t += 2) PG8_KITER(t);
	s_setprio 0
	s_add_i32 s53, 0, 0x18000
	s_add_i32 s55, 0, 0x1c000
	v_add_u32_e32 v146, s53, v1
	v_add_u32_e32 v147, s55, v1
	s_nop 0
	ds_read_b128 v[10:13], v146
	ds_read_b128 v[14:17], v146 offset:1024
	ds_read_b128 v[18:21], v146 offset:2048
	ds_read_b128 v[22:25], v146 offset:3072
	ds_read_b128 v[208:211], v147
	ds_read_b128 v[212:215], v147 offset:1024
	ds_read_b128 v[216:219], v147 offset:2048
	ds_read_b128 v[220:223], v147 offset:3072
	s_add_u32 s22, s18, 0x2b0100
	s_addc_u32 s23, s19, 0
	s_mov_b32 m0, s30
	v_lshl_add_u64 v[90:91], s[22:23], 0, v[130:131]
	ds_read_b128 v[26:29], v154 offset:32768
	ds_read_b128 v[30:33], v154 offset:33792
	ds_read_b128 v[62:65], v154 offset:34816
	ds_read_b128 v[224:227], v154 offset:35840
	ds_read_b128 v[228:231], v154 offset:36864
	ds_read_b128 v[232:235], v154 offset:37888
	ds_read_b128 v[236:239], v154 offset:38912
	ds_read_b128 v[240:243], v154 offset:39936
	global_load_lds_dwordx4 v[90:91], off
	v_lshl_add_u64 v[90:91], s[22:23], 0, v[134:135]
	s_mov_b32 m0, s31
	s_nop 0
	global_load_lds_dwordx4 v[90:91], off
	s_waitcnt vmcnt(8)
	s_waitcnt lgkmcnt(0)
	s_setprio 1
	s_barrier
	v_mfma_f32_16x16x32_bf16 v[66:69], v[10:13], v[26:29], v[66:69]
	v_mfma_f32_16x16x32_bf16 v[126:129], v[14:17], v[30:33], v[66:69]
	v_mfma_f32_16x16x32_bf16 v[66:69], v[18:21], v[26:29], v[70:73]
	v_mfma_f32_16x16x32_bf16 v[122:125], v[22:25], v[30:33], v[66:69]
	v_mfma_f32_16x16x32_bf16 v[66:69], v[10:13], v[62:65], v[74:77]
	v_mfma_f32_16x16x32_bf16 v[110:113], v[14:17], v[224:227], v[66:69]
	v_mfma_f32_16x16x32_bf16 v[66:69], v[18:21], v[62:65], v[78:81]
	v_mfma_f32_16x16x32_bf16 v[106:109], v[22:25], v[224:227], v[66:69]
	v_mfma_f32_16x16x32_bf16 v[66:69], v[10:13], v[228:231], v[82:85]
	v_mfma_f32_16x16x32_bf16 v[94:97], v[14:17], v[232:235], v[66:69]
	v_mfma_f32_16x16x32_bf16 v[66:69], v[18:21], v[228:231], v[86:89]
	v_mfma_f32_16x16x32_bf16 v[90:93], v[22:25], v[232:235], v[66:69]
	v_mfma_f32_16x16x32_bf16 v[66:69], v[10:13], v[236:239], v[98:101]
	v_mfma_f32_16x16x32_bf16 v[78:81], v[14:17], v[240:243], v[66:69]
	v_mfma_f32_16x16x32_bf16 v[66:69], v[18:21], v[236:239], v[102:105]
	v_mfma_f32_16x16x32_bf16 v[74:77], v[22:25], v[240:243], v[66:69]
	s_setprio 0
	s_setprio 1
	v_mfma_f32_16x16x32_bf16 v[66:69], v[208:211], v[26:29], v[114:117]
	v_mfma_f32_16x16x32_bf16 v[26:29], v[216:219], v[26:29], v[34:37]
	v_mfma_f32_16x16x32_bf16 v[114:117], v[220:223], v[30:33], v[26:29]
	v_mfma_f32_16x16x32_bf16 v[26:29], v[208:211], v[62:65], v[38:41]
	v_mfma_f32_16x16x32_bf16 v[102:105], v[212:215], v[224:227], v[26:29]
	v_mfma_f32_16x16x32_bf16 v[26:29], v[216:219], v[62:65], v[42:45]
	v_mfma_f32_16x16x32_bf16 v[98:101], v[220:223], v[224:227], v[26:29]
	v_mfma_f32_16x16x32_bf16 v[26:29], v[208:211], v[228:231], v[46:49]
	v_mfma_f32_16x16x32_bf16 v[86:89], v[212:215], v[232:235], v[26:29]
	v_mfma_f32_16x16x32_bf16 v[26:29], v[216:219], v[228:231], v[50:53]
	v_mfma_f32_16x16x32_bf16 v[82:85], v[220:223], v[232:235], v[26:29]
	v_mfma_f32_16x16x32_bf16 v[26:29], v[208:211], v[236:239], v[54:57]
	v_mfma_f32_16x16x32_bf16 v[70:73], v[212:215], v[240:243], v[26:29]
	v_mfma_f32_16x16x32_bf16 v[26:29], v[216:219], v[236:239], v[58:61]
	v_mfma_f32_16x16x32_bf16 v[118:121], v[212:215], v[30:33], v[66:69]
	v_mfma_f32_16x16x32_bf16 v[66:69], v[220:223], v[240:243], v[26:29]
	s_barrier
	s_setprio 0
	s_add_i32 s53, s53, s25
	s_add_i32 s54, s53, 0x2000
	s_nop 1
	v_lshl_add_u64 v[26:27], v[248:249], 0, s[14:15]
	s_mov_b32 m0, s53
	s_add_u32 s22, s20, 0x2b0180
	ds_read_b128 v[34:37], v154 offset:49152
	ds_read_b128 v[38:41], v154 offset:50176
	ds_read_b128 v[224:227], v154 offset:51200
	ds_read_b128 v[228:231], v154 offset:52224
	ds_read_b128 v[232:235], v154 offset:53248
	ds_read_b128 v[236:239], v154 offset:54272
	ds_read_b128 v[240:243], v154 offset:55296
	ds_read_b128 v[244:247], v154 offset:56320
	global_load_lds_dwordx4 v[26:27], off
	v_lshl_add_u64 v[26:27], v[250:251], 0, s[14:15]
	s_mov_b32 m0, s54
	s_addc_u32 s23, s21, 0
	s_add_i32 s55, s55, s25
	global_load_lds_dwordx4 v[26:27], off
	v_lshl_add_u64 v[26:27], s[22:23], 0, v[132:133]
	s_mov_b32 m0, s55
	s_add_i32 s56, s55, 0x2000
	global_load_lds_dwordx4 v[26:27], off
	v_lshl_add_u64 v[26:27], s[22:23], 0, v[136:137]
	s_mov_b32 m0, s56
	s_nop 0
	global_load_lds_dwordx4 v[26:27], off
	v_lshl_add_u64 v[26:27], v[252:253], 0, s[14:15]
	s_mov_b32 m0, s34
	s_nop 0
	global_load_lds_dwordx4 v[26:27], off
	v_lshl_add_u64 v[26:27], v[142:143], 0, s[14:15]
	s_mov_b32 m0, s35
	s_nop 0
	global_load_lds_dwordx4 v[26:27], off
	s_waitcnt vmcnt(8)
	s_waitcnt lgkmcnt(0)
	s_setprio 1
	s_barrier
	v_mfma_f32_16x16x32_bf16 v[26:29], v[10:13], v[34:37], v[148:151]
	v_mfma_f32_16x16x32_bf16 v[62:65], v[14:17], v[38:41], v[26:29]
	v_mfma_f32_16x16x32_bf16 v[26:29], v[18:21], v[34:37], v[156:159]
	v_mfma_f32_16x16x32_bf16 v[58:61], v[22:25], v[38:41], v[26:29]
	v_mfma_f32_16x16x32_bf16 v[26:29], v[10:13], v[224:227], v[160:163]
	v_mfma_f32_16x16x32_bf16 v[46:49], v[14:17], v[228:231], v[26:29]
	v_mfma_f32_16x16x32_bf16 v[26:29], v[18:21], v[224:227], v[164:167]
	v_mfma_f32_16x16x32_bf16 v[42:45], v[22:25], v[228:231], v[26:29]
	v_mfma_f32_16x16x32_bf16 v[26:29], v[10:13], v[232:235], v[168:171]
	v_mfma_f32_16x16x32_bf16 v[2:5], v[10:13], v[240:243], v[2:5]
	v_mfma_f32_16x16x32_bf16 v[30:33], v[14:17], v[236:239], v[26:29]
	v_mfma_f32_16x16x32_bf16 v[26:29], v[18:21], v[232:235], v[172:175]
	v_mfma_f32_16x16x32_bf16 v[14:17], v[14:17], v[244:247], v[2:5]
	v_mfma_f32_16x16x32_bf16 v[2:5], v[18:21], v[240:243], v[6:9]
	v_mfma_f32_16x16x32_bf16 v[26:29], v[22:25], v[236:239], v[26:29]
	v_mfma_f32_16x16x32_bf16 v[10:13], v[22:25], v[244:247], v[2:5]
	s_setprio 0
	s_setprio 1
	v_mfma_f32_16x16x32_bf16 v[2:5], v[208:211], v[34:37], v[176:179]
	v_mfma_f32_16x16x32_bf16 v[54:57], v[212:215], v[38:41], v[2:5]
	v_mfma_f32_16x16x32_bf16 v[2:5], v[216:219], v[34:37], v[180:183]
	v_mfma_f32_16x16x32_bf16 v[50:53], v[220:223], v[38:41], v[2:5]
	v_mfma_f32_16x16x32_bf16 v[2:5], v[208:211], v[224:227], v[184:187]
	v_mfma_f32_16x16x32_bf16 v[38:41], v[212:215], v[228:231], v[2:5]
	v_mfma_f32_16x16x32_bf16 v[2:5], v[216:219], v[224:227], v[188:191]
	v_mfma_f32_16x16x32_bf16 v[34:37], v[220:223], v[228:231], v[2:5]
	v_mfma_f32_16x16x32_bf16 v[2:5], v[208:211], v[232:235], v[192:195]
	v_mfma_f32_16x16x32_bf16 v[22:25], v[212:215], v[236:239], v[2:5]
	v_mfma_f32_16x16x32_bf16 v[2:5], v[216:219], v[232:235], v[196:199]
	v_mfma_f32_16x16x32_bf16 v[18:21], v[220:223], v[236:239], v[2:5]
	v_mfma_f32_16x16x32_bf16 v[2:5], v[208:211], v[240:243], v[200:203]
	v_mfma_f32_16x16x32_bf16 v[6:9], v[212:215], v[244:247], v[2:5]
	v_mfma_f32_16x16x32_bf16 v[2:5], v[216:219], v[240:243], v[204:207]
	v_mfma_f32_16x16x32_bf16 v[2:5], v[220:223], v[244:247], v[2:5]
	s_barrier
	s_setprio 0
	s_add_u32 s26, s20, 0x200
	s_addc_u32 s27, s21, 0
	s_mov_b32 s57, 0
	.p2align	6
